# GEMM load segments: first LDS-DMA issued right after the first LDS read (interleaving TA work with the remaining fragment reads)
# speedup vs baseline: 1.0077x; 1.0067x over previous
; #define PG8_STAGE(bufoff, gbase, voff) do { _Pragma("unroll") for (int _i = 0; _i < 2; ++_i) \
;         __builtin_amdgcn_global_load_lds((const unsigned*)((const char*)(gbase) + (voff)[_i]), (LAS unsigned*)(lds + (bufoff) + ldsw + _i * 8192), 16, 0, 0); } while (0)
; #define PG8_LDA(dst, b, h) do { _Pragma("unroll") for (int m = 0; m < 4; ++m) _Pragma("unroll") for (int k = 0; k < 2; ++k) dst[m][k] = *(const LAS bf16x8*)(lds + PG8_SA(b, h) + aoff + m * 2048 + k * 1024); } while (0)
; #define PG8_LDB(dst, b, h) do { _Pragma("unroll") for (int n = 0; n < 2; ++n) _Pragma("unroll") for (int k = 0; k < 2; ++k) dst[n][k] = *(const LAS bf16x8*)(lds + PG8_SB(b, h) + boff + n * 2048 + k * 1024); } while (0)
; #define PG8_MMA(ai, bj, At, Bt) do { __builtin_amdgcn_s_setprio(1); _Pragma("unroll") for (int m = 0; m < 4; ++m) _Pragma("unroll") for (int n = 0; n < 2; ++n) _Pragma("unroll") for (int k = 0; k < 2; ++k) \
;         acc[ai][bj][m][n] = __builtin_amdgcn_mfma_f32_16x16x32_bf16(Bt[n][k], At[m][k], acc[ai][bj][m][n], 0, 0, 0); __builtin_amdgcn_s_setprio(0); } while (0)
; #define PG8_WAIT_V(n) asm volatile("s_waitcnt vmcnt(" #n ")" ::: "memory")
; #define PG8_WAIT_L(n) asm volatile("s_waitcnt lgkmcnt(" #n ")" ::: "memory")
; template <class Map, class Epi>
; DI void gemm_phase(LAS unsigned char* lds, const Map& MP, const Epi& E, const int nM, const int nN, const int K, const int lda, const int ldb) {
;     ...
;         for (int t = 0; t < nt; t += 2) {
;             const bool last = (t == nt - 2);
;             const char* a1 = cA + (size_t)(t + 1) * kstep;
;             const char* a2 = last ? nA : cA + (size_t)(t + 2) * kstep; const char* b2 = last ? nB : cB + (size_t)(t + 2) * kstep;
;             const char* a3 = a2 + kstep; const char* b3 = b2 + kstep;
;             PG8_LDB(B0, 0, 0); PG8_SCHED; PG8_LDA(At, 0, 0); PG8_STAGE(PG8_SA(1, 1), a1 + hstepA, voffA);
;             PG8_WAIT_L(8); PG8_BAR; PG8_WAIT_L(0); PG8_MMA(0, 0, At, B0); PG8_BAR; PG8_SCHED;
;             PG8_LDB(B1, 0, 1); PG8_STAGE(PG8_SB(0, 0), b2, voffB);
;             PG8_BAR; PG8_WAIT_L(0); PG8_MMA(0, 1, At, B1); PG8_BAR;
;             PG8_LDA(At, 0, 1); PG8_STAGE(PG8_SA(0, 0), a2, voffA);
;             PG8_BAR; PG8_WAIT_L(0); PG8_MMA(1, 0, At, B0); PG8_BAR; PG8_SCHED;
;             PG8_STAGE(PG8_SB(0, 1), b2 + hstepB, voffB);
;             PG8_WAIT_V(6); PG8_BAR; PG8_MMA(1, 1, At, B1); PG8_BAR;
.LBB1_229:
	s_add_u32 s26, s24, 0xfff80080
	s_addc_u32 s27, s25, -1
	s_cmp_eq_u32 s57, 4
	s_cselect_b32 s29, s17, s27
	s_cselect_b32 s28, s43, s26
	s_cselect_b32 s27, s53, s56
	s_cselect_b32 s26, s54, s55
	s_add_i32 m0, s2, 0xc000
	ds_read_b128 v[160:163], v168
	global_load_lds_dwordx4 v154, s[24:25]
	ds_read_b128 v[170:173], v168 offset:1024
	ds_read_b128 v[174:177], v168 offset:2048
	ds_read_b128 v[178:181], v168 offset:3072
	ds_read_b128 v[182:185], v168 offset:4096
	ds_read_b128 v[186:189], v168 offset:5120
	ds_read_b128 v[190:193], v168 offset:6144
	ds_read_b128 v[198:201], v168 offset:7168
	s_add_i32 m0, s2, 0xe000
	s_nop 0
	global_load_lds_dwordx4 v152, s[24:25]
	s_waitcnt lgkmcnt(8)
	s_setprio 1
	s_barrier
	s_waitcnt lgkmcnt(7)
	v_mfma_f32_16x16x32_bf16 v[140:143], v[72:75], v[160:163], v[140:143]
	v_mfma_f32_16x16x32_bf16 v[136:139], v[80:83], v[160:163], v[136:139]
	s_waitcnt lgkmcnt(5)
	v_mfma_f32_16x16x32_bf16 v[124:127], v[72:75], v[174:177], v[124:127]
	v_mfma_f32_16x16x32_bf16 v[120:123], v[80:83], v[174:177], v[120:123]
	s_waitcnt lgkmcnt(3)
	v_mfma_f32_16x16x32_bf16 v[108:111], v[72:75], v[182:185], v[108:111]
	v_mfma_f32_16x16x32_bf16 v[104:107], v[80:83], v[182:185], v[104:107]
	s_waitcnt lgkmcnt(1)
	v_mfma_f32_16x16x32_bf16 v[92:95], v[72:75], v[190:193], v[92:95]
	v_mfma_f32_16x16x32_bf16 v[88:91], v[80:83], v[190:193], v[88:91]
	v_mfma_f32_16x16x32_bf16 v[140:143], v[76:79], v[170:173], v[140:143]
	s_add_i32 s58, s48, s34
	v_mfma_f32_16x16x32_bf16 v[136:139], v[84:87], v[170:173], v[136:139]
	v_lshl_add_u64 v[194:195], s[26:27], 0, v[148:149]
	v_mfma_f32_16x16x32_bf16 v[124:127], v[76:79], v[178:181], v[124:127]
	v_lshl_add_u64 v[218:219], s[26:27], 0, v[144:145]
	v_mfma_f32_16x16x32_bf16 v[120:123], v[84:87], v[178:181], v[120:123]
	v_mfma_f32_16x16x32_bf16 v[108:111], v[76:79], v[186:189], v[108:111]
	v_mfma_f32_16x16x32_bf16 v[104:107], v[84:87], v[186:189], v[104:107]
	s_waitcnt lgkmcnt(0)
	v_mfma_f32_16x16x32_bf16 v[92:95], v[76:79], v[198:201], v[92:95]
	v_mfma_f32_16x16x32_bf16 v[88:91], v[84:87], v[198:201], v[88:91]
	s_barrier
	s_setprio 0
	s_mov_b32 m0, s58
	ds_read_b128 v[202:205], v169
	global_load_lds_dwordx4 v[194:195], off
	ds_read_b128 v[206:209], v169 offset:1024
	ds_read_b128 v[210:213], v169 offset:2048
	ds_read_b128 v[214:217], v169 offset:3072
	s_add_i32 m0, s58, 0x2000
	s_nop 0
	global_load_lds_dwordx4 v[218:219], off
	s_setprio 1
	s_barrier
	s_waitcnt lgkmcnt(3)
	v_mfma_f32_16x16x32_bf16 v[132:135], v[202:205], v[160:163], v[132:135]
	s_waitcnt lgkmcnt(1)
	v_mfma_f32_16x16x32_bf16 v[128:131], v[210:213], v[160:163], v[128:131]
	v_mfma_f32_16x16x32_bf16 v[116:119], v[202:205], v[174:177], v[116:119]
	v_mfma_f32_16x16x32_bf16 v[112:115], v[210:213], v[174:177], v[112:115]
	v_mfma_f32_16x16x32_bf16 v[100:103], v[202:205], v[182:185], v[100:103]
	v_mfma_f32_16x16x32_bf16 v[96:99], v[210:213], v[182:185], v[96:99]
	v_mfma_f32_16x16x32_bf16 v[68:71], v[202:205], v[190:193], v[68:71]
	v_mfma_f32_16x16x32_bf16 v[64:67], v[210:213], v[190:193], v[64:67]
	v_mfma_f32_16x16x32_bf16 v[132:135], v[206:209], v[170:173], v[132:135]
	v_lshl_add_u64 v[222:223], s[28:29], 0, v[146:147]
	s_mov_b32 m0, s2
	s_waitcnt lgkmcnt(0)
	v_mfma_f32_16x16x32_bf16 v[128:131], v[214:217], v[170:173], v[128:131]
	v_lshl_add_u64 v[220:221], s[28:29], 0, v[150:151]
	v_mfma_f32_16x16x32_bf16 v[116:119], v[206:209], v[178:181], v[116:119]
	v_mfma_f32_16x16x32_bf16 v[112:115], v[214:217], v[178:181], v[112:115]
	v_mfma_f32_16x16x32_bf16 v[100:103], v[206:209], v[186:189], v[100:103]
	v_mfma_f32_16x16x32_bf16 v[96:99], v[214:217], v[186:189], v[96:99]
	v_mfma_f32_16x16x32_bf16 v[68:71], v[206:209], v[198:201], v[68:71]
	v_mfma_f32_16x16x32_bf16 v[64:67], v[214:217], v[198:201], v[64:67]
	s_barrier
	s_setprio 0
	ds_read_b128 v[160:163], v168 offset:16384
	global_load_lds_dwordx4 v[220:221], off
	ds_read_b128 v[170:173], v168 offset:17408
	ds_read_b128 v[174:177], v168 offset:18432
	ds_read_b128 v[178:181], v168 offset:19456
	ds_read_b128 v[182:185], v168 offset:20480
	ds_read_b128 v[186:189], v168 offset:21504
	ds_read_b128 v[190:193], v168 offset:22528
	ds_read_b128 v[198:201], v168 offset:23552
	s_mov_b32 m0, s4
	s_nop 0
	global_load_lds_dwordx4 v[222:223], off
	s_waitcnt vmcnt(10)
	s_setprio 1
	s_barrier
	s_waitcnt lgkmcnt(7)
	v_mfma_f32_16x16x32_bf16 v[60:63], v[72:75], v[160:163], v[60:63]
	v_mfma_f32_16x16x32_bf16 v[56:59], v[80:83], v[160:163], v[56:59]
	s_waitcnt lgkmcnt(5)
	v_mfma_f32_16x16x32_bf16 v[44:47], v[72:75], v[174:177], v[44:47]
	v_mfma_f32_16x16x32_bf16 v[40:43], v[80:83], v[174:177], v[40:43]
	s_waitcnt lgkmcnt(3)
	v_mfma_f32_16x16x32_bf16 v[28:31], v[72:75], v[182:185], v[28:31]
	v_mfma_f32_16x16x32_bf16 v[24:27], v[80:83], v[182:185], v[24:27]
	s_waitcnt lgkmcnt(1)
	v_mfma_f32_16x16x32_bf16 v[12:15], v[72:75], v[190:193], v[12:15]
	v_mfma_f32_16x16x32_bf16 v[8:11], v[80:83], v[190:193], v[8:11]
	v_mfma_f32_16x16x32_bf16 v[60:63], v[76:79], v[170:173], v[60:63]
	s_add_u32 s58, s26, 0x20000
	s_addc_u32 s59, s27, 0
	v_mfma_f32_16x16x32_bf16 v[56:59], v[84:87], v[170:173], v[56:59]
	s_add_i32 s60, s49, s34
	v_mfma_f32_16x16x32_bf16 v[44:47], v[76:79], v[178:181], v[44:47]
	v_mfma_f32_16x16x32_bf16 v[40:43], v[84:87], v[178:181], v[40:43]
	v_mfma_f32_16x16x32_bf16 v[28:31], v[76:79], v[186:189], v[28:31]
	v_mfma_f32_16x16x32_bf16 v[24:27], v[84:87], v[186:189], v[24:27]
	s_waitcnt lgkmcnt(0)
	v_mfma_f32_16x16x32_bf16 v[12:15], v[76:79], v[198:201], v[12:15]
	v_mfma_f32_16x16x32_bf16 v[8:11], v[84:87], v[198:201], v[8:11]
	s_barrier
; #define PG8_STAGE(bufoff, gbase, voff) do { _Pragma("unroll") for (int _i = 0; _i < 2; ++_i) \
;         __builtin_amdgcn_global_load_lds((const unsigned*)((const char*)(gbase) + (voff)[_i]), (LAS unsigned*)(lds + (bufoff) + ldsw + _i * 8192), 16, 0, 0); } while (0)
; #define PG8_LDA(dst, b, h) do { _Pragma("unroll") for (int m = 0; m < 4; ++m) _Pragma("unroll") for (int k = 0; k < 2; ++k) dst[m][k] = *(const LAS bf16x8*)(lds + PG8_SA(b, h) + aoff + m * 2048 + k * 1024); } while (0)
; #define PG8_LDB(dst, b, h) do { _Pragma("unroll") for (int n = 0; n < 2; ++n) _Pragma("unroll") for (int k = 0; k < 2; ++k) dst[n][k] = *(const LAS bf16x8*)(lds + PG8_SB(b, h) + boff + n * 2048 + k * 1024); } while (0)
; #define PG8_MMA(ai, bj, At, Bt) do { __builtin_amdgcn_s_setprio(1); _Pragma("unroll") for (int m = 0; m < 4; ++m) _Pragma("unroll") for (int n = 0; n < 2; ++n) _Pragma("unroll") for (int k = 0; k < 2; ++k) \
;         acc[ai][bj][m][n] = __builtin_amdgcn_mfma_f32_16x16x32_bf16(Bt[n][k], At[m][k], acc[ai][bj][m][n], 0, 0, 0); __builtin_amdgcn_s_setprio(0); } while (0)
; #define PG8_WAIT_V(n) asm volatile("s_waitcnt vmcnt(" #n ")" ::: "memory")
; #define PG8_WAIT_L(n) asm volatile("s_waitcnt lgkmcnt(" #n ")" ::: "memory")
; #define PG8_BAR __builtin_amdgcn_s_barrier()
; #define PG8_SCHED __builtin_amdgcn_sched_barrier(0)
; template <class Map, class Epi>
; DI void gemm_phase(LAS unsigned char* lds, const Map& MP, const Epi& E, const int nM, const int nN, const int K, const int lda, const int ldb) {
;     ...
;             PG8_WAIT_V(6); PG8_BAR; PG8_MMA(1, 1, At, B1); PG8_BAR;
;             PG8_LDB(B0, 1, 0); PG8_SCHED; PG8_LDA(At, 1, 0); PG8_STAGE(PG8_SA(0, 1), a2 + hstepA, voffA);
;             PG8_WAIT_L(8); PG8_BAR; PG8_WAIT_L(0); PG8_MMA(0, 0, At, B0); PG8_BAR; PG8_SCHED;
;             PG8_LDB(B1, 1, 1); PG8_STAGE(PG8_SB(1, 0), b3, voffB);
;             PG8_BAR; PG8_WAIT_L(0); PG8_MMA(0, 1, At, B1); PG8_BAR;
;             PG8_LDA(At, 1, 1); PG8_STAGE(PG8_SA(1, 0), a3, voffA);
;             PG8_BAR; PG8_WAIT_L(0); PG8_MMA(1, 0, At, B0); PG8_BAR; PG8_SCHED;
	s_setprio 0
	s_mov_b32 m0, s60
	s_nop 0
	global_load_lds_dwordx4 v148, s[58:59]
	s_add_i32 m0, s60, 0x2000
	s_nop 0
	global_load_lds_dwordx4 v144, s[58:59]
	s_waitcnt vmcnt(6)
	s_setprio 1
	s_barrier
	v_mfma_f32_16x16x32_bf16 v[52:55], v[202:205], v[160:163], v[52:55]
	v_mfma_f32_16x16x32_bf16 v[48:51], v[210:213], v[160:163], v[48:51]
	s_add_i32 s58, 0, 0x18000
	v_add_u32_e32 v84, s58, v166
	ds_read_b128 v[72:75], v84
	v_mfma_f32_16x16x32_bf16 v[36:39], v[202:205], v[174:177], v[36:39]
	v_mfma_f32_16x16x32_bf16 v[32:35], v[210:213], v[174:177], v[32:35]
	ds_read_b128 v[76:79], v84 offset:1024
	v_mfma_f32_16x16x32_bf16 v[20:23], v[202:205], v[182:185], v[20:23]
	v_mfma_f32_16x16x32_bf16 v[16:19], v[210:213], v[182:185], v[16:19]
	ds_read_b128 v[80:83], v84 offset:2048
	v_mfma_f32_16x16x32_bf16 v[4:7], v[202:205], v[190:193], v[4:7]
	v_mfma_f32_16x16x32_bf16 v[0:3], v[210:213], v[190:193], v[0:3]
	ds_read_b128 v[84:87], v84 offset:3072
	v_mfma_f32_16x16x32_bf16 v[52:55], v[206:209], v[170:173], v[52:55]
	s_add_u32 s28, s28, 0x80000
	s_addc_u32 s29, s29, 0
	v_mfma_f32_16x16x32_bf16 v[48:51], v[214:217], v[170:173], v[48:51]
	v_mfma_f32_16x16x32_bf16 v[36:39], v[206:209], v[178:181], v[36:39]
	v_mfma_f32_16x16x32_bf16 v[32:35], v[214:217], v[178:181], v[32:35]
	v_mfma_f32_16x16x32_bf16 v[20:23], v[206:209], v[186:189], v[20:23]
	v_mfma_f32_16x16x32_bf16 v[16:19], v[214:217], v[186:189], v[16:19]
	v_mfma_f32_16x16x32_bf16 v[4:7], v[206:209], v[198:201], v[4:7]
	v_mfma_f32_16x16x32_bf16 v[0:3], v[214:217], v[198:201], v[0:3]
	s_barrier
	s_setprio 0
	s_mov_b32 m0, s5
	ds_read_b128 v[160:163], v168 offset:32768
	global_load_lds_dwordx4 v150, s[28:29]
	ds_read_b128 v[170:173], v168 offset:33792
	ds_read_b128 v[174:177], v168 offset:34816
	ds_read_b128 v[178:181], v168 offset:35840
	ds_read_b128 v[182:185], v168 offset:36864
	ds_read_b128 v[186:189], v168 offset:37888
	ds_read_b128 v[190:193], v168 offset:38912
	ds_read_b128 v[198:201], v168 offset:39936
	s_mov_b32 m0, s23
	s_nop 0
	global_load_lds_dwordx4 v146, s[28:29]
	s_waitcnt lgkmcnt(8)
	s_setprio 1
	s_barrier
	s_waitcnt lgkmcnt(7)
	v_mfma_f32_16x16x32_bf16 v[140:143], v[72:75], v[160:163], v[140:143]
	v_mfma_f32_16x16x32_bf16 v[136:139], v[80:83], v[160:163], v[136:139]
	s_waitcnt lgkmcnt(5)
	v_mfma_f32_16x16x32_bf16 v[124:127], v[72:75], v[174:177], v[124:127]
	v_mfma_f32_16x16x32_bf16 v[120:123], v[80:83], v[174:177], v[120:123]
	s_waitcnt lgkmcnt(3)
	v_mfma_f32_16x16x32_bf16 v[108:111], v[72:75], v[182:185], v[108:111]
	v_mfma_f32_16x16x32_bf16 v[104:107], v[80:83], v[182:185], v[104:107]
	s_waitcnt lgkmcnt(1)
	v_mfma_f32_16x16x32_bf16 v[92:95], v[72:75], v[190:193], v[92:95]
	v_mfma_f32_16x16x32_bf16 v[88:91], v[80:83], v[190:193], v[88:91]
	v_mfma_f32_16x16x32_bf16 v[140:143], v[76:79], v[170:173], v[140:143]
	s_add_i32 s28, 0, 0x1c000
	v_mfma_f32_16x16x32_bf16 v[136:139], v[84:87], v[170:173], v[136:139]
	s_add_i32 s29, s58, s34
	v_mfma_f32_16x16x32_bf16 v[124:127], v[76:79], v[178:181], v[124:127]
	v_add_u32_e32 v196, s28, v166
	v_mfma_f32_16x16x32_bf16 v[120:123], v[84:87], v[178:181], v[120:123]
	v_lshl_add_u64 v[194:195], v[194:195], 0, s[12:13]
	v_mfma_f32_16x16x32_bf16 v[108:111], v[76:79], v[186:189], v[108:111]
	v_mfma_f32_16x16x32_bf16 v[104:107], v[84:87], v[186:189], v[104:107]
	s_waitcnt lgkmcnt(0)
	v_mfma_f32_16x16x32_bf16 v[92:95], v[76:79], v[198:201], v[92:95]
	v_mfma_f32_16x16x32_bf16 v[88:91], v[84:87], v[198:201], v[88:91]
	s_barrier
	s_setprio 0
	s_mov_b32 m0, s29
	ds_read_b128 v[202:205], v196
	global_load_lds_dwordx4 v[194:195], off
	ds_read_b128 v[206:209], v196 offset:1024
	ds_read_b128 v[210:213], v196 offset:2048
	ds_read_b128 v[214:217], v196 offset:3072
	v_lshl_add_u64 v[194:195], v[218:219], 0, s[12:13]
	s_add_i32 m0, s29, 0x2000
	s_nop 0
	global_load_lds_dwordx4 v[194:195], off
	s_setprio 1
	s_barrier
	s_waitcnt lgkmcnt(3)
	v_mfma_f32_16x16x32_bf16 v[132:135], v[202:205], v[160:163], v[132:135]
	s_waitcnt lgkmcnt(1)
	v_mfma_f32_16x16x32_bf16 v[128:131], v[210:213], v[160:163], v[128:131]
	v_mfma_f32_16x16x32_bf16 v[116:119], v[202:205], v[174:177], v[116:119]
	v_mfma_f32_16x16x32_bf16 v[112:115], v[210:213], v[174:177], v[112:115]
	v_mfma_f32_16x16x32_bf16 v[100:103], v[202:205], v[182:185], v[100:103]
	v_mfma_f32_16x16x32_bf16 v[96:99], v[210:213], v[182:185], v[96:99]
	v_mfma_f32_16x16x32_bf16 v[68:71], v[202:205], v[190:193], v[68:71]
	v_mfma_f32_16x16x32_bf16 v[64:67], v[210:213], v[190:193], v[64:67]
	v_mfma_f32_16x16x32_bf16 v[132:135], v[206:209], v[170:173], v[132:135]
	s_mov_b32 m0, s39
	s_waitcnt lgkmcnt(0)
	v_mfma_f32_16x16x32_bf16 v[128:131], v[214:217], v[170:173], v[128:131]
	v_lshl_add_u64 v[194:195], v[220:221], 0, s[12:13]
	v_mfma_f32_16x16x32_bf16 v[116:119], v[206:209], v[178:181], v[116:119]
	v_mfma_f32_16x16x32_bf16 v[112:115], v[214:217], v[178:181], v[112:115]
	v_mfma_f32_16x16x32_bf16 v[100:103], v[206:209], v[186:189], v[100:103]
	v_mfma_f32_16x16x32_bf16 v[96:99], v[214:217], v[186:189], v[96:99]
	v_mfma_f32_16x16x32_bf16 v[68:71], v[206:209], v[198:201], v[68:71]
	v_mfma_f32_16x16x32_bf16 v[64:67], v[214:217], v[198:201], v[64:67]
	s_barrier
; #define PG8_STAGE(bufoff, gbase, voff) do { _Pragma("unroll") for (int _i = 0; _i < 2; ++_i) \
;         __builtin_amdgcn_global_load_lds((const unsigned*)((const char*)(gbase) + (voff)[_i]), (LAS unsigned*)(lds + (bufoff) + ldsw + _i * 8192), 16, 0, 0); } while (0)
; #define PG8_LDA(dst, b, h) do { _Pragma("unroll") for (int m = 0; m < 4; ++m) _Pragma("unroll") for (int k = 0; k < 2; ++k) dst[m][k] = *(const LAS bf16x8*)(lds + PG8_SA(b, h) + aoff + m * 2048 + k * 1024); } while (0)
; #define PG8_MMA(ai, bj, At, Bt) do { __builtin_amdgcn_s_setprio(1); _Pragma("unroll") for (int m = 0; m < 4; ++m) _Pragma("unroll") for (int n = 0; n < 2; ++n) _Pragma("unroll") for (int k = 0; k < 2; ++k) \
;         acc[ai][bj][m][n] = __builtin_amdgcn_mfma_f32_16x16x32_bf16(Bt[n][k], At[m][k], acc[ai][bj][m][n], 0, 0, 0); __builtin_amdgcn_s_setprio(0); } while (0)
; #define PG8_WAIT_V(n) asm volatile("s_waitcnt vmcnt(" #n ")" ::: "memory")
; #define PG8_WAIT_L(n) asm volatile("s_waitcnt lgkmcnt(" #n ")" ::: "memory")
; #define PG8_BAR __builtin_amdgcn_s_barrier()
; #define PG8_SCHED __builtin_amdgcn_sched_barrier(0)
;     DI void operator()(const f32x4 (&acc)[2][2][4][2], const Unit& u, int wr, int wc, int fr, int fq) const {
;         const int row0 = u.pm * BM + wr * 64 + fr, col0 = u.pn * BM + wc * 32 + 8 * fq;
;         f32x4 sc[2][2];
; #pragma unroll
;         for (int bj = 0; bj < 2; ++bj)
; #pragma unroll
;             for (int n = 0; n < 2; ++n) sc[bj][n] = scale ? *(const f32x4*)(scale + col0 + bj * HALF + 4 * n) : (f32x4){1.f, 1.f, 1.f, 1.f};
; #pragma unroll
; template <class Map, class Epi>
; DI void gemm_phase(LAS unsigned char* lds, const Map& MP, const Epi& E, const int nM, const int nN, const int K, const int lda, const int ldb) {
;     ...
;             PG8_LDA(At, 1, 1); PG8_STAGE(PG8_SA(1, 0), a3, voffA);
;             PG8_BAR; PG8_WAIT_L(0); PG8_MMA(1, 0, At, B0); PG8_BAR; PG8_SCHED;
;             PG8_STAGE(PG8_SB(1, 1), b3 + hstepB, voffB);
;             PG8_WAIT_V(6); PG8_BAR; PG8_MMA(1, 1, At, B1); PG8_BAR;
;         }
	s_setprio 0
	ds_read_b128 v[160:163], v168 offset:49152
	global_load_lds_dwordx4 v[194:195], off
	ds_read_b128 v[170:173], v168 offset:50176
	ds_read_b128 v[174:177], v168 offset:51200
	ds_read_b128 v[178:181], v168 offset:52224
	ds_read_b128 v[182:185], v168 offset:53248
	ds_read_b128 v[186:189], v168 offset:54272
	ds_read_b128 v[190:193], v168 offset:55296
	ds_read_b128 v[198:201], v168 offset:56320
	v_lshl_add_u64 v[194:195], v[222:223], 0, s[12:13]
	s_mov_b32 m0, s46
	s_nop 0
	global_load_lds_dwordx4 v[194:195], off
	s_waitcnt vmcnt(10)
	s_setprio 1
	s_barrier
	s_waitcnt lgkmcnt(7)
	v_mfma_f32_16x16x32_bf16 v[60:63], v[72:75], v[160:163], v[60:63]
	v_mfma_f32_16x16x32_bf16 v[56:59], v[80:83], v[160:163], v[56:59]
	s_waitcnt lgkmcnt(5)
	v_mfma_f32_16x16x32_bf16 v[44:47], v[72:75], v[174:177], v[44:47]
	v_mfma_f32_16x16x32_bf16 v[40:43], v[80:83], v[174:177], v[40:43]
	s_waitcnt lgkmcnt(3)
	v_mfma_f32_16x16x32_bf16 v[28:31], v[72:75], v[182:185], v[28:31]
	v_mfma_f32_16x16x32_bf16 v[24:27], v[80:83], v[182:185], v[24:27]
	s_waitcnt lgkmcnt(1)
	v_mfma_f32_16x16x32_bf16 v[12:15], v[72:75], v[190:193], v[12:15]
	v_mfma_f32_16x16x32_bf16 v[8:11], v[80:83], v[190:193], v[8:11]
	v_mfma_f32_16x16x32_bf16 v[60:63], v[76:79], v[170:173], v[60:63]
	s_add_u32 s26, s26, 0x20080
	s_addc_u32 s27, s27, 0
	v_mfma_f32_16x16x32_bf16 v[56:59], v[84:87], v[170:173], v[56:59]
	s_add_i32 s28, s28, s34
	v_mfma_f32_16x16x32_bf16 v[44:47], v[76:79], v[178:181], v[44:47]
	v_mfma_f32_16x16x32_bf16 v[40:43], v[84:87], v[178:181], v[40:43]
	v_mfma_f32_16x16x32_bf16 v[28:31], v[76:79], v[186:189], v[28:31]
	v_mfma_f32_16x16x32_bf16 v[24:27], v[84:87], v[186:189], v[24:27]
	s_waitcnt lgkmcnt(0)
	v_mfma_f32_16x16x32_bf16 v[12:15], v[76:79], v[198:201], v[12:15]
	v_mfma_f32_16x16x32_bf16 v[8:11], v[84:87], v[198:201], v[8:11]
	s_barrier
	s_setprio 0
	s_mov_b32 m0, s28
	s_nop 0
	global_load_lds_dwordx4 v148, s[26:27]
	s_add_i32 m0, s28, 0x2000
	s_nop 0
	global_load_lds_dwordx4 v144, s[26:27]
	s_waitcnt vmcnt(6)
	s_setprio 1
	s_barrier
	v_mfma_f32_16x16x32_bf16 v[52:55], v[202:205], v[160:163], v[52:55]
	v_mfma_f32_16x16x32_bf16 v[48:51], v[210:213], v[160:163], v[48:51]
	ds_read_b128 v[72:75], v167
	v_mfma_f32_16x16x32_bf16 v[36:39], v[202:205], v[174:177], v[36:39]
	v_mfma_f32_16x16x32_bf16 v[32:35], v[210:213], v[174:177], v[32:35]
	ds_read_b128 v[76:79], v167 offset:1024
	v_mfma_f32_16x16x32_bf16 v[20:23], v[202:205], v[182:185], v[20:23]
	v_mfma_f32_16x16x32_bf16 v[16:19], v[210:213], v[182:185], v[16:19]
	ds_read_b128 v[80:83], v167 offset:2048
	v_mfma_f32_16x16x32_bf16 v[4:7], v[202:205], v[190:193], v[4:7]
	v_mfma_f32_16x16x32_bf16 v[0:3], v[210:213], v[190:193], v[0:3]
	ds_read_b128 v[84:87], v167 offset:3072
	v_mfma_f32_16x16x32_bf16 v[52:55], v[206:209], v[170:173], v[52:55]
	s_add_i32 s57, s57, 2
	v_mfma_f32_16x16x32_bf16 v[48:51], v[214:217], v[170:173], v[48:51]
	s_add_u32 s55, s55, 0x100
	s_addc_u32 s56, s56, 0
	v_mfma_f32_16x16x32_bf16 v[36:39], v[206:209], v[178:181], v[36:39]
	s_add_u32 s24, s24, 0x100
	s_addc_u32 s25, s25, 0
	v_mfma_f32_16x16x32_bf16 v[32:35], v[214:217], v[178:181], v[32:35]
	s_cmp_gt_u32 s57, 5
	v_mfma_f32_16x16x32_bf16 v[20:23], v[206:209], v[186:189], v[20:23]
	v_mfma_f32_16x16x32_bf16 v[16:19], v[214:217], v[186:189], v[16:19]
	v_mfma_f32_16x16x32_bf16 v[4:7], v[206:209], v[198:201], v[4:7]
	v_mfma_f32_16x16x32_bf16 v[0:3], v[214:217], v[198:201], v[0:3]
	s_barrier
	s_setprio 0
	s_cbranch_scc0 .LBB1_229
	s_waitcnt lgkmcnt(0)
	s_lshl_b32 s17, s42, 8
	v_mov_b32_e32 v170, v164
	v_mov_b32_e32 v72, v165
	s_or_b32 s17, s17, s38
	v_mov_b32_e32 v80, 1.0
	v_lshl_add_u32 v160, v72, 3, s17
	v_ashrrev_i32_e32 v161, 31, v160
	v_cndmask_b32_e64 v72, 0, 1, s[14:15]
	v_lshl_add_u64 v[162:163], v[160:161], 2, s[8:9]
	v_cmp_ne_u32_e64 s[42:43], 1, v72
	s_andn2_b64 vcc, exec, s[14:15]
	v_mov_b32_e32 v84, 1.0
	v_mov_b32_e32 v85, 1.0
	v_mov_b32_e32 v86, 1.0
	v_mov_b32_e32 v87, 1.0
	s_cbranch_vccnz .LBB1_232
	global_load_dwordx4 v[84:87], v[162:163], off

; #define PG8_STAGE(bufoff, gbase, voff) do { _Pragma("unroll") for (int _i = 0; _i < 2; ++_i) \
;         __builtin_amdgcn_global_load_lds((const unsigned*)((const char*)(gbase) + (voff)[_i]), (LAS unsigned*)(lds + (bufoff) + ldsw + _i * 8192), 16, 0, 0); } while (0)
; #define PG8_LDA(dst, b, h) do { _Pragma("unroll") for (int m = 0; m < 4; ++m) _Pragma("unroll") for (int k = 0; k < 2; ++k) dst[m][k] = *(const LAS bf16x8*)(lds + PG8_SA(b, h) + aoff + m * 2048 + k * 1024); } while (0)
; #define PG8_LDB(dst, b, h) do { _Pragma("unroll") for (int n = 0; n < 2; ++n) _Pragma("unroll") for (int k = 0; k < 2; ++k) dst[n][k] = *(const LAS bf16x8*)(lds + PG8_SB(b, h) + boff + n * 2048 + k * 1024); } while (0)
; #define PG8_MMA(ai, bj, At, Bt) do { __builtin_amdgcn_s_setprio(1); _Pragma("unroll") for (int m = 0; m < 4; ++m) _Pragma("unroll") for (int n = 0; n < 2; ++n) _Pragma("unroll") for (int k = 0; k < 2; ++k) \
;         acc[ai][bj][m][n] = __builtin_amdgcn_mfma_f32_16x16x32_bf16(Bt[n][k], At[m][k], acc[ai][bj][m][n], 0, 0, 0); __builtin_amdgcn_s_setprio(0); } while (0)
; #define PG8_WAIT_V(n) asm volatile("s_waitcnt vmcnt(" #n ")" ::: "memory")
; #define PG8_WAIT_L(n) asm volatile("s_waitcnt lgkmcnt(" #n ")" ::: "memory")
; template <class Map, class Epi>
; DI void gemm_phase(LAS unsigned char* lds, const Map& MP, const Epi& E, const int nM, const int nN, const int K, const int lda, const int ldb) {
;     ...
;             const bool last = (t == nt - 2);
;             const char* a1 = cA + (size_t)(t + 1) * kstep;
;             const char* a2 = last ? nA : cA + (size_t)(t + 2) * kstep; const char* b2 = last ? nB : cB + (size_t)(t + 2) * kstep;
;             const char* a3 = a2 + kstep; const char* b3 = b2 + kstep;
;             PG8_LDB(B0, 0, 0); PG8_SCHED; PG8_LDA(At, 0, 0); PG8_STAGE(PG8_SA(1, 1), a1 + hstepA, voffA);
;             PG8_WAIT_L(8); PG8_BAR; PG8_WAIT_L(0); PG8_MMA(0, 0, At, B0); PG8_BAR; PG8_SCHED;
;             PG8_LDB(B1, 0, 1); PG8_STAGE(PG8_SB(0, 0), b2, voffB);
;             PG8_BAR; PG8_WAIT_L(0); PG8_MMA(0, 1, At, B1); PG8_BAR;
;             PG8_LDA(At, 0, 1); PG8_STAGE(PG8_SA(0, 0), a2, voffA);
;             PG8_BAR; PG8_WAIT_L(0); PG8_MMA(1, 0, At, B0); PG8_BAR; PG8_SCHED;
;             PG8_STAGE(PG8_SB(0, 1), b2 + hstepB, voffB);
;             PG8_WAIT_V(6); PG8_BAR; PG8_MMA(1, 1, At, B1); PG8_BAR;
.LBB1_380:
	s_add_u32 s28, s44, 0xfff80080
	s_addc_u32 s29, s45, -1
	s_cmp_eq_u32 vcc_hi, 28
	s_cselect_b32 s47, s23, s29
	s_cselect_b32 s46, s61, s28
	s_cselect_b32 s29, s21, vcc_lo
	s_cselect_b32 s28, s58, s59
	s_add_i32 m0, s38, 0xc000
	ds_read_b128 v[96:99], v190
	global_load_lds_dwordx4 v178, s[44:45]
	ds_read_b128 v[100:103], v190 offset:1024
	ds_read_b128 v[108:111], v190 offset:2048
	ds_read_b128 v[112:115], v190 offset:3072
	ds_read_b128 v[160:163], v190 offset:4096
	ds_read_b128 v[164:167], v190 offset:5120
	ds_read_b128 v[198:201], v190 offset:6144
	ds_read_b128 v[202:205], v190 offset:7168
	s_add_i32 m0, s38, 0xe000
	s_nop 0
	global_load_lds_dwordx4 v176, s[44:45]
	s_waitcnt lgkmcnt(8)
	s_setprio 1
	s_barrier
	s_waitcnt lgkmcnt(7)
	v_mfma_f32_16x16x32_bf16 v[148:151], v[80:83], v[96:99], v[148:151]
	v_mfma_f32_16x16x32_bf16 v[144:147], v[88:91], v[96:99], v[144:147]
	s_waitcnt lgkmcnt(5)
	v_mfma_f32_16x16x32_bf16 v[136:139], v[80:83], v[108:111], v[136:139]
	v_mfma_f32_16x16x32_bf16 v[128:131], v[88:91], v[108:111], v[128:131]
	s_waitcnt lgkmcnt(3)
	v_mfma_f32_16x16x32_bf16 v[120:123], v[80:83], v[160:163], v[120:123]
	v_mfma_f32_16x16x32_bf16 v[104:107], v[88:91], v[160:163], v[104:107]
	s_waitcnt lgkmcnt(1)
	v_mfma_f32_16x16x32_bf16 v[76:79], v[80:83], v[198:201], v[76:79]
	v_mfma_f32_16x16x32_bf16 v[72:75], v[88:91], v[198:201], v[72:75]
	v_mfma_f32_16x16x32_bf16 v[148:151], v[84:87], v[100:103], v[148:151]
	s_add_i32 s68, s5, s37
	v_mfma_f32_16x16x32_bf16 v[144:147], v[92:95], v[100:103], v[144:147]
	v_lshl_add_u64 v[184:185], s[28:29], 0, v[172:173]
	v_mfma_f32_16x16x32_bf16 v[136:139], v[84:87], v[112:115], v[136:139]
	v_lshl_add_u64 v[194:195], s[28:29], 0, v[168:169]
	v_mfma_f32_16x16x32_bf16 v[128:131], v[92:95], v[112:115], v[128:131]
	v_mfma_f32_16x16x32_bf16 v[120:123], v[84:87], v[164:167], v[120:123]
	v_mfma_f32_16x16x32_bf16 v[104:107], v[92:95], v[164:167], v[104:107]
	s_waitcnt lgkmcnt(0)
	v_mfma_f32_16x16x32_bf16 v[76:79], v[84:87], v[202:205], v[76:79]
	v_mfma_f32_16x16x32_bf16 v[72:75], v[92:95], v[202:205], v[72:75]
	s_barrier
	s_setprio 0
	s_mov_b32 m0, s68
	ds_read_b128 v[206:209], v191
	global_load_lds_dwordx4 v[184:185], off
	ds_read_b128 v[210:213], v191 offset:1024
	ds_read_b128 v[214:217], v191 offset:2048
	ds_read_b128 v[218:221], v191 offset:3072
	s_add_i32 m0, s68, 0x2000
	s_nop 0
	global_load_lds_dwordx4 v[194:195], off
	s_setprio 1
	s_barrier
	s_waitcnt lgkmcnt(3)
	v_mfma_f32_16x16x32_bf16 v[156:159], v[206:209], v[96:99], v[156:159]
	s_waitcnt lgkmcnt(1)
	v_mfma_f32_16x16x32_bf16 v[96:99], v[214:217], v[96:99], v[152:155]
	v_mfma_f32_16x16x32_bf16 v[156:159], v[210:213], v[100:103], v[156:159]
	s_waitcnt lgkmcnt(0)
	v_mfma_f32_16x16x32_bf16 v[96:99], v[218:221], v[100:103], v[96:99]
	v_mfma_f32_16x16x32_bf16 v[100:103], v[206:209], v[108:111], v[140:143]
	v_mfma_f32_16x16x32_bf16 v[108:111], v[214:217], v[108:111], v[132:135]
	v_mfma_f32_16x16x32_bf16 v[116:119], v[214:217], v[160:163], v[116:119]
	v_mfma_f32_16x16x32_bf16 v[68:71], v[206:209], v[198:201], v[68:71]
	v_mfma_f32_16x16x32_bf16 v[64:67], v[214:217], v[198:201], v[64:67]
	v_lshl_add_u64 v[234:235], s[46:47], 0, v[170:171]
	s_mov_b32 m0, s38
	v_mfma_f32_16x16x32_bf16 v[100:103], v[210:213], v[112:115], v[100:103]
	v_lshl_add_u64 v[226:227], s[46:47], 0, v[174:175]
	v_mfma_f32_16x16x32_bf16 v[108:111], v[218:221], v[112:115], v[108:111]
	v_mfma_f32_16x16x32_bf16 v[112:115], v[206:209], v[160:163], v[124:127]
	v_mfma_f32_16x16x32_bf16 v[116:119], v[218:221], v[164:167], v[116:119]
	v_mfma_f32_16x16x32_bf16 v[68:71], v[210:213], v[202:205], v[68:71]
	v_mfma_f32_16x16x32_bf16 v[64:67], v[218:221], v[202:205], v[64:67]
	v_mfma_f32_16x16x32_bf16 v[112:115], v[210:213], v[164:167], v[112:115]
	s_barrier
	s_setprio 0
	ds_read_b128 v[124:127], v190 offset:16384
	global_load_lds_dwordx4 v[226:227], off
	ds_read_b128 v[132:135], v190 offset:17408
	ds_read_b128 v[140:143], v190 offset:18432
	ds_read_b128 v[152:155], v190 offset:19456
	ds_read_b128 v[160:163], v190 offset:20480
	ds_read_b128 v[164:167], v190 offset:21504
	ds_read_b128 v[198:201], v190 offset:22528
	ds_read_b128 v[202:205], v190 offset:23552
	s_mov_b32 m0, s39
	s_nop 0
	global_load_lds_dwordx4 v[234:235], off
	s_waitcnt vmcnt(10)
	s_setprio 1
	s_barrier
	s_waitcnt lgkmcnt(7)
	v_mfma_f32_16x16x32_bf16 v[60:63], v[80:83], v[124:127], v[60:63]
	v_mfma_f32_16x16x32_bf16 v[48:51], v[88:91], v[124:127], v[48:51]
	s_waitcnt lgkmcnt(5)
	v_mfma_f32_16x16x32_bf16 v[40:43], v[80:83], v[140:143], v[40:43]
	v_mfma_f32_16x16x32_bf16 v[32:35], v[88:91], v[140:143], v[32:35]
	s_waitcnt lgkmcnt(3)
	v_mfma_f32_16x16x32_bf16 v[24:27], v[80:83], v[160:163], v[24:27]
	v_mfma_f32_16x16x32_bf16 v[16:19], v[88:91], v[160:163], v[16:19]
	s_waitcnt lgkmcnt(1)
	v_mfma_f32_16x16x32_bf16 v[12:15], v[80:83], v[198:201], v[12:15]
	v_mfma_f32_16x16x32_bf16 v[8:11], v[88:91], v[198:201], v[8:11]
	v_mfma_f32_16x16x32_bf16 v[60:63], v[84:87], v[132:135], v[60:63]
	s_add_u32 s68, s28, 0x80000
	s_addc_u32 s69, s29, 0
	v_mfma_f32_16x16x32_bf16 v[48:51], v[92:95], v[132:135], v[48:51]
	s_add_i32 s70, s2, s37
	v_mfma_f32_16x16x32_bf16 v[40:43], v[84:87], v[152:155], v[40:43]
	v_mfma_f32_16x16x32_bf16 v[32:35], v[92:95], v[152:155], v[32:35]
	v_mfma_f32_16x16x32_bf16 v[24:27], v[84:87], v[164:167], v[24:27]
	v_mfma_f32_16x16x32_bf16 v[16:19], v[92:95], v[164:167], v[16:19]
	s_waitcnt lgkmcnt(0)
	v_mfma_f32_16x16x32_bf16 v[12:15], v[84:87], v[202:205], v[12:15]
	v_mfma_f32_16x16x32_bf16 v[8:11], v[92:95], v[202:205], v[8:11]
	s_barrier
; #define PG8_STAGE(bufoff, gbase, voff) do { _Pragma("unroll") for (int _i = 0; _i < 2; ++_i) \
;         __builtin_amdgcn_global_load_lds((const unsigned*)((const char*)(gbase) + (voff)[_i]), (LAS unsigned*)(lds + (bufoff) + ldsw + _i * 8192), 16, 0, 0); } while (0)
; #define PG8_LDA(dst, b, h) do { _Pragma("unroll") for (int m = 0; m < 4; ++m) _Pragma("unroll") for (int k = 0; k < 2; ++k) dst[m][k] = *(const LAS bf16x8*)(lds + PG8_SA(b, h) + aoff + m * 2048 + k * 1024); } while (0)
; #define PG8_LDB(dst, b, h) do { _Pragma("unroll") for (int n = 0; n < 2; ++n) _Pragma("unroll") for (int k = 0; k < 2; ++k) dst[n][k] = *(const LAS bf16x8*)(lds + PG8_SB(b, h) + boff + n * 2048 + k * 1024); } while (0)
; #define PG8_MMA(ai, bj, At, Bt) do { __builtin_amdgcn_s_setprio(1); _Pragma("unroll") for (int m = 0; m < 4; ++m) _Pragma("unroll") for (int n = 0; n < 2; ++n) _Pragma("unroll") for (int k = 0; k < 2; ++k) \
;         acc[ai][bj][m][n] = __builtin_amdgcn_mfma_f32_16x16x32_bf16(Bt[n][k], At[m][k], acc[ai][bj][m][n], 0, 0, 0); __builtin_amdgcn_s_setprio(0); } while (0)
; #define PG8_WAIT_V(n) asm volatile("s_waitcnt vmcnt(" #n ")" ::: "memory")
; #define PG8_WAIT_L(n) asm volatile("s_waitcnt lgkmcnt(" #n ")" ::: "memory")
; #define PG8_BAR __builtin_amdgcn_s_barrier()
; #define PG8_SCHED __builtin_amdgcn_sched_barrier(0)
; template <class Map, class Epi>
; DI void gemm_phase(LAS unsigned char* lds, const Map& MP, const Epi& E, const int nM, const int nN, const int K, const int lda, const int ldb) {
;     ...
;             PG8_WAIT_V(6); PG8_BAR; PG8_MMA(1, 1, At, B1); PG8_BAR;
;             PG8_LDB(B0, 1, 0); PG8_SCHED; PG8_LDA(At, 1, 0); PG8_STAGE(PG8_SA(0, 1), a2 + hstepA, voffA);
;             PG8_WAIT_L(8); PG8_BAR; PG8_WAIT_L(0); PG8_MMA(0, 0, At, B0); PG8_BAR; PG8_SCHED;
;             PG8_LDB(B1, 1, 1); PG8_STAGE(PG8_SB(1, 0), b3, voffB);
;             PG8_BAR; PG8_WAIT_L(0); PG8_MMA(0, 1, At, B1); PG8_BAR;
;             PG8_LDA(At, 1, 1); PG8_STAGE(PG8_SA(1, 0), a3, voffA);
;             PG8_BAR; PG8_WAIT_L(0); PG8_MMA(1, 0, At, B0); PG8_BAR; PG8_SCHED;
;             PG8_STAGE(PG8_SB(1, 1), b3 + hstepB, voffB);
	s_setprio 0
	s_mov_b32 m0, s70
	s_nop 0
	global_load_lds_dwordx4 v172, s[68:69]
	s_add_i32 m0, s70, 0x2000
	s_nop 0
	global_load_lds_dwordx4 v168, s[68:69]
	s_waitcnt vmcnt(6)
	s_setprio 1
	s_barrier
	v_mfma_f32_16x16x32_bf16 v[56:59], v[206:209], v[124:127], v[56:59]
	v_mfma_f32_16x16x32_bf16 v[52:55], v[214:217], v[124:127], v[52:55]
	s_add_i32 s68, 0, 0x18000
	v_add_u32_e32 v92, s68, v188
	ds_read_b128 v[80:83], v92
	v_mfma_f32_16x16x32_bf16 v[44:47], v[206:209], v[140:143], v[44:47]
	v_mfma_f32_16x16x32_bf16 v[36:39], v[214:217], v[140:143], v[36:39]
	ds_read_b128 v[84:87], v92 offset:1024
	v_mfma_f32_16x16x32_bf16 v[28:31], v[206:209], v[160:163], v[28:31]
	v_mfma_f32_16x16x32_bf16 v[20:23], v[214:217], v[160:163], v[20:23]
	ds_read_b128 v[88:91], v92 offset:2048
	v_mfma_f32_16x16x32_bf16 v[4:7], v[206:209], v[198:201], v[4:7]
	v_mfma_f32_16x16x32_bf16 v[0:3], v[214:217], v[198:201], v[0:3]
	ds_read_b128 v[92:95], v92 offset:3072
	v_mfma_f32_16x16x32_bf16 v[56:59], v[210:213], v[132:135], v[56:59]
	s_add_u32 s46, s46, 0x80000
	s_addc_u32 s47, s47, 0
	v_mfma_f32_16x16x32_bf16 v[52:55], v[218:221], v[132:135], v[52:55]
	v_mfma_f32_16x16x32_bf16 v[44:47], v[210:213], v[152:155], v[44:47]
	v_mfma_f32_16x16x32_bf16 v[36:39], v[218:221], v[152:155], v[36:39]
	v_mfma_f32_16x16x32_bf16 v[28:31], v[210:213], v[164:167], v[28:31]
	v_mfma_f32_16x16x32_bf16 v[20:23], v[218:221], v[164:167], v[20:23]
	v_mfma_f32_16x16x32_bf16 v[4:7], v[210:213], v[202:205], v[4:7]
	v_mfma_f32_16x16x32_bf16 v[0:3], v[218:221], v[202:205], v[0:3]
	s_barrier
	s_setprio 0
	s_mov_b32 m0, s56
	ds_read_b128 v[124:127], v190 offset:32768
	global_load_lds_dwordx4 v174, s[46:47]
	ds_read_b128 v[132:135], v190 offset:33792
	ds_read_b128 v[160:163], v190 offset:34816
	ds_read_b128 v[164:167], v190 offset:35840
	ds_read_b128 v[198:201], v190 offset:36864
	ds_read_b128 v[202:205], v190 offset:37888
	ds_read_b128 v[206:209], v190 offset:38912
	ds_read_b128 v[210:213], v190 offset:39936
	s_mov_b32 m0, s57
	s_nop 0
	global_load_lds_dwordx4 v170, s[46:47]
	s_waitcnt lgkmcnt(8)
	s_setprio 1
	s_barrier
	s_waitcnt lgkmcnt(7)
	v_mfma_f32_16x16x32_bf16 v[140:143], v[80:83], v[124:127], v[148:151]
	s_waitcnt lgkmcnt(6)
	v_mfma_f32_16x16x32_bf16 v[148:151], v[84:87], v[132:135], v[140:143]
	v_mfma_f32_16x16x32_bf16 v[140:143], v[88:91], v[124:127], v[144:147]
	s_waitcnt lgkmcnt(5)
	v_mfma_f32_16x16x32_bf16 v[136:139], v[80:83], v[160:163], v[136:139]
	v_mfma_f32_16x16x32_bf16 v[128:131], v[88:91], v[160:163], v[128:131]
	s_waitcnt lgkmcnt(3)
	v_mfma_f32_16x16x32_bf16 v[120:123], v[80:83], v[198:201], v[120:123]
	v_mfma_f32_16x16x32_bf16 v[104:107], v[88:91], v[198:201], v[104:107]
	s_waitcnt lgkmcnt(1)
	v_mfma_f32_16x16x32_bf16 v[76:79], v[80:83], v[206:209], v[76:79]
	v_mfma_f32_16x16x32_bf16 v[72:75], v[88:91], v[206:209], v[72:75]
	s_add_i32 s46, 0, 0x1c000
	v_mfma_f32_16x16x32_bf16 v[144:147], v[92:95], v[132:135], v[140:143]
	v_add_u32_e32 v140, s46, v188
	v_mfma_f32_16x16x32_bf16 v[136:139], v[84:87], v[164:167], v[136:139]
	s_add_i32 s47, s68, s37
	v_mfma_f32_16x16x32_bf16 v[128:131], v[92:95], v[164:167], v[128:131]
	v_mfma_f32_16x16x32_bf16 v[120:123], v[84:87], v[202:205], v[120:123]
	v_mfma_f32_16x16x32_bf16 v[104:107], v[92:95], v[202:205], v[104:107]
	s_waitcnt lgkmcnt(0)
	v_mfma_f32_16x16x32_bf16 v[76:79], v[84:87], v[210:213], v[76:79]
	v_mfma_f32_16x16x32_bf16 v[72:75], v[92:95], v[210:213], v[72:75]
	s_barrier
	s_setprio 0
	ds_read_b128 v[214:217], v140
	ds_read_b128 v[218:221], v140 offset:1024
	ds_read_b128 v[222:225], v140 offset:2048
	ds_read_b128 v[230:233], v140 offset:3072
	v_lshl_add_u64 v[140:141], v[184:185], 0, s[14:15]
	s_mov_b32 m0, s47
	s_nop 0
	global_load_lds_dwordx4 v[140:141], off
	v_lshl_add_u64 v[140:141], v[194:195], 0, s[14:15]
	s_add_i32 m0, s47, 0x2000
	s_nop 0
	global_load_lds_dwordx4 v[140:141], off
	s_setprio 1
	s_barrier
	s_waitcnt lgkmcnt(1)
	v_mfma_f32_16x16x32_bf16 v[96:99], v[222:225], v[124:127], v[96:99]
	v_mfma_f32_16x16x32_bf16 v[140:143], v[214:217], v[124:127], v[156:159]
	s_waitcnt lgkmcnt(0)
	v_mfma_f32_16x16x32_bf16 v[152:155], v[230:233], v[132:135], v[96:99]
	v_mfma_f32_16x16x32_bf16 v[96:99], v[214:217], v[160:163], v[100:103]
	v_mfma_f32_16x16x32_bf16 v[156:159], v[218:221], v[132:135], v[140:143]
	v_mfma_f32_16x16x32_bf16 v[140:143], v[218:221], v[164:167], v[96:99]
	v_mfma_f32_16x16x32_bf16 v[96:99], v[222:225], v[160:163], v[108:111]
	v_mfma_f32_16x16x32_bf16 v[132:135], v[230:233], v[164:167], v[96:99]
	v_mfma_f32_16x16x32_bf16 v[96:99], v[214:217], v[198:201], v[112:115]
	s_mov_b32 m0, s62
	v_mfma_f32_16x16x32_bf16 v[124:127], v[218:221], v[202:205], v[96:99]
	v_lshl_add_u64 v[184:185], v[226:227], 0, s[14:15]
	v_mfma_f32_16x16x32_bf16 v[96:99], v[222:225], v[198:201], v[116:119]
	v_mfma_f32_16x16x32_bf16 v[68:71], v[214:217], v[206:209], v[68:71]
	v_mfma_f32_16x16x32_bf16 v[64:67], v[222:225], v[206:209], v[64:67]
	v_mfma_f32_16x16x32_bf16 v[116:119], v[230:233], v[202:205], v[96:99]
	v_mfma_f32_16x16x32_bf16 v[68:71], v[218:221], v[210:213], v[68:71]
	v_mfma_f32_16x16x32_bf16 v[64:67], v[230:233], v[210:213], v[64:67]
	s_barrier
	s_setprio 0
	ds_read_b128 v[96:99], v190 offset:49152
	global_load_lds_dwordx4 v[184:185], off
	ds_read_b128 v[100:103], v190 offset:50176
	ds_read_b128 v[108:111], v190 offset:51200
	ds_read_b128 v[112:115], v190 offset:52224
	ds_read_b128 v[160:163], v190 offset:53248
	ds_read_b128 v[164:167], v190 offset:54272
	ds_read_b128 v[198:201], v190 offset:55296
	ds_read_b128 v[202:205], v190 offset:56320
	v_lshl_add_u64 v[184:185], v[234:235], 0, s[14:15]
	s_mov_b32 m0, s63
	s_nop 0
	global_load_lds_dwordx4 v[184:185], off
	s_waitcnt vmcnt(10)
	s_setprio 1
	s_barrier
; #define PG8_STAGE(bufoff, gbase, voff) do { _Pragma("unroll") for (int _i = 0; _i < 2; ++_i) \
;         __builtin_amdgcn_global_load_lds((const unsigned*)((const char*)(gbase) + (voff)[_i]), (LAS unsigned*)(lds + (bufoff) + ldsw + _i * 8192), 16, 0, 0); } while (0)
; #define PG8_MMA(ai, bj, At, Bt) do { __builtin_amdgcn_s_setprio(1); _Pragma("unroll") for (int m = 0; m < 4; ++m) _Pragma("unroll") for (int n = 0; n < 2; ++n) _Pragma("unroll") for (int k = 0; k < 2; ++k) \
;         acc[ai][bj][m][n] = __builtin_amdgcn_mfma_f32_16x16x32_bf16(Bt[n][k], At[m][k], acc[ai][bj][m][n], 0, 0, 0); __builtin_amdgcn_s_setprio(0); } while (0)
; #define PG8_WAIT_V(n) asm volatile("s_waitcnt vmcnt(" #n ")" ::: "memory")
; #define PG8_BAR __builtin_amdgcn_s_barrier()
; template <class Map, class Epi>
; DI void gemm_phase(LAS unsigned char* lds, const Map& MP, const Epi& E, const int nM, const int nN, const int K, const int lda, const int ldb) {
;     ...
;             PG8_STAGE(PG8_SB(1, 1), b3 + hstepB, voffB);
;             PG8_WAIT_V(6); PG8_BAR; PG8_MMA(1, 1, At, B1); PG8_BAR;
;         }
	s_waitcnt lgkmcnt(7)
	v_mfma_f32_16x16x32_bf16 v[60:63], v[80:83], v[96:99], v[60:63]
	v_mfma_f32_16x16x32_bf16 v[48:51], v[88:91], v[96:99], v[48:51]
	s_waitcnt lgkmcnt(5)
	v_mfma_f32_16x16x32_bf16 v[40:43], v[80:83], v[108:111], v[40:43]
	v_mfma_f32_16x16x32_bf16 v[32:35], v[88:91], v[108:111], v[32:35]
	s_waitcnt lgkmcnt(3)
	v_mfma_f32_16x16x32_bf16 v[24:27], v[80:83], v[160:163], v[24:27]
	v_mfma_f32_16x16x32_bf16 v[16:19], v[88:91], v[160:163], v[16:19]
	s_waitcnt lgkmcnt(1)
	v_mfma_f32_16x16x32_bf16 v[12:15], v[80:83], v[198:201], v[12:15]
	v_mfma_f32_16x16x32_bf16 v[8:11], v[88:91], v[198:201], v[8:11]
	v_mfma_f32_16x16x32_bf16 v[60:63], v[84:87], v[100:103], v[60:63]
	s_add_u32 s28, s28, 0x80080
	s_addc_u32 s29, s29, 0
	v_mfma_f32_16x16x32_bf16 v[48:51], v[92:95], v[100:103], v[48:51]
	s_add_i32 s46, s46, s37
	v_mfma_f32_16x16x32_bf16 v[40:43], v[84:87], v[112:115], v[40:43]
	v_mfma_f32_16x16x32_bf16 v[32:35], v[92:95], v[112:115], v[32:35]
	v_mfma_f32_16x16x32_bf16 v[24:27], v[84:87], v[164:167], v[24:27]
	v_mfma_f32_16x16x32_bf16 v[16:19], v[92:95], v[164:167], v[16:19]
	s_waitcnt lgkmcnt(0)
	v_mfma_f32_16x16x32_bf16 v[12:15], v[84:87], v[202:205], v[12:15]
	v_mfma_f32_16x16x32_bf16 v[8:11], v[92:95], v[202:205], v[8:11]
	s_barrier
	s_setprio 0
	s_mov_b32 m0, s46
	s_nop 0
	global_load_lds_dwordx4 v172, s[28:29]
	s_add_i32 m0, s46, 0x2000
	s_nop 0
	global_load_lds_dwordx4 v168, s[28:29]
	s_waitcnt vmcnt(6)
	s_setprio 1
	s_barrier
	v_mfma_f32_16x16x32_bf16 v[56:59], v[214:217], v[96:99], v[56:59]
	v_mfma_f32_16x16x32_bf16 v[52:55], v[222:225], v[96:99], v[52:55]
	ds_read_b128 v[80:83], v189
	v_mfma_f32_16x16x32_bf16 v[44:47], v[214:217], v[108:111], v[44:47]
	v_mfma_f32_16x16x32_bf16 v[36:39], v[222:225], v[108:111], v[36:39]
	ds_read_b128 v[84:87], v189 offset:1024
	v_mfma_f32_16x16x32_bf16 v[28:31], v[214:217], v[160:163], v[28:31]
	v_mfma_f32_16x16x32_bf16 v[20:23], v[222:225], v[160:163], v[20:23]
	ds_read_b128 v[88:91], v189 offset:2048
	v_mfma_f32_16x16x32_bf16 v[4:7], v[214:217], v[198:201], v[4:7]
	v_mfma_f32_16x16x32_bf16 v[0:3], v[222:225], v[198:201], v[0:3]
	ds_read_b128 v[92:95], v189 offset:3072
	v_mfma_f32_16x16x32_bf16 v[56:59], v[218:221], v[100:103], v[56:59]
	s_add_i32 vcc_hi, vcc_hi, 2
	v_mfma_f32_16x16x32_bf16 v[52:55], v[230:233], v[100:103], v[52:55]
	s_add_u32 s59, s59, 0x100
	s_addc_u32 vcc_lo, vcc_lo, 0
	v_mfma_f32_16x16x32_bf16 v[44:47], v[218:221], v[112:115], v[44:47]
	s_add_u32 s44, s44, 0x100
	s_addc_u32 s45, s45, 0
	v_mfma_f32_16x16x32_bf16 v[36:39], v[230:233], v[112:115], v[36:39]
	s_cmp_gt_u32 vcc_hi, 29
	v_mfma_f32_16x16x32_bf16 v[28:31], v[218:221], v[164:167], v[28:31]
	v_mfma_f32_16x16x32_bf16 v[20:23], v[230:233], v[164:167], v[20:23]
	v_mfma_f32_16x16x32_bf16 v[4:7], v[218:221], v[202:205], v[4:7]
	v_mfma_f32_16x16x32_bf16 v[0:3], v[230:233], v[202:205], v[0:3]
	s_barrier
	s_setprio 0
	s_cbranch_scc0 .LBB1_380
; DI float silu_mul(float g, float v) { return g * v * __builtin_amdgcn_rcpf(1.0f + __builtin_amdgcn_exp2f(-LOG2E * g)); }
;     DI void operator()(const f32x4 (&acc)[2][2][4][2], const Unit& u, int wr, int wc, int fr, int fq) const {
;         const int row0 = u.pm * BM + wr * 64 + fr, ch0 = u.pn * 128 + wc * 32 + 8 * fq;
;         f32x4 w0[2], w1[2], w2[2], bb[2];
; #pragma unroll
;         for (int n = 0; n < 2; ++n) { w0[n] = *(const f32x4*)(cw + ch0 + 4 * n); w1[n] = *(const f32x4*)(cw + DFF + ch0 + 4 * n); w2[n] = *(const f32x4*)(cw + 2 * DFF + ch0 + 4 * n); bb[n] = *(const f32x4*)(cb + ch0 + 4 * n); }
; #pragma unroll
;         for (int ai = 0; ai < 2; ++ai)
; #pragma unroll
;             for (int m = 0; m < 4; ++m) {
;                 const bool efirst = (m == 0) && (fr == 0), elast = (m == 3) && (fr == 15);
;                 const int row = row0 + ai * HALF + m * 16;
;                 f32x4 gc[2];
; #pragma unroll
;                 for (int n = 0; n < 2; ++n) {
;                     const f32x4 g = acc[ai][0][m][n];
;                     const f32x4 gprev = acc[ai][0][m > 0 ? m - 1 : 0][n], gnext = acc[ai][0][m < 3 ? m + 1 : 3][n];
;                     f32x4 up, dn;
; #pragma unroll
;                     for (int e = 0; e < 4; ++e) {
;                         const float pu = (m > 0 && fr == 15) ? gprev[e] : g[e];
;                         const float pd = (m < 3 && fr == 0) ? gnext[e] : g[e];
;                         up[e] = dpp_ror1(pu); dn[e] = dpp_ror15(pd);
;                     }
;                     if (efirst) up = (f32x4){0.f, 0.f, 0.f, 0.f};
;                     if (elast) dn = (f32x4){0.f, 0.f, 0.f, 0.f};
;                     gc[n] = w0[n] * up + w1[n] * g + w2[n] * dn + bb[n];
;                 }
;                 if (efirst || elast) {
;                     const size_t eo = (size_t)((row >> 6) * 2 + (elast ? 1 : 0)) * DFF + ch0;
; #pragma unroll
;                     for (int n = 0; n < 2; ++n) { *(f32x4*)(EP + eo + 4 * n) = gc[n]; *(f32x4*)(ER + eo + 4 * n) = acc[ai][0][m][n]; *(f32x4*)(EV + eo + 4 * n) = acc[ai][1][m][n]; }
;                 } else {
;                     const f32x4 v0 = acc[ai][1][m][0], v1 = acc[ai][1][m][1];
;                     u32x4 o;
;                     o[0] = pack2(silu_mul(gc[0][0], v0[0]), silu_mul(gc[0][1], v0[1])); o[1] = pack2(silu_mul(gc[0][2], v0[2]), silu_mul(gc[0][3], v0[3]));
	s_waitcnt lgkmcnt(0)
	s_lshl_b32 s23, s43, 7
	v_mov_b32_e32 v194, v186
	v_mov_b32_e32 v80, v187
	s_or_b32 s23, s23, s67
	v_lshl_add_u32 v184, v80, 3, s23
	v_ashrrev_i32_e32 v185, 31, v184
	v_lshlrev_b64 v[80:81], 2, v[184:185]
	v_lshl_add_u64 v[84:85], s[52:53], 0, v[80:81]
	v_lshl_add_u64 v[88:89], s[16:17], 0, v[80:81]
	v_lshl_add_u64 v[92:93], s[18:19], 0, v[80:81]
	v_lshl_add_u64 v[112:113], s[54:55], 0, v[80:81]
	global_load_dwordx4 v[80:83], v[84:85], off offset:16
	global_load_dwordx4 v[96:99], v[84:85], off
	s_nop 0
	global_load_dwordx4 v[84:87], v[88:89], off offset:16
	global_load_dwordx4 v[100:103], v[88:89], off
	s_nop 0
	global_load_dwordx4 v[88:91], v[92:93], off offset:16
	global_load_dwordx4 v[108:111], v[92:93], off
	s_nop 0
	global_load_dwordx4 v[92:95], v[112:113], off offset:16
	s_nop 0
	global_load_dwordx4 v[112:115], v[112:113], off
	v_cmp_eq_u32_e32 vcc, 0, v194
	s_nop 0
	s_nop 0
	v_cndmask_b32_e32 v161, v148, v136, vcc
	v_cndmask_b32_e32 v162, v149, v137, vcc
	v_cndmask_b32_e32 v163, v150, v138, vcc
	v_mov_b32_dpp v160, v161 row_ror:15 row_mask:0xf bank_mask:0xf
	s_nop 0
	s_nop 0
	v_mov_b32_dpp v161, v162 row_ror:15 row_mask:0xf bank_mask:0xf
	v_mov_b32_dpp v164, v150 row_ror:1 row_mask:0xf bank_mask:0xf
	v_cndmask_b32_e32 v165, v151, v139, vcc
	v_mov_b32_dpp v162, v163 row_ror:15 row_mask:0xf bank_mask:0xf
	v_mov_b32_dpp v195, v151 row_ror:1 row_mask:0xf bank_mask:0xf
	v_mov_b32_dpp v166, v148 row_ror:1 row_mask:0xf bank_mask:0xf
	v_mov_b32_dpp v167, v149 row_ror:1 row_mask:0xf bank_mask:0xf
	v_mov_b32_dpp v163, v165 row_ror:15 row_mask:0xf bank_mask:0xf
	v_cndmask_b32_e64 v165, v195, 0, vcc
	v_cndmask_b32_e64 v164, v164, 0, vcc
	v_cndmask_b32_e64 v167, v167, 0, vcc
	v_cndmask_b32_e64 v166, v166, 0, vcc
	s_nop 0
	s_nop 0
	v_mov_b32_dpp v195, v144 row_ror:1 row_mask:0xf bank_mask:0xf
	v_mov_b32_dpp v196, v145 row_ror:1 row_mask:0xf bank_mask:0xf
	v_mov_b32_dpp v198, v146 row_ror:1 row_mask:0xf bank_mask:0xf
	v_cndmask_b32_e32 v199, v147, v131, vcc
	v_mov_b32_dpp v200, v147 row_ror:1 row_mask:0xf bank_mask:0xf
	v_cndmask_b32_e64 v198, v198, 0, vcc
	v_cndmask_b32_e64 v201, v196, 0, vcc
	s_lshl_b32 s21, s42, 8
	s_add_i32 s21, s21, s49
	v_add_u32_e32 v193, s21, v194
	v_cmp_ne_u32_e64 s[46:47], 0, v194
	s_waitcnt vmcnt(0)
	v_pk_mul_f32 v[164:165], v[98:99], v[164:165]
	v_pk_mul_f32 v[166:167], v[96:97], v[166:167]
	v_pk_fma_f32 v[164:165], v[150:151], v[102:103], v[164:165]
	v_pk_fma_f32 v[166:167], v[148:149], v[100:101], v[166:167]
	v_pk_fma_f32 v[162:163], v[110:111], v[162:163], v[164:165]
	v_cndmask_b32_e32 v165, v144, v128, vcc
	v_pk_fma_f32 v[160:161], v[108:109], v[160:161], v[166:167]
	v_cndmask_b32_e32 v166, v145, v129, vcc
	v_mov_b32_dpp v164, v165 row_ror:15 row_mask:0xf bank_mask:0xf
	v_cndmask_b32_e32 v167, v146, v130, vcc
	v_pk_add_f32 v[162:163], v[114:115], v[162:163]
	v_mov_b32_dpp v165, v166 row_ror:15 row_mask:0xf bank_mask:0xf
	v_pk_add_f32 v[160:161], v[112:113], v[160:161]
	s_nop 0
	v_mov_b32_dpp v166, v167 row_ror:15 row_mask:0xf bank_mask:0xf
	s_nop 1
	v_mov_b32_dpp v167, v199 row_ror:15 row_mask:0xf bank_mask:0xf
	v_cndmask_b32_e64 v199, v200, 0, vcc
	v_cndmask_b32_e64 v200, v195, 0, vcc
	v_pk_mul_f32 v[200:201], v[80:81], v[200:201]
	v_pk_mul_f32 v[198:199], v[82:83], v[198:199]
	v_pk_fma_f32 v[200:201], v[144:145], v[84:85], v[200:201]
	v_pk_fma_f32 v[198:199], v[146:147], v[86:87], v[198:199]
	v_pk_fma_f32 v[164:165], v[88:89], v[164:165], v[200:201]
	v_pk_fma_f32 v[166:167], v[90:91], v[166:167], v[198:199]
	v_pk_add_f32 v[164:165], v[92:93], v[164:165]
	v_pk_add_f32 v[166:167], v[94:95], v[166:167]
	s_and_saveexec_b64 s[28:29], s[46:47]
	s_xor_b64 s[28:29], exec, s[28:29]
	s_cbranch_execz .LBB1_383
	v_mul_f32_e32 v195, 0xbfb8aa3b, v160
	v_exp_f32_e32 v195, v195
	v_mul_f32_e32 v196, 0xbfb8aa3b, v161
	v_exp_f32_e32 v196, v196
	v_pk_mul_f32 v[160:161], v[156:157], v[160:161]
	v_add_f32_e32 v195, 1.0, v195
	v_rcp_f32_e32 v198, v195
	v_add_f32_e32 v196, 1.0, v196
	v_mul_f32_e32 v195, 0xbfb8aa3b, v162
	v_rcp_f32_e32 v199, v196
	v_exp_f32_e32 v195, v195
	v_mul_f32_e32 v196, 0xbfb8aa3b, v163
	v_exp_f32_e32 v196, v196
	v_pk_mul_f32 v[160:161], v[160:161], v[198:199]
	v_add_f32_e32 v195, 1.0, v195
	v_rcp_f32_e32 v200, v195
	v_add_f32_e32 v195, 1.0, v196
	v_rcp_f32_e32 v201, v195
	v_cvt_pk_bf16_f32 v160, v160, v161
	v_mul_f32_e32 v161, 0xbfb8aa3b, v164
	v_exp_f32_e32 v195, v161
	v_mul_f32_e32 v161, 0xbfb8aa3b, v165
	v_exp_f32_e32 v196, v161
	v_pk_mul_f32 v[162:163], v[158:159], v[162:163]
	v_pk_mul_f32 v[164:165], v[152:153], v[164:165]
	v_pk_mul_f32 v[162:163], v[162:163], v[200:201]
	s_nop 0
	v_cvt_pk_bf16_f32 v161, v162, v163
	v_add_f32_e32 v162, 1.0, v195
	v_mul_f32_e32 v195, 0xbfb8aa3b, v166
	v_add_f32_e32 v163, 1.0, v196
	v_exp_f32_e32 v195, v195
	v_mul_f32_e32 v196, 0xbfb8aa3b, v167
	v_exp_f32_e32 v196, v196
	v_rcp_f32_e32 v162, v162
	v_add_f32_e32 v195, 1.0, v195
	v_rcp_f32_e32 v198, v195
	v_add_f32_e32 v195, 1.0, v196
	v_rcp_f32_e32 v163, v163
	v_rcp_f32_e32 v199, v195
	v_pk_mul_f32 v[166:167], v[154:155], v[166:167]
	v_pk_mul_f32 v[162:163], v[164:165], v[162:163]
	v_pk_mul_f32 v[164:165], v[166:167], v[198:199]
	v_cvt_pk_bf16_f32 v162, v162, v163
	v_cvt_pk_bf16_f32 v163, v164, v165
	v_mov_b64_e32 v[164:165], s[6:7]
	v_mad_i64_i32 v[164:165], s[42:43], v193, s30, v[164:165]
	v_lshl_add_u64 v[164:165], v[184:185], 1, v[164:165]
	global_store_dwordx4 v[164:165], v[160:163], off

; #define PG8_STAGE(bufoff, gbase, voff) do { _Pragma("unroll") for (int _i = 0; _i < 2; ++_i) \
;         __builtin_amdgcn_global_load_lds((const unsigned*)((const char*)(gbase) + (voff)[_i]), (LAS unsigned*)(lds + (bufoff) + ldsw + _i * 8192), 16, 0, 0); } while (0)
; #define PG8_LDA(dst, b, h) do { _Pragma("unroll") for (int m = 0; m < 4; ++m) _Pragma("unroll") for (int k = 0; k < 2; ++k) dst[m][k] = *(const LAS bf16x8*)(lds + PG8_SA(b, h) + aoff + m * 2048 + k * 1024); } while (0)
; #define PG8_WAIT_V(n) asm volatile("s_waitcnt vmcnt(" #n ")" ::: "memory")
; #define PG8_BAR __builtin_amdgcn_s_barrier()
; template <class Map, class Epi>
; DI void gemm_phase(LAS unsigned char* lds, const Map& MP, const Epi& E, const int nM, const int nN, const int K, const int lda, const int ldb) {
;     ...
;         for (int t = 0; t < nt; t += 2) {
;             const bool last = (t == nt - 2);
;             const char* a1 = cA + (size_t)(t + 1) * kstep;
;             const char* a2 = last ? nA : cA + (size_t)(t + 2) * kstep; const char* b2 = last ? nB : cB + (size_t)(t + 2) * kstep;
;             const char* a3 = a2 + kstep; const char* b3 = b2 + kstep;
;             PG8_LDB(B0, 0, 0); PG8_SCHED; PG8_LDA(At, 0, 0); PG8_STAGE(PG8_SA(1, 1), a1 + hstepA, voffA);
;             PG8_WAIT_L(8); PG8_BAR; PG8_WAIT_L(0); PG8_MMA(0, 0, At, B0); PG8_BAR; PG8_SCHED;
;             PG8_LDB(B1, 0, 1); PG8_STAGE(PG8_SB(0, 0), b2, voffB);
;             PG8_BAR; PG8_WAIT_L(0); PG8_MMA(0, 1, At, B1); PG8_BAR;
;             PG8_LDA(At, 0, 1); PG8_STAGE(PG8_SA(0, 0), a2, voffA);
;             PG8_BAR; PG8_WAIT_L(0); PG8_MMA(1, 0, At, B0); PG8_BAR; PG8_SCHED;
;             PG8_STAGE(PG8_SB(0, 1), b2 + hstepB, voffB);
;             PG8_WAIT_V(6); PG8_BAR; PG8_MMA(1, 1, At, B1); PG8_BAR;
;             PG8_LDB(B0, 1, 0); PG8_SCHED; PG8_LDA(At, 1, 0); PG8_STAGE(PG8_SA(0, 1), a2 + hstepA, voffA);
;             PG8_WAIT_L(8); PG8_BAR; PG8_WAIT_L(0); PG8_MMA(0, 0, At, B0); PG8_BAR; PG8_SCHED;
;             PG8_LDB(B1, 1, 1); PG8_STAGE(PG8_SB(1, 0), b3, voffB);
;             PG8_BAR; PG8_WAIT_L(0); PG8_MMA(0, 1, At, B1); PG8_BAR;
;             PG8_LDA(At, 1, 1); PG8_STAGE(PG8_SA(1, 0), a3, voffA);
;             PG8_BAR; PG8_WAIT_L(0); PG8_MMA(1, 0, At, B0); PG8_BAR; PG8_SCHED;
;             PG8_STAGE(PG8_SB(1, 1), b3 + hstepB, voffB);
;             PG8_WAIT_V(6); PG8_BAR; PG8_MMA(1, 1, At, B1); PG8_BAR;
.LBB1_550:
	s_add_u32 s10, s8, 0x100
	s_addc_u32 s11, s9, 0
	s_cmpk_eq_i32 s3, 0x54
	s_cselect_b32 s15, s43, s11
	s_cselect_b32 s14, s42, s10
	s_cselect_b32 s13, s7, s38
	s_cselect_b32 s12, s6, s5
	s_add_i32 m0, s24, 0xc000
	ds_read_b128 v[168:171], v150
	global_load_lds_dwordx4 v138, s[8:9]
	ds_read_b128 v[172:175], v150 offset:1024
	ds_read_b128 v[176:179], v150 offset:2048
	ds_read_b128 v[180:183], v150 offset:3072
	ds_read_b128 v[184:187], v150 offset:4096
	ds_read_b128 v[188:191], v150 offset:5120
	ds_read_b128 v[192:195], v150 offset:6144
	ds_read_b128 v[198:201], v150 offset:7168
	s_add_i32 m0, s24, 0xe000
	s_nop 0
	global_load_lds_dwordx4 v136, s[8:9]
	s_waitcnt lgkmcnt(8)
	s_setprio 1
	s_barrier
	s_waitcnt lgkmcnt(7)
	v_mfma_f32_16x16x32_bf16 v[124:127], v[152:155], v[168:171], v[124:127]
	v_mfma_f32_16x16x32_bf16 v[120:123], v[160:163], v[168:171], v[120:123]
	s_waitcnt lgkmcnt(5)
	v_mfma_f32_16x16x32_bf16 v[108:111], v[152:155], v[176:179], v[108:111]
	v_mfma_f32_16x16x32_bf16 v[104:107], v[160:163], v[176:179], v[104:107]
	s_waitcnt lgkmcnt(3)
	v_mfma_f32_16x16x32_bf16 v[92:95], v[152:155], v[184:187], v[92:95]
	v_mfma_f32_16x16x32_bf16 v[88:91], v[160:163], v[184:187], v[88:91]
	s_waitcnt lgkmcnt(1)
	v_mfma_f32_16x16x32_bf16 v[76:79], v[152:155], v[192:195], v[76:79]
	v_mfma_f32_16x16x32_bf16 v[72:75], v[160:163], v[192:195], v[72:75]
	v_mfma_f32_16x16x32_bf16 v[124:127], v[156:159], v[172:175], v[124:127]
	s_add_i32 s8, s35, s22
	v_mfma_f32_16x16x32_bf16 v[120:123], v[164:167], v[172:175], v[120:123]
	v_lshl_add_u64 v[144:145], s[12:13], 0, v[132:133]
	v_mfma_f32_16x16x32_bf16 v[108:111], v[156:159], v[180:183], v[108:111]
	v_lshl_add_u64 v[218:219], s[12:13], 0, v[128:129]
	v_mfma_f32_16x16x32_bf16 v[104:107], v[164:167], v[180:183], v[104:107]
	v_mfma_f32_16x16x32_bf16 v[92:95], v[156:159], v[188:191], v[92:95]
	v_mfma_f32_16x16x32_bf16 v[88:91], v[164:167], v[188:191], v[88:91]
	s_waitcnt lgkmcnt(0)
	v_mfma_f32_16x16x32_bf16 v[76:79], v[156:159], v[198:201], v[76:79]
	v_mfma_f32_16x16x32_bf16 v[72:75], v[164:167], v[198:201], v[72:75]
	s_barrier
	s_setprio 0
	s_mov_b32 m0, s8
	ds_read_b128 v[202:205], v151
	global_load_lds_dwordx4 v[144:145], off
	ds_read_b128 v[206:209], v151 offset:1024
	ds_read_b128 v[210:213], v151 offset:2048
	ds_read_b128 v[214:217], v151 offset:3072
	s_add_i32 m0, s8, 0x2000
	s_nop 0
	global_load_lds_dwordx4 v[218:219], off
	s_setprio 1
	s_barrier
	s_waitcnt lgkmcnt(3)
	v_mfma_f32_16x16x32_bf16 v[116:119], v[202:205], v[168:171], v[116:119]
	s_waitcnt lgkmcnt(1)
	v_mfma_f32_16x16x32_bf16 v[112:115], v[210:213], v[168:171], v[112:115]
	v_mfma_f32_16x16x32_bf16 v[100:103], v[202:205], v[176:179], v[100:103]
	v_mfma_f32_16x16x32_bf16 v[96:99], v[210:213], v[176:179], v[96:99]
	v_mfma_f32_16x16x32_bf16 v[84:87], v[202:205], v[184:187], v[84:87]
	v_mfma_f32_16x16x32_bf16 v[80:83], v[210:213], v[184:187], v[80:83]
	v_mfma_f32_16x16x32_bf16 v[68:71], v[202:205], v[192:195], v[68:71]
	v_mfma_f32_16x16x32_bf16 v[64:67], v[210:213], v[192:195], v[64:67]
	v_mfma_f32_16x16x32_bf16 v[116:119], v[206:209], v[172:175], v[116:119]
	v_lshl_add_u64 v[222:223], s[14:15], 0, v[130:131]
	s_mov_b32 m0, s24
	s_waitcnt lgkmcnt(0)
	v_mfma_f32_16x16x32_bf16 v[112:115], v[214:217], v[172:175], v[112:115]
	v_lshl_add_u64 v[220:221], s[14:15], 0, v[134:135]
	v_mfma_f32_16x16x32_bf16 v[100:103], v[206:209], v[180:183], v[100:103]
	v_mfma_f32_16x16x32_bf16 v[96:99], v[214:217], v[180:183], v[96:99]
	v_mfma_f32_16x16x32_bf16 v[84:87], v[206:209], v[188:191], v[84:87]
	v_mfma_f32_16x16x32_bf16 v[80:83], v[214:217], v[188:191], v[80:83]
	v_mfma_f32_16x16x32_bf16 v[68:71], v[206:209], v[198:201], v[68:71]
	v_mfma_f32_16x16x32_bf16 v[64:67], v[214:217], v[198:201], v[64:67]
	s_barrier
	s_setprio 0
	ds_read_b128 v[168:171], v150 offset:16384
	global_load_lds_dwordx4 v[220:221], off
	ds_read_b128 v[172:175], v150 offset:17408
	ds_read_b128 v[176:179], v150 offset:18432
	ds_read_b128 v[180:183], v150 offset:19456
	ds_read_b128 v[184:187], v150 offset:20480
	ds_read_b128 v[188:191], v150 offset:21504
	ds_read_b128 v[192:195], v150 offset:22528
	ds_read_b128 v[198:201], v150 offset:23552
	s_mov_b32 m0, s25
	s_nop 0
	global_load_lds_dwordx4 v[222:223], off
	s_waitcnt vmcnt(10)
	s_setprio 1
	s_barrier
	s_waitcnt lgkmcnt(7)
	v_mfma_f32_16x16x32_bf16 v[60:63], v[152:155], v[168:171], v[60:63]
	v_mfma_f32_16x16x32_bf16 v[56:59], v[160:163], v[168:171], v[56:59]
	s_waitcnt lgkmcnt(5)
	v_mfma_f32_16x16x32_bf16 v[44:47], v[152:155], v[176:179], v[44:47]
	v_mfma_f32_16x16x32_bf16 v[40:43], v[160:163], v[176:179], v[40:43]
	s_waitcnt lgkmcnt(3)
	v_mfma_f32_16x16x32_bf16 v[28:31], v[152:155], v[184:187], v[28:31]
	v_mfma_f32_16x16x32_bf16 v[24:27], v[160:163], v[184:187], v[24:27]
	s_waitcnt lgkmcnt(1)
	v_mfma_f32_16x16x32_bf16 v[12:15], v[152:155], v[192:195], v[12:15]
	v_mfma_f32_16x16x32_bf16 v[8:11], v[160:163], v[192:195], v[8:11]
	v_mfma_f32_16x16x32_bf16 v[60:63], v[156:159], v[172:175], v[60:63]
	s_add_u32 s8, s12, 0x160000
	s_addc_u32 s9, s13, 0
	v_mfma_f32_16x16x32_bf16 v[56:59], v[164:167], v[172:175], v[56:59]
	s_add_i32 s39, s36, s22
	v_mfma_f32_16x16x32_bf16 v[44:47], v[156:159], v[180:183], v[44:47]
	v_mfma_f32_16x16x32_bf16 v[40:43], v[164:167], v[180:183], v[40:43]
	v_mfma_f32_16x16x32_bf16 v[28:31], v[156:159], v[188:191], v[28:31]
	v_mfma_f32_16x16x32_bf16 v[24:27], v[164:167], v[188:191], v[24:27]
	s_waitcnt lgkmcnt(0)
	v_mfma_f32_16x16x32_bf16 v[12:15], v[156:159], v[198:201], v[12:15]
	v_mfma_f32_16x16x32_bf16 v[8:11], v[164:167], v[198:201], v[8:11]
	s_barrier
; #define PG8_STAGE(bufoff, gbase, voff) do { _Pragma("unroll") for (int _i = 0; _i < 2; ++_i) \
;         __builtin_amdgcn_global_load_lds((const unsigned*)((const char*)(gbase) + (voff)[_i]), (LAS unsigned*)(lds + (bufoff) + ldsw + _i * 8192), 16, 0, 0); } while (0)
; #define PG8_LDA(dst, b, h) do { _Pragma("unroll") for (int m = 0; m < 4; ++m) _Pragma("unroll") for (int k = 0; k < 2; ++k) dst[m][k] = *(const LAS bf16x8*)(lds + PG8_SA(b, h) + aoff + m * 2048 + k * 1024); } while (0)
; #define PG8_WAIT_V(n) asm volatile("s_waitcnt vmcnt(" #n ")" ::: "memory")
; #define PG8_BAR __builtin_amdgcn_s_barrier()
; template <class Map, class Epi>
; DI void gemm_phase(LAS unsigned char* lds, const Map& MP, const Epi& E, const int nM, const int nN, const int K, const int lda, const int ldb) {
;     ...
;         for (int t = 0; t < nt; t += 2) {
;             const bool last = (t == nt - 2);
;             const char* a1 = cA + (size_t)(t + 1) * kstep;
;             const char* a2 = last ? nA : cA + (size_t)(t + 2) * kstep; const char* b2 = last ? nB : cB + (size_t)(t + 2) * kstep;
;             const char* a3 = a2 + kstep; const char* b3 = b2 + kstep;
;             PG8_LDB(B0, 0, 0); PG8_SCHED; PG8_LDA(At, 0, 0); PG8_STAGE(PG8_SA(1, 1), a1 + hstepA, voffA);
;             PG8_WAIT_L(8); PG8_BAR; PG8_WAIT_L(0); PG8_MMA(0, 0, At, B0); PG8_BAR; PG8_SCHED;
;             PG8_LDB(B1, 0, 1); PG8_STAGE(PG8_SB(0, 0), b2, voffB);
;             PG8_BAR; PG8_WAIT_L(0); PG8_MMA(0, 1, At, B1); PG8_BAR;
;             PG8_LDA(At, 0, 1); PG8_STAGE(PG8_SA(0, 0), a2, voffA);
;             PG8_BAR; PG8_WAIT_L(0); PG8_MMA(1, 0, At, B0); PG8_BAR; PG8_SCHED;
;             PG8_STAGE(PG8_SB(0, 1), b2 + hstepB, voffB);
;             PG8_WAIT_V(6); PG8_BAR; PG8_MMA(1, 1, At, B1); PG8_BAR;
;             PG8_LDB(B0, 1, 0); PG8_SCHED; PG8_LDA(At, 1, 0); PG8_STAGE(PG8_SA(0, 1), a2 + hstepA, voffA);
;             PG8_WAIT_L(8); PG8_BAR; PG8_WAIT_L(0); PG8_MMA(0, 0, At, B0); PG8_BAR; PG8_SCHED;
;             PG8_LDB(B1, 1, 1); PG8_STAGE(PG8_SB(1, 0), b3, voffB);
;             PG8_BAR; PG8_WAIT_L(0); PG8_MMA(0, 1, At, B1); PG8_BAR;
;             PG8_LDA(At, 1, 1); PG8_STAGE(PG8_SA(1, 0), a3, voffA);
;             PG8_BAR; PG8_WAIT_L(0); PG8_MMA(1, 0, At, B0); PG8_BAR; PG8_SCHED;
;             PG8_STAGE(PG8_SB(1, 1), b3 + hstepB, voffB);
;             PG8_WAIT_V(6); PG8_BAR; PG8_MMA(1, 1, At, B1); PG8_BAR;
	s_setprio 0
	s_mov_b32 m0, s39
	s_nop 0
	global_load_lds_dwordx4 v132, s[8:9]
	s_add_i32 m0, s39, 0x2000
	s_nop 0
	global_load_lds_dwordx4 v128, s[8:9]
	s_waitcnt vmcnt(6)
	s_setprio 1
	s_barrier
	v_mfma_f32_16x16x32_bf16 v[52:55], v[202:205], v[168:171], v[52:55]
	v_mfma_f32_16x16x32_bf16 v[48:51], v[210:213], v[168:171], v[48:51]
	s_add_i32 s39, 0, 0x18000
	v_add_u32_e32 v164, s39, v148
	ds_read_b128 v[152:155], v164
	v_mfma_f32_16x16x32_bf16 v[36:39], v[202:205], v[176:179], v[36:39]
	v_mfma_f32_16x16x32_bf16 v[32:35], v[210:213], v[176:179], v[32:35]
	ds_read_b128 v[156:159], v164 offset:1024
	v_mfma_f32_16x16x32_bf16 v[20:23], v[202:205], v[184:187], v[20:23]
	v_mfma_f32_16x16x32_bf16 v[16:19], v[210:213], v[184:187], v[16:19]
	ds_read_b128 v[160:163], v164 offset:2048
	v_mfma_f32_16x16x32_bf16 v[4:7], v[202:205], v[192:195], v[4:7]
	v_mfma_f32_16x16x32_bf16 v[0:3], v[210:213], v[192:195], v[0:3]
	ds_read_b128 v[164:167], v164 offset:3072
	v_mfma_f32_16x16x32_bf16 v[52:55], v[206:209], v[172:175], v[52:55]
	s_add_u32 s8, s14, 0x160000
	s_addc_u32 s9, s15, 0
	v_mfma_f32_16x16x32_bf16 v[48:51], v[214:217], v[172:175], v[48:51]
	v_mfma_f32_16x16x32_bf16 v[36:39], v[206:209], v[180:183], v[36:39]
	v_mfma_f32_16x16x32_bf16 v[32:35], v[214:217], v[180:183], v[32:35]
	v_mfma_f32_16x16x32_bf16 v[20:23], v[206:209], v[188:191], v[20:23]
	v_mfma_f32_16x16x32_bf16 v[16:19], v[214:217], v[188:191], v[16:19]
	v_mfma_f32_16x16x32_bf16 v[4:7], v[206:209], v[198:201], v[4:7]
	v_mfma_f32_16x16x32_bf16 v[0:3], v[214:217], v[198:201], v[0:3]
	s_barrier
	s_setprio 0
	s_mov_b32 m0, s26
	ds_read_b128 v[168:171], v150 offset:32768
	global_load_lds_dwordx4 v134, s[8:9]
	ds_read_b128 v[172:175], v150 offset:33792
	ds_read_b128 v[176:179], v150 offset:34816
	ds_read_b128 v[180:183], v150 offset:35840
	ds_read_b128 v[184:187], v150 offset:36864
	ds_read_b128 v[188:191], v150 offset:37888
	ds_read_b128 v[192:195], v150 offset:38912
	ds_read_b128 v[198:201], v150 offset:39936
	s_mov_b32 m0, s27
	s_nop 0
	global_load_lds_dwordx4 v130, s[8:9]
	s_waitcnt lgkmcnt(8)
	s_setprio 1
	s_barrier
	s_waitcnt lgkmcnt(7)
	v_mfma_f32_16x16x32_bf16 v[124:127], v[152:155], v[168:171], v[124:127]
	v_mfma_f32_16x16x32_bf16 v[120:123], v[160:163], v[168:171], v[120:123]
	s_waitcnt lgkmcnt(5)
	v_mfma_f32_16x16x32_bf16 v[108:111], v[152:155], v[176:179], v[108:111]
	v_mfma_f32_16x16x32_bf16 v[104:107], v[160:163], v[176:179], v[104:107]
	s_waitcnt lgkmcnt(3)
	v_mfma_f32_16x16x32_bf16 v[92:95], v[152:155], v[184:187], v[92:95]
	v_mfma_f32_16x16x32_bf16 v[88:91], v[160:163], v[184:187], v[88:91]
	s_waitcnt lgkmcnt(1)
	v_mfma_f32_16x16x32_bf16 v[76:79], v[152:155], v[192:195], v[76:79]
	v_mfma_f32_16x16x32_bf16 v[72:75], v[160:163], v[192:195], v[72:75]
	v_mfma_f32_16x16x32_bf16 v[124:127], v[156:159], v[172:175], v[124:127]
	s_add_i32 s14, 0, 0x1c000
	v_mfma_f32_16x16x32_bf16 v[120:123], v[164:167], v[172:175], v[120:123]
	s_add_i32 s8, s39, s22
	v_mfma_f32_16x16x32_bf16 v[108:111], v[156:159], v[180:183], v[108:111]
	v_add_u32_e32 v196, s14, v148
	v_mfma_f32_16x16x32_bf16 v[104:107], v[164:167], v[180:183], v[104:107]
	v_lshl_add_u64 v[144:145], v[144:145], 0, s[52:53]
	v_mfma_f32_16x16x32_bf16 v[92:95], v[156:159], v[188:191], v[92:95]
	v_mfma_f32_16x16x32_bf16 v[88:91], v[164:167], v[188:191], v[88:91]
	s_waitcnt lgkmcnt(0)
	v_mfma_f32_16x16x32_bf16 v[76:79], v[156:159], v[198:201], v[76:79]
	v_mfma_f32_16x16x32_bf16 v[72:75], v[164:167], v[198:201], v[72:75]
	s_barrier
	s_setprio 0
	s_mov_b32 m0, s8
	ds_read_b128 v[202:205], v196
	global_load_lds_dwordx4 v[144:145], off
	ds_read_b128 v[206:209], v196 offset:1024
	ds_read_b128 v[210:213], v196 offset:2048
	ds_read_b128 v[214:217], v196 offset:3072
	v_lshl_add_u64 v[144:145], v[218:219], 0, s[52:53]
	s_add_i32 m0, s8, 0x2000
	s_nop 0
	global_load_lds_dwordx4 v[144:145], off
	s_setprio 1
	s_barrier
	s_waitcnt lgkmcnt(3)
	v_mfma_f32_16x16x32_bf16 v[116:119], v[202:205], v[168:171], v[116:119]
	s_waitcnt lgkmcnt(1)
	v_mfma_f32_16x16x32_bf16 v[112:115], v[210:213], v[168:171], v[112:115]
	v_mfma_f32_16x16x32_bf16 v[100:103], v[202:205], v[176:179], v[100:103]
	v_mfma_f32_16x16x32_bf16 v[96:99], v[210:213], v[176:179], v[96:99]
	v_mfma_f32_16x16x32_bf16 v[84:87], v[202:205], v[184:187], v[84:87]
	v_mfma_f32_16x16x32_bf16 v[80:83], v[210:213], v[184:187], v[80:83]
	v_mfma_f32_16x16x32_bf16 v[68:71], v[202:205], v[192:195], v[68:71]
	v_mfma_f32_16x16x32_bf16 v[64:67], v[210:213], v[192:195], v[64:67]
	v_mfma_f32_16x16x32_bf16 v[116:119], v[206:209], v[172:175], v[116:119]
	s_mov_b32 m0, s30
	s_waitcnt lgkmcnt(0)
	v_mfma_f32_16x16x32_bf16 v[112:115], v[214:217], v[172:175], v[112:115]
	v_lshl_add_u64 v[144:145], v[220:221], 0, s[52:53]
	v_mfma_f32_16x16x32_bf16 v[100:103], v[206:209], v[180:183], v[100:103]
	v_mfma_f32_16x16x32_bf16 v[96:99], v[214:217], v[180:183], v[96:99]
	v_mfma_f32_16x16x32_bf16 v[84:87], v[206:209], v[188:191], v[84:87]
	v_mfma_f32_16x16x32_bf16 v[80:83], v[214:217], v[188:191], v[80:83]
	v_mfma_f32_16x16x32_bf16 v[68:71], v[206:209], v[198:201], v[68:71]
	v_mfma_f32_16x16x32_bf16 v[64:67], v[214:217], v[198:201], v[64:67]
	s_barrier
	s_setprio 0
	ds_read_b128 v[168:171], v150 offset:49152
	global_load_lds_dwordx4 v[144:145], off
	ds_read_b128 v[172:175], v150 offset:50176
	ds_read_b128 v[176:179], v150 offset:51200
	ds_read_b128 v[180:183], v150 offset:52224
	ds_read_b128 v[184:187], v150 offset:53248
	ds_read_b128 v[188:191], v150 offset:54272
	ds_read_b128 v[192:195], v150 offset:55296
	ds_read_b128 v[198:201], v150 offset:56320
	v_lshl_add_u64 v[144:145], v[222:223], 0, s[52:53]
	s_mov_b32 m0, s31
	s_nop 0
	global_load_lds_dwordx4 v[144:145], off
	s_waitcnt vmcnt(10)
	s_setprio 1
	s_barrier
; #define PG8_WAIT_V(n) asm volatile("s_waitcnt vmcnt(" #n ")" ::: "memory")
;     DI void operator()(const f32x4 (&acc)[2][2][4][2], const Unit& u, int wr, int wc, int fr, int fq) const {
;         const int row0 = u.pm * BM + wr * 64 + fr, col0 = u.pn * BM + wc * 32 + 8 * fq;
;         f32x4 sc[2][2];
; #pragma unroll
;         for (int bj = 0; bj < 2; ++bj)
; #pragma unroll
;             for (int n = 0; n < 2; ++n) sc[bj][n] = scale ? *(const f32x4*)(scale + col0 + bj * HALF + 4 * n) : (f32x4){1.f, 1.f, 1.f, 1.f};
; #pragma unroll
;         for (int ai = 0; ai < 2; ++ai)
; #pragma unroll
; template <class Map, class Epi>
; DI void gemm_phase(LAS unsigned char* lds, const Map& MP, const Epi& E, const int nM, const int nN, const int K, const int lda, const int ldb) {
;     ...
;         for (int t = 0; t < nt; t += 2) {
;             const bool last = (t == nt - 2);
;             const char* a1 = cA + (size_t)(t + 1) * kstep;
;             const char* a2 = last ? nA : cA + (size_t)(t + 2) * kstep; const char* b2 = last ? nB : cB + (size_t)(t + 2) * kstep;
;             const char* a3 = a2 + kstep; const char* b3 = b2 + kstep;
;             PG8_LDB(B0, 0, 0); PG8_SCHED; PG8_LDA(At, 0, 0); PG8_STAGE(PG8_SA(1, 1), a1 + hstepA, voffA);
;             PG8_WAIT_L(8); PG8_BAR; PG8_WAIT_L(0); PG8_MMA(0, 0, At, B0); PG8_BAR; PG8_SCHED;
;             PG8_LDB(B1, 0, 1); PG8_STAGE(PG8_SB(0, 0), b2, voffB);
;             PG8_BAR; PG8_WAIT_L(0); PG8_MMA(0, 1, At, B1); PG8_BAR;
;             PG8_LDA(At, 0, 1); PG8_STAGE(PG8_SA(0, 0), a2, voffA);
;             PG8_BAR; PG8_WAIT_L(0); PG8_MMA(1, 0, At, B0); PG8_BAR; PG8_SCHED;
;             PG8_STAGE(PG8_SB(0, 1), b2 + hstepB, voffB);
;             PG8_WAIT_V(6); PG8_BAR; PG8_MMA(1, 1, At, B1); PG8_BAR;
;             PG8_LDB(B0, 1, 0); PG8_SCHED; PG8_LDA(At, 1, 0); PG8_STAGE(PG8_SA(0, 1), a2 + hstepA, voffA);
;             PG8_WAIT_L(8); PG8_BAR; PG8_WAIT_L(0); PG8_MMA(0, 0, At, B0); PG8_BAR; PG8_SCHED;
;             PG8_LDB(B1, 1, 1); PG8_STAGE(PG8_SB(1, 0), b3, voffB);
;             PG8_BAR; PG8_WAIT_L(0); PG8_MMA(0, 1, At, B1); PG8_BAR;
;             PG8_LDA(At, 1, 1); PG8_STAGE(PG8_SA(1, 0), a3, voffA);
;             PG8_BAR; PG8_WAIT_L(0); PG8_MMA(1, 0, At, B0); PG8_BAR; PG8_SCHED;
;             PG8_STAGE(PG8_SB(1, 1), b3 + hstepB, voffB);
;             PG8_WAIT_V(6); PG8_BAR; PG8_MMA(1, 1, At, B1); PG8_BAR;
	s_waitcnt lgkmcnt(7)
	v_mfma_f32_16x16x32_bf16 v[60:63], v[152:155], v[168:171], v[60:63]
	v_mfma_f32_16x16x32_bf16 v[56:59], v[160:163], v[168:171], v[56:59]
	s_waitcnt lgkmcnt(5)
	v_mfma_f32_16x16x32_bf16 v[44:47], v[152:155], v[176:179], v[44:47]
	v_mfma_f32_16x16x32_bf16 v[40:43], v[160:163], v[176:179], v[40:43]
	s_waitcnt lgkmcnt(3)
	v_mfma_f32_16x16x32_bf16 v[28:31], v[152:155], v[184:187], v[28:31]
	v_mfma_f32_16x16x32_bf16 v[24:27], v[160:163], v[184:187], v[24:27]
	s_waitcnt lgkmcnt(1)
	v_mfma_f32_16x16x32_bf16 v[12:15], v[152:155], v[192:195], v[12:15]
	v_mfma_f32_16x16x32_bf16 v[8:11], v[160:163], v[192:195], v[8:11]
	v_mfma_f32_16x16x32_bf16 v[60:63], v[156:159], v[172:175], v[60:63]
	s_add_u32 s8, s12, 0x160080
	s_addc_u32 s9, s13, 0
	v_mfma_f32_16x16x32_bf16 v[56:59], v[164:167], v[172:175], v[56:59]
	s_add_i32 s12, s14, s22
	v_mfma_f32_16x16x32_bf16 v[44:47], v[156:159], v[180:183], v[44:47]
	v_mfma_f32_16x16x32_bf16 v[40:43], v[164:167], v[180:183], v[40:43]
	v_mfma_f32_16x16x32_bf16 v[28:31], v[156:159], v[188:191], v[28:31]
	v_mfma_f32_16x16x32_bf16 v[24:27], v[164:167], v[188:191], v[24:27]
	s_waitcnt lgkmcnt(0)
	v_mfma_f32_16x16x32_bf16 v[12:15], v[156:159], v[198:201], v[12:15]
	v_mfma_f32_16x16x32_bf16 v[8:11], v[164:167], v[198:201], v[8:11]
	s_barrier
	s_setprio 0
	s_mov_b32 m0, s12
	s_nop 0
	global_load_lds_dwordx4 v132, s[8:9]
	s_add_i32 m0, s12, 0x2000
	s_nop 0
	global_load_lds_dwordx4 v128, s[8:9]
	s_waitcnt vmcnt(6)
	s_setprio 1
	s_barrier
	v_mfma_f32_16x16x32_bf16 v[52:55], v[202:205], v[168:171], v[52:55]
	v_mfma_f32_16x16x32_bf16 v[48:51], v[210:213], v[168:171], v[48:51]
	ds_read_b128 v[152:155], v149
	v_mfma_f32_16x16x32_bf16 v[36:39], v[202:205], v[176:179], v[36:39]
	v_mfma_f32_16x16x32_bf16 v[32:35], v[210:213], v[176:179], v[32:35]
	ds_read_b128 v[156:159], v149 offset:1024
	v_mfma_f32_16x16x32_bf16 v[20:23], v[202:205], v[184:187], v[20:23]
	v_mfma_f32_16x16x32_bf16 v[16:19], v[210:213], v[184:187], v[16:19]
	ds_read_b128 v[160:163], v149 offset:2048
	v_mfma_f32_16x16x32_bf16 v[4:7], v[202:205], v[192:195], v[4:7]
	v_mfma_f32_16x16x32_bf16 v[0:3], v[210:213], v[192:195], v[0:3]
	ds_read_b128 v[164:167], v149 offset:3072
	v_mfma_f32_16x16x32_bf16 v[52:55], v[206:209], v[172:175], v[52:55]
	s_add_i32 s3, s3, 2
	v_mfma_f32_16x16x32_bf16 v[48:51], v[214:217], v[172:175], v[48:51]
	s_add_u32 s5, s5, 0x100
	s_addc_u32 s38, s38, 0
	v_mfma_f32_16x16x32_bf16 v[36:39], v[206:209], v[180:183], v[36:39]
	s_cmpk_gt_u32 s3, 0x55
	v_mfma_f32_16x16x32_bf16 v[32:35], v[214:217], v[180:183], v[32:35]
	s_mov_b64 s[8:9], s[10:11]
	v_mfma_f32_16x16x32_bf16 v[20:23], v[206:209], v[188:191], v[20:23]
	v_mfma_f32_16x16x32_bf16 v[16:19], v[214:217], v[188:191], v[16:19]
	v_mfma_f32_16x16x32_bf16 v[4:7], v[206:209], v[198:201], v[4:7]
	v_mfma_f32_16x16x32_bf16 v[0:3], v[214:217], v[198:201], v[0:3]
	s_barrier
	s_setprio 0
	s_cbranch_scc0 .LBB1_550
	s_waitcnt lgkmcnt(0)
	v_mov_b32_e32 v144, v146
	v_mov_b32_e32 v152, v147
	s_lshl_b32 s2, s2, 8
	s_add_i32 s2, s2, s29
	s_lshl_b32 s3, s4, 8
	v_add_u32_e32 v152, s2, v152
	s_or_b32 s3, s3, s54
	v_ashrrev_i32_e32 v153, 31, v152
	v_lshl_add_u32 v144, v144, 3, s3
	v_lshlrev_b64 v[152:153], 12, v[152:153]
	v_ashrrev_i32_e32 v145, 31, v144
	v_lshl_add_u64 v[152:153], s[46:47], 0, v[152:153]
	v_lshl_add_u64 v[144:145], v[144:145], 1, v[152:153]
	global_load_dwordx4 v[160:163], v[144:145], off
	global_load_dwordx4 v[164:167], v[144:145], off offset:256
	s_mov_b64 s[98:99], 0x10000
	v_lshl_add_u64 v[154:155], v[144:145], 0, s[98:99]
	global_load_dwordx4 v[168:171], v[154:155], off
	global_load_dwordx4 v[172:175], v[154:155], off offset:256
	s_mov_b64 s[98:99], 0x20000
	v_lshl_add_u64 v[154:155], v[144:145], 0, s[98:99]
	global_load_dwordx4 v[176:179], v[154:155], off
	global_load_dwordx4 v[180:183], v[154:155], off offset:256
	s_mov_b64 s[98:99], 0x30000
	v_lshl_add_u64 v[154:155], v[144:145], 0, s[98:99]
	global_load_dwordx4 v[184:187], v[154:155], off
	global_load_dwordx4 v[188:191], v[154:155], off offset:256
	s_mov_b64 s[98:99], 0x80000
	v_lshl_add_u64 v[154:155], v[144:145], 0, s[98:99]
	global_load_dwordx4 v[192:195], v[154:155], off
	global_load_dwordx4 v[198:201], v[154:155], off offset:256
	s_mov_b64 s[98:99], 0x90000
	v_lshl_add_u64 v[154:155], v[144:145], 0, s[98:99]
	global_load_dwordx4 v[202:205], v[154:155], off
	global_load_dwordx4 v[206:209], v[154:155], off offset:256
	s_mov_b64 s[98:99], 0xa0000
	v_lshl_add_u64 v[154:155], v[144:145], 0, s[98:99]
	global_load_dwordx4 v[210:213], v[154:155], off
	global_load_dwordx4 v[214:217], v[154:155], off offset:256
	s_mov_b64 s[98:99], 0xb0000
	v_lshl_add_u64 v[154:155], v[144:145], 0, s[98:99]
	global_load_dwordx4 v[248:251], v[154:155], off
	global_load_dwordx4 v[252:255], v[154:155], off offset:256
	s_waitcnt vmcnt(15)
	s_nop 1
	v_mov_b32_e32 v152, v160
	v_mov_b32_e32 v153, v161
	v_mov_b32_e32 v154, v162
	v_mov_b32_e32 v155, v163
	s_mov_b64 s[2:3], 0x10000
	s_mov_b32 s4, s37
	s_mov_b64 s[10:11], s[6:7]
	s_mov_b64 s[8:9], s[42:43]
	s_waitcnt lgkmcnt(0)
	v_lshlrev_b32_e32 v156, 16, v152
	v_and_b32_e32 v157, 0xffff0000, v152
	v_lshlrev_b32_e32 v152, 16, v153
	v_and_b32_e32 v153, 0xffff0000, v153
	v_lshlrev_b32_e32 v158, 16, v154
	v_and_b32_e32 v159, 0xffff0000, v154
	v_lshlrev_b32_e32 v154, 16, v155
	v_and_b32_e32 v155, 0xffff0000, v155
	v_pk_add_f32 v[126:127], v[126:127], v[152:153]
	v_pk_add_f32 v[124:125], v[124:125], v[156:157]
	v_pk_add_f32 v[152:153], v[122:123], v[154:155]
	v_pk_add_f32 v[122:123], v[120:121], v[158:159]
	v_cvt_pk_bf16_f32 v120, v124, v125
	v_cvt_pk_bf16_f32 v121, v126, v127
	v_cvt_pk_bf16_f32 v122, v122, v123
	v_cvt_pk_bf16_f32 v123, v152, v153
	global_store_dwordx4 v[144:145], v[120:123], off
	s_waitcnt vmcnt(15)
; DI unsigned pack2(float a, float b) { f32x2 v = {a, b}; hwbf16x2 r = __builtin_convertvector(v, hwbf16x2); return __builtin_bit_cast(unsigned, r); }
; DI float bflo(unsigned w) { return __uint_as_float(w << 16); }
; DI float bfhi(unsigned w) { return __uint_as_float(w & 0xffff0000u); }
;     DI void operator()(const f32x4 (&acc)[2][2][4][2], const Unit& u, int wr, int wc, int fr, int fq) const {
;         const int row0 = u.pm * BM + wr * 64 + fr, col0 = u.pn * BM + wc * 32 + 8 * fq;
;         f32x4 sc[2][2];
; #pragma unroll
;         for (int bj = 0; bj < 2; ++bj)
; #pragma unroll
;             for (int n = 0; n < 2; ++n) sc[bj][n] = scale ? *(const f32x4*)(scale + col0 + bj * HALF + 4 * n) : (f32x4){1.f, 1.f, 1.f, 1.f};
; #pragma unroll
;         for (int ai = 0; ai < 2; ++ai)
; #pragma unroll
;             for (int m = 0; m < 4; ++m) { const size_t ro = (size_t)(row0 + ai * HALF + m * 16) * D + col0;
; #pragma unroll
;                 for (int bj = 0; bj < 2; ++bj) {
;                     f32x4 x0, x1;
;                     if constexpr (IB) { const u32x4 w = *(const u32x4*)((const bf16_t*)Xin + ro + bj * HALF);
;                         x0 = (f32x4){bflo(w[0]), bfhi(w[0]), bflo(w[1]), bfhi(w[1])}; x1 = (f32x4){bflo(w[2]), bfhi(w[2]), bflo(w[3]), bfhi(w[3])}; }
;                     else { x0 = *(const f32x4*)((const float*)Xin + ro + bj * HALF); x1 = *(const f32x4*)((const float*)Xin + ro + bj * HALF + 4); }
;                     x0 += acc[ai][bj][m][0] * sc[bj][0]; x1 += acc[ai][bj][m][1] * sc[bj][1];
;                     if constexpr (OB) { u32x4 o; o[0] = pack2(x0[0], x0[1]); o[1] = pack2(x0[2], x0[3]); o[2] = pack2(x1[0], x1[1]); o[3] = pack2(x1[2], x1[3]);
;                         *(u32x4*)((bf16_t*)Xout + ro + bj * HALF) = o; }
;                     else { *(f32x4*)((float*)Xout + ro + bj * HALF) = x0; *(f32x4*)((float*)Xout + ro + bj * HALF + 4) = x1; } } }
	s_nop 1
	v_mov_b32_e32 v120, v164
	v_mov_b32_e32 v121, v165
	v_mov_b32_e32 v122, v166
	v_mov_b32_e32 v123, v167
	s_waitcnt lgkmcnt(0)
	v_lshlrev_b32_e32 v124, 16, v120
	v_and_b32_e32 v125, 0xffff0000, v120
	v_lshlrev_b32_e32 v120, 16, v121
	v_and_b32_e32 v121, 0xffff0000, v121
	v_lshlrev_b32_e32 v126, 16, v122
	v_and_b32_e32 v127, 0xffff0000, v122
	v_lshlrev_b32_e32 v122, 16, v123
	v_and_b32_e32 v123, 0xffff0000, v123
	v_pk_add_f32 v[116:117], v[116:117], v[124:125]
	v_pk_add_f32 v[118:119], v[118:119], v[120:121]
	v_pk_add_f32 v[120:121], v[114:115], v[122:123]
	v_pk_add_f32 v[114:115], v[112:113], v[126:127]
	v_cvt_pk_bf16_f32 v112, v116, v117
	v_lshl_add_u64 v[116:117], v[144:145], 0, s[2:3]
	s_mov_b32 s2, 0x10000
	v_cvt_pk_bf16_f32 v113, v118, v119
	v_add_co_u32_e32 v118, vcc, s2, v144
	v_cvt_pk_bf16_f32 v114, v114, v115
	v_cvt_pk_bf16_f32 v115, v120, v121
	v_addc_co_u32_e32 v119, vcc, 0, v145, vcc
	global_store_dwordx4 v[144:145], v[112:115], off offset:256
	s_waitcnt vmcnt(15)
	s_nop 1
	v_mov_b32_e32 v112, v168
	v_mov_b32_e32 v113, v169
	v_mov_b32_e32 v114, v170
	v_mov_b32_e32 v115, v171
	s_mov_b64 s[2:3], 0x20000
	s_waitcnt lgkmcnt(0)
	v_lshlrev_b32_e32 v120, 16, v112
	v_and_b32_e32 v121, 0xffff0000, v112
	v_lshlrev_b32_e32 v112, 16, v113
	v_and_b32_e32 v113, 0xffff0000, v113
	v_lshlrev_b32_e32 v122, 16, v114
	v_and_b32_e32 v123, 0xffff0000, v114
	v_lshlrev_b32_e32 v114, 16, v115
	v_and_b32_e32 v115, 0xffff0000, v115
	v_pk_add_f32 v[110:111], v[110:111], v[112:113]
	v_pk_add_f32 v[108:109], v[108:109], v[120:121]
	v_pk_add_f32 v[112:113], v[106:107], v[114:115]
	v_pk_add_f32 v[106:107], v[104:105], v[122:123]
	v_cvt_pk_bf16_f32 v104, v108, v109
	v_cvt_pk_bf16_f32 v105, v110, v111
	v_cvt_pk_bf16_f32 v106, v106, v107
	v_cvt_pk_bf16_f32 v107, v112, v113
	global_store_dwordx4 v[118:119], v[104:107], off
	s_waitcnt vmcnt(15)
	s_nop 1
	v_mov_b32_e32 v104, v172
	v_mov_b32_e32 v105, v173
	v_mov_b32_e32 v106, v174
	v_mov_b32_e32 v107, v175
	s_waitcnt lgkmcnt(0)
	v_lshlrev_b32_e32 v108, 16, v104
	v_and_b32_e32 v109, 0xffff0000, v104
	v_lshlrev_b32_e32 v104, 16, v105
	v_and_b32_e32 v105, 0xffff0000, v105
	v_lshlrev_b32_e32 v110, 16, v106
	v_and_b32_e32 v111, 0xffff0000, v106
	v_lshlrev_b32_e32 v106, 16, v107
	v_and_b32_e32 v107, 0xffff0000, v107
	v_pk_add_f32 v[100:101], v[100:101], v[108:109]
	v_pk_add_f32 v[102:103], v[102:103], v[104:105]
	v_pk_add_f32 v[104:105], v[98:99], v[106:107]
	v_pk_add_f32 v[98:99], v[96:97], v[110:111]
	v_cvt_pk_bf16_f32 v96, v100, v101
	v_lshl_add_u64 v[100:101], v[144:145], 0, s[2:3]
	s_mov_b32 s2, 0x20000
	v_cvt_pk_bf16_f32 v97, v102, v103
	v_add_co_u32_e32 v102, vcc, s2, v144
	v_cvt_pk_bf16_f32 v98, v98, v99
	v_cvt_pk_bf16_f32 v99, v104, v105
	v_addc_co_u32_e32 v103, vcc, 0, v145, vcc
	global_store_dwordx4 v[116:117], v[96:99], off offset:256
	s_waitcnt vmcnt(15)
	s_nop 1
	v_mov_b32_e32 v96, v176
	v_mov_b32_e32 v97, v177
	v_mov_b32_e32 v98, v178
	v_mov_b32_e32 v99, v179
	s_mov_b64 s[2:3], 0x30000
	s_waitcnt lgkmcnt(0)
	v_lshlrev_b32_e32 v104, 16, v96
	v_and_b32_e32 v105, 0xffff0000, v96
	v_lshlrev_b32_e32 v96, 16, v97
	v_and_b32_e32 v97, 0xffff0000, v97
	v_lshlrev_b32_e32 v106, 16, v98
	v_and_b32_e32 v107, 0xffff0000, v98
	v_lshlrev_b32_e32 v98, 16, v99
	v_and_b32_e32 v99, 0xffff0000, v99
	v_pk_add_f32 v[94:95], v[94:95], v[96:97]
	v_pk_add_f32 v[92:93], v[92:93], v[104:105]
	v_pk_add_f32 v[96:97], v[90:91], v[98:99]
	v_pk_add_f32 v[90:91], v[88:89], v[106:107]
	v_cvt_pk_bf16_f32 v88, v92, v93
	v_cvt_pk_bf16_f32 v89, v94, v95
	v_cvt_pk_bf16_f32 v90, v90, v91
	v_cvt_pk_bf16_f32 v91, v96, v97
	global_store_dwordx4 v[102:103], v[88:91], off
	s_waitcnt vmcnt(15)
	s_nop 1
	v_mov_b32_e32 v88, v180
	v_mov_b32_e32 v89, v181
	v_mov_b32_e32 v90, v182
	v_mov_b32_e32 v91, v183
	s_waitcnt lgkmcnt(0)
	v_lshlrev_b32_e32 v92, 16, v88
	v_and_b32_e32 v93, 0xffff0000, v88
	v_lshlrev_b32_e32 v88, 16, v89
	v_and_b32_e32 v89, 0xffff0000, v89
	v_lshlrev_b32_e32 v94, 16, v90
	v_and_b32_e32 v95, 0xffff0000, v90
	v_lshlrev_b32_e32 v90, 16, v91
	v_and_b32_e32 v91, 0xffff0000, v91
	v_pk_add_f32 v[86:87], v[86:87], v[88:89]
	v_pk_add_f32 v[84:85], v[84:85], v[92:93]
	v_pk_add_f32 v[88:89], v[82:83], v[90:91]
	v_pk_add_f32 v[82:83], v[80:81], v[94:95]
	v_cvt_pk_bf16_f32 v80, v84, v85
	v_cvt_pk_bf16_f32 v81, v86, v87
	v_cvt_pk_bf16_f32 v82, v82, v83
	v_cvt_pk_bf16_f32 v83, v88, v89
	global_store_dwordx4 v[100:101], v[80:83], off offset:256
	s_nop 1
	v_lshl_add_u64 v[80:81], v[144:145], 0, s[2:3]
	s_mov_b32 s2, 0x30000
	v_add_co_u32_e32 v86, vcc, s2, v144
	s_mov_b64 s[2:3], 0x80000
	s_nop 0
	v_addc_co_u32_e32 v87, vcc, 0, v145, vcc
	s_waitcnt vmcnt(15)
	s_nop 1
	v_mov_b32_e32 v82, v184
	v_mov_b32_e32 v83, v185
	v_mov_b32_e32 v84, v186
	v_mov_b32_e32 v85, v187
	s_waitcnt lgkmcnt(0)
	v_lshlrev_b32_e32 v88, 16, v82
	v_and_b32_e32 v89, 0xffff0000, v82
	v_lshlrev_b32_e32 v82, 16, v83
	v_and_b32_e32 v83, 0xffff0000, v83
	v_lshlrev_b32_e32 v90, 16, v84
	v_and_b32_e32 v91, 0xffff0000, v84
	v_lshlrev_b32_e32 v84, 16, v85
	v_and_b32_e32 v85, 0xffff0000, v85
	v_pk_add_f32 v[78:79], v[78:79], v[82:83]
	v_pk_add_f32 v[76:77], v[76:77], v[88:89]
	v_pk_add_f32 v[82:83], v[74:75], v[84:85]
	v_pk_add_f32 v[74:75], v[72:73], v[90:91]
	v_cvt_pk_bf16_f32 v72, v76, v77
	v_cvt_pk_bf16_f32 v73, v78, v79
	v_cvt_pk_bf16_f32 v74, v74, v75
	v_cvt_pk_bf16_f32 v75, v82, v83
	global_store_dwordx4 v[86:87], v[72:75], off
	s_waitcnt vmcnt(15)
	s_nop 1
	v_mov_b32_e32 v72, v188
	v_mov_b32_e32 v73, v189
	v_mov_b32_e32 v74, v190
	v_mov_b32_e32 v75, v191
	s_waitcnt lgkmcnt(0)
; DI unsigned pack2(float a, float b) { f32x2 v = {a, b}; hwbf16x2 r = __builtin_convertvector(v, hwbf16x2); return __builtin_bit_cast(unsigned, r); }
; DI float bflo(unsigned w) { return __uint_as_float(w << 16); }
; DI float bfhi(unsigned w) { return __uint_as_float(w & 0xffff0000u); }
;     DI void operator()(const f32x4 (&acc)[2][2][4][2], const Unit& u, int wr, int wc, int fr, int fq) const {
;         const int row0 = u.pm * BM + wr * 64 + fr, col0 = u.pn * BM + wc * 32 + 8 * fq;
;         f32x4 sc[2][2];
; #pragma unroll
;         for (int bj = 0; bj < 2; ++bj)
; #pragma unroll
;             for (int n = 0; n < 2; ++n) sc[bj][n] = scale ? *(const f32x4*)(scale + col0 + bj * HALF + 4 * n) : (f32x4){1.f, 1.f, 1.f, 1.f};
; #pragma unroll
;         for (int ai = 0; ai < 2; ++ai)
; #pragma unroll
;             for (int m = 0; m < 4; ++m) { const size_t ro = (size_t)(row0 + ai * HALF + m * 16) * D + col0;
; #pragma unroll
;                 for (int bj = 0; bj < 2; ++bj) {
;                     f32x4 x0, x1;
;                     if constexpr (IB) { const u32x4 w = *(const u32x4*)((const bf16_t*)Xin + ro + bj * HALF);
;                         x0 = (f32x4){bflo(w[0]), bfhi(w[0]), bflo(w[1]), bfhi(w[1])}; x1 = (f32x4){bflo(w[2]), bfhi(w[2]), bflo(w[3]), bfhi(w[3])}; }
;                     else { x0 = *(const f32x4*)((const float*)Xin + ro + bj * HALF); x1 = *(const f32x4*)((const float*)Xin + ro + bj * HALF + 4); }
;                     x0 += acc[ai][bj][m][0] * sc[bj][0]; x1 += acc[ai][bj][m][1] * sc[bj][1];
;                     if constexpr (OB) { u32x4 o; o[0] = pack2(x0[0], x0[1]); o[1] = pack2(x0[2], x0[3]); o[2] = pack2(x1[0], x1[1]); o[3] = pack2(x1[2], x1[3]);
;                         *(u32x4*)((bf16_t*)Xout + ro + bj * HALF) = o; }
;                     else { *(f32x4*)((float*)Xout + ro + bj * HALF) = x0; *(f32x4*)((float*)Xout + ro + bj * HALF + 4) = x1; } } }
	v_lshlrev_b32_e32 v76, 16, v72
	v_and_b32_e32 v77, 0xffff0000, v72
	v_lshlrev_b32_e32 v72, 16, v73
	v_and_b32_e32 v73, 0xffff0000, v73
	v_lshlrev_b32_e32 v78, 16, v74
	v_and_b32_e32 v79, 0xffff0000, v74
	v_lshlrev_b32_e32 v74, 16, v75
	v_and_b32_e32 v75, 0xffff0000, v75
	v_pk_add_f32 v[70:71], v[70:71], v[72:73]
	v_pk_add_f32 v[68:69], v[68:69], v[76:77]
	v_pk_add_f32 v[72:73], v[66:67], v[74:75]
	v_pk_add_f32 v[66:67], v[64:65], v[78:79]
	v_cvt_pk_bf16_f32 v64, v68, v69
	v_cvt_pk_bf16_f32 v65, v70, v71
	v_cvt_pk_bf16_f32 v66, v66, v67
	v_cvt_pk_bf16_f32 v67, v72, v73
	global_store_dwordx4 v[80:81], v[64:67], off offset:256
	s_nop 1
	v_lshl_add_u64 v[64:65], v[144:145], 0, s[2:3]
	s_mov_b32 s2, 0x80000
	v_add_co_u32_e32 v70, vcc, s2, v144
	s_mov_b64 s[2:3], 0x90000
	s_nop 0
	v_addc_co_u32_e32 v71, vcc, 0, v145, vcc
	s_waitcnt vmcnt(15)
	s_nop 1
	v_mov_b32_e32 v66, v192
	v_mov_b32_e32 v67, v193
	v_mov_b32_e32 v68, v194
	v_mov_b32_e32 v69, v195
	s_waitcnt lgkmcnt(0)
	v_lshlrev_b32_e32 v72, 16, v66
	v_and_b32_e32 v73, 0xffff0000, v66
	v_lshlrev_b32_e32 v66, 16, v67
	v_and_b32_e32 v67, 0xffff0000, v67
	v_lshlrev_b32_e32 v74, 16, v68
	v_and_b32_e32 v75, 0xffff0000, v68
	v_lshlrev_b32_e32 v68, 16, v69
	v_and_b32_e32 v69, 0xffff0000, v69
	v_pk_add_f32 v[62:63], v[62:63], v[66:67]
	v_pk_add_f32 v[60:61], v[60:61], v[72:73]
	v_pk_add_f32 v[66:67], v[58:59], v[68:69]
	v_pk_add_f32 v[58:59], v[56:57], v[74:75]
	v_cvt_pk_bf16_f32 v56, v60, v61
	v_cvt_pk_bf16_f32 v57, v62, v63
	v_cvt_pk_bf16_f32 v58, v58, v59
	v_cvt_pk_bf16_f32 v59, v66, v67
	global_store_dwordx4 v[70:71], v[56:59], off
	s_waitcnt vmcnt(15)
	s_nop 1
	v_mov_b32_e32 v56, v198
	v_mov_b32_e32 v57, v199
	v_mov_b32_e32 v58, v200
	v_mov_b32_e32 v59, v201
	s_waitcnt lgkmcnt(0)
	v_lshlrev_b32_e32 v60, 16, v56
	v_and_b32_e32 v61, 0xffff0000, v56
	v_lshlrev_b32_e32 v56, 16, v57
	v_and_b32_e32 v57, 0xffff0000, v57
	v_lshlrev_b32_e32 v62, 16, v58
	v_and_b32_e32 v63, 0xffff0000, v58
	v_lshlrev_b32_e32 v58, 16, v59
	v_and_b32_e32 v59, 0xffff0000, v59
	v_pk_add_f32 v[54:55], v[54:55], v[56:57]
	v_pk_add_f32 v[52:53], v[52:53], v[60:61]
	v_pk_add_f32 v[56:57], v[50:51], v[58:59]
	v_pk_add_f32 v[50:51], v[48:49], v[62:63]
	v_cvt_pk_bf16_f32 v48, v52, v53
	v_cvt_pk_bf16_f32 v49, v54, v55
	v_cvt_pk_bf16_f32 v50, v50, v51
	v_cvt_pk_bf16_f32 v51, v56, v57
	global_store_dwordx4 v[64:65], v[48:51], off offset:256
	s_nop 1
	v_lshl_add_u64 v[48:49], v[144:145], 0, s[2:3]
	s_mov_b32 s2, 0x90000
	v_add_co_u32_e32 v54, vcc, s2, v144
	s_mov_b64 s[2:3], 0xa0000
	s_nop 0
	v_addc_co_u32_e32 v55, vcc, 0, v145, vcc
	s_waitcnt vmcnt(15)
	s_nop 1
	v_mov_b32_e32 v50, v202
	v_mov_b32_e32 v51, v203
	v_mov_b32_e32 v52, v204
	v_mov_b32_e32 v53, v205
	s_waitcnt lgkmcnt(0)
	v_lshlrev_b32_e32 v56, 16, v50
	v_and_b32_e32 v57, 0xffff0000, v50
	v_lshlrev_b32_e32 v50, 16, v51
	v_and_b32_e32 v51, 0xffff0000, v51
	v_lshlrev_b32_e32 v58, 16, v52
	v_and_b32_e32 v59, 0xffff0000, v52
	v_lshlrev_b32_e32 v52, 16, v53
	v_and_b32_e32 v53, 0xffff0000, v53
	v_pk_add_f32 v[46:47], v[46:47], v[50:51]
	v_pk_add_f32 v[44:45], v[44:45], v[56:57]
	v_pk_add_f32 v[50:51], v[42:43], v[52:53]
	v_pk_add_f32 v[42:43], v[40:41], v[58:59]
	v_cvt_pk_bf16_f32 v40, v44, v45
	v_cvt_pk_bf16_f32 v41, v46, v47
	v_cvt_pk_bf16_f32 v42, v42, v43
	v_cvt_pk_bf16_f32 v43, v50, v51
	global_store_dwordx4 v[54:55], v[40:43], off
	s_waitcnt vmcnt(15)
	s_nop 1
	v_mov_b32_e32 v40, v206
	v_mov_b32_e32 v41, v207
	v_mov_b32_e32 v42, v208
	v_mov_b32_e32 v43, v209
	s_waitcnt lgkmcnt(0)
; #define PG8_BAR __builtin_amdgcn_s_barrier()
;     DI void operator()(const f32x4 (&acc)[2][2][4][2], const Unit& u, int wr, int wc, int fr, int fq) const {
;         const int row0 = u.pm * BM + wr * 64 + fr, col0 = u.pn * BM + wc * 32 + 8 * fq;
;         f32x4 sc[2][2];
; #pragma unroll
;         for (int bj = 0; bj < 2; ++bj)
; #pragma unroll
;             for (int n = 0; n < 2; ++n) sc[bj][n] = scale ? *(const f32x4*)(scale + col0 + bj * HALF + 4 * n) : (f32x4){1.f, 1.f, 1.f, 1.f};
; #pragma unroll
;         for (int ai = 0; ai < 2; ++ai)
; #pragma unroll
;             for (int m = 0; m < 4; ++m) { const size_t ro = (size_t)(row0 + ai * HALF + m * 16) * D + col0;
; #pragma unroll
;                 for (int bj = 0; bj < 2; ++bj) {
;                     f32x4 x0, x1;
;                     if constexpr (IB) { const u32x4 w = *(const u32x4*)((const bf16_t*)Xin + ro + bj * HALF);
;                         x0 = (f32x4){bflo(w[0]), bfhi(w[0]), bflo(w[1]), bfhi(w[1])}; x1 = (f32x4){bflo(w[2]), bfhi(w[2]), bflo(w[3]), bfhi(w[3])}; }
;                     else { x0 = *(const f32x4*)((const float*)Xin + ro + bj * HALF); x1 = *(const f32x4*)((const float*)Xin + ro + bj * HALF + 4); }
;                     x0 += acc[ai][bj][m][0] * sc[bj][0]; x1 += acc[ai][bj][m][1] * sc[bj][1];
;                     if constexpr (OB) { u32x4 o; o[0] = pack2(x0[0], x0[1]); o[1] = pack2(x0[2], x0[3]); o[2] = pack2(x1[0], x1[1]); o[3] = pack2(x1[2], x1[3]);
;                         *(u32x4*)((bf16_t*)Xout + ro + bj * HALF) = o; }
;                     else { *(f32x4*)((float*)Xout + ro + bj * HALF) = x0; *(f32x4*)((float*)Xout + ro + bj * HALF + 4) = x1; } } }
; template <class Map, class Epi>
; DI void gemm_phase(LAS unsigned char* lds, const Map& MP, const Epi& E, const int nM, const int nN, const int K, const int lda, const int ldb) {
;     ...
;         { int frr = fr, fqq = fq; asm volatile("" : "+v"(frr), "+v"(fqq)); E(acc, cur, wr, wc, frr, fqq); }
;         if (!has_next) break;
; #pragma unroll
;         for (int a = 0; a < 2; ++a)
; #pragma unroll
;             for (int b = 0; b < 2; ++b)
; #pragma unroll
;                 for (int m = 0; m < 4; ++m)
; #pragma unroll
;                     for (int n = 0; n < 2; ++n) acc[a][b][m][n] = (f32x4){0.f, 0.f, 0.f, 0.f};
;         cur = nxt; cA = nA; cB = nB; ++ui;
;     }
;     PG8_WAIT_V(0);
;     if (wr == 0) PG8_BAR;
;     PG8_BAR;
	v_lshlrev_b32_e32 v44, 16, v40
	v_and_b32_e32 v45, 0xffff0000, v40
	v_lshlrev_b32_e32 v40, 16, v41
	v_and_b32_e32 v41, 0xffff0000, v41
	v_lshlrev_b32_e32 v46, 16, v42
	v_and_b32_e32 v47, 0xffff0000, v42
	v_lshlrev_b32_e32 v42, 16, v43
	v_and_b32_e32 v43, 0xffff0000, v43
	v_pk_add_f32 v[38:39], v[38:39], v[40:41]
	v_pk_add_f32 v[36:37], v[36:37], v[44:45]
	v_pk_add_f32 v[40:41], v[34:35], v[42:43]
	v_pk_add_f32 v[34:35], v[32:33], v[46:47]
	v_cvt_pk_bf16_f32 v32, v36, v37
	v_cvt_pk_bf16_f32 v33, v38, v39
	v_cvt_pk_bf16_f32 v34, v34, v35
	v_cvt_pk_bf16_f32 v35, v40, v41
	global_store_dwordx4 v[48:49], v[32:35], off offset:256
	s_nop 1
	v_lshl_add_u64 v[32:33], v[144:145], 0, s[2:3]
	s_mov_b32 s2, 0xa0000
	v_add_co_u32_e32 v38, vcc, s2, v144
	s_mov_b64 s[2:3], 0xb0000
	s_nop 0
	v_addc_co_u32_e32 v39, vcc, 0, v145, vcc
	s_waitcnt vmcnt(15)
	s_nop 1
	v_mov_b32_e32 v34, v210
	v_mov_b32_e32 v35, v211
	v_mov_b32_e32 v36, v212
	v_mov_b32_e32 v37, v213
	s_waitcnt lgkmcnt(0)
	v_lshlrev_b32_e32 v40, 16, v34
	v_and_b32_e32 v41, 0xffff0000, v34
	v_lshlrev_b32_e32 v34, 16, v35
	v_and_b32_e32 v35, 0xffff0000, v35
	v_lshlrev_b32_e32 v42, 16, v36
	v_and_b32_e32 v43, 0xffff0000, v36
	v_lshlrev_b32_e32 v36, 16, v37
	v_and_b32_e32 v37, 0xffff0000, v37
	v_pk_add_f32 v[30:31], v[30:31], v[34:35]
	v_pk_add_f32 v[28:29], v[28:29], v[40:41]
	v_pk_add_f32 v[34:35], v[26:27], v[36:37]
	v_pk_add_f32 v[26:27], v[24:25], v[42:43]
	v_cvt_pk_bf16_f32 v24, v28, v29
	v_cvt_pk_bf16_f32 v25, v30, v31
	v_cvt_pk_bf16_f32 v26, v26, v27
	v_cvt_pk_bf16_f32 v27, v34, v35
	global_store_dwordx4 v[38:39], v[24:27], off
	s_waitcnt vmcnt(15)
	s_nop 1
	v_mov_b32_e32 v24, v214
	v_mov_b32_e32 v25, v215
	v_mov_b32_e32 v26, v216
	v_mov_b32_e32 v27, v217
	s_waitcnt lgkmcnt(0)
	v_lshlrev_b32_e32 v28, 16, v24
	v_and_b32_e32 v29, 0xffff0000, v24
	v_lshlrev_b32_e32 v24, 16, v25
	v_and_b32_e32 v25, 0xffff0000, v25
	v_lshlrev_b32_e32 v30, 16, v26
	v_and_b32_e32 v31, 0xffff0000, v26
	v_lshlrev_b32_e32 v26, 16, v27
	v_and_b32_e32 v27, 0xffff0000, v27
	v_pk_add_f32 v[22:23], v[22:23], v[24:25]
	v_pk_add_f32 v[20:21], v[20:21], v[28:29]
	v_pk_add_f32 v[24:25], v[18:19], v[26:27]
	v_pk_add_f32 v[18:19], v[16:17], v[30:31]
	v_cvt_pk_bf16_f32 v16, v20, v21
	v_cvt_pk_bf16_f32 v17, v22, v23
	v_cvt_pk_bf16_f32 v18, v18, v19
	v_cvt_pk_bf16_f32 v19, v24, v25
	global_store_dwordx4 v[32:33], v[16:19], off offset:256
	s_nop 1
	v_lshl_add_u64 v[16:17], v[144:145], 0, s[2:3]
	s_mov_b32 s2, 0xb0000
	v_add_co_u32_e32 v22, vcc, s2, v144
	s_mov_b32 s2, s55
	s_nop 0
	v_addc_co_u32_e32 v23, vcc, 0, v145, vcc
	s_waitcnt vmcnt(15)
	s_nop 1
	v_mov_b32_e32 v18, v248
	v_mov_b32_e32 v19, v249
	v_mov_b32_e32 v20, v250
	v_mov_b32_e32 v21, v251
	s_and_b64 vcc, exec, s[40:41]
	s_waitcnt lgkmcnt(0)
	v_lshlrev_b32_e32 v24, 16, v18
	v_and_b32_e32 v25, 0xffff0000, v18
	v_lshlrev_b32_e32 v18, 16, v19
	v_and_b32_e32 v19, 0xffff0000, v19
	v_lshlrev_b32_e32 v26, 16, v20
	v_and_b32_e32 v27, 0xffff0000, v20
	v_lshlrev_b32_e32 v20, 16, v21
	v_and_b32_e32 v21, 0xffff0000, v21
	v_pk_add_f32 v[14:15], v[14:15], v[18:19]
	v_pk_add_f32 v[12:13], v[12:13], v[24:25]
	v_pk_add_f32 v[18:19], v[10:11], v[20:21]
	v_pk_add_f32 v[10:11], v[8:9], v[26:27]
	v_cvt_pk_bf16_f32 v8, v12, v13
	v_cvt_pk_bf16_f32 v9, v14, v15
	v_cvt_pk_bf16_f32 v10, v10, v11
	v_cvt_pk_bf16_f32 v11, v18, v19
	global_store_dwordx4 v[22:23], v[8:11], off
	s_waitcnt vmcnt(15)
	s_nop 1
	v_mov_b32_e32 v8, v252
	v_mov_b32_e32 v9, v253
	v_mov_b32_e32 v10, v254
	v_mov_b32_e32 v11, v255
	s_waitcnt lgkmcnt(0)
	v_lshlrev_b32_e32 v12, 16, v8
	v_and_b32_e32 v13, 0xffff0000, v8
	v_lshlrev_b32_e32 v8, 16, v9
	v_and_b32_e32 v9, 0xffff0000, v9
	v_lshlrev_b32_e32 v14, 16, v10
	v_and_b32_e32 v15, 0xffff0000, v10
	v_lshlrev_b32_e32 v10, 16, v11
	v_and_b32_e32 v11, 0xffff0000, v11
	v_pk_add_f32 v[6:7], v[6:7], v[8:9]
	v_pk_add_f32 v[4:5], v[4:5], v[12:13]
	v_pk_add_f32 v[8:9], v[2:3], v[10:11]
	v_pk_add_f32 v[2:3], v[0:1], v[14:15]
	v_cvt_pk_bf16_f32 v0, v4, v5
	v_cvt_pk_bf16_f32 v1, v6, v7
	v_cvt_pk_bf16_f32 v2, v2, v3
	v_cvt_pk_bf16_f32 v3, v8, v9
	global_store_dwordx4 v[16:17], v[0:3], off offset:256
	s_cbranch_vccz .LBB1_543
	s_waitcnt vmcnt(0)
	s_cmpk_gt_u32 s17, 0xff
	s_cbranch_scc1 .LBB1_554
	s_barrier

; #define PG8_STAGE(bufoff, gbase, voff) do { _Pragma("unroll") for (int _i = 0; _i < 2; ++_i) \
;         __builtin_amdgcn_global_load_lds((const unsigned*)((const char*)(gbase) + (voff)[_i]), (LAS unsigned*)(lds + (bufoff) + ldsw + _i * 8192), 16, 0, 0); } while (0)
; #define PG8_LDA(dst, b, h) do { _Pragma("unroll") for (int m = 0; m < 4; ++m) _Pragma("unroll") for (int k = 0; k < 2; ++k) dst[m][k] = *(const LAS bf16x8*)(lds + PG8_SA(b, h) + aoff + m * 2048 + k * 1024); } while (0)
; #define PG8_WAIT_V(n) asm volatile("s_waitcnt vmcnt(" #n ")" ::: "memory")
; #define PG8_BAR __builtin_amdgcn_s_barrier()
; template <class Map, class Epi>
; DI void gemm_phase(LAS unsigned char* lds, const Map& MP, const Epi& E, const int nM, const int nN, const int K, const int lda, const int ldb) {
;     ...
;         for (int t = 0; t < nt; t += 2) {
;             const bool last = (t == nt - 2);
;             const char* a1 = cA + (size_t)(t + 1) * kstep;
;             const char* a2 = last ? nA : cA + (size_t)(t + 2) * kstep; const char* b2 = last ? nB : cB + (size_t)(t + 2) * kstep;
;             const char* a3 = a2 + kstep; const char* b3 = b2 + kstep;
;             PG8_LDB(B0, 0, 0); PG8_SCHED; PG8_LDA(At, 0, 0); PG8_STAGE(PG8_SA(1, 1), a1 + hstepA, voffA);
;             PG8_WAIT_L(8); PG8_BAR; PG8_WAIT_L(0); PG8_MMA(0, 0, At, B0); PG8_BAR; PG8_SCHED;
;             PG8_LDB(B1, 0, 1); PG8_STAGE(PG8_SB(0, 0), b2, voffB);
;             PG8_BAR; PG8_WAIT_L(0); PG8_MMA(0, 1, At, B1); PG8_BAR;
;             PG8_LDA(At, 0, 1); PG8_STAGE(PG8_SA(0, 0), a2, voffA);
;             PG8_BAR; PG8_WAIT_L(0); PG8_MMA(1, 0, At, B0); PG8_BAR; PG8_SCHED;
;             PG8_STAGE(PG8_SB(0, 1), b2 + hstepB, voffB);
;             PG8_WAIT_V(6); PG8_BAR; PG8_MMA(1, 1, At, B1); PG8_BAR;
;             PG8_LDB(B0, 1, 0); PG8_SCHED; PG8_LDA(At, 1, 0); PG8_STAGE(PG8_SA(0, 1), a2 + hstepA, voffA);
;             PG8_WAIT_L(8); PG8_BAR; PG8_WAIT_L(0); PG8_MMA(0, 0, At, B0); PG8_BAR; PG8_SCHED;
;             PG8_LDB(B1, 1, 1); PG8_STAGE(PG8_SB(1, 0), b3, voffB);
;             PG8_BAR; PG8_WAIT_L(0); PG8_MMA(0, 1, At, B1); PG8_BAR;
;             PG8_LDA(At, 1, 1); PG8_STAGE(PG8_SA(1, 0), a3, voffA);
;             PG8_BAR; PG8_WAIT_L(0); PG8_MMA(1, 0, At, B0); PG8_BAR; PG8_SCHED;
;             PG8_STAGE(PG8_SB(1, 1), b3 + hstepB, voffB);
;             PG8_WAIT_V(6); PG8_BAR; PG8_MMA(1, 1, At, B1); PG8_BAR;
.LBB1_693:
	s_add_u32 s3, s20, 0xfff80080
	s_addc_u32 s22, s21, -1
	s_cmp_eq_u32 s54, 28
	s_cselect_b32 s25, s15, s22
	s_cselect_b32 s24, s48, s3
	s_cselect_b32 s23, s13, s53
	s_cselect_b32 s22, s49, s52
	s_add_i32 m0, s31, 0xc000
	ds_read_b128 v[166:169], v148
	global_load_lds_dwordx4 v138, s[20:21]
	ds_read_b128 v[170:173], v148 offset:1024
	ds_read_b128 v[174:177], v148 offset:2048
	ds_read_b128 v[178:181], v148 offset:3072
	ds_read_b128 v[182:185], v148 offset:4096
	ds_read_b128 v[186:189], v148 offset:5120
	ds_read_b128 v[190:193], v148 offset:6144
	ds_read_b128 v[198:201], v148 offset:7168
	s_add_i32 m0, s31, 0xe000
	s_nop 0
	global_load_lds_dwordx4 v136, s[20:21]
	s_waitcnt lgkmcnt(8)
	s_setprio 1
	s_barrier
	s_waitcnt lgkmcnt(7)
	v_mfma_f32_16x16x32_bf16 v[124:127], v[150:153], v[166:169], v[124:127]
	v_mfma_f32_16x16x32_bf16 v[120:123], v[158:161], v[166:169], v[120:123]
	s_waitcnt lgkmcnt(5)
	v_mfma_f32_16x16x32_bf16 v[116:119], v[150:153], v[174:177], v[116:119]
	v_mfma_f32_16x16x32_bf16 v[112:115], v[158:161], v[174:177], v[112:115]
	s_waitcnt lgkmcnt(3)
	v_mfma_f32_16x16x32_bf16 v[100:103], v[150:153], v[182:185], v[100:103]
	v_mfma_f32_16x16x32_bf16 v[96:99], v[158:161], v[182:185], v[96:99]
	s_waitcnt lgkmcnt(1)
	v_mfma_f32_16x16x32_bf16 v[84:87], v[150:153], v[190:193], v[84:87]
	v_mfma_f32_16x16x32_bf16 v[80:83], v[158:161], v[190:193], v[80:83]
	v_mfma_f32_16x16x32_bf16 v[124:127], v[154:157], v[170:173], v[124:127]
	s_add_i32 s3, s44, s29
	v_mfma_f32_16x16x32_bf16 v[120:123], v[162:165], v[170:173], v[120:123]
	v_lshl_add_u64 v[194:195], s[22:23], 0, v[132:133]
	v_mfma_f32_16x16x32_bf16 v[116:119], v[154:157], v[178:181], v[116:119]
	v_lshl_add_u64 v[218:219], s[22:23], 0, v[128:129]
	v_mfma_f32_16x16x32_bf16 v[112:115], v[162:165], v[178:181], v[112:115]
	v_mfma_f32_16x16x32_bf16 v[100:103], v[154:157], v[186:189], v[100:103]
	v_mfma_f32_16x16x32_bf16 v[96:99], v[162:165], v[186:189], v[96:99]
	s_waitcnt lgkmcnt(0)
	v_mfma_f32_16x16x32_bf16 v[84:87], v[154:157], v[198:201], v[84:87]
	v_mfma_f32_16x16x32_bf16 v[80:83], v[162:165], v[198:201], v[80:83]
	s_barrier
	s_setprio 0
	s_mov_b32 m0, s3
	ds_read_b128 v[202:205], v149
	global_load_lds_dwordx4 v[194:195], off
	ds_read_b128 v[206:209], v149 offset:1024
	ds_read_b128 v[210:213], v149 offset:2048
	ds_read_b128 v[214:217], v149 offset:3072
	s_add_i32 m0, s3, 0x2000
	s_nop 0
	global_load_lds_dwordx4 v[218:219], off
	s_setprio 1
	s_barrier
	s_waitcnt lgkmcnt(3)
	v_mfma_f32_16x16x32_bf16 v[108:111], v[202:205], v[166:169], v[108:111]
	s_waitcnt lgkmcnt(1)
	v_mfma_f32_16x16x32_bf16 v[104:107], v[210:213], v[166:169], v[104:107]
	v_mfma_f32_16x16x32_bf16 v[92:95], v[202:205], v[174:177], v[92:95]
	v_mfma_f32_16x16x32_bf16 v[88:91], v[210:213], v[174:177], v[88:91]
	v_mfma_f32_16x16x32_bf16 v[76:79], v[202:205], v[182:185], v[76:79]
	v_mfma_f32_16x16x32_bf16 v[72:75], v[210:213], v[182:185], v[72:75]
	v_mfma_f32_16x16x32_bf16 v[68:71], v[202:205], v[190:193], v[68:71]
	v_mfma_f32_16x16x32_bf16 v[64:67], v[210:213], v[190:193], v[64:67]
	v_mfma_f32_16x16x32_bf16 v[108:111], v[206:209], v[170:173], v[108:111]
	v_lshl_add_u64 v[222:223], s[24:25], 0, v[130:131]
	s_mov_b32 m0, s31
	s_waitcnt lgkmcnt(0)
	v_mfma_f32_16x16x32_bf16 v[104:107], v[214:217], v[170:173], v[104:107]
	v_lshl_add_u64 v[220:221], s[24:25], 0, v[134:135]
	v_mfma_f32_16x16x32_bf16 v[92:95], v[206:209], v[178:181], v[92:95]
	v_mfma_f32_16x16x32_bf16 v[88:91], v[214:217], v[178:181], v[88:91]
	v_mfma_f32_16x16x32_bf16 v[76:79], v[206:209], v[186:189], v[76:79]
	v_mfma_f32_16x16x32_bf16 v[72:75], v[214:217], v[186:189], v[72:75]
	v_mfma_f32_16x16x32_bf16 v[68:71], v[206:209], v[198:201], v[68:71]
	v_mfma_f32_16x16x32_bf16 v[64:67], v[214:217], v[198:201], v[64:67]
	s_barrier
	s_setprio 0
	ds_read_b128 v[166:169], v148 offset:16384
	global_load_lds_dwordx4 v[220:221], off
	ds_read_b128 v[170:173], v148 offset:17408
	ds_read_b128 v[174:177], v148 offset:18432
	ds_read_b128 v[178:181], v148 offset:19456
	ds_read_b128 v[182:185], v148 offset:20480
	ds_read_b128 v[186:189], v148 offset:21504
	ds_read_b128 v[190:193], v148 offset:22528
	ds_read_b128 v[198:201], v148 offset:23552
	s_mov_b32 m0, s11
	s_nop 0
	global_load_lds_dwordx4 v[222:223], off
	s_waitcnt vmcnt(10)
	s_setprio 1
	s_barrier
	s_waitcnt lgkmcnt(7)
	v_mfma_f32_16x16x32_bf16 v[60:63], v[150:153], v[166:169], v[60:63]
	v_mfma_f32_16x16x32_bf16 v[56:59], v[158:161], v[166:169], v[56:59]
	s_waitcnt lgkmcnt(5)
	v_mfma_f32_16x16x32_bf16 v[52:55], v[150:153], v[174:177], v[52:55]
	v_mfma_f32_16x16x32_bf16 v[48:51], v[158:161], v[174:177], v[48:51]
	s_waitcnt lgkmcnt(3)
	v_mfma_f32_16x16x32_bf16 v[36:39], v[150:153], v[182:185], v[36:39]
	v_mfma_f32_16x16x32_bf16 v[32:35], v[158:161], v[182:185], v[32:35]
	s_waitcnt lgkmcnt(1)
	v_mfma_f32_16x16x32_bf16 v[20:23], v[150:153], v[190:193], v[20:23]
	v_mfma_f32_16x16x32_bf16 v[16:19], v[158:161], v[190:193], v[16:19]
	v_mfma_f32_16x16x32_bf16 v[60:63], v[154:157], v[170:173], v[60:63]
	s_add_u32 s56, s22, 0x80000
	s_addc_u32 s57, s23, 0
	v_mfma_f32_16x16x32_bf16 v[56:59], v[162:165], v[170:173], v[56:59]
	s_add_i32 s3, s45, s29
	v_mfma_f32_16x16x32_bf16 v[52:55], v[154:157], v[178:181], v[52:55]
	v_mfma_f32_16x16x32_bf16 v[48:51], v[162:165], v[178:181], v[48:51]
	v_mfma_f32_16x16x32_bf16 v[36:39], v[154:157], v[186:189], v[36:39]
	v_mfma_f32_16x16x32_bf16 v[32:35], v[162:165], v[186:189], v[32:35]
	s_waitcnt lgkmcnt(0)
	v_mfma_f32_16x16x32_bf16 v[20:23], v[154:157], v[198:201], v[20:23]
	v_mfma_f32_16x16x32_bf16 v[16:19], v[162:165], v[198:201], v[16:19]
	s_barrier
; #define PG8_STAGE(bufoff, gbase, voff) do { _Pragma("unroll") for (int _i = 0; _i < 2; ++_i) \
;         __builtin_amdgcn_global_load_lds((const unsigned*)((const char*)(gbase) + (voff)[_i]), (LAS unsigned*)(lds + (bufoff) + ldsw + _i * 8192), 16, 0, 0); } while (0)
; #define PG8_LDA(dst, b, h) do { _Pragma("unroll") for (int m = 0; m < 4; ++m) _Pragma("unroll") for (int k = 0; k < 2; ++k) dst[m][k] = *(const LAS bf16x8*)(lds + PG8_SA(b, h) + aoff + m * 2048 + k * 1024); } while (0)
; #define PG8_WAIT_V(n) asm volatile("s_waitcnt vmcnt(" #n ")" ::: "memory")
; #define PG8_BAR __builtin_amdgcn_s_barrier()
; template <class Map, class Epi>
; DI void gemm_phase(LAS unsigned char* lds, const Map& MP, const Epi& E, const int nM, const int nN, const int K, const int lda, const int ldb) {
;     ...
;         for (int t = 0; t < nt; t += 2) {
;             const bool last = (t == nt - 2);
;             const char* a1 = cA + (size_t)(t + 1) * kstep;
;             const char* a2 = last ? nA : cA + (size_t)(t + 2) * kstep; const char* b2 = last ? nB : cB + (size_t)(t + 2) * kstep;
;             const char* a3 = a2 + kstep; const char* b3 = b2 + kstep;
;             PG8_LDB(B0, 0, 0); PG8_SCHED; PG8_LDA(At, 0, 0); PG8_STAGE(PG8_SA(1, 1), a1 + hstepA, voffA);
;             PG8_WAIT_L(8); PG8_BAR; PG8_WAIT_L(0); PG8_MMA(0, 0, At, B0); PG8_BAR; PG8_SCHED;
;             PG8_LDB(B1, 0, 1); PG8_STAGE(PG8_SB(0, 0), b2, voffB);
;             PG8_BAR; PG8_WAIT_L(0); PG8_MMA(0, 1, At, B1); PG8_BAR;
;             PG8_LDA(At, 0, 1); PG8_STAGE(PG8_SA(0, 0), a2, voffA);
;             PG8_BAR; PG8_WAIT_L(0); PG8_MMA(1, 0, At, B0); PG8_BAR; PG8_SCHED;
;             PG8_STAGE(PG8_SB(0, 1), b2 + hstepB, voffB);
;             PG8_WAIT_V(6); PG8_BAR; PG8_MMA(1, 1, At, B1); PG8_BAR;
;             PG8_LDB(B0, 1, 0); PG8_SCHED; PG8_LDA(At, 1, 0); PG8_STAGE(PG8_SA(0, 1), a2 + hstepA, voffA);
;             PG8_WAIT_L(8); PG8_BAR; PG8_WAIT_L(0); PG8_MMA(0, 0, At, B0); PG8_BAR; PG8_SCHED;
;             PG8_LDB(B1, 1, 1); PG8_STAGE(PG8_SB(1, 0), b3, voffB);
;             PG8_BAR; PG8_WAIT_L(0); PG8_MMA(0, 1, At, B1); PG8_BAR;
;             PG8_LDA(At, 1, 1); PG8_STAGE(PG8_SA(1, 0), a3, voffA);
;             PG8_BAR; PG8_WAIT_L(0); PG8_MMA(1, 0, At, B0); PG8_BAR; PG8_SCHED;
;             PG8_STAGE(PG8_SB(1, 1), b3 + hstepB, voffB);
;             PG8_WAIT_V(6); PG8_BAR; PG8_MMA(1, 1, At, B1); PG8_BAR;
	s_setprio 0
	s_mov_b32 m0, s3
	s_nop 0
	global_load_lds_dwordx4 v132, s[56:57]
	s_add_i32 m0, s3, 0x2000
	s_nop 0
	global_load_lds_dwordx4 v128, s[56:57]
	s_waitcnt vmcnt(6)
	s_setprio 1
	s_barrier
	v_mfma_f32_16x16x32_bf16 v[44:47], v[202:205], v[166:169], v[44:47]
	v_mfma_f32_16x16x32_bf16 v[40:43], v[210:213], v[166:169], v[40:43]
	s_add_i32 s3, 0, 0x18000
	v_add_u32_e32 v162, s3, v146
	ds_read_b128 v[150:153], v162
	v_mfma_f32_16x16x32_bf16 v[28:31], v[202:205], v[174:177], v[28:31]
	v_mfma_f32_16x16x32_bf16 v[24:27], v[210:213], v[174:177], v[24:27]
	ds_read_b128 v[154:157], v162 offset:1024
	v_mfma_f32_16x16x32_bf16 v[12:15], v[202:205], v[182:185], v[12:15]
	v_mfma_f32_16x16x32_bf16 v[8:11], v[210:213], v[182:185], v[8:11]
	ds_read_b128 v[158:161], v162 offset:2048
	v_mfma_f32_16x16x32_bf16 v[4:7], v[202:205], v[190:193], v[4:7]
	v_mfma_f32_16x16x32_bf16 v[0:3], v[210:213], v[190:193], v[0:3]
	ds_read_b128 v[162:165], v162 offset:3072
	v_mfma_f32_16x16x32_bf16 v[44:47], v[206:209], v[170:173], v[44:47]
	s_add_u32 s24, s24, 0x80000
	s_addc_u32 s25, s25, 0
	v_mfma_f32_16x16x32_bf16 v[40:43], v[214:217], v[170:173], v[40:43]
	v_mfma_f32_16x16x32_bf16 v[28:31], v[206:209], v[178:181], v[28:31]
	v_mfma_f32_16x16x32_bf16 v[24:27], v[214:217], v[178:181], v[24:27]
	v_mfma_f32_16x16x32_bf16 v[12:15], v[206:209], v[186:189], v[12:15]
	v_mfma_f32_16x16x32_bf16 v[8:11], v[214:217], v[186:189], v[8:11]
	v_mfma_f32_16x16x32_bf16 v[4:7], v[206:209], v[198:201], v[4:7]
	v_mfma_f32_16x16x32_bf16 v[0:3], v[214:217], v[198:201], v[0:3]
	s_barrier
	s_setprio 0
	s_mov_b32 m0, s34
	ds_read_b128 v[166:169], v148 offset:32768
	global_load_lds_dwordx4 v134, s[24:25]
	ds_read_b128 v[170:173], v148 offset:33792
	ds_read_b128 v[174:177], v148 offset:34816
	ds_read_b128 v[178:181], v148 offset:35840
	ds_read_b128 v[182:185], v148 offset:36864
	ds_read_b128 v[186:189], v148 offset:37888
	ds_read_b128 v[190:193], v148 offset:38912
	ds_read_b128 v[198:201], v148 offset:39936
	s_mov_b32 m0, s35
	s_nop 0
	global_load_lds_dwordx4 v130, s[24:25]
	s_waitcnt lgkmcnt(8)
	s_setprio 1
	s_barrier
	s_waitcnt lgkmcnt(7)
	v_mfma_f32_16x16x32_bf16 v[124:127], v[150:153], v[166:169], v[124:127]
	v_mfma_f32_16x16x32_bf16 v[120:123], v[158:161], v[166:169], v[120:123]
	s_waitcnt lgkmcnt(5)
	v_mfma_f32_16x16x32_bf16 v[116:119], v[150:153], v[174:177], v[116:119]
	v_mfma_f32_16x16x32_bf16 v[112:115], v[158:161], v[174:177], v[112:115]
	s_waitcnt lgkmcnt(3)
	v_mfma_f32_16x16x32_bf16 v[100:103], v[150:153], v[182:185], v[100:103]
	v_mfma_f32_16x16x32_bf16 v[96:99], v[158:161], v[182:185], v[96:99]
	s_waitcnt lgkmcnt(1)
	v_mfma_f32_16x16x32_bf16 v[84:87], v[150:153], v[190:193], v[84:87]
	v_mfma_f32_16x16x32_bf16 v[80:83], v[158:161], v[190:193], v[80:83]
	v_mfma_f32_16x16x32_bf16 v[124:127], v[154:157], v[170:173], v[124:127]
	s_add_i32 s24, 0, 0x1c000
	v_mfma_f32_16x16x32_bf16 v[120:123], v[162:165], v[170:173], v[120:123]
	s_add_i32 s3, s3, s29
	v_mfma_f32_16x16x32_bf16 v[116:119], v[154:157], v[178:181], v[116:119]
	v_add_u32_e32 v196, s24, v146
	v_mfma_f32_16x16x32_bf16 v[112:115], v[162:165], v[178:181], v[112:115]
	v_lshl_add_u64 v[194:195], v[194:195], 0, s[8:9]
	v_mfma_f32_16x16x32_bf16 v[100:103], v[154:157], v[186:189], v[100:103]
	v_mfma_f32_16x16x32_bf16 v[96:99], v[162:165], v[186:189], v[96:99]
	s_waitcnt lgkmcnt(0)
	v_mfma_f32_16x16x32_bf16 v[84:87], v[154:157], v[198:201], v[84:87]
	v_mfma_f32_16x16x32_bf16 v[80:83], v[162:165], v[198:201], v[80:83]
	s_barrier
	s_setprio 0
	s_mov_b32 m0, s3
	ds_read_b128 v[202:205], v196
	global_load_lds_dwordx4 v[194:195], off
	ds_read_b128 v[206:209], v196 offset:1024
	ds_read_b128 v[210:213], v196 offset:2048
	ds_read_b128 v[214:217], v196 offset:3072
	v_lshl_add_u64 v[194:195], v[218:219], 0, s[8:9]
	s_add_i32 m0, s3, 0x2000
	s_nop 0
	global_load_lds_dwordx4 v[194:195], off
	s_setprio 1
	s_barrier
	s_waitcnt lgkmcnt(3)
	v_mfma_f32_16x16x32_bf16 v[108:111], v[202:205], v[166:169], v[108:111]
	s_waitcnt lgkmcnt(1)
	v_mfma_f32_16x16x32_bf16 v[104:107], v[210:213], v[166:169], v[104:107]
	v_mfma_f32_16x16x32_bf16 v[92:95], v[202:205], v[174:177], v[92:95]
	v_mfma_f32_16x16x32_bf16 v[88:91], v[210:213], v[174:177], v[88:91]
	v_mfma_f32_16x16x32_bf16 v[76:79], v[202:205], v[182:185], v[76:79]
	v_mfma_f32_16x16x32_bf16 v[72:75], v[210:213], v[182:185], v[72:75]
	v_mfma_f32_16x16x32_bf16 v[68:71], v[202:205], v[190:193], v[68:71]
	v_mfma_f32_16x16x32_bf16 v[64:67], v[210:213], v[190:193], v[64:67]
	v_mfma_f32_16x16x32_bf16 v[108:111], v[206:209], v[170:173], v[108:111]
	s_mov_b32 m0, s39
	s_waitcnt lgkmcnt(0)
	v_mfma_f32_16x16x32_bf16 v[104:107], v[214:217], v[170:173], v[104:107]
	v_lshl_add_u64 v[194:195], v[220:221], 0, s[8:9]
	v_mfma_f32_16x16x32_bf16 v[92:95], v[206:209], v[178:181], v[92:95]
	v_mfma_f32_16x16x32_bf16 v[88:91], v[214:217], v[178:181], v[88:91]
	v_mfma_f32_16x16x32_bf16 v[76:79], v[206:209], v[186:189], v[76:79]
	v_mfma_f32_16x16x32_bf16 v[72:75], v[214:217], v[186:189], v[72:75]
	v_mfma_f32_16x16x32_bf16 v[68:71], v[206:209], v[198:201], v[68:71]
	v_mfma_f32_16x16x32_bf16 v[64:67], v[214:217], v[198:201], v[64:67]
	s_barrier
	s_setprio 0
	ds_read_b128 v[166:169], v148 offset:49152
	global_load_lds_dwordx4 v[194:195], off
	ds_read_b128 v[170:173], v148 offset:50176
	ds_read_b128 v[174:177], v148 offset:51200
	ds_read_b128 v[178:181], v148 offset:52224
	ds_read_b128 v[182:185], v148 offset:53248
	ds_read_b128 v[186:189], v148 offset:54272
	ds_read_b128 v[190:193], v148 offset:55296
	ds_read_b128 v[198:201], v148 offset:56320
	v_lshl_add_u64 v[194:195], v[222:223], 0, s[8:9]
	s_mov_b32 m0, s42
	s_nop 0
	global_load_lds_dwordx4 v[194:195], off
	s_waitcnt vmcnt(10)
	s_setprio 1
	s_barrier
; #define PG8_STAGE(bufoff, gbase, voff) do { _Pragma("unroll") for (int _i = 0; _i < 2; ++_i) \
;         __builtin_amdgcn_global_load_lds((const unsigned*)((const char*)(gbase) + (voff)[_i]), (LAS unsigned*)(lds + (bufoff) + ldsw + _i * 8192), 16, 0, 0); } while (0)
; #define PG8_LDA(dst, b, h) do { _Pragma("unroll") for (int m = 0; m < 4; ++m) _Pragma("unroll") for (int k = 0; k < 2; ++k) dst[m][k] = *(const LAS bf16x8*)(lds + PG8_SA(b, h) + aoff + m * 2048 + k * 1024); } while (0)
; #define PG8_WAIT_V(n) asm volatile("s_waitcnt vmcnt(" #n ")" ::: "memory")
; #define PG8_BAR __builtin_amdgcn_s_barrier()
; template <class Map, class Epi>
; DI void gemm_phase(LAS unsigned char* lds, const Map& MP, const Epi& E, const int nM, const int nN, const int K, const int lda, const int ldb) {
;     ...
;         for (int t = 0; t < nt; t += 2) {
;             const bool last = (t == nt - 2);
;             const char* a1 = cA + (size_t)(t + 1) * kstep;
;             const char* a2 = last ? nA : cA + (size_t)(t + 2) * kstep; const char* b2 = last ? nB : cB + (size_t)(t + 2) * kstep;
;             const char* a3 = a2 + kstep; const char* b3 = b2 + kstep;
;             PG8_LDB(B0, 0, 0); PG8_SCHED; PG8_LDA(At, 0, 0); PG8_STAGE(PG8_SA(1, 1), a1 + hstepA, voffA);
;             PG8_WAIT_L(8); PG8_BAR; PG8_WAIT_L(0); PG8_MMA(0, 0, At, B0); PG8_BAR; PG8_SCHED;
;             PG8_LDB(B1, 0, 1); PG8_STAGE(PG8_SB(0, 0), b2, voffB);
;             PG8_BAR; PG8_WAIT_L(0); PG8_MMA(0, 1, At, B1); PG8_BAR;
;             PG8_LDA(At, 0, 1); PG8_STAGE(PG8_SA(0, 0), a2, voffA);
;             PG8_BAR; PG8_WAIT_L(0); PG8_MMA(1, 0, At, B0); PG8_BAR; PG8_SCHED;
;             PG8_STAGE(PG8_SB(0, 1), b2 + hstepB, voffB);
;             PG8_WAIT_V(6); PG8_BAR; PG8_MMA(1, 1, At, B1); PG8_BAR;
;             PG8_LDB(B0, 1, 0); PG8_SCHED; PG8_LDA(At, 1, 0); PG8_STAGE(PG8_SA(0, 1), a2 + hstepA, voffA);
;             PG8_WAIT_L(8); PG8_BAR; PG8_WAIT_L(0); PG8_MMA(0, 0, At, B0); PG8_BAR; PG8_SCHED;
;             PG8_LDB(B1, 1, 1); PG8_STAGE(PG8_SB(1, 0), b3, voffB);
;             PG8_BAR; PG8_WAIT_L(0); PG8_MMA(0, 1, At, B1); PG8_BAR;
;             PG8_LDA(At, 1, 1); PG8_STAGE(PG8_SA(1, 0), a3, voffA);
;             PG8_BAR; PG8_WAIT_L(0); PG8_MMA(1, 0, At, B0); PG8_BAR; PG8_SCHED;
;             PG8_STAGE(PG8_SB(1, 1), b3 + hstepB, voffB);
;             PG8_WAIT_V(6); PG8_BAR; PG8_MMA(1, 1, At, B1); PG8_BAR;
	s_waitcnt lgkmcnt(7)
	v_mfma_f32_16x16x32_bf16 v[60:63], v[150:153], v[166:169], v[60:63]
	v_mfma_f32_16x16x32_bf16 v[56:59], v[158:161], v[166:169], v[56:59]
	s_waitcnt lgkmcnt(5)
	v_mfma_f32_16x16x32_bf16 v[52:55], v[150:153], v[174:177], v[52:55]
	v_mfma_f32_16x16x32_bf16 v[48:51], v[158:161], v[174:177], v[48:51]
	s_waitcnt lgkmcnt(3)
	v_mfma_f32_16x16x32_bf16 v[36:39], v[150:153], v[182:185], v[36:39]
	v_mfma_f32_16x16x32_bf16 v[32:35], v[158:161], v[182:185], v[32:35]
	s_waitcnt lgkmcnt(1)
	v_mfma_f32_16x16x32_bf16 v[20:23], v[150:153], v[190:193], v[20:23]
	v_mfma_f32_16x16x32_bf16 v[16:19], v[158:161], v[190:193], v[16:19]
	v_mfma_f32_16x16x32_bf16 v[60:63], v[154:157], v[170:173], v[60:63]
	s_add_u32 s22, s22, 0x80080
	s_addc_u32 s23, s23, 0
	v_mfma_f32_16x16x32_bf16 v[56:59], v[162:165], v[170:173], v[56:59]
	s_add_i32 s3, s24, s29
	v_mfma_f32_16x16x32_bf16 v[52:55], v[154:157], v[178:181], v[52:55]
	v_mfma_f32_16x16x32_bf16 v[48:51], v[162:165], v[178:181], v[48:51]
	v_mfma_f32_16x16x32_bf16 v[36:39], v[154:157], v[186:189], v[36:39]
	v_mfma_f32_16x16x32_bf16 v[32:35], v[162:165], v[186:189], v[32:35]
	s_waitcnt lgkmcnt(0)
	v_mfma_f32_16x16x32_bf16 v[20:23], v[154:157], v[198:201], v[20:23]
	v_mfma_f32_16x16x32_bf16 v[16:19], v[162:165], v[198:201], v[16:19]
	s_barrier
	s_setprio 0
	s_mov_b32 m0, s3
	s_nop 0
	global_load_lds_dwordx4 v132, s[22:23]
	s_add_i32 m0, s3, 0x2000
	s_nop 0
	global_load_lds_dwordx4 v128, s[22:23]
	s_waitcnt vmcnt(6)
	s_setprio 1
	s_barrier
	v_mfma_f32_16x16x32_bf16 v[44:47], v[202:205], v[166:169], v[44:47]
	v_mfma_f32_16x16x32_bf16 v[40:43], v[210:213], v[166:169], v[40:43]
	ds_read_b128 v[150:153], v147
	v_mfma_f32_16x16x32_bf16 v[28:31], v[202:205], v[174:177], v[28:31]
	v_mfma_f32_16x16x32_bf16 v[24:27], v[210:213], v[174:177], v[24:27]
	ds_read_b128 v[154:157], v147 offset:1024
	v_mfma_f32_16x16x32_bf16 v[12:15], v[202:205], v[182:185], v[12:15]
	v_mfma_f32_16x16x32_bf16 v[8:11], v[210:213], v[182:185], v[8:11]
	ds_read_b128 v[158:161], v147 offset:2048
	v_mfma_f32_16x16x32_bf16 v[4:7], v[202:205], v[190:193], v[4:7]
	v_mfma_f32_16x16x32_bf16 v[0:3], v[210:213], v[190:193], v[0:3]
	ds_read_b128 v[162:165], v147 offset:3072
	v_mfma_f32_16x16x32_bf16 v[44:47], v[206:209], v[170:173], v[44:47]
	s_add_i32 s54, s54, 2
	v_mfma_f32_16x16x32_bf16 v[40:43], v[214:217], v[170:173], v[40:43]
	s_add_u32 s52, s52, 0x100
	s_addc_u32 s53, s53, 0
	v_mfma_f32_16x16x32_bf16 v[28:31], v[206:209], v[178:181], v[28:31]
	s_add_u32 s20, s20, 0x100
	s_addc_u32 s21, s21, 0
	v_mfma_f32_16x16x32_bf16 v[24:27], v[214:217], v[178:181], v[24:27]
	s_cmp_gt_u32 s54, 29
	v_mfma_f32_16x16x32_bf16 v[12:15], v[206:209], v[186:189], v[12:15]
	v_mfma_f32_16x16x32_bf16 v[8:11], v[214:217], v[186:189], v[8:11]
	v_mfma_f32_16x16x32_bf16 v[4:7], v[206:209], v[198:201], v[4:7]
	v_mfma_f32_16x16x32_bf16 v[0:3], v[214:217], v[198:201], v[0:3]
	s_barrier
	s_setprio 0
	s_cbranch_scc0 .LBB1_693
; DI unsigned pack2(float a, float b) { f32x2 v = {a, b}; hwbf16x2 r = __builtin_convertvector(v, hwbf16x2); return __builtin_bit_cast(unsigned, r); }
;     DI const char* a(const Unit& u) const { return (const char*)(A + (size_t)u.pm * BM * lda); }
;     DI const char* a(const Unit& u) const { return (const char*)(A + (size_t)u.pm * BM * 2048 + (u.pn >> 1) * 512); }
;     DI const char* a(const Unit& u) const { return (const char*)((u.pn < 12 ? A1 : A2) + (size_t)u.pm * BM * 512); }
; #define PG8_WAIT_V(n) asm volatile("s_waitcnt vmcnt(" #n ")" ::: "memory")
; #define PG8_BAR __builtin_amdgcn_s_barrier()
;     DI void operator()(const f32x4 (&acc)[2][2][4][2], const Unit& u, int wr, int wc, int fr, int fq) const {
;         bf16_t* O = O1; int ldc = ldc1, pn = u.pn; if (pn >= split) { O = O2; ldc = ldc2; pn -= split; }
;         const int row0 = u.pm * BM + wr * 64 + fr, col0 = pn * BM + wc * 32 + 8 * fq;
; #pragma unroll
;         for (int ai = 0; ai < 2; ++ai)
; #pragma unroll
;             for (int m = 0; m < 4; ++m) { bf16_t* rowp = O + (size_t)(row0 + ai * HALF + m * 16) * ldc + col0;
; #pragma unroll
;                 for (int bj = 0; bj < 2; ++bj) { const f32x4 v0 = acc[ai][bj][m][0], v1 = acc[ai][bj][m][1];
;                     u32x4 o; o[0] = pack2(v0[0], v0[1]); o[1] = pack2(v0[2], v0[3]); o[2] = pack2(v1[0], v1[1]); o[3] = pack2(v1[2], v1[3]);
;                     *(u32x4*)(rowp + bj * HALF) = o; } }
;     }
; template <class Map, class Epi>
; DI void gemm_phase(LAS unsigned char* lds, const Map& MP, const Epi& E, const int nM, const int nN, const int K, const int lda, const int ldb) {
;     ...
;         { int frr = fr, fqq = fq; asm volatile("" : "+v"(frr), "+v"(fqq)); E(acc, cur, wr, wc, frr, fqq); }
;         if (!has_next) break;
; #pragma unroll
;         for (int a = 0; a < 2; ++a)
; #pragma unroll
;             for (int b = 0; b < 2; ++b)
; #pragma unroll
;                 for (int m = 0; m < 4; ++m)
; #pragma unroll
;                     for (int n = 0; n < 2; ++n) acc[a][b][m][n] = (f32x4){0.f, 0.f, 0.f, 0.f};
;         cur = nxt; cA = nA; cB = nB; ++ui;
;     }
;     PG8_WAIT_V(0);
;     if (wr == 0) PG8_BAR;
;     PG8_BAR;
	s_waitcnt lgkmcnt(0)
	s_lshl_b32 s3, s10, 8
	v_mov_b32_e32 v150, v144
	v_mov_b32_e32 v151, v145
	s_add_i32 s3, s3, s37
	v_cvt_pk_bf16_f32 v68, v68, v69
	v_add_u32_e32 v154, s3, v150
	s_lshl_b32 s3, s47, 8
	s_or_b32 s3, s3, s38
	v_lshl_add_u32 v150, v151, 3, s3
	v_ashrrev_i32_e32 v151, 31, v150
	v_lshl_add_u64 v[150:151], v[150:151], 1, s[6:7]
	v_cvt_pk_bf16_f32 v69, v70, v71
	v_cvt_pk_bf16_f32 v70, v64, v65
	v_add_u32_e32 v64, 0x80, v154
	v_mad_i64_i32 v[152:153], s[20:21], v154, s46, v[150:151]
	v_cvt_pk_bf16_f32 v108, v108, v109
	v_cvt_pk_bf16_f32 v109, v110, v111
	v_cvt_pk_bf16_f32 v110, v104, v105
	v_cvt_pk_bf16_f32 v111, v106, v107
	v_add_u32_e32 v104, 16, v154
	v_mad_i64_i32 v[64:65], s[20:21], v64, s46, v[150:151]
	v_cvt_pk_bf16_f32 v44, v44, v45
	v_cvt_pk_bf16_f32 v45, v46, v47
	v_cvt_pk_bf16_f32 v46, v40, v41
	v_cvt_pk_bf16_f32 v47, v42, v43
	v_add_u32_e32 v40, 0x90, v154
	global_store_dwordx4 v[152:153], v[108:111], off offset:256
	v_cvt_pk_bf16_f32 v92, v92, v93
	v_cvt_pk_bf16_f32 v93, v94, v95
	v_mad_i64_i32 v[108:109], s[20:21], v104, s46, v[150:151]
	v_cvt_pk_bf16_f32 v94, v88, v89
	v_cvt_pk_bf16_f32 v95, v90, v91
	v_add_u32_e32 v88, 32, v154
	global_store_dwordx4 v[64:65], v[44:47], off offset:256
	v_cvt_pk_bf16_f32 v28, v28, v29
	v_cvt_pk_bf16_f32 v29, v30, v31
	v_mad_i64_i32 v[44:45], s[20:21], v40, s46, v[150:151]
	v_cvt_pk_bf16_f32 v30, v24, v25
	v_cvt_pk_bf16_f32 v31, v26, v27
	v_add_u32_e32 v24, 0xa0, v154
	global_store_dwordx4 v[108:109], v[92:95], off offset:256
	v_cvt_pk_bf16_f32 v76, v76, v77
	v_cvt_pk_bf16_f32 v77, v78, v79
	v_mad_i64_i32 v[92:93], s[20:21], v88, s46, v[150:151]
	v_cvt_pk_bf16_f32 v78, v72, v73
	v_cvt_pk_bf16_f32 v79, v74, v75
	v_add_u32_e32 v72, 48, v154
	global_store_dwordx4 v[44:45], v[28:31], off offset:256
	v_cvt_pk_bf16_f32 v12, v12, v13
	v_cvt_pk_bf16_f32 v13, v14, v15
	v_mad_i64_i32 v[28:29], s[20:21], v24, s46, v[150:151]
	v_cvt_pk_bf16_f32 v14, v8, v9
	v_cvt_pk_bf16_f32 v15, v10, v11
	v_add_u32_e32 v8, 0xb0, v154
	global_store_dwordx4 v[92:93], v[76:79], off offset:256
	global_store_dwordx4 v[28:29], v[12:15], off offset:256
	v_cvt_pk_bf16_f32 v124, v124, v125
	v_mad_i64_i32 v[76:77], s[20:21], v72, s46, v[150:151]
	v_mad_i64_i32 v[12:13], s[20:21], v8, s46, v[150:151]
	v_cvt_pk_bf16_f32 v125, v126, v127
	v_cvt_pk_bf16_f32 v126, v120, v121
	v_cvt_pk_bf16_f32 v127, v122, v123
	v_cvt_pk_bf16_f32 v104, v116, v117
	v_cvt_pk_bf16_f32 v105, v118, v119
	v_cvt_pk_bf16_f32 v106, v112, v113
	v_cvt_pk_bf16_f32 v107, v114, v115
	v_cvt_pk_bf16_f32 v88, v100, v101
	v_cvt_pk_bf16_f32 v89, v102, v103
	v_cvt_pk_bf16_f32 v90, v96, v97
	v_cvt_pk_bf16_f32 v91, v98, v99
	v_cvt_pk_bf16_f32 v72, v84, v85
	v_cvt_pk_bf16_f32 v73, v86, v87
	v_cvt_pk_bf16_f32 v74, v80, v81
	v_cvt_pk_bf16_f32 v75, v82, v83
	v_cvt_pk_bf16_f32 v71, v66, v67
	v_cvt_pk_bf16_f32 v60, v60, v61
	v_cvt_pk_bf16_f32 v61, v62, v63
	v_cvt_pk_bf16_f32 v62, v56, v57
	v_cvt_pk_bf16_f32 v63, v58, v59
	v_cvt_pk_bf16_f32 v40, v52, v53
	v_cvt_pk_bf16_f32 v41, v54, v55
	v_cvt_pk_bf16_f32 v42, v48, v49
	v_cvt_pk_bf16_f32 v43, v50, v51
	v_cvt_pk_bf16_f32 v24, v36, v37
	v_cvt_pk_bf16_f32 v25, v38, v39
	v_cvt_pk_bf16_f32 v26, v32, v33
	v_cvt_pk_bf16_f32 v27, v34, v35
	v_cvt_pk_bf16_f32 v8, v20, v21
	v_cvt_pk_bf16_f32 v9, v22, v23
	v_cvt_pk_bf16_f32 v10, v16, v17
	v_cvt_pk_bf16_f32 v11, v18, v19
	v_cvt_pk_bf16_f32 v4, v4, v5
	v_cvt_pk_bf16_f32 v5, v6, v7
	v_cvt_pk_bf16_f32 v6, v0, v1
	v_cvt_pk_bf16_f32 v7, v2, v3
	s_and_b64 vcc, exec, s[40:41]
	s_mov_b32 s47, s12
	s_mov_b32 s10, s14
	s_mov_b64 s[20:21], s[18:19]
	s_mov_b64 s[22:23], s[16:17]
	global_store_dwordx4 v[152:153], v[124:127], off
	global_store_dwordx4 v[108:109], v[104:107], off
	global_store_dwordx4 v[92:93], v[88:91], off
	global_store_dwordx4 v[76:77], v[72:75], off
	global_store_dwordx4 v[76:77], v[68:71], off offset:256
	global_store_dwordx4 v[64:65], v[60:63], off
	global_store_dwordx4 v[44:45], v[40:43], off
	global_store_dwordx4 v[28:29], v[24:27], off
	global_store_dwordx4 v[12:13], v[8:11], off
	global_store_dwordx4 v[12:13], v[4:7], off offset:256
	s_cbranch_vccz .LBB1_690
	s_waitcnt vmcnt(0)
	s_cmpk_gt_u32 s4, 0xff
	s_cbranch_scc1 .LBB1_697
	s_barrier

; #define PG8_STAGE(bufoff, gbase, voff) do { _Pragma("unroll") for (int _i = 0; _i < 2; ++_i) \
;         __builtin_amdgcn_global_load_lds((const unsigned*)((const char*)(gbase) + (voff)[_i]), (LAS unsigned*)(lds + (bufoff) + ldsw + _i * 8192), 16, 0, 0); } while (0)
; #define PG8_LDA(dst, b, h) do { _Pragma("unroll") for (int m = 0; m < 4; ++m) _Pragma("unroll") for (int k = 0; k < 2; ++k) dst[m][k] = *(const LAS bf16x8*)(lds + PG8_SA(b, h) + aoff + m * 2048 + k * 1024); } while (0)
; #define PG8_WAIT_V(n) asm volatile("s_waitcnt vmcnt(" #n ")" ::: "memory")
; #define PG8_BAR __builtin_amdgcn_s_barrier()
; template <class Map, class Epi>
; DI void gemm_phase(LAS unsigned char* lds, const Map& MP, const Epi& E, const int nM, const int nN, const int K, const int lda, const int ldb) {
;     ...
;         for (int t = 0; t < nt; t += 2) {
;             const bool last = (t == nt - 2);
;             const char* a1 = cA + (size_t)(t + 1) * kstep;
;             const char* a2 = last ? nA : cA + (size_t)(t + 2) * kstep; const char* b2 = last ? nB : cB + (size_t)(t + 2) * kstep;
;             const char* a3 = a2 + kstep; const char* b3 = b2 + kstep;
;             PG8_LDB(B0, 0, 0); PG8_SCHED; PG8_LDA(At, 0, 0); PG8_STAGE(PG8_SA(1, 1), a1 + hstepA, voffA);
;             PG8_WAIT_L(8); PG8_BAR; PG8_WAIT_L(0); PG8_MMA(0, 0, At, B0); PG8_BAR; PG8_SCHED;
;             PG8_LDB(B1, 0, 1); PG8_STAGE(PG8_SB(0, 0), b2, voffB);
;             PG8_BAR; PG8_WAIT_L(0); PG8_MMA(0, 1, At, B1); PG8_BAR;
;             PG8_LDA(At, 0, 1); PG8_STAGE(PG8_SA(0, 0), a2, voffA);
;             PG8_BAR; PG8_WAIT_L(0); PG8_MMA(1, 0, At, B0); PG8_BAR; PG8_SCHED;
;             PG8_STAGE(PG8_SB(0, 1), b2 + hstepB, voffB);
;             PG8_WAIT_V(6); PG8_BAR; PG8_MMA(1, 1, At, B1); PG8_BAR;
;             PG8_LDB(B0, 1, 0); PG8_SCHED; PG8_LDA(At, 1, 0); PG8_STAGE(PG8_SA(0, 1), a2 + hstepA, voffA);
;             PG8_WAIT_L(8); PG8_BAR; PG8_WAIT_L(0); PG8_MMA(0, 0, At, B0); PG8_BAR; PG8_SCHED;
;             PG8_LDB(B1, 1, 1); PG8_STAGE(PG8_SB(1, 0), b3, voffB);
;             PG8_BAR; PG8_WAIT_L(0); PG8_MMA(0, 1, At, B1); PG8_BAR;
;             PG8_LDA(At, 1, 1); PG8_STAGE(PG8_SA(1, 0), a3, voffA);
;             PG8_BAR; PG8_WAIT_L(0); PG8_MMA(1, 0, At, B0); PG8_BAR; PG8_SCHED;
;             PG8_STAGE(PG8_SB(1, 1), b3 + hstepB, voffB);
;             PG8_WAIT_V(6); PG8_BAR; PG8_MMA(1, 1, At, B1); PG8_BAR;
.LBB1_925:
	s_add_u32 s3, s10, 0xfff80080
	s_addc_u32 s12, s11, -1
	s_cmp_eq_u32 s48, 28
	s_cselect_b32 s15, s4, s12
	s_cselect_b32 s14, s5, s3
	s_cselect_b32 s13, s37, s47
	s_cselect_b32 s12, s38, s39
	s_add_i32 m0, s24, 0xc000
	ds_read_b128 v[168:171], v150
	global_load_lds_dwordx4 v138, s[10:11]
	ds_read_b128 v[172:175], v150 offset:1024
	ds_read_b128 v[176:179], v150 offset:2048
	ds_read_b128 v[180:183], v150 offset:3072
	ds_read_b128 v[184:187], v150 offset:4096
	ds_read_b128 v[188:191], v150 offset:5120
	ds_read_b128 v[192:195], v150 offset:6144
	ds_read_b128 v[198:201], v150 offset:7168
	s_add_i32 m0, s24, 0xe000
	s_nop 0
	global_load_lds_dwordx4 v136, s[10:11]
	s_waitcnt lgkmcnt(8)
	s_setprio 1
	s_barrier
	s_waitcnt lgkmcnt(7)
	v_mfma_f32_16x16x32_bf16 v[124:127], v[152:155], v[168:171], v[124:127]
	v_mfma_f32_16x16x32_bf16 v[120:123], v[160:163], v[168:171], v[120:123]
	s_waitcnt lgkmcnt(5)
	v_mfma_f32_16x16x32_bf16 v[108:111], v[152:155], v[176:179], v[108:111]
	v_mfma_f32_16x16x32_bf16 v[104:107], v[160:163], v[176:179], v[104:107]
	s_waitcnt lgkmcnt(3)
	v_mfma_f32_16x16x32_bf16 v[92:95], v[152:155], v[184:187], v[92:95]
	v_mfma_f32_16x16x32_bf16 v[88:91], v[160:163], v[184:187], v[88:91]
	s_waitcnt lgkmcnt(1)
	v_mfma_f32_16x16x32_bf16 v[76:79], v[152:155], v[192:195], v[76:79]
	v_mfma_f32_16x16x32_bf16 v[72:75], v[160:163], v[192:195], v[72:75]
	v_mfma_f32_16x16x32_bf16 v[124:127], v[156:159], v[172:175], v[124:127]
	s_add_i32 s3, s35, s22
	v_mfma_f32_16x16x32_bf16 v[120:123], v[164:167], v[172:175], v[120:123]
	v_lshl_add_u64 v[144:145], s[12:13], 0, v[132:133]
	v_mfma_f32_16x16x32_bf16 v[108:111], v[156:159], v[180:183], v[108:111]
	v_lshl_add_u64 v[218:219], s[12:13], 0, v[128:129]
	v_mfma_f32_16x16x32_bf16 v[104:107], v[164:167], v[180:183], v[104:107]
	v_mfma_f32_16x16x32_bf16 v[92:95], v[156:159], v[188:191], v[92:95]
	v_mfma_f32_16x16x32_bf16 v[88:91], v[164:167], v[188:191], v[88:91]
	s_waitcnt lgkmcnt(0)
	v_mfma_f32_16x16x32_bf16 v[76:79], v[156:159], v[198:201], v[76:79]
	v_mfma_f32_16x16x32_bf16 v[72:75], v[164:167], v[198:201], v[72:75]
	s_barrier
	s_setprio 0
	s_mov_b32 m0, s3
	ds_read_b128 v[202:205], v151
	global_load_lds_dwordx4 v[144:145], off
	ds_read_b128 v[206:209], v151 offset:1024
	ds_read_b128 v[210:213], v151 offset:2048
	ds_read_b128 v[214:217], v151 offset:3072
	s_add_i32 m0, s3, 0x2000
	s_nop 0
	global_load_lds_dwordx4 v[218:219], off
	s_setprio 1
	s_barrier
	s_waitcnt lgkmcnt(3)
	v_mfma_f32_16x16x32_bf16 v[116:119], v[202:205], v[168:171], v[116:119]
	s_waitcnt lgkmcnt(1)
	v_mfma_f32_16x16x32_bf16 v[112:115], v[210:213], v[168:171], v[112:115]
	v_mfma_f32_16x16x32_bf16 v[100:103], v[202:205], v[176:179], v[100:103]
	v_mfma_f32_16x16x32_bf16 v[96:99], v[210:213], v[176:179], v[96:99]
	v_mfma_f32_16x16x32_bf16 v[84:87], v[202:205], v[184:187], v[84:87]
	v_mfma_f32_16x16x32_bf16 v[80:83], v[210:213], v[184:187], v[80:83]
	v_mfma_f32_16x16x32_bf16 v[68:71], v[202:205], v[192:195], v[68:71]
	v_mfma_f32_16x16x32_bf16 v[64:67], v[210:213], v[192:195], v[64:67]
	v_mfma_f32_16x16x32_bf16 v[116:119], v[206:209], v[172:175], v[116:119]
	v_lshl_add_u64 v[222:223], s[14:15], 0, v[130:131]
	s_mov_b32 m0, s24
	s_waitcnt lgkmcnt(0)
	v_mfma_f32_16x16x32_bf16 v[112:115], v[214:217], v[172:175], v[112:115]
	v_lshl_add_u64 v[220:221], s[14:15], 0, v[134:135]
	v_mfma_f32_16x16x32_bf16 v[100:103], v[206:209], v[180:183], v[100:103]
	v_mfma_f32_16x16x32_bf16 v[96:99], v[214:217], v[180:183], v[96:99]
	v_mfma_f32_16x16x32_bf16 v[84:87], v[206:209], v[188:191], v[84:87]
	v_mfma_f32_16x16x32_bf16 v[80:83], v[214:217], v[188:191], v[80:83]
	v_mfma_f32_16x16x32_bf16 v[68:71], v[206:209], v[198:201], v[68:71]
	v_mfma_f32_16x16x32_bf16 v[64:67], v[214:217], v[198:201], v[64:67]
	s_barrier
	s_setprio 0
	ds_read_b128 v[168:171], v150 offset:16384
	global_load_lds_dwordx4 v[220:221], off
	ds_read_b128 v[172:175], v150 offset:17408
	ds_read_b128 v[176:179], v150 offset:18432
	ds_read_b128 v[180:183], v150 offset:19456
	ds_read_b128 v[184:187], v150 offset:20480
	ds_read_b128 v[188:191], v150 offset:21504
	ds_read_b128 v[192:195], v150 offset:22528
	ds_read_b128 v[198:201], v150 offset:23552
	s_mov_b32 m0, s9
	s_nop 0
	global_load_lds_dwordx4 v[222:223], off
	s_waitcnt vmcnt(10)
	s_setprio 1
	s_barrier
	s_waitcnt lgkmcnt(7)
	v_mfma_f32_16x16x32_bf16 v[60:63], v[152:155], v[168:171], v[60:63]
	v_mfma_f32_16x16x32_bf16 v[56:59], v[160:163], v[168:171], v[56:59]
	s_waitcnt lgkmcnt(5)
	v_mfma_f32_16x16x32_bf16 v[44:47], v[152:155], v[176:179], v[44:47]
	v_mfma_f32_16x16x32_bf16 v[40:43], v[160:163], v[176:179], v[40:43]
	s_waitcnt lgkmcnt(3)
	v_mfma_f32_16x16x32_bf16 v[28:31], v[152:155], v[184:187], v[28:31]
	v_mfma_f32_16x16x32_bf16 v[24:27], v[160:163], v[184:187], v[24:27]
	s_waitcnt lgkmcnt(1)
	v_mfma_f32_16x16x32_bf16 v[12:15], v[152:155], v[192:195], v[12:15]
	v_mfma_f32_16x16x32_bf16 v[8:11], v[160:163], v[192:195], v[8:11]
	v_mfma_f32_16x16x32_bf16 v[60:63], v[156:159], v[172:175], v[60:63]
	s_add_u32 s56, s12, 0x80000
	s_addc_u32 s57, s13, 0
	v_mfma_f32_16x16x32_bf16 v[56:59], v[164:167], v[172:175], v[56:59]
	s_add_i32 s3, s36, s22
	v_mfma_f32_16x16x32_bf16 v[44:47], v[156:159], v[180:183], v[44:47]
	v_mfma_f32_16x16x32_bf16 v[40:43], v[164:167], v[180:183], v[40:43]
	v_mfma_f32_16x16x32_bf16 v[28:31], v[156:159], v[188:191], v[28:31]
	v_mfma_f32_16x16x32_bf16 v[24:27], v[164:167], v[188:191], v[24:27]
	s_waitcnt lgkmcnt(0)
	v_mfma_f32_16x16x32_bf16 v[12:15], v[156:159], v[198:201], v[12:15]
	v_mfma_f32_16x16x32_bf16 v[8:11], v[164:167], v[198:201], v[8:11]
	s_barrier
; #define PG8_STAGE(bufoff, gbase, voff) do { _Pragma("unroll") for (int _i = 0; _i < 2; ++_i) \
;         __builtin_amdgcn_global_load_lds((const unsigned*)((const char*)(gbase) + (voff)[_i]), (LAS unsigned*)(lds + (bufoff) + ldsw + _i * 8192), 16, 0, 0); } while (0)
; #define PG8_LDA(dst, b, h) do { _Pragma("unroll") for (int m = 0; m < 4; ++m) _Pragma("unroll") for (int k = 0; k < 2; ++k) dst[m][k] = *(const LAS bf16x8*)(lds + PG8_SA(b, h) + aoff + m * 2048 + k * 1024); } while (0)
; #define PG8_WAIT_V(n) asm volatile("s_waitcnt vmcnt(" #n ")" ::: "memory")
; #define PG8_BAR __builtin_amdgcn_s_barrier()
; template <class Map, class Epi>
; DI void gemm_phase(LAS unsigned char* lds, const Map& MP, const Epi& E, const int nM, const int nN, const int K, const int lda, const int ldb) {
;     ...
;         for (int t = 0; t < nt; t += 2) {
;             const bool last = (t == nt - 2);
;             const char* a1 = cA + (size_t)(t + 1) * kstep;
;             const char* a2 = last ? nA : cA + (size_t)(t + 2) * kstep; const char* b2 = last ? nB : cB + (size_t)(t + 2) * kstep;
;             const char* a3 = a2 + kstep; const char* b3 = b2 + kstep;
;             PG8_LDB(B0, 0, 0); PG8_SCHED; PG8_LDA(At, 0, 0); PG8_STAGE(PG8_SA(1, 1), a1 + hstepA, voffA);
;             PG8_WAIT_L(8); PG8_BAR; PG8_WAIT_L(0); PG8_MMA(0, 0, At, B0); PG8_BAR; PG8_SCHED;
;             PG8_LDB(B1, 0, 1); PG8_STAGE(PG8_SB(0, 0), b2, voffB);
;             PG8_BAR; PG8_WAIT_L(0); PG8_MMA(0, 1, At, B1); PG8_BAR;
;             PG8_LDA(At, 0, 1); PG8_STAGE(PG8_SA(0, 0), a2, voffA);
;             PG8_BAR; PG8_WAIT_L(0); PG8_MMA(1, 0, At, B0); PG8_BAR; PG8_SCHED;
;             PG8_STAGE(PG8_SB(0, 1), b2 + hstepB, voffB);
;             PG8_WAIT_V(6); PG8_BAR; PG8_MMA(1, 1, At, B1); PG8_BAR;
;             PG8_LDB(B0, 1, 0); PG8_SCHED; PG8_LDA(At, 1, 0); PG8_STAGE(PG8_SA(0, 1), a2 + hstepA, voffA);
;             PG8_WAIT_L(8); PG8_BAR; PG8_WAIT_L(0); PG8_MMA(0, 0, At, B0); PG8_BAR; PG8_SCHED;
;             PG8_LDB(B1, 1, 1); PG8_STAGE(PG8_SB(1, 0), b3, voffB);
;             PG8_BAR; PG8_WAIT_L(0); PG8_MMA(0, 1, At, B1); PG8_BAR;
;             PG8_LDA(At, 1, 1); PG8_STAGE(PG8_SA(1, 0), a3, voffA);
;             PG8_BAR; PG8_WAIT_L(0); PG8_MMA(1, 0, At, B0); PG8_BAR; PG8_SCHED;
;             PG8_STAGE(PG8_SB(1, 1), b3 + hstepB, voffB);
;             PG8_WAIT_V(6); PG8_BAR; PG8_MMA(1, 1, At, B1); PG8_BAR;
	s_setprio 0
	s_mov_b32 m0, s3
	s_nop 0
	global_load_lds_dwordx4 v132, s[56:57]
	s_add_i32 m0, s3, 0x2000
	s_nop 0
	global_load_lds_dwordx4 v128, s[56:57]
	s_waitcnt vmcnt(6)
	s_setprio 1
	s_barrier
	v_mfma_f32_16x16x32_bf16 v[52:55], v[202:205], v[168:171], v[52:55]
	v_mfma_f32_16x16x32_bf16 v[48:51], v[210:213], v[168:171], v[48:51]
	s_add_i32 s3, 0, 0x18000
	v_add_u32_e32 v164, s3, v148
	ds_read_b128 v[152:155], v164
	v_mfma_f32_16x16x32_bf16 v[36:39], v[202:205], v[176:179], v[36:39]
	v_mfma_f32_16x16x32_bf16 v[32:35], v[210:213], v[176:179], v[32:35]
	ds_read_b128 v[156:159], v164 offset:1024
	v_mfma_f32_16x16x32_bf16 v[20:23], v[202:205], v[184:187], v[20:23]
	v_mfma_f32_16x16x32_bf16 v[16:19], v[210:213], v[184:187], v[16:19]
	ds_read_b128 v[160:163], v164 offset:2048
	v_mfma_f32_16x16x32_bf16 v[4:7], v[202:205], v[192:195], v[4:7]
	v_mfma_f32_16x16x32_bf16 v[0:3], v[210:213], v[192:195], v[0:3]
	ds_read_b128 v[164:167], v164 offset:3072
	v_mfma_f32_16x16x32_bf16 v[52:55], v[206:209], v[172:175], v[52:55]
	s_add_u32 s14, s14, 0x80000
	s_addc_u32 s15, s15, 0
	v_mfma_f32_16x16x32_bf16 v[48:51], v[214:217], v[172:175], v[48:51]
	v_mfma_f32_16x16x32_bf16 v[36:39], v[206:209], v[180:183], v[36:39]
	v_mfma_f32_16x16x32_bf16 v[32:35], v[214:217], v[180:183], v[32:35]
	v_mfma_f32_16x16x32_bf16 v[20:23], v[206:209], v[188:191], v[20:23]
	v_mfma_f32_16x16x32_bf16 v[16:19], v[214:217], v[188:191], v[16:19]
	v_mfma_f32_16x16x32_bf16 v[4:7], v[206:209], v[198:201], v[4:7]
	v_mfma_f32_16x16x32_bf16 v[0:3], v[214:217], v[198:201], v[0:3]
	s_barrier
	s_setprio 0
	s_mov_b32 m0, s25
	ds_read_b128 v[168:171], v150 offset:32768
	global_load_lds_dwordx4 v134, s[14:15]
	ds_read_b128 v[172:175], v150 offset:33792
	ds_read_b128 v[176:179], v150 offset:34816
	ds_read_b128 v[180:183], v150 offset:35840
	ds_read_b128 v[184:187], v150 offset:36864
	ds_read_b128 v[188:191], v150 offset:37888
	ds_read_b128 v[192:195], v150 offset:38912
	ds_read_b128 v[198:201], v150 offset:39936
	s_mov_b32 m0, s26
	s_nop 0
	global_load_lds_dwordx4 v130, s[14:15]
	s_waitcnt lgkmcnt(8)
	s_setprio 1
	s_barrier
	s_waitcnt lgkmcnt(7)
	v_mfma_f32_16x16x32_bf16 v[124:127], v[152:155], v[168:171], v[124:127]
	v_mfma_f32_16x16x32_bf16 v[120:123], v[160:163], v[168:171], v[120:123]
	s_waitcnt lgkmcnt(5)
	v_mfma_f32_16x16x32_bf16 v[108:111], v[152:155], v[176:179], v[108:111]
	v_mfma_f32_16x16x32_bf16 v[104:107], v[160:163], v[176:179], v[104:107]
	s_waitcnt lgkmcnt(3)
	v_mfma_f32_16x16x32_bf16 v[92:95], v[152:155], v[184:187], v[92:95]
	v_mfma_f32_16x16x32_bf16 v[88:91], v[160:163], v[184:187], v[88:91]
	s_waitcnt lgkmcnt(1)
	v_mfma_f32_16x16x32_bf16 v[76:79], v[152:155], v[192:195], v[76:79]
	v_mfma_f32_16x16x32_bf16 v[72:75], v[160:163], v[192:195], v[72:75]
	v_mfma_f32_16x16x32_bf16 v[124:127], v[156:159], v[172:175], v[124:127]
	s_add_i32 s14, 0, 0x1c000
	v_mfma_f32_16x16x32_bf16 v[120:123], v[164:167], v[172:175], v[120:123]
	s_add_i32 s3, s3, s22
	v_mfma_f32_16x16x32_bf16 v[108:111], v[156:159], v[180:183], v[108:111]
	v_add_u32_e32 v196, s14, v148
	v_mfma_f32_16x16x32_bf16 v[104:107], v[164:167], v[180:183], v[104:107]
	v_lshl_add_u64 v[144:145], v[144:145], 0, s[44:45]
	v_mfma_f32_16x16x32_bf16 v[92:95], v[156:159], v[188:191], v[92:95]
	v_mfma_f32_16x16x32_bf16 v[88:91], v[164:167], v[188:191], v[88:91]
	s_waitcnt lgkmcnt(0)
	v_mfma_f32_16x16x32_bf16 v[76:79], v[156:159], v[198:201], v[76:79]
	v_mfma_f32_16x16x32_bf16 v[72:75], v[164:167], v[198:201], v[72:75]
	s_barrier
	s_setprio 0
	s_mov_b32 m0, s3
	ds_read_b128 v[202:205], v196
	global_load_lds_dwordx4 v[144:145], off
	ds_read_b128 v[206:209], v196 offset:1024
	ds_read_b128 v[210:213], v196 offset:2048
	ds_read_b128 v[214:217], v196 offset:3072
	v_lshl_add_u64 v[144:145], v[218:219], 0, s[44:45]
	s_add_i32 m0, s3, 0x2000
	s_nop 0
	global_load_lds_dwordx4 v[144:145], off
	s_setprio 1
	s_barrier
	s_waitcnt lgkmcnt(3)
	v_mfma_f32_16x16x32_bf16 v[116:119], v[202:205], v[168:171], v[116:119]
	s_waitcnt lgkmcnt(1)
	v_mfma_f32_16x16x32_bf16 v[112:115], v[210:213], v[168:171], v[112:115]
	v_mfma_f32_16x16x32_bf16 v[100:103], v[202:205], v[176:179], v[100:103]
	v_mfma_f32_16x16x32_bf16 v[96:99], v[210:213], v[176:179], v[96:99]
	v_mfma_f32_16x16x32_bf16 v[84:87], v[202:205], v[184:187], v[84:87]
	v_mfma_f32_16x16x32_bf16 v[80:83], v[210:213], v[184:187], v[80:83]
	v_mfma_f32_16x16x32_bf16 v[68:71], v[202:205], v[192:195], v[68:71]
	v_mfma_f32_16x16x32_bf16 v[64:67], v[210:213], v[192:195], v[64:67]
	v_mfma_f32_16x16x32_bf16 v[116:119], v[206:209], v[172:175], v[116:119]
	s_mov_b32 m0, s30
	s_waitcnt lgkmcnt(0)
	v_mfma_f32_16x16x32_bf16 v[112:115], v[214:217], v[172:175], v[112:115]
	v_lshl_add_u64 v[144:145], v[220:221], 0, s[44:45]
	v_mfma_f32_16x16x32_bf16 v[100:103], v[206:209], v[180:183], v[100:103]
	v_mfma_f32_16x16x32_bf16 v[96:99], v[214:217], v[180:183], v[96:99]
	v_mfma_f32_16x16x32_bf16 v[84:87], v[206:209], v[188:191], v[84:87]
	v_mfma_f32_16x16x32_bf16 v[80:83], v[214:217], v[188:191], v[80:83]
	v_mfma_f32_16x16x32_bf16 v[68:71], v[206:209], v[198:201], v[68:71]
	v_mfma_f32_16x16x32_bf16 v[64:67], v[214:217], v[198:201], v[64:67]
	s_barrier
	s_setprio 0
	ds_read_b128 v[168:171], v150 offset:49152
	global_load_lds_dwordx4 v[144:145], off
	ds_read_b128 v[172:175], v150 offset:50176
	ds_read_b128 v[176:179], v150 offset:51200
	ds_read_b128 v[180:183], v150 offset:52224
	ds_read_b128 v[184:187], v150 offset:53248
	ds_read_b128 v[188:191], v150 offset:54272
	ds_read_b128 v[192:195], v150 offset:55296
	ds_read_b128 v[198:201], v150 offset:56320
	v_lshl_add_u64 v[144:145], v[222:223], 0, s[44:45]
	s_mov_b32 m0, s31
	s_nop 0
	global_load_lds_dwordx4 v[144:145], off
	s_waitcnt vmcnt(10)
	s_setprio 1
	s_barrier
; #define PG8_WAIT_V(n) asm volatile("s_waitcnt vmcnt(" #n ")" ::: "memory")
;     DI void operator()(const f32x4 (&acc)[2][2][4][2], const Unit& u, int wr, int wc, int fr, int fq) const {
;         const int row0 = u.pm * BM + wr * 64 + fr, col0 = u.pn * BM + wc * 32 + 8 * fq;
;         f32x4 sc[2][2];
; #pragma unroll
;         for (int bj = 0; bj < 2; ++bj)
; #pragma unroll
;             for (int n = 0; n < 2; ++n) sc[bj][n] = scale ? *(const f32x4*)(scale + col0 + bj * HALF + 4 * n) : (f32x4){1.f, 1.f, 1.f, 1.f};
; #pragma unroll
;         for (int ai = 0; ai < 2; ++ai)
; #pragma unroll
; template <class Map, class Epi>
; DI void gemm_phase(LAS unsigned char* lds, const Map& MP, const Epi& E, const int nM, const int nN, const int K, const int lda, const int ldb) {
;     ...
;         for (int t = 0; t < nt; t += 2) {
;             const bool last = (t == nt - 2);
;             const char* a1 = cA + (size_t)(t + 1) * kstep;
;             const char* a2 = last ? nA : cA + (size_t)(t + 2) * kstep; const char* b2 = last ? nB : cB + (size_t)(t + 2) * kstep;
;             const char* a3 = a2 + kstep; const char* b3 = b2 + kstep;
;             PG8_LDB(B0, 0, 0); PG8_SCHED; PG8_LDA(At, 0, 0); PG8_STAGE(PG8_SA(1, 1), a1 + hstepA, voffA);
;             PG8_WAIT_L(8); PG8_BAR; PG8_WAIT_L(0); PG8_MMA(0, 0, At, B0); PG8_BAR; PG8_SCHED;
;             PG8_LDB(B1, 0, 1); PG8_STAGE(PG8_SB(0, 0), b2, voffB);
;             PG8_BAR; PG8_WAIT_L(0); PG8_MMA(0, 1, At, B1); PG8_BAR;
;             PG8_LDA(At, 0, 1); PG8_STAGE(PG8_SA(0, 0), a2, voffA);
;             PG8_BAR; PG8_WAIT_L(0); PG8_MMA(1, 0, At, B0); PG8_BAR; PG8_SCHED;
;             PG8_STAGE(PG8_SB(0, 1), b2 + hstepB, voffB);
;             PG8_WAIT_V(6); PG8_BAR; PG8_MMA(1, 1, At, B1); PG8_BAR;
;             PG8_LDB(B0, 1, 0); PG8_SCHED; PG8_LDA(At, 1, 0); PG8_STAGE(PG8_SA(0, 1), a2 + hstepA, voffA);
;             PG8_WAIT_L(8); PG8_BAR; PG8_WAIT_L(0); PG8_MMA(0, 0, At, B0); PG8_BAR; PG8_SCHED;
;             PG8_LDB(B1, 1, 1); PG8_STAGE(PG8_SB(1, 0), b3, voffB);
;             PG8_BAR; PG8_WAIT_L(0); PG8_MMA(0, 1, At, B1); PG8_BAR;
;             PG8_LDA(At, 1, 1); PG8_STAGE(PG8_SA(1, 0), a3, voffA);
;             PG8_BAR; PG8_WAIT_L(0); PG8_MMA(1, 0, At, B0); PG8_BAR; PG8_SCHED;
;             PG8_STAGE(PG8_SB(1, 1), b3 + hstepB, voffB);
;             PG8_WAIT_V(6); PG8_BAR; PG8_MMA(1, 1, At, B1); PG8_BAR;
	s_waitcnt lgkmcnt(7)
	v_mfma_f32_16x16x32_bf16 v[60:63], v[152:155], v[168:171], v[60:63]
	v_mfma_f32_16x16x32_bf16 v[56:59], v[160:163], v[168:171], v[56:59]
	s_waitcnt lgkmcnt(5)
	v_mfma_f32_16x16x32_bf16 v[44:47], v[152:155], v[176:179], v[44:47]
	v_mfma_f32_16x16x32_bf16 v[40:43], v[160:163], v[176:179], v[40:43]
	s_waitcnt lgkmcnt(3)
	v_mfma_f32_16x16x32_bf16 v[28:31], v[152:155], v[184:187], v[28:31]
	v_mfma_f32_16x16x32_bf16 v[24:27], v[160:163], v[184:187], v[24:27]
	s_waitcnt lgkmcnt(1)
	v_mfma_f32_16x16x32_bf16 v[12:15], v[152:155], v[192:195], v[12:15]
	v_mfma_f32_16x16x32_bf16 v[8:11], v[160:163], v[192:195], v[8:11]
	v_mfma_f32_16x16x32_bf16 v[60:63], v[156:159], v[172:175], v[60:63]
	s_add_u32 s12, s12, 0x80080
	s_addc_u32 s13, s13, 0
	v_mfma_f32_16x16x32_bf16 v[56:59], v[164:167], v[172:175], v[56:59]
	s_add_i32 s3, s14, s22
	v_mfma_f32_16x16x32_bf16 v[44:47], v[156:159], v[180:183], v[44:47]
	v_mfma_f32_16x16x32_bf16 v[40:43], v[164:167], v[180:183], v[40:43]
	v_mfma_f32_16x16x32_bf16 v[28:31], v[156:159], v[188:191], v[28:31]
	v_mfma_f32_16x16x32_bf16 v[24:27], v[164:167], v[188:191], v[24:27]
	s_waitcnt lgkmcnt(0)
	v_mfma_f32_16x16x32_bf16 v[12:15], v[156:159], v[198:201], v[12:15]
	v_mfma_f32_16x16x32_bf16 v[8:11], v[164:167], v[198:201], v[8:11]
	s_barrier
	s_setprio 0
	s_mov_b32 m0, s3
	s_nop 0
	global_load_lds_dwordx4 v132, s[12:13]
	s_add_i32 m0, s3, 0x2000
	s_nop 0
	global_load_lds_dwordx4 v128, s[12:13]
	s_waitcnt vmcnt(6)
	s_setprio 1
	s_barrier
	v_mfma_f32_16x16x32_bf16 v[52:55], v[202:205], v[168:171], v[52:55]
	v_mfma_f32_16x16x32_bf16 v[48:51], v[210:213], v[168:171], v[48:51]
	ds_read_b128 v[152:155], v149
	v_mfma_f32_16x16x32_bf16 v[36:39], v[202:205], v[176:179], v[36:39]
	v_mfma_f32_16x16x32_bf16 v[32:35], v[210:213], v[176:179], v[32:35]
	ds_read_b128 v[156:159], v149 offset:1024
	v_mfma_f32_16x16x32_bf16 v[20:23], v[202:205], v[184:187], v[20:23]
	v_mfma_f32_16x16x32_bf16 v[16:19], v[210:213], v[184:187], v[16:19]
	ds_read_b128 v[160:163], v149 offset:2048
	v_mfma_f32_16x16x32_bf16 v[4:7], v[202:205], v[192:195], v[4:7]
	v_mfma_f32_16x16x32_bf16 v[0:3], v[210:213], v[192:195], v[0:3]
	ds_read_b128 v[164:167], v149 offset:3072
	v_mfma_f32_16x16x32_bf16 v[52:55], v[206:209], v[172:175], v[52:55]
	s_add_i32 s48, s48, 2
	v_mfma_f32_16x16x32_bf16 v[48:51], v[214:217], v[172:175], v[48:51]
	s_add_u32 s39, s39, 0x100
	s_addc_u32 s47, s47, 0
	v_mfma_f32_16x16x32_bf16 v[36:39], v[206:209], v[180:183], v[36:39]
	s_add_u32 s10, s10, 0x100
	s_addc_u32 s11, s11, 0
	v_mfma_f32_16x16x32_bf16 v[32:35], v[214:217], v[180:183], v[32:35]
	s_cmp_gt_u32 s48, 29
	v_mfma_f32_16x16x32_bf16 v[20:23], v[206:209], v[188:191], v[20:23]
	v_mfma_f32_16x16x32_bf16 v[16:19], v[214:217], v[188:191], v[16:19]
	v_mfma_f32_16x16x32_bf16 v[4:7], v[206:209], v[198:201], v[4:7]
	v_mfma_f32_16x16x32_bf16 v[0:3], v[214:217], v[198:201], v[0:3]
	s_barrier
	s_setprio 0
	s_cbranch_scc0 .LBB1_925
	s_waitcnt lgkmcnt(0)
	v_mov_b32_e32 v152, v147
	v_mov_b32_e32 v144, v146
	s_lshl_b32 s2, s2, 8
	s_or_b32 s2, s2, s29
	v_lshl_add_u32 v144, v144, 3, s2
	s_lshl_b32 s2, s8, 8
	s_add_i32 s2, s2, s28
	v_add_u32_e32 v152, s2, v152
	v_ashrrev_i32_e32 v153, 31, v152
	v_lshlrev_b64 v[152:153], 12, v[152:153]
	v_ashrrev_i32_e32 v145, 31, v144
	v_lshl_add_u64 v[152:153], s[42:43], 0, v[152:153]
	v_lshl_add_u64 v[144:145], v[144:145], 1, v[152:153]
	global_load_dwordx4 v[160:163], v[144:145], off
	global_load_dwordx4 v[164:167], v[144:145], off offset:256
	s_mov_b64 s[98:99], 0x10000
	v_lshl_add_u64 v[154:155], v[144:145], 0, s[98:99]
	global_load_dwordx4 v[168:171], v[154:155], off
	global_load_dwordx4 v[172:175], v[154:155], off offset:256
	s_mov_b64 s[98:99], 0x20000
	v_lshl_add_u64 v[154:155], v[144:145], 0, s[98:99]
	global_load_dwordx4 v[176:179], v[154:155], off
	global_load_dwordx4 v[180:183], v[154:155], off offset:256
	s_mov_b64 s[98:99], 0x30000
	v_lshl_add_u64 v[154:155], v[144:145], 0, s[98:99]
	global_load_dwordx4 v[184:187], v[154:155], off
	global_load_dwordx4 v[188:191], v[154:155], off offset:256
	s_mov_b64 s[98:99], 0x80000
	v_lshl_add_u64 v[154:155], v[144:145], 0, s[98:99]
	global_load_dwordx4 v[192:195], v[154:155], off
	global_load_dwordx4 v[198:201], v[154:155], off offset:256
	s_mov_b64 s[98:99], 0x90000
	v_lshl_add_u64 v[154:155], v[144:145], 0, s[98:99]
	global_load_dwordx4 v[202:205], v[154:155], off
	global_load_dwordx4 v[206:209], v[154:155], off offset:256
	s_mov_b64 s[98:99], 0xa0000
	v_lshl_add_u64 v[154:155], v[144:145], 0, s[98:99]
	global_load_dwordx4 v[210:213], v[154:155], off
	global_load_dwordx4 v[214:217], v[154:155], off offset:256
	s_mov_b64 s[98:99], 0xb0000
	v_lshl_add_u64 v[154:155], v[144:145], 0, s[98:99]
	global_load_dwordx4 v[248:251], v[154:155], off
	global_load_dwordx4 v[252:255], v[154:155], off offset:256
	s_waitcnt vmcnt(15)
	s_nop 1
	v_mov_b32_e32 v152, v160
	v_mov_b32_e32 v153, v161
	v_mov_b32_e32 v154, v162
	v_mov_b32_e32 v155, v163
	s_mov_b64 s[2:3], 0x10000
	s_mov_b32 s8, s52
	s_mov_b64 s[10:11], s[6:7]
	s_mov_b64 s[12:13], s[54:55]
	s_waitcnt lgkmcnt(0)
	v_lshlrev_b32_e32 v156, 16, v152
	v_and_b32_e32 v157, 0xffff0000, v152
	v_lshlrev_b32_e32 v152, 16, v153
	v_and_b32_e32 v153, 0xffff0000, v153
	v_lshlrev_b32_e32 v158, 16, v154
	v_and_b32_e32 v159, 0xffff0000, v154
	v_lshlrev_b32_e32 v154, 16, v155
	v_and_b32_e32 v155, 0xffff0000, v155
	v_pk_add_f32 v[126:127], v[126:127], v[152:153]
	v_pk_add_f32 v[124:125], v[124:125], v[156:157]
	v_pk_add_f32 v[152:153], v[122:123], v[154:155]
	v_pk_add_f32 v[122:123], v[120:121], v[158:159]
	v_cvt_pk_bf16_f32 v120, v124, v125
	v_cvt_pk_bf16_f32 v121, v126, v127
	v_cvt_pk_bf16_f32 v122, v122, v123
	v_cvt_pk_bf16_f32 v123, v152, v153
	global_store_dwordx4 v[144:145], v[120:123], off
	s_waitcnt vmcnt(15)
; DI unsigned pack2(float a, float b) { f32x2 v = {a, b}; hwbf16x2 r = __builtin_convertvector(v, hwbf16x2); return __builtin_bit_cast(unsigned, r); }
; DI float bflo(unsigned w) { return __uint_as_float(w << 16); }
; DI float bfhi(unsigned w) { return __uint_as_float(w & 0xffff0000u); }
;     DI void operator()(const f32x4 (&acc)[2][2][4][2], const Unit& u, int wr, int wc, int fr, int fq) const {
;         const int row0 = u.pm * BM + wr * 64 + fr, col0 = u.pn * BM + wc * 32 + 8 * fq;
;         f32x4 sc[2][2];
; #pragma unroll
;         for (int bj = 0; bj < 2; ++bj)
; #pragma unroll
;             for (int n = 0; n < 2; ++n) sc[bj][n] = scale ? *(const f32x4*)(scale + col0 + bj * HALF + 4 * n) : (f32x4){1.f, 1.f, 1.f, 1.f};
; #pragma unroll
;         for (int ai = 0; ai < 2; ++ai)
; #pragma unroll
;             for (int m = 0; m < 4; ++m) { const size_t ro = (size_t)(row0 + ai * HALF + m * 16) * D + col0;
; #pragma unroll
;                 for (int bj = 0; bj < 2; ++bj) {
;                     f32x4 x0, x1;
;                     if constexpr (IB) { const u32x4 w = *(const u32x4*)((const bf16_t*)Xin + ro + bj * HALF);
;                         x0 = (f32x4){bflo(w[0]), bfhi(w[0]), bflo(w[1]), bfhi(w[1])}; x1 = (f32x4){bflo(w[2]), bfhi(w[2]), bflo(w[3]), bfhi(w[3])}; }
;                     else { x0 = *(const f32x4*)((const float*)Xin + ro + bj * HALF); x1 = *(const f32x4*)((const float*)Xin + ro + bj * HALF + 4); }
;                     x0 += acc[ai][bj][m][0] * sc[bj][0]; x1 += acc[ai][bj][m][1] * sc[bj][1];
;                     if constexpr (OB) { u32x4 o; o[0] = pack2(x0[0], x0[1]); o[1] = pack2(x0[2], x0[3]); o[2] = pack2(x1[0], x1[1]); o[3] = pack2(x1[2], x1[3]);
;                         *(u32x4*)((bf16_t*)Xout + ro + bj * HALF) = o; }
;                     else { *(f32x4*)((float*)Xout + ro + bj * HALF) = x0; *(f32x4*)((float*)Xout + ro + bj * HALF + 4) = x1; } } }
	s_nop 1
	v_mov_b32_e32 v120, v164
	v_mov_b32_e32 v121, v165
	v_mov_b32_e32 v122, v166
	v_mov_b32_e32 v123, v167
	s_waitcnt lgkmcnt(0)
	v_lshlrev_b32_e32 v124, 16, v120
	v_and_b32_e32 v125, 0xffff0000, v120
	v_lshlrev_b32_e32 v120, 16, v121
	v_and_b32_e32 v121, 0xffff0000, v121
	v_lshlrev_b32_e32 v126, 16, v122
	v_and_b32_e32 v127, 0xffff0000, v122
	v_lshlrev_b32_e32 v122, 16, v123
	v_and_b32_e32 v123, 0xffff0000, v123
	v_pk_add_f32 v[116:117], v[116:117], v[124:125]
	v_pk_add_f32 v[118:119], v[118:119], v[120:121]
	v_pk_add_f32 v[120:121], v[114:115], v[122:123]
	v_pk_add_f32 v[114:115], v[112:113], v[126:127]
	v_cvt_pk_bf16_f32 v112, v116, v117
	v_lshl_add_u64 v[116:117], v[144:145], 0, s[2:3]
	s_mov_b32 s2, 0x10000
	v_cvt_pk_bf16_f32 v113, v118, v119
	v_add_co_u32_e32 v118, vcc, s2, v144
	v_cvt_pk_bf16_f32 v114, v114, v115
	v_cvt_pk_bf16_f32 v115, v120, v121
	v_addc_co_u32_e32 v119, vcc, 0, v145, vcc
	global_store_dwordx4 v[144:145], v[112:115], off offset:256
	s_waitcnt vmcnt(15)
	s_nop 1
	v_mov_b32_e32 v112, v168
	v_mov_b32_e32 v113, v169
	v_mov_b32_e32 v114, v170
	v_mov_b32_e32 v115, v171
	s_mov_b64 s[2:3], 0x20000
	s_waitcnt lgkmcnt(0)
	v_lshlrev_b32_e32 v120, 16, v112
	v_and_b32_e32 v121, 0xffff0000, v112
	v_lshlrev_b32_e32 v112, 16, v113
	v_and_b32_e32 v113, 0xffff0000, v113
	v_lshlrev_b32_e32 v122, 16, v114
	v_and_b32_e32 v123, 0xffff0000, v114
	v_lshlrev_b32_e32 v114, 16, v115
	v_and_b32_e32 v115, 0xffff0000, v115
	v_pk_add_f32 v[110:111], v[110:111], v[112:113]
	v_pk_add_f32 v[108:109], v[108:109], v[120:121]
	v_pk_add_f32 v[112:113], v[106:107], v[114:115]
	v_pk_add_f32 v[106:107], v[104:105], v[122:123]
	v_cvt_pk_bf16_f32 v104, v108, v109
	v_cvt_pk_bf16_f32 v105, v110, v111
	v_cvt_pk_bf16_f32 v106, v106, v107
	v_cvt_pk_bf16_f32 v107, v112, v113
	global_store_dwordx4 v[118:119], v[104:107], off
	s_waitcnt vmcnt(15)
	s_nop 1
	v_mov_b32_e32 v104, v172
	v_mov_b32_e32 v105, v173
	v_mov_b32_e32 v106, v174
	v_mov_b32_e32 v107, v175
	s_waitcnt lgkmcnt(0)
	v_lshlrev_b32_e32 v108, 16, v104
	v_and_b32_e32 v109, 0xffff0000, v104
	v_lshlrev_b32_e32 v104, 16, v105
	v_and_b32_e32 v105, 0xffff0000, v105
	v_lshlrev_b32_e32 v110, 16, v106
	v_and_b32_e32 v111, 0xffff0000, v106
	v_lshlrev_b32_e32 v106, 16, v107
	v_and_b32_e32 v107, 0xffff0000, v107
	v_pk_add_f32 v[100:101], v[100:101], v[108:109]
	v_pk_add_f32 v[102:103], v[102:103], v[104:105]
	v_pk_add_f32 v[104:105], v[98:99], v[106:107]
	v_pk_add_f32 v[98:99], v[96:97], v[110:111]
	v_cvt_pk_bf16_f32 v96, v100, v101
	v_lshl_add_u64 v[100:101], v[144:145], 0, s[2:3]
	s_mov_b32 s2, 0x20000
	v_cvt_pk_bf16_f32 v97, v102, v103
	v_add_co_u32_e32 v102, vcc, s2, v144
	v_cvt_pk_bf16_f32 v98, v98, v99
	v_cvt_pk_bf16_f32 v99, v104, v105
	v_addc_co_u32_e32 v103, vcc, 0, v145, vcc
	global_store_dwordx4 v[116:117], v[96:99], off offset:256
	s_waitcnt vmcnt(15)
	s_nop 1
	v_mov_b32_e32 v96, v176
	v_mov_b32_e32 v97, v177
	v_mov_b32_e32 v98, v178
	v_mov_b32_e32 v99, v179
	s_mov_b64 s[2:3], 0x30000
	s_waitcnt lgkmcnt(0)
	v_lshlrev_b32_e32 v104, 16, v96
	v_and_b32_e32 v105, 0xffff0000, v96
	v_lshlrev_b32_e32 v96, 16, v97
	v_and_b32_e32 v97, 0xffff0000, v97
	v_lshlrev_b32_e32 v106, 16, v98
	v_and_b32_e32 v107, 0xffff0000, v98
	v_lshlrev_b32_e32 v98, 16, v99
	v_and_b32_e32 v99, 0xffff0000, v99
	v_pk_add_f32 v[94:95], v[94:95], v[96:97]
	v_pk_add_f32 v[92:93], v[92:93], v[104:105]
	v_pk_add_f32 v[96:97], v[90:91], v[98:99]
	v_pk_add_f32 v[90:91], v[88:89], v[106:107]
	v_cvt_pk_bf16_f32 v88, v92, v93
	v_cvt_pk_bf16_f32 v89, v94, v95
	v_cvt_pk_bf16_f32 v90, v90, v91
	v_cvt_pk_bf16_f32 v91, v96, v97
	global_store_dwordx4 v[102:103], v[88:91], off
	s_waitcnt vmcnt(15)
	s_nop 1
	v_mov_b32_e32 v88, v180
	v_mov_b32_e32 v89, v181
	v_mov_b32_e32 v90, v182
	v_mov_b32_e32 v91, v183
	s_waitcnt lgkmcnt(0)
	v_lshlrev_b32_e32 v92, 16, v88
	v_and_b32_e32 v93, 0xffff0000, v88
	v_lshlrev_b32_e32 v88, 16, v89
	v_and_b32_e32 v89, 0xffff0000, v89
	v_lshlrev_b32_e32 v94, 16, v90
	v_and_b32_e32 v95, 0xffff0000, v90
	v_lshlrev_b32_e32 v90, 16, v91
	v_and_b32_e32 v91, 0xffff0000, v91
	v_pk_add_f32 v[86:87], v[86:87], v[88:89]
	v_pk_add_f32 v[84:85], v[84:85], v[92:93]
	v_pk_add_f32 v[88:89], v[82:83], v[90:91]
	v_pk_add_f32 v[82:83], v[80:81], v[94:95]
	v_cvt_pk_bf16_f32 v80, v84, v85
	v_cvt_pk_bf16_f32 v81, v86, v87
	v_cvt_pk_bf16_f32 v82, v82, v83
	v_cvt_pk_bf16_f32 v83, v88, v89
	global_store_dwordx4 v[100:101], v[80:83], off offset:256
	s_nop 1
	v_lshl_add_u64 v[80:81], v[144:145], 0, s[2:3]
	s_mov_b32 s2, 0x30000
	v_add_co_u32_e32 v86, vcc, s2, v144
	s_mov_b64 s[2:3], 0x80000
	s_nop 0
	v_addc_co_u32_e32 v87, vcc, 0, v145, vcc
	s_waitcnt vmcnt(15)
	s_nop 1
	v_mov_b32_e32 v82, v184
	v_mov_b32_e32 v83, v185
	v_mov_b32_e32 v84, v186
	v_mov_b32_e32 v85, v187
	s_waitcnt lgkmcnt(0)
	v_lshlrev_b32_e32 v88, 16, v82
	v_and_b32_e32 v89, 0xffff0000, v82
	v_lshlrev_b32_e32 v82, 16, v83
	v_and_b32_e32 v83, 0xffff0000, v83
	v_lshlrev_b32_e32 v90, 16, v84
	v_and_b32_e32 v91, 0xffff0000, v84
	v_lshlrev_b32_e32 v84, 16, v85
	v_and_b32_e32 v85, 0xffff0000, v85
	v_pk_add_f32 v[78:79], v[78:79], v[82:83]
	v_pk_add_f32 v[76:77], v[76:77], v[88:89]
	v_pk_add_f32 v[82:83], v[74:75], v[84:85]
	v_pk_add_f32 v[74:75], v[72:73], v[90:91]
	v_cvt_pk_bf16_f32 v72, v76, v77
	v_cvt_pk_bf16_f32 v73, v78, v79
	v_cvt_pk_bf16_f32 v74, v74, v75
	v_cvt_pk_bf16_f32 v75, v82, v83
	global_store_dwordx4 v[86:87], v[72:75], off
	s_waitcnt vmcnt(15)
	s_nop 1
	v_mov_b32_e32 v72, v188
	v_mov_b32_e32 v73, v189
	v_mov_b32_e32 v74, v190
	v_mov_b32_e32 v75, v191
	s_waitcnt lgkmcnt(0)
; DI unsigned pack2(float a, float b) { f32x2 v = {a, b}; hwbf16x2 r = __builtin_convertvector(v, hwbf16x2); return __builtin_bit_cast(unsigned, r); }
; DI float bflo(unsigned w) { return __uint_as_float(w << 16); }
; DI float bfhi(unsigned w) { return __uint_as_float(w & 0xffff0000u); }
;     DI void operator()(const f32x4 (&acc)[2][2][4][2], const Unit& u, int wr, int wc, int fr, int fq) const {
;         const int row0 = u.pm * BM + wr * 64 + fr, col0 = u.pn * BM + wc * 32 + 8 * fq;
;         f32x4 sc[2][2];
; #pragma unroll
;         for (int bj = 0; bj < 2; ++bj)
; #pragma unroll
;             for (int n = 0; n < 2; ++n) sc[bj][n] = scale ? *(const f32x4*)(scale + col0 + bj * HALF + 4 * n) : (f32x4){1.f, 1.f, 1.f, 1.f};
; #pragma unroll
;         for (int ai = 0; ai < 2; ++ai)
; #pragma unroll
;             for (int m = 0; m < 4; ++m) { const size_t ro = (size_t)(row0 + ai * HALF + m * 16) * D + col0;
; #pragma unroll
;                 for (int bj = 0; bj < 2; ++bj) {
;                     f32x4 x0, x1;
;                     if constexpr (IB) { const u32x4 w = *(const u32x4*)((const bf16_t*)Xin + ro + bj * HALF);
;                         x0 = (f32x4){bflo(w[0]), bfhi(w[0]), bflo(w[1]), bfhi(w[1])}; x1 = (f32x4){bflo(w[2]), bfhi(w[2]), bflo(w[3]), bfhi(w[3])}; }
;                     else { x0 = *(const f32x4*)((const float*)Xin + ro + bj * HALF); x1 = *(const f32x4*)((const float*)Xin + ro + bj * HALF + 4); }
;                     x0 += acc[ai][bj][m][0] * sc[bj][0]; x1 += acc[ai][bj][m][1] * sc[bj][1];
;                     if constexpr (OB) { u32x4 o; o[0] = pack2(x0[0], x0[1]); o[1] = pack2(x0[2], x0[3]); o[2] = pack2(x1[0], x1[1]); o[3] = pack2(x1[2], x1[3]);
;                         *(u32x4*)((bf16_t*)Xout + ro + bj * HALF) = o; }
;                     else { *(f32x4*)((float*)Xout + ro + bj * HALF) = x0; *(f32x4*)((float*)Xout + ro + bj * HALF + 4) = x1; } } }
	v_lshlrev_b32_e32 v76, 16, v72
	v_and_b32_e32 v77, 0xffff0000, v72
	v_lshlrev_b32_e32 v72, 16, v73
	v_and_b32_e32 v73, 0xffff0000, v73
	v_lshlrev_b32_e32 v78, 16, v74
	v_and_b32_e32 v79, 0xffff0000, v74
	v_lshlrev_b32_e32 v74, 16, v75
	v_and_b32_e32 v75, 0xffff0000, v75
	v_pk_add_f32 v[70:71], v[70:71], v[72:73]
	v_pk_add_f32 v[68:69], v[68:69], v[76:77]
	v_pk_add_f32 v[72:73], v[66:67], v[74:75]
	v_pk_add_f32 v[66:67], v[64:65], v[78:79]
	v_cvt_pk_bf16_f32 v64, v68, v69
	v_cvt_pk_bf16_f32 v65, v70, v71
	v_cvt_pk_bf16_f32 v66, v66, v67
	v_cvt_pk_bf16_f32 v67, v72, v73
	global_store_dwordx4 v[80:81], v[64:67], off offset:256
	s_nop 1
	v_lshl_add_u64 v[64:65], v[144:145], 0, s[2:3]
	s_mov_b32 s2, 0x80000
	v_add_co_u32_e32 v70, vcc, s2, v144
	s_mov_b64 s[2:3], 0x90000
	s_nop 0
	v_addc_co_u32_e32 v71, vcc, 0, v145, vcc
	s_waitcnt vmcnt(15)
	s_nop 1
	v_mov_b32_e32 v66, v192
	v_mov_b32_e32 v67, v193
	v_mov_b32_e32 v68, v194
	v_mov_b32_e32 v69, v195
	s_waitcnt lgkmcnt(0)
	v_lshlrev_b32_e32 v72, 16, v66
	v_and_b32_e32 v73, 0xffff0000, v66
	v_lshlrev_b32_e32 v66, 16, v67
	v_and_b32_e32 v67, 0xffff0000, v67
	v_lshlrev_b32_e32 v74, 16, v68
	v_and_b32_e32 v75, 0xffff0000, v68
	v_lshlrev_b32_e32 v68, 16, v69
	v_and_b32_e32 v69, 0xffff0000, v69
	v_pk_add_f32 v[62:63], v[62:63], v[66:67]
	v_pk_add_f32 v[60:61], v[60:61], v[72:73]
	v_pk_add_f32 v[66:67], v[58:59], v[68:69]
	v_pk_add_f32 v[58:59], v[56:57], v[74:75]
	v_cvt_pk_bf16_f32 v56, v60, v61
	v_cvt_pk_bf16_f32 v57, v62, v63
	v_cvt_pk_bf16_f32 v58, v58, v59
	v_cvt_pk_bf16_f32 v59, v66, v67
	global_store_dwordx4 v[70:71], v[56:59], off
	s_waitcnt vmcnt(15)
	s_nop 1
	v_mov_b32_e32 v56, v198
	v_mov_b32_e32 v57, v199
	v_mov_b32_e32 v58, v200
	v_mov_b32_e32 v59, v201
	s_waitcnt lgkmcnt(0)
	v_lshlrev_b32_e32 v60, 16, v56
	v_and_b32_e32 v61, 0xffff0000, v56
	v_lshlrev_b32_e32 v56, 16, v57
	v_and_b32_e32 v57, 0xffff0000, v57
	v_lshlrev_b32_e32 v62, 16, v58
	v_and_b32_e32 v63, 0xffff0000, v58
	v_lshlrev_b32_e32 v58, 16, v59
	v_and_b32_e32 v59, 0xffff0000, v59
	v_pk_add_f32 v[54:55], v[54:55], v[56:57]
	v_pk_add_f32 v[52:53], v[52:53], v[60:61]
	v_pk_add_f32 v[56:57], v[50:51], v[58:59]
	v_pk_add_f32 v[50:51], v[48:49], v[62:63]
	v_cvt_pk_bf16_f32 v48, v52, v53
	v_cvt_pk_bf16_f32 v49, v54, v55
	v_cvt_pk_bf16_f32 v50, v50, v51
	v_cvt_pk_bf16_f32 v51, v56, v57
	global_store_dwordx4 v[64:65], v[48:51], off offset:256
	s_nop 1
	v_lshl_add_u64 v[48:49], v[144:145], 0, s[2:3]
	s_mov_b32 s2, 0x90000
	v_add_co_u32_e32 v54, vcc, s2, v144
	s_mov_b64 s[2:3], 0xa0000
	s_nop 0
	v_addc_co_u32_e32 v55, vcc, 0, v145, vcc
	s_waitcnt vmcnt(15)
	s_nop 1
	v_mov_b32_e32 v50, v202
	v_mov_b32_e32 v51, v203
	v_mov_b32_e32 v52, v204
	v_mov_b32_e32 v53, v205
	s_waitcnt lgkmcnt(0)
	v_lshlrev_b32_e32 v56, 16, v50
	v_and_b32_e32 v57, 0xffff0000, v50
	v_lshlrev_b32_e32 v50, 16, v51
	v_and_b32_e32 v51, 0xffff0000, v51
	v_lshlrev_b32_e32 v58, 16, v52
	v_and_b32_e32 v59, 0xffff0000, v52
	v_lshlrev_b32_e32 v52, 16, v53
	v_and_b32_e32 v53, 0xffff0000, v53
	v_pk_add_f32 v[46:47], v[46:47], v[50:51]
	v_pk_add_f32 v[44:45], v[44:45], v[56:57]
	v_pk_add_f32 v[50:51], v[42:43], v[52:53]
	v_pk_add_f32 v[42:43], v[40:41], v[58:59]
	v_cvt_pk_bf16_f32 v40, v44, v45
	v_cvt_pk_bf16_f32 v41, v46, v47
	v_cvt_pk_bf16_f32 v42, v42, v43
	v_cvt_pk_bf16_f32 v43, v50, v51
	global_store_dwordx4 v[54:55], v[40:43], off
	s_waitcnt vmcnt(15)
	s_nop 1
	v_mov_b32_e32 v40, v206
	v_mov_b32_e32 v41, v207
	v_mov_b32_e32 v42, v208
	v_mov_b32_e32 v43, v209
	s_waitcnt lgkmcnt(0)
; #define PG8_BAR __builtin_amdgcn_s_barrier()
;     DI void operator()(const f32x4 (&acc)[2][2][4][2], const Unit& u, int wr, int wc, int fr, int fq) const {
;         const int row0 = u.pm * BM + wr * 64 + fr, col0 = u.pn * BM + wc * 32 + 8 * fq;
;         f32x4 sc[2][2];
; #pragma unroll
;         for (int bj = 0; bj < 2; ++bj)
; #pragma unroll
;             for (int n = 0; n < 2; ++n) sc[bj][n] = scale ? *(const f32x4*)(scale + col0 + bj * HALF + 4 * n) : (f32x4){1.f, 1.f, 1.f, 1.f};
; #pragma unroll
;         for (int ai = 0; ai < 2; ++ai)
; #pragma unroll
;             for (int m = 0; m < 4; ++m) { const size_t ro = (size_t)(row0 + ai * HALF + m * 16) * D + col0;
; #pragma unroll
;                 for (int bj = 0; bj < 2; ++bj) {
;                     f32x4 x0, x1;
;                     if constexpr (IB) { const u32x4 w = *(const u32x4*)((const bf16_t*)Xin + ro + bj * HALF);
;                         x0 = (f32x4){bflo(w[0]), bfhi(w[0]), bflo(w[1]), bfhi(w[1])}; x1 = (f32x4){bflo(w[2]), bfhi(w[2]), bflo(w[3]), bfhi(w[3])}; }
;                     else { x0 = *(const f32x4*)((const float*)Xin + ro + bj * HALF); x1 = *(const f32x4*)((const float*)Xin + ro + bj * HALF + 4); }
;                     x0 += acc[ai][bj][m][0] * sc[bj][0]; x1 += acc[ai][bj][m][1] * sc[bj][1];
;                     if constexpr (OB) { u32x4 o; o[0] = pack2(x0[0], x0[1]); o[1] = pack2(x0[2], x0[3]); o[2] = pack2(x1[0], x1[1]); o[3] = pack2(x1[2], x1[3]);
;                         *(u32x4*)((bf16_t*)Xout + ro + bj * HALF) = o; }
;                     else { *(f32x4*)((float*)Xout + ro + bj * HALF) = x0; *(f32x4*)((float*)Xout + ro + bj * HALF + 4) = x1; } } }
; template <class Map, class Epi>
; DI void gemm_phase(LAS unsigned char* lds, const Map& MP, const Epi& E, const int nM, const int nN, const int K, const int lda, const int ldb) {
;     ...
;         { int frr = fr, fqq = fq; asm volatile("" : "+v"(frr), "+v"(fqq)); E(acc, cur, wr, wc, frr, fqq); }
;         if (!has_next) break;
; #pragma unroll
;         for (int a = 0; a < 2; ++a)
; #pragma unroll
;             for (int b = 0; b < 2; ++b)
; #pragma unroll
;                 for (int m = 0; m < 4; ++m)
; #pragma unroll
;                     for (int n = 0; n < 2; ++n) acc[a][b][m][n] = (f32x4){0.f, 0.f, 0.f, 0.f};
;         cur = nxt; cA = nA; cB = nB; ++ui;
;     }
;     PG8_WAIT_V(0);
;     if (wr == 0) PG8_BAR;
;     PG8_BAR;
	v_lshlrev_b32_e32 v44, 16, v40
	v_and_b32_e32 v45, 0xffff0000, v40
	v_lshlrev_b32_e32 v40, 16, v41
	v_and_b32_e32 v41, 0xffff0000, v41
	v_lshlrev_b32_e32 v46, 16, v42
	v_and_b32_e32 v47, 0xffff0000, v42
	v_lshlrev_b32_e32 v42, 16, v43
	v_and_b32_e32 v43, 0xffff0000, v43
	v_pk_add_f32 v[38:39], v[38:39], v[40:41]
	v_pk_add_f32 v[36:37], v[36:37], v[44:45]
	v_pk_add_f32 v[40:41], v[34:35], v[42:43]
	v_pk_add_f32 v[34:35], v[32:33], v[46:47]
	v_cvt_pk_bf16_f32 v32, v36, v37
	v_cvt_pk_bf16_f32 v33, v38, v39
	v_cvt_pk_bf16_f32 v34, v34, v35
	v_cvt_pk_bf16_f32 v35, v40, v41
	global_store_dwordx4 v[48:49], v[32:35], off offset:256
	s_nop 1
	v_lshl_add_u64 v[32:33], v[144:145], 0, s[2:3]
	s_mov_b32 s2, 0xa0000
	v_add_co_u32_e32 v38, vcc, s2, v144
	s_mov_b64 s[2:3], 0xb0000
	s_nop 0
	v_addc_co_u32_e32 v39, vcc, 0, v145, vcc
	s_waitcnt vmcnt(15)
	s_nop 1
	v_mov_b32_e32 v34, v210
	v_mov_b32_e32 v35, v211
	v_mov_b32_e32 v36, v212
	v_mov_b32_e32 v37, v213
	s_waitcnt lgkmcnt(0)
	v_lshlrev_b32_e32 v40, 16, v34
	v_and_b32_e32 v41, 0xffff0000, v34
	v_lshlrev_b32_e32 v34, 16, v35
	v_and_b32_e32 v35, 0xffff0000, v35
	v_lshlrev_b32_e32 v42, 16, v36
	v_and_b32_e32 v43, 0xffff0000, v36
	v_lshlrev_b32_e32 v36, 16, v37
	v_and_b32_e32 v37, 0xffff0000, v37
	v_pk_add_f32 v[30:31], v[30:31], v[34:35]
	v_pk_add_f32 v[28:29], v[28:29], v[40:41]
	v_pk_add_f32 v[34:35], v[26:27], v[36:37]
	v_pk_add_f32 v[26:27], v[24:25], v[42:43]
	v_cvt_pk_bf16_f32 v24, v28, v29
	v_cvt_pk_bf16_f32 v25, v30, v31
	v_cvt_pk_bf16_f32 v26, v26, v27
	v_cvt_pk_bf16_f32 v27, v34, v35
	global_store_dwordx4 v[38:39], v[24:27], off
	s_waitcnt vmcnt(15)
	s_nop 1
	v_mov_b32_e32 v24, v214
	v_mov_b32_e32 v25, v215
	v_mov_b32_e32 v26, v216
	v_mov_b32_e32 v27, v217
	s_waitcnt lgkmcnt(0)
	v_lshlrev_b32_e32 v28, 16, v24
	v_and_b32_e32 v29, 0xffff0000, v24
	v_lshlrev_b32_e32 v24, 16, v25
	v_and_b32_e32 v25, 0xffff0000, v25
	v_lshlrev_b32_e32 v30, 16, v26
	v_and_b32_e32 v31, 0xffff0000, v26
	v_lshlrev_b32_e32 v26, 16, v27
	v_and_b32_e32 v27, 0xffff0000, v27
	v_pk_add_f32 v[22:23], v[22:23], v[24:25]
	v_pk_add_f32 v[20:21], v[20:21], v[28:29]
	v_pk_add_f32 v[24:25], v[18:19], v[26:27]
	v_pk_add_f32 v[18:19], v[16:17], v[30:31]
	v_cvt_pk_bf16_f32 v16, v20, v21
	v_cvt_pk_bf16_f32 v17, v22, v23
	v_cvt_pk_bf16_f32 v18, v18, v19
	v_cvt_pk_bf16_f32 v19, v24, v25
	global_store_dwordx4 v[32:33], v[16:19], off offset:256
	s_nop 1
	v_lshl_add_u64 v[16:17], v[144:145], 0, s[2:3]
	s_mov_b32 s2, 0xb0000
	v_add_co_u32_e32 v22, vcc, s2, v144
	s_mov_b32 s2, s46
	s_nop 0
	v_addc_co_u32_e32 v23, vcc, 0, v145, vcc
	s_waitcnt vmcnt(15)
	s_nop 1
	v_mov_b32_e32 v18, v248
	v_mov_b32_e32 v19, v249
	v_mov_b32_e32 v20, v250
	v_mov_b32_e32 v21, v251
	s_and_b64 vcc, exec, s[40:41]
	s_waitcnt lgkmcnt(0)
	v_lshlrev_b32_e32 v24, 16, v18
	v_and_b32_e32 v25, 0xffff0000, v18
	v_lshlrev_b32_e32 v18, 16, v19
	v_and_b32_e32 v19, 0xffff0000, v19
	v_lshlrev_b32_e32 v26, 16, v20
	v_and_b32_e32 v27, 0xffff0000, v20
	v_lshlrev_b32_e32 v20, 16, v21
	v_and_b32_e32 v21, 0xffff0000, v21
	v_pk_add_f32 v[14:15], v[14:15], v[18:19]
	v_pk_add_f32 v[12:13], v[12:13], v[24:25]
	v_pk_add_f32 v[18:19], v[10:11], v[20:21]
	v_pk_add_f32 v[10:11], v[8:9], v[26:27]
	v_cvt_pk_bf16_f32 v8, v12, v13
	v_cvt_pk_bf16_f32 v9, v14, v15
	v_cvt_pk_bf16_f32 v10, v10, v11
	v_cvt_pk_bf16_f32 v11, v18, v19
	global_store_dwordx4 v[22:23], v[8:11], off
	s_waitcnt vmcnt(15)
	s_nop 1
	v_mov_b32_e32 v8, v252
	v_mov_b32_e32 v9, v253
	v_mov_b32_e32 v10, v254
	v_mov_b32_e32 v11, v255
	s_waitcnt lgkmcnt(0)
	v_lshlrev_b32_e32 v12, 16, v8
	v_and_b32_e32 v13, 0xffff0000, v8
	v_lshlrev_b32_e32 v8, 16, v9
	v_and_b32_e32 v9, 0xffff0000, v9
	v_lshlrev_b32_e32 v14, 16, v10
	v_and_b32_e32 v15, 0xffff0000, v10
	v_lshlrev_b32_e32 v10, 16, v11
	v_and_b32_e32 v11, 0xffff0000, v11
	v_pk_add_f32 v[6:7], v[6:7], v[8:9]
	v_pk_add_f32 v[4:5], v[4:5], v[12:13]
	v_pk_add_f32 v[8:9], v[2:3], v[10:11]
	v_pk_add_f32 v[2:3], v[0:1], v[14:15]
	v_cvt_pk_bf16_f32 v0, v4, v5
	v_cvt_pk_bf16_f32 v1, v6, v7
	v_cvt_pk_bf16_f32 v2, v2, v3
	v_cvt_pk_bf16_f32 v3, v8, v9
	global_store_dwordx4 v[16:17], v[0:3], off offset:256
	s_cbranch_vccz .LBB1_922
	s_waitcnt vmcnt(0)
	s_cmpk_gt_u32 s17, 0xff
	s_cbranch_scc1 .LBB1_929
	s_barrier

; #define PG8_STAGE(bufoff, gbase, voff) do { _Pragma("unroll") for (int _i = 0; _i < 2; ++_i) \
;         __builtin_amdgcn_global_load_lds((const unsigned*)((const char*)(gbase) + (voff)[_i]), (LAS unsigned*)(lds + (bufoff) + ldsw + _i * 8192), 16, 0, 0); } while (0)
; #define PG8_LDA(dst, b, h) do { _Pragma("unroll") for (int m = 0; m < 4; ++m) _Pragma("unroll") for (int k = 0; k < 2; ++k) dst[m][k] = *(const LAS bf16x8*)(lds + PG8_SA(b, h) + aoff + m * 2048 + k * 1024); } while (0)
; #define PG8_WAIT_V(n) asm volatile("s_waitcnt vmcnt(" #n ")" ::: "memory")
; #define PG8_BAR __builtin_amdgcn_s_barrier()
; template <class Map, class Epi>
; DI void gemm_phase(LAS unsigned char* lds, const Map& MP, const Epi& E, const int nM, const int nN, const int K, const int lda, const int ldb) {
;     ...
;         for (int t = 0; t < nt; t += 2) {
;             const bool last = (t == nt - 2);
;             const char* a1 = cA + (size_t)(t + 1) * kstep;
;             const char* a2 = last ? nA : cA + (size_t)(t + 2) * kstep; const char* b2 = last ? nB : cB + (size_t)(t + 2) * kstep;
;             const char* a3 = a2 + kstep; const char* b3 = b2 + kstep;
;             PG8_LDB(B0, 0, 0); PG8_SCHED; PG8_LDA(At, 0, 0); PG8_STAGE(PG8_SA(1, 1), a1 + hstepA, voffA);
;             PG8_WAIT_L(8); PG8_BAR; PG8_WAIT_L(0); PG8_MMA(0, 0, At, B0); PG8_BAR; PG8_SCHED;
;             PG8_LDB(B1, 0, 1); PG8_STAGE(PG8_SB(0, 0), b2, voffB);
;             PG8_BAR; PG8_WAIT_L(0); PG8_MMA(0, 1, At, B1); PG8_BAR;
;             PG8_LDA(At, 0, 1); PG8_STAGE(PG8_SA(0, 0), a2, voffA);
;             PG8_BAR; PG8_WAIT_L(0); PG8_MMA(1, 0, At, B0); PG8_BAR; PG8_SCHED;
;             PG8_STAGE(PG8_SB(0, 1), b2 + hstepB, voffB);
;             PG8_WAIT_V(6); PG8_BAR; PG8_MMA(1, 1, At, B1); PG8_BAR;
;             PG8_LDB(B0, 1, 0); PG8_SCHED; PG8_LDA(At, 1, 0); PG8_STAGE(PG8_SA(0, 1), a2 + hstepA, voffA);
;             PG8_WAIT_L(8); PG8_BAR; PG8_WAIT_L(0); PG8_MMA(0, 0, At, B0); PG8_BAR; PG8_SCHED;
;             PG8_LDB(B1, 1, 1); PG8_STAGE(PG8_SB(1, 0), b3, voffB);
;             PG8_BAR; PG8_WAIT_L(0); PG8_MMA(0, 1, At, B1); PG8_BAR;
;             PG8_LDA(At, 1, 1); PG8_STAGE(PG8_SA(1, 0), a3, voffA);
;             PG8_BAR; PG8_WAIT_L(0); PG8_MMA(1, 0, At, B0); PG8_BAR; PG8_SCHED;
;             PG8_STAGE(PG8_SB(1, 1), b3 + hstepB, voffB);
;             PG8_WAIT_V(6); PG8_BAR; PG8_MMA(1, 1, At, B1); PG8_BAR;
.LBB1_1069:
	s_add_u32 s24, s42, 0xfff80080
	s_addc_u32 s25, s43, -1
	s_cmp_eq_u32 s3, 28
	s_cselect_b32 s47, s23, s25
	s_cselect_b32 s46, s58, s24
	s_cselect_b32 s25, s21, vcc_hi
	s_cselect_b32 s24, s59, vcc_lo
	s_add_i32 m0, s38, 0xc000
	ds_read_b128 v[96:99], v190
	global_load_lds_dwordx4 v178, s[42:43]
	ds_read_b128 v[100:103], v190 offset:1024
	ds_read_b128 v[108:111], v190 offset:2048
	ds_read_b128 v[112:115], v190 offset:3072
	ds_read_b128 v[160:163], v190 offset:4096
	ds_read_b128 v[164:167], v190 offset:5120
	ds_read_b128 v[198:201], v190 offset:6144
	ds_read_b128 v[202:205], v190 offset:7168
	s_add_i32 m0, s38, 0xe000
	s_nop 0
	global_load_lds_dwordx4 v176, s[42:43]
	s_waitcnt lgkmcnt(8)
	s_setprio 1
	s_barrier
	s_waitcnt lgkmcnt(7)
	v_mfma_f32_16x16x32_bf16 v[148:151], v[80:83], v[96:99], v[148:151]
	v_mfma_f32_16x16x32_bf16 v[144:147], v[88:91], v[96:99], v[144:147]
	s_waitcnt lgkmcnt(5)
	v_mfma_f32_16x16x32_bf16 v[136:139], v[80:83], v[108:111], v[136:139]
	v_mfma_f32_16x16x32_bf16 v[128:131], v[88:91], v[108:111], v[128:131]
	s_waitcnt lgkmcnt(3)
	v_mfma_f32_16x16x32_bf16 v[120:123], v[80:83], v[160:163], v[120:123]
	v_mfma_f32_16x16x32_bf16 v[104:107], v[88:91], v[160:163], v[104:107]
	s_waitcnt lgkmcnt(1)
	v_mfma_f32_16x16x32_bf16 v[76:79], v[80:83], v[198:201], v[76:79]
	v_mfma_f32_16x16x32_bf16 v[72:75], v[88:91], v[198:201], v[72:75]
	v_mfma_f32_16x16x32_bf16 v[148:151], v[84:87], v[100:103], v[148:151]
	s_add_i32 s68, s31, s66
	v_mfma_f32_16x16x32_bf16 v[144:147], v[92:95], v[100:103], v[144:147]
	v_lshl_add_u64 v[184:185], s[24:25], 0, v[172:173]
	v_mfma_f32_16x16x32_bf16 v[136:139], v[84:87], v[112:115], v[136:139]
	v_lshl_add_u64 v[194:195], s[24:25], 0, v[168:169]
	v_mfma_f32_16x16x32_bf16 v[128:131], v[92:95], v[112:115], v[128:131]
	v_mfma_f32_16x16x32_bf16 v[120:123], v[84:87], v[164:167], v[120:123]
	v_mfma_f32_16x16x32_bf16 v[104:107], v[92:95], v[164:167], v[104:107]
	s_waitcnt lgkmcnt(0)
	v_mfma_f32_16x16x32_bf16 v[76:79], v[84:87], v[202:205], v[76:79]
	v_mfma_f32_16x16x32_bf16 v[72:75], v[92:95], v[202:205], v[72:75]
	s_barrier
	s_setprio 0
	s_mov_b32 m0, s68
	ds_read_b128 v[206:209], v191
	global_load_lds_dwordx4 v[184:185], off
	ds_read_b128 v[210:213], v191 offset:1024
	ds_read_b128 v[214:217], v191 offset:2048
	ds_read_b128 v[218:221], v191 offset:3072
	s_add_i32 m0, s68, 0x2000
	s_nop 0
	global_load_lds_dwordx4 v[194:195], off
	s_setprio 1
	s_barrier
	s_waitcnt lgkmcnt(3)
	v_mfma_f32_16x16x32_bf16 v[156:159], v[206:209], v[96:99], v[156:159]
	s_waitcnt lgkmcnt(1)
	v_mfma_f32_16x16x32_bf16 v[96:99], v[214:217], v[96:99], v[152:155]
	v_mfma_f32_16x16x32_bf16 v[156:159], v[210:213], v[100:103], v[156:159]
	s_waitcnt lgkmcnt(0)
	v_mfma_f32_16x16x32_bf16 v[96:99], v[218:221], v[100:103], v[96:99]
	v_mfma_f32_16x16x32_bf16 v[100:103], v[206:209], v[108:111], v[140:143]
	v_mfma_f32_16x16x32_bf16 v[108:111], v[214:217], v[108:111], v[132:135]
	v_mfma_f32_16x16x32_bf16 v[116:119], v[214:217], v[160:163], v[116:119]
	v_mfma_f32_16x16x32_bf16 v[68:71], v[206:209], v[198:201], v[68:71]
	v_mfma_f32_16x16x32_bf16 v[64:67], v[214:217], v[198:201], v[64:67]
	v_lshl_add_u64 v[234:235], s[46:47], 0, v[170:171]
	s_mov_b32 m0, s38
	v_mfma_f32_16x16x32_bf16 v[100:103], v[210:213], v[112:115], v[100:103]
	v_lshl_add_u64 v[226:227], s[46:47], 0, v[174:175]
	v_mfma_f32_16x16x32_bf16 v[108:111], v[218:221], v[112:115], v[108:111]
	v_mfma_f32_16x16x32_bf16 v[112:115], v[206:209], v[160:163], v[124:127]
	v_mfma_f32_16x16x32_bf16 v[116:119], v[218:221], v[164:167], v[116:119]
	v_mfma_f32_16x16x32_bf16 v[68:71], v[210:213], v[202:205], v[68:71]
	v_mfma_f32_16x16x32_bf16 v[64:67], v[218:221], v[202:205], v[64:67]
	v_mfma_f32_16x16x32_bf16 v[112:115], v[210:213], v[164:167], v[112:115]
	s_barrier
	s_setprio 0
	ds_read_b128 v[124:127], v190 offset:16384
	global_load_lds_dwordx4 v[226:227], off
	ds_read_b128 v[132:135], v190 offset:17408
	ds_read_b128 v[140:143], v190 offset:18432
	ds_read_b128 v[152:155], v190 offset:19456
	ds_read_b128 v[160:163], v190 offset:20480
	ds_read_b128 v[164:167], v190 offset:21504
	ds_read_b128 v[198:201], v190 offset:22528
	ds_read_b128 v[202:205], v190 offset:23552
	s_mov_b32 m0, s39
	s_nop 0
	global_load_lds_dwordx4 v[234:235], off
	s_waitcnt vmcnt(10)
	s_setprio 1
	s_barrier
	s_waitcnt lgkmcnt(7)
	v_mfma_f32_16x16x32_bf16 v[60:63], v[80:83], v[124:127], v[60:63]
	v_mfma_f32_16x16x32_bf16 v[48:51], v[88:91], v[124:127], v[48:51]
	s_waitcnt lgkmcnt(5)
	v_mfma_f32_16x16x32_bf16 v[40:43], v[80:83], v[140:143], v[40:43]
	v_mfma_f32_16x16x32_bf16 v[32:35], v[88:91], v[140:143], v[32:35]
	s_waitcnt lgkmcnt(3)
	v_mfma_f32_16x16x32_bf16 v[24:27], v[80:83], v[160:163], v[24:27]
	v_mfma_f32_16x16x32_bf16 v[16:19], v[88:91], v[160:163], v[16:19]
	s_waitcnt lgkmcnt(1)
	v_mfma_f32_16x16x32_bf16 v[12:15], v[80:83], v[198:201], v[12:15]
	v_mfma_f32_16x16x32_bf16 v[8:11], v[88:91], v[198:201], v[8:11]
	v_mfma_f32_16x16x32_bf16 v[60:63], v[84:87], v[132:135], v[60:63]
	s_add_u32 s68, s24, 0x80000
	s_addc_u32 s69, s25, 0
	v_mfma_f32_16x16x32_bf16 v[48:51], v[92:95], v[132:135], v[48:51]
	s_add_i32 s70, s2, s66
	v_mfma_f32_16x16x32_bf16 v[40:43], v[84:87], v[152:155], v[40:43]
	v_mfma_f32_16x16x32_bf16 v[32:35], v[92:95], v[152:155], v[32:35]
	v_mfma_f32_16x16x32_bf16 v[24:27], v[84:87], v[164:167], v[24:27]
	v_mfma_f32_16x16x32_bf16 v[16:19], v[92:95], v[164:167], v[16:19]
	s_waitcnt lgkmcnt(0)
	v_mfma_f32_16x16x32_bf16 v[12:15], v[84:87], v[202:205], v[12:15]
	v_mfma_f32_16x16x32_bf16 v[8:11], v[92:95], v[202:205], v[8:11]
	s_barrier
; #define PG8_STAGE(bufoff, gbase, voff) do { _Pragma("unroll") for (int _i = 0; _i < 2; ++_i) \
;         __builtin_amdgcn_global_load_lds((const unsigned*)((const char*)(gbase) + (voff)[_i]), (LAS unsigned*)(lds + (bufoff) + ldsw + _i * 8192), 16, 0, 0); } while (0)
; #define PG8_LDA(dst, b, h) do { _Pragma("unroll") for (int m = 0; m < 4; ++m) _Pragma("unroll") for (int k = 0; k < 2; ++k) dst[m][k] = *(const LAS bf16x8*)(lds + PG8_SA(b, h) + aoff + m * 2048 + k * 1024); } while (0)
; #define PG8_WAIT_V(n) asm volatile("s_waitcnt vmcnt(" #n ")" ::: "memory")
; #define PG8_BAR __builtin_amdgcn_s_barrier()
; template <class Map, class Epi>
; DI void gemm_phase(LAS unsigned char* lds, const Map& MP, const Epi& E, const int nM, const int nN, const int K, const int lda, const int ldb) {
;     ...
;         for (int t = 0; t < nt; t += 2) {
;             const bool last = (t == nt - 2);
;             const char* a1 = cA + (size_t)(t + 1) * kstep;
;             const char* a2 = last ? nA : cA + (size_t)(t + 2) * kstep; const char* b2 = last ? nB : cB + (size_t)(t + 2) * kstep;
;             const char* a3 = a2 + kstep; const char* b3 = b2 + kstep;
;             PG8_LDB(B0, 0, 0); PG8_SCHED; PG8_LDA(At, 0, 0); PG8_STAGE(PG8_SA(1, 1), a1 + hstepA, voffA);
;             PG8_WAIT_L(8); PG8_BAR; PG8_WAIT_L(0); PG8_MMA(0, 0, At, B0); PG8_BAR; PG8_SCHED;
;             PG8_LDB(B1, 0, 1); PG8_STAGE(PG8_SB(0, 0), b2, voffB);
;             PG8_BAR; PG8_WAIT_L(0); PG8_MMA(0, 1, At, B1); PG8_BAR;
;             PG8_LDA(At, 0, 1); PG8_STAGE(PG8_SA(0, 0), a2, voffA);
;             PG8_BAR; PG8_WAIT_L(0); PG8_MMA(1, 0, At, B0); PG8_BAR; PG8_SCHED;
;             PG8_STAGE(PG8_SB(0, 1), b2 + hstepB, voffB);
;             PG8_WAIT_V(6); PG8_BAR; PG8_MMA(1, 1, At, B1); PG8_BAR;
;             PG8_LDB(B0, 1, 0); PG8_SCHED; PG8_LDA(At, 1, 0); PG8_STAGE(PG8_SA(0, 1), a2 + hstepA, voffA);
;             PG8_WAIT_L(8); PG8_BAR; PG8_WAIT_L(0); PG8_MMA(0, 0, At, B0); PG8_BAR; PG8_SCHED;
;             PG8_LDB(B1, 1, 1); PG8_STAGE(PG8_SB(1, 0), b3, voffB);
;             PG8_BAR; PG8_WAIT_L(0); PG8_MMA(0, 1, At, B1); PG8_BAR;
;             PG8_LDA(At, 1, 1); PG8_STAGE(PG8_SA(1, 0), a3, voffA);
;             PG8_BAR; PG8_WAIT_L(0); PG8_MMA(1, 0, At, B0); PG8_BAR; PG8_SCHED;
;             PG8_STAGE(PG8_SB(1, 1), b3 + hstepB, voffB);
;             PG8_WAIT_V(6); PG8_BAR; PG8_MMA(1, 1, At, B1); PG8_BAR;
	s_setprio 0
	s_mov_b32 m0, s70
	s_nop 0
	global_load_lds_dwordx4 v172, s[68:69]
	s_add_i32 m0, s70, 0x2000
	s_nop 0
	global_load_lds_dwordx4 v168, s[68:69]
	s_waitcnt vmcnt(6)
	s_setprio 1
	s_barrier
	v_mfma_f32_16x16x32_bf16 v[56:59], v[206:209], v[124:127], v[56:59]
	v_mfma_f32_16x16x32_bf16 v[52:55], v[214:217], v[124:127], v[52:55]
	s_add_i32 s68, 0, 0x18000
	v_add_u32_e32 v92, s68, v188
	ds_read_b128 v[80:83], v92
	v_mfma_f32_16x16x32_bf16 v[44:47], v[206:209], v[140:143], v[44:47]
	v_mfma_f32_16x16x32_bf16 v[36:39], v[214:217], v[140:143], v[36:39]
	ds_read_b128 v[84:87], v92 offset:1024
	v_mfma_f32_16x16x32_bf16 v[28:31], v[206:209], v[160:163], v[28:31]
	v_mfma_f32_16x16x32_bf16 v[20:23], v[214:217], v[160:163], v[20:23]
	ds_read_b128 v[88:91], v92 offset:2048
	v_mfma_f32_16x16x32_bf16 v[4:7], v[206:209], v[198:201], v[4:7]
	v_mfma_f32_16x16x32_bf16 v[0:3], v[214:217], v[198:201], v[0:3]
	ds_read_b128 v[92:95], v92 offset:3072
	v_mfma_f32_16x16x32_bf16 v[56:59], v[210:213], v[132:135], v[56:59]
	s_add_u32 s46, s46, 0x80000
	s_addc_u32 s47, s47, 0
	v_mfma_f32_16x16x32_bf16 v[52:55], v[218:221], v[132:135], v[52:55]
	v_mfma_f32_16x16x32_bf16 v[44:47], v[210:213], v[152:155], v[44:47]
	v_mfma_f32_16x16x32_bf16 v[36:39], v[218:221], v[152:155], v[36:39]
	v_mfma_f32_16x16x32_bf16 v[28:31], v[210:213], v[164:167], v[28:31]
	v_mfma_f32_16x16x32_bf16 v[20:23], v[218:221], v[164:167], v[20:23]
	v_mfma_f32_16x16x32_bf16 v[4:7], v[210:213], v[202:205], v[4:7]
	v_mfma_f32_16x16x32_bf16 v[0:3], v[218:221], v[202:205], v[0:3]
	s_barrier
	s_setprio 0
	s_mov_b32 m0, s56
	ds_read_b128 v[124:127], v190 offset:32768
	global_load_lds_dwordx4 v174, s[46:47]
	ds_read_b128 v[132:135], v190 offset:33792
	ds_read_b128 v[160:163], v190 offset:34816
	ds_read_b128 v[164:167], v190 offset:35840
	ds_read_b128 v[198:201], v190 offset:36864
	ds_read_b128 v[202:205], v190 offset:37888
	ds_read_b128 v[206:209], v190 offset:38912
	ds_read_b128 v[210:213], v190 offset:39936
	s_mov_b32 m0, s57
	s_nop 0
	global_load_lds_dwordx4 v170, s[46:47]
	s_waitcnt lgkmcnt(8)
	s_setprio 1
	s_barrier
	s_waitcnt lgkmcnt(7)
	v_mfma_f32_16x16x32_bf16 v[140:143], v[80:83], v[124:127], v[148:151]
	s_waitcnt lgkmcnt(6)
	v_mfma_f32_16x16x32_bf16 v[148:151], v[84:87], v[132:135], v[140:143]
	v_mfma_f32_16x16x32_bf16 v[140:143], v[88:91], v[124:127], v[144:147]
	s_waitcnt lgkmcnt(5)
	v_mfma_f32_16x16x32_bf16 v[136:139], v[80:83], v[160:163], v[136:139]
	v_mfma_f32_16x16x32_bf16 v[128:131], v[88:91], v[160:163], v[128:131]
	s_waitcnt lgkmcnt(3)
	v_mfma_f32_16x16x32_bf16 v[120:123], v[80:83], v[198:201], v[120:123]
	v_mfma_f32_16x16x32_bf16 v[104:107], v[88:91], v[198:201], v[104:107]
	s_waitcnt lgkmcnt(1)
	v_mfma_f32_16x16x32_bf16 v[76:79], v[80:83], v[206:209], v[76:79]
	v_mfma_f32_16x16x32_bf16 v[72:75], v[88:91], v[206:209], v[72:75]
	s_add_i32 s46, 0, 0x1c000
	v_mfma_f32_16x16x32_bf16 v[144:147], v[92:95], v[132:135], v[140:143]
	v_add_u32_e32 v140, s46, v188
	v_mfma_f32_16x16x32_bf16 v[136:139], v[84:87], v[164:167], v[136:139]
	s_add_i32 s47, s68, s66
	v_mfma_f32_16x16x32_bf16 v[128:131], v[92:95], v[164:167], v[128:131]
	v_mfma_f32_16x16x32_bf16 v[120:123], v[84:87], v[202:205], v[120:123]
	v_mfma_f32_16x16x32_bf16 v[104:107], v[92:95], v[202:205], v[104:107]
	s_waitcnt lgkmcnt(0)
	v_mfma_f32_16x16x32_bf16 v[76:79], v[84:87], v[210:213], v[76:79]
	v_mfma_f32_16x16x32_bf16 v[72:75], v[92:95], v[210:213], v[72:75]
	s_barrier
	s_setprio 0
	ds_read_b128 v[214:217], v140
	ds_read_b128 v[218:221], v140 offset:1024
	ds_read_b128 v[222:225], v140 offset:2048
	ds_read_b128 v[230:233], v140 offset:3072
	v_lshl_add_u64 v[140:141], v[184:185], 0, s[14:15]
	s_mov_b32 m0, s47
	s_nop 0
	global_load_lds_dwordx4 v[140:141], off
	v_lshl_add_u64 v[140:141], v[194:195], 0, s[14:15]
	s_add_i32 m0, s47, 0x2000
	s_nop 0
	global_load_lds_dwordx4 v[140:141], off
	s_setprio 1
	s_barrier
	s_waitcnt lgkmcnt(1)
	v_mfma_f32_16x16x32_bf16 v[96:99], v[222:225], v[124:127], v[96:99]
	v_mfma_f32_16x16x32_bf16 v[140:143], v[214:217], v[124:127], v[156:159]
	s_waitcnt lgkmcnt(0)
	v_mfma_f32_16x16x32_bf16 v[152:155], v[230:233], v[132:135], v[96:99]
	v_mfma_f32_16x16x32_bf16 v[96:99], v[214:217], v[160:163], v[100:103]
	v_mfma_f32_16x16x32_bf16 v[156:159], v[218:221], v[132:135], v[140:143]
	v_mfma_f32_16x16x32_bf16 v[140:143], v[218:221], v[164:167], v[96:99]
	v_mfma_f32_16x16x32_bf16 v[96:99], v[222:225], v[160:163], v[108:111]
	v_mfma_f32_16x16x32_bf16 v[132:135], v[230:233], v[164:167], v[96:99]
	v_mfma_f32_16x16x32_bf16 v[96:99], v[214:217], v[198:201], v[112:115]
	s_mov_b32 m0, s63
	v_mfma_f32_16x16x32_bf16 v[124:127], v[218:221], v[202:205], v[96:99]
	v_lshl_add_u64 v[184:185], v[226:227], 0, s[14:15]
	v_mfma_f32_16x16x32_bf16 v[96:99], v[222:225], v[198:201], v[116:119]
	v_mfma_f32_16x16x32_bf16 v[68:71], v[214:217], v[206:209], v[68:71]
	v_mfma_f32_16x16x32_bf16 v[64:67], v[222:225], v[206:209], v[64:67]
	v_mfma_f32_16x16x32_bf16 v[116:119], v[230:233], v[202:205], v[96:99]
	v_mfma_f32_16x16x32_bf16 v[68:71], v[218:221], v[210:213], v[68:71]
	v_mfma_f32_16x16x32_bf16 v[64:67], v[230:233], v[210:213], v[64:67]
	s_barrier
	s_setprio 0
	ds_read_b128 v[96:99], v190 offset:49152
	global_load_lds_dwordx4 v[184:185], off
	ds_read_b128 v[100:103], v190 offset:50176
	ds_read_b128 v[108:111], v190 offset:51200
	ds_read_b128 v[112:115], v190 offset:52224
	ds_read_b128 v[160:163], v190 offset:53248
	ds_read_b128 v[164:167], v190 offset:54272
	ds_read_b128 v[198:201], v190 offset:55296
	ds_read_b128 v[202:205], v190 offset:56320
	v_lshl_add_u64 v[184:185], v[234:235], 0, s[14:15]
	s_mov_b32 m0, s4
	s_nop 0
	global_load_lds_dwordx4 v[184:185], off
	s_waitcnt vmcnt(10)
	s_setprio 1
	s_barrier
; #define PG8_STAGE(bufoff, gbase, voff) do { _Pragma("unroll") for (int _i = 0; _i < 2; ++_i) \
;         __builtin_amdgcn_global_load_lds((const unsigned*)((const char*)(gbase) + (voff)[_i]), (LAS unsigned*)(lds + (bufoff) + ldsw + _i * 8192), 16, 0, 0); } while (0)
; #define PG8_LDA(dst, b, h) do { _Pragma("unroll") for (int m = 0; m < 4; ++m) _Pragma("unroll") for (int k = 0; k < 2; ++k) dst[m][k] = *(const LAS bf16x8*)(lds + PG8_SA(b, h) + aoff + m * 2048 + k * 1024); } while (0)
; #define PG8_WAIT_V(n) asm volatile("s_waitcnt vmcnt(" #n ")" ::: "memory")
; #define PG8_BAR __builtin_amdgcn_s_barrier()
; template <class Map, class Epi>
; DI void gemm_phase(LAS unsigned char* lds, const Map& MP, const Epi& E, const int nM, const int nN, const int K, const int lda, const int ldb) {
;     ...
;         for (int t = 0; t < nt; t += 2) {
;             const bool last = (t == nt - 2);
;             const char* a1 = cA + (size_t)(t + 1) * kstep;
;             const char* a2 = last ? nA : cA + (size_t)(t + 2) * kstep; const char* b2 = last ? nB : cB + (size_t)(t + 2) * kstep;
;             const char* a3 = a2 + kstep; const char* b3 = b2 + kstep;
;             PG8_LDB(B0, 0, 0); PG8_SCHED; PG8_LDA(At, 0, 0); PG8_STAGE(PG8_SA(1, 1), a1 + hstepA, voffA);
;             PG8_WAIT_L(8); PG8_BAR; PG8_WAIT_L(0); PG8_MMA(0, 0, At, B0); PG8_BAR; PG8_SCHED;
;             PG8_LDB(B1, 0, 1); PG8_STAGE(PG8_SB(0, 0), b2, voffB);
;             PG8_BAR; PG8_WAIT_L(0); PG8_MMA(0, 1, At, B1); PG8_BAR;
;             PG8_LDA(At, 0, 1); PG8_STAGE(PG8_SA(0, 0), a2, voffA);
;             PG8_BAR; PG8_WAIT_L(0); PG8_MMA(1, 0, At, B0); PG8_BAR; PG8_SCHED;
;             PG8_STAGE(PG8_SB(0, 1), b2 + hstepB, voffB);
;             PG8_WAIT_V(6); PG8_BAR; PG8_MMA(1, 1, At, B1); PG8_BAR;
;             PG8_LDB(B0, 1, 0); PG8_SCHED; PG8_LDA(At, 1, 0); PG8_STAGE(PG8_SA(0, 1), a2 + hstepA, voffA);
;             PG8_WAIT_L(8); PG8_BAR; PG8_WAIT_L(0); PG8_MMA(0, 0, At, B0); PG8_BAR; PG8_SCHED;
;             PG8_LDB(B1, 1, 1); PG8_STAGE(PG8_SB(1, 0), b3, voffB);
;             PG8_BAR; PG8_WAIT_L(0); PG8_MMA(0, 1, At, B1); PG8_BAR;
;             PG8_LDA(At, 1, 1); PG8_STAGE(PG8_SA(1, 0), a3, voffA);
;             PG8_BAR; PG8_WAIT_L(0); PG8_MMA(1, 0, At, B0); PG8_BAR; PG8_SCHED;
;             PG8_STAGE(PG8_SB(1, 1), b3 + hstepB, voffB);
;             PG8_WAIT_V(6); PG8_BAR; PG8_MMA(1, 1, At, B1); PG8_BAR;
	s_waitcnt lgkmcnt(7)
	v_mfma_f32_16x16x32_bf16 v[60:63], v[80:83], v[96:99], v[60:63]
	v_mfma_f32_16x16x32_bf16 v[48:51], v[88:91], v[96:99], v[48:51]
	s_waitcnt lgkmcnt(5)
	v_mfma_f32_16x16x32_bf16 v[40:43], v[80:83], v[108:111], v[40:43]
	v_mfma_f32_16x16x32_bf16 v[32:35], v[88:91], v[108:111], v[32:35]
	s_waitcnt lgkmcnt(3)
	v_mfma_f32_16x16x32_bf16 v[24:27], v[80:83], v[160:163], v[24:27]
	v_mfma_f32_16x16x32_bf16 v[16:19], v[88:91], v[160:163], v[16:19]
	s_waitcnt lgkmcnt(1)
	v_mfma_f32_16x16x32_bf16 v[12:15], v[80:83], v[198:201], v[12:15]
	v_mfma_f32_16x16x32_bf16 v[8:11], v[88:91], v[198:201], v[8:11]
	v_mfma_f32_16x16x32_bf16 v[60:63], v[84:87], v[100:103], v[60:63]
	s_add_u32 s24, s24, 0x80080
	s_addc_u32 s25, s25, 0
	v_mfma_f32_16x16x32_bf16 v[48:51], v[92:95], v[100:103], v[48:51]
	s_add_i32 s46, s46, s66
	v_mfma_f32_16x16x32_bf16 v[40:43], v[84:87], v[112:115], v[40:43]
	v_mfma_f32_16x16x32_bf16 v[32:35], v[92:95], v[112:115], v[32:35]
	v_mfma_f32_16x16x32_bf16 v[24:27], v[84:87], v[164:167], v[24:27]
	v_mfma_f32_16x16x32_bf16 v[16:19], v[92:95], v[164:167], v[16:19]
	s_waitcnt lgkmcnt(0)
	v_mfma_f32_16x16x32_bf16 v[12:15], v[84:87], v[202:205], v[12:15]
	v_mfma_f32_16x16x32_bf16 v[8:11], v[92:95], v[202:205], v[8:11]
	s_barrier
	s_setprio 0
	s_mov_b32 m0, s46
	s_nop 0
	global_load_lds_dwordx4 v172, s[24:25]
	s_add_i32 m0, s46, 0x2000
	s_nop 0
	global_load_lds_dwordx4 v168, s[24:25]
	s_waitcnt vmcnt(6)
	s_setprio 1
	s_barrier
	v_mfma_f32_16x16x32_bf16 v[56:59], v[214:217], v[96:99], v[56:59]
	v_mfma_f32_16x16x32_bf16 v[52:55], v[222:225], v[96:99], v[52:55]
	ds_read_b128 v[80:83], v189
	v_mfma_f32_16x16x32_bf16 v[44:47], v[214:217], v[108:111], v[44:47]
	v_mfma_f32_16x16x32_bf16 v[36:39], v[222:225], v[108:111], v[36:39]
	ds_read_b128 v[84:87], v189 offset:1024
	v_mfma_f32_16x16x32_bf16 v[28:31], v[214:217], v[160:163], v[28:31]
	v_mfma_f32_16x16x32_bf16 v[20:23], v[222:225], v[160:163], v[20:23]
	ds_read_b128 v[88:91], v189 offset:2048
	v_mfma_f32_16x16x32_bf16 v[4:7], v[214:217], v[198:201], v[4:7]
	v_mfma_f32_16x16x32_bf16 v[0:3], v[222:225], v[198:201], v[0:3]
	ds_read_b128 v[92:95], v189 offset:3072
	v_mfma_f32_16x16x32_bf16 v[56:59], v[218:221], v[100:103], v[56:59]
	s_add_i32 s3, s3, 2
	v_mfma_f32_16x16x32_bf16 v[52:55], v[230:233], v[100:103], v[52:55]
	s_add_u32 vcc_lo, vcc_lo, 0x100
	s_addc_u32 vcc_hi, vcc_hi, 0
	v_mfma_f32_16x16x32_bf16 v[44:47], v[218:221], v[112:115], v[44:47]
	s_add_u32 s42, s42, 0x100
	s_addc_u32 s43, s43, 0
	v_mfma_f32_16x16x32_bf16 v[36:39], v[230:233], v[112:115], v[36:39]
	s_cmp_gt_u32 s3, 29
	v_mfma_f32_16x16x32_bf16 v[28:31], v[218:221], v[164:167], v[28:31]
	v_mfma_f32_16x16x32_bf16 v[20:23], v[230:233], v[164:167], v[20:23]
	v_mfma_f32_16x16x32_bf16 v[4:7], v[218:221], v[202:205], v[4:7]
	v_mfma_f32_16x16x32_bf16 v[0:3], v[230:233], v[202:205], v[0:3]
	s_barrier
	s_setprio 0
	s_cbranch_scc0 .LBB1_1069
; DI float silu_mul(float g, float v) { return g * v * __builtin_amdgcn_rcpf(1.0f + __builtin_amdgcn_exp2f(-LOG2E * g)); }
;     DI void operator()(const f32x4 (&acc)[2][2][4][2], const Unit& u, int wr, int wc, int fr, int fq) const {
;         const int row0 = u.pm * BM + wr * 64 + fr, ch0 = u.pn * 128 + wc * 32 + 8 * fq;
;         f32x4 w0[2], w1[2], w2[2], bb[2];
; #pragma unroll
;         for (int n = 0; n < 2; ++n) { w0[n] = *(const f32x4*)(cw + ch0 + 4 * n); w1[n] = *(const f32x4*)(cw + DFF + ch0 + 4 * n); w2[n] = *(const f32x4*)(cw + 2 * DFF + ch0 + 4 * n); bb[n] = *(const f32x4*)(cb + ch0 + 4 * n); }
; #pragma unroll
;         for (int ai = 0; ai < 2; ++ai)
; #pragma unroll
;             for (int m = 0; m < 4; ++m) {
;                 const bool efirst = (m == 0) && (fr == 0), elast = (m == 3) && (fr == 15);
;                 const int row = row0 + ai * HALF + m * 16;
;                 f32x4 gc[2];
; #pragma unroll
;                 for (int n = 0; n < 2; ++n) {
;                     const f32x4 g = acc[ai][0][m][n];
;                     const f32x4 gprev = acc[ai][0][m > 0 ? m - 1 : 0][n], gnext = acc[ai][0][m < 3 ? m + 1 : 3][n];
;                     f32x4 up, dn;
; #pragma unroll
;                     for (int e = 0; e < 4; ++e) {
;                         const float pu = (m > 0 && fr == 15) ? gprev[e] : g[e];
;                         const float pd = (m < 3 && fr == 0) ? gnext[e] : g[e];
;                         up[e] = dpp_ror1(pu); dn[e] = dpp_ror15(pd);
;                     }
;                     if (efirst) up = (f32x4){0.f, 0.f, 0.f, 0.f};
;                     if (elast) dn = (f32x4){0.f, 0.f, 0.f, 0.f};
;                     gc[n] = w0[n] * up + w1[n] * g + w2[n] * dn + bb[n];
;                 }
;                 if (efirst || elast) {
;                     const size_t eo = (size_t)((row >> 6) * 2 + (elast ? 1 : 0)) * DFF + ch0;
; #pragma unroll
;                     for (int n = 0; n < 2; ++n) { *(f32x4*)(EP + eo + 4 * n) = gc[n]; *(f32x4*)(ER + eo + 4 * n) = acc[ai][0][m][n]; *(f32x4*)(EV + eo + 4 * n) = acc[ai][1][m][n]; }
;                 } else {
;                     const f32x4 v0 = acc[ai][1][m][0], v1 = acc[ai][1][m][1];
;                     u32x4 o;
;                     o[0] = pack2(silu_mul(gc[0][0], v0[0]), silu_mul(gc[0][1], v0[1])); o[1] = pack2(silu_mul(gc[0][2], v0[2]), silu_mul(gc[0][3], v0[3]));
	s_waitcnt lgkmcnt(0)
	s_lshl_b32 s21, s45, 7
	v_mov_b32_e32 v194, v186
	v_mov_b32_e32 v80, v187
	s_or_b32 s21, s21, s62
	v_lshl_add_u32 v184, v80, 3, s21
	v_ashrrev_i32_e32 v185, 31, v184
	v_lshlrev_b64 v[80:81], 2, v[184:185]
	v_lshl_add_u64 v[84:85], s[6:7], 0, v[80:81]
	v_lshl_add_u64 v[88:89], s[16:17], 0, v[80:81]
	v_lshl_add_u64 v[92:93], s[18:19], 0, v[80:81]
	v_lshl_add_u64 v[112:113], s[52:53], 0, v[80:81]
	global_load_dwordx4 v[80:83], v[84:85], off offset:16
	global_load_dwordx4 v[96:99], v[84:85], off
	s_nop 0
	global_load_dwordx4 v[84:87], v[88:89], off offset:16
	global_load_dwordx4 v[100:103], v[88:89], off
	s_nop 0
	global_load_dwordx4 v[88:91], v[92:93], off offset:16
	global_load_dwordx4 v[108:111], v[92:93], off
	s_nop 0
	global_load_dwordx4 v[92:95], v[112:113], off offset:16
	s_nop 0
	global_load_dwordx4 v[112:115], v[112:113], off
	v_cmp_eq_u32_e32 vcc, 0, v194
	s_nop 0
	s_nop 0
	v_cndmask_b32_e32 v161, v148, v136, vcc
	v_cndmask_b32_e32 v162, v149, v137, vcc
	v_cndmask_b32_e32 v163, v150, v138, vcc
	v_mov_b32_dpp v160, v161 row_ror:15 row_mask:0xf bank_mask:0xf
	s_nop 0
	s_nop 0
	v_mov_b32_dpp v161, v162 row_ror:15 row_mask:0xf bank_mask:0xf
	v_mov_b32_dpp v164, v150 row_ror:1 row_mask:0xf bank_mask:0xf
	v_cndmask_b32_e32 v165, v151, v139, vcc
	v_mov_b32_dpp v162, v163 row_ror:15 row_mask:0xf bank_mask:0xf
	v_mov_b32_dpp v195, v151 row_ror:1 row_mask:0xf bank_mask:0xf
	v_mov_b32_dpp v166, v148 row_ror:1 row_mask:0xf bank_mask:0xf
	v_mov_b32_dpp v167, v149 row_ror:1 row_mask:0xf bank_mask:0xf
	v_mov_b32_dpp v163, v165 row_ror:15 row_mask:0xf bank_mask:0xf
	v_cndmask_b32_e64 v165, v195, 0, vcc
	v_cndmask_b32_e64 v164, v164, 0, vcc
	v_cndmask_b32_e64 v167, v167, 0, vcc
	v_cndmask_b32_e64 v166, v166, 0, vcc
	s_nop 0
	s_nop 0
	v_mov_b32_dpp v195, v144 row_ror:1 row_mask:0xf bank_mask:0xf
	v_mov_b32_dpp v196, v145 row_ror:1 row_mask:0xf bank_mask:0xf
	v_mov_b32_dpp v198, v146 row_ror:1 row_mask:0xf bank_mask:0xf
	v_cndmask_b32_e32 v199, v147, v131, vcc
	v_mov_b32_dpp v200, v147 row_ror:1 row_mask:0xf bank_mask:0xf
	v_cndmask_b32_e64 v198, v198, 0, vcc
	v_cndmask_b32_e64 v201, v196, 0, vcc
	s_lshl_b32 s3, s44, 8
	s_add_i32 s3, s3, s49
	v_add_u32_e32 v193, s3, v194
	v_cmp_ne_u32_e64 s[46:47], 0, v194
	s_waitcnt vmcnt(0)
	v_pk_mul_f32 v[164:165], v[98:99], v[164:165]
	v_pk_mul_f32 v[166:167], v[96:97], v[166:167]
	v_pk_fma_f32 v[164:165], v[150:151], v[102:103], v[164:165]
	v_pk_fma_f32 v[166:167], v[148:149], v[100:101], v[166:167]
	v_pk_fma_f32 v[162:163], v[110:111], v[162:163], v[164:165]
	v_cndmask_b32_e32 v165, v144, v128, vcc
	v_pk_fma_f32 v[160:161], v[108:109], v[160:161], v[166:167]
	v_cndmask_b32_e32 v166, v145, v129, vcc
	v_mov_b32_dpp v164, v165 row_ror:15 row_mask:0xf bank_mask:0xf
	v_cndmask_b32_e32 v167, v146, v130, vcc
	v_pk_add_f32 v[162:163], v[114:115], v[162:163]
	v_mov_b32_dpp v165, v166 row_ror:15 row_mask:0xf bank_mask:0xf
	v_pk_add_f32 v[160:161], v[112:113], v[160:161]
	s_nop 0
	v_mov_b32_dpp v166, v167 row_ror:15 row_mask:0xf bank_mask:0xf
	s_nop 1
	v_mov_b32_dpp v167, v199 row_ror:15 row_mask:0xf bank_mask:0xf
	v_cndmask_b32_e64 v199, v200, 0, vcc
	v_cndmask_b32_e64 v200, v195, 0, vcc
	v_pk_mul_f32 v[200:201], v[80:81], v[200:201]
	v_pk_mul_f32 v[198:199], v[82:83], v[198:199]
	v_pk_fma_f32 v[200:201], v[144:145], v[84:85], v[200:201]
	v_pk_fma_f32 v[198:199], v[146:147], v[86:87], v[198:199]
	v_pk_fma_f32 v[164:165], v[88:89], v[164:165], v[200:201]
	v_pk_fma_f32 v[166:167], v[90:91], v[166:167], v[198:199]
	v_pk_add_f32 v[164:165], v[92:93], v[164:165]
	v_pk_add_f32 v[166:167], v[94:95], v[166:167]
	s_and_saveexec_b64 s[24:25], s[46:47]
	s_xor_b64 s[24:25], exec, s[24:25]
	s_cbranch_execz .LBB1_1072
	v_mul_f32_e32 v195, 0xbfb8aa3b, v160
	v_exp_f32_e32 v195, v195
	v_mul_f32_e32 v196, 0xbfb8aa3b, v161
	v_exp_f32_e32 v196, v196
	v_pk_mul_f32 v[160:161], v[156:157], v[160:161]
	v_add_f32_e32 v195, 1.0, v195
	v_rcp_f32_e32 v198, v195
	v_add_f32_e32 v196, 1.0, v196
	v_mul_f32_e32 v195, 0xbfb8aa3b, v162
	v_rcp_f32_e32 v199, v196
	v_exp_f32_e32 v195, v195
	v_mul_f32_e32 v196, 0xbfb8aa3b, v163
	v_exp_f32_e32 v196, v196
	v_pk_mul_f32 v[160:161], v[160:161], v[198:199]
	v_add_f32_e32 v195, 1.0, v195
	v_rcp_f32_e32 v200, v195
	v_add_f32_e32 v195, 1.0, v196
	v_rcp_f32_e32 v201, v195
	v_cvt_pk_bf16_f32 v160, v160, v161
	v_mul_f32_e32 v161, 0xbfb8aa3b, v164
	v_exp_f32_e32 v195, v161
	v_mul_f32_e32 v161, 0xbfb8aa3b, v165
	v_exp_f32_e32 v196, v161
	v_pk_mul_f32 v[162:163], v[158:159], v[162:163]
	v_pk_mul_f32 v[164:165], v[152:153], v[164:165]
	v_pk_mul_f32 v[162:163], v[162:163], v[200:201]
	s_nop 0
	v_cvt_pk_bf16_f32 v161, v162, v163
	v_add_f32_e32 v162, 1.0, v195
	v_mul_f32_e32 v195, 0xbfb8aa3b, v166
	v_add_f32_e32 v163, 1.0, v196
	v_exp_f32_e32 v195, v195
	v_mul_f32_e32 v196, 0xbfb8aa3b, v167
	v_exp_f32_e32 v196, v196
	v_rcp_f32_e32 v162, v162
	v_add_f32_e32 v195, 1.0, v195
	v_rcp_f32_e32 v198, v195
	v_add_f32_e32 v195, 1.0, v196
	v_rcp_f32_e32 v163, v163
	v_rcp_f32_e32 v199, v195
	v_pk_mul_f32 v[166:167], v[154:155], v[166:167]
	v_pk_mul_f32 v[162:163], v[164:165], v[162:163]
	v_pk_mul_f32 v[164:165], v[166:167], v[198:199]
	v_cvt_pk_bf16_f32 v162, v162, v163
	v_cvt_pk_bf16_f32 v163, v164, v165
	v_mov_b64_e32 v[164:165], s[54:55]
	v_mad_i64_i32 v[164:165], s[42:43], v193, s60, v[164:165]
	v_lshl_add_u64 v[164:165], v[184:185], 1, v[164:165]
	global_store_dwordx4 v[164:165], v[160:163], off

; #define PG8_STAGE(bufoff, gbase, voff) do { _Pragma("unroll") for (int _i = 0; _i < 2; ++_i) \
;         __builtin_amdgcn_global_load_lds((const unsigned*)((const char*)(gbase) + (voff)[_i]), (LAS unsigned*)(lds + (bufoff) + ldsw + _i * 8192), 16, 0, 0); } while (0)
; #define PG8_LDA(dst, b, h) do { _Pragma("unroll") for (int m = 0; m < 4; ++m) _Pragma("unroll") for (int k = 0; k < 2; ++k) dst[m][k] = *(const LAS bf16x8*)(lds + PG8_SA(b, h) + aoff + m * 2048 + k * 1024); } while (0)
; #define PG8_WAIT_V(n) asm volatile("s_waitcnt vmcnt(" #n ")" ::: "memory")
; #define PG8_BAR __builtin_amdgcn_s_barrier()
; template <class Map, class Epi>
; DI void gemm_phase(LAS unsigned char* lds, const Map& MP, const Epi& E, const int nM, const int nN, const int K, const int lda, const int ldb) {
;     ...
;         for (int t = 0; t < nt; t += 2) {
;             const bool last = (t == nt - 2);
;             const char* a1 = cA + (size_t)(t + 1) * kstep;
;             const char* a2 = last ? nA : cA + (size_t)(t + 2) * kstep; const char* b2 = last ? nB : cB + (size_t)(t + 2) * kstep;
;             const char* a3 = a2 + kstep; const char* b3 = b2 + kstep;
;             PG8_LDB(B0, 0, 0); PG8_SCHED; PG8_LDA(At, 0, 0); PG8_STAGE(PG8_SA(1, 1), a1 + hstepA, voffA);
;             PG8_WAIT_L(8); PG8_BAR; PG8_WAIT_L(0); PG8_MMA(0, 0, At, B0); PG8_BAR; PG8_SCHED;
;             PG8_LDB(B1, 0, 1); PG8_STAGE(PG8_SB(0, 0), b2, voffB);
;             PG8_BAR; PG8_WAIT_L(0); PG8_MMA(0, 1, At, B1); PG8_BAR;
;             PG8_LDA(At, 0, 1); PG8_STAGE(PG8_SA(0, 0), a2, voffA);
;             PG8_BAR; PG8_WAIT_L(0); PG8_MMA(1, 0, At, B0); PG8_BAR; PG8_SCHED;
;             PG8_STAGE(PG8_SB(0, 1), b2 + hstepB, voffB);
;             PG8_WAIT_V(6); PG8_BAR; PG8_MMA(1, 1, At, B1); PG8_BAR;
;             PG8_LDB(B0, 1, 0); PG8_SCHED; PG8_LDA(At, 1, 0); PG8_STAGE(PG8_SA(0, 1), a2 + hstepA, voffA);
;             PG8_WAIT_L(8); PG8_BAR; PG8_WAIT_L(0); PG8_MMA(0, 0, At, B0); PG8_BAR; PG8_SCHED;
;             PG8_LDB(B1, 1, 1); PG8_STAGE(PG8_SB(1, 0), b3, voffB);
;             PG8_BAR; PG8_WAIT_L(0); PG8_MMA(0, 1, At, B1); PG8_BAR;
;             PG8_LDA(At, 1, 1); PG8_STAGE(PG8_SA(1, 0), a3, voffA);
;             PG8_BAR; PG8_WAIT_L(0); PG8_MMA(1, 0, At, B0); PG8_BAR; PG8_SCHED;
;             PG8_STAGE(PG8_SB(1, 1), b3 + hstepB, voffB);
;             PG8_WAIT_V(6); PG8_BAR; PG8_MMA(1, 1, At, B1); PG8_BAR;
.LBB1_1239:
	s_add_u32 s10, s8, 0x100
	s_addc_u32 s11, s9, 0
	s_cmpk_eq_i32 s3, 0x54
	s_cselect_b32 s15, s43, s11
	s_cselect_b32 s14, s42, s10
	s_cselect_b32 s13, s7, s38
	s_cselect_b32 s12, s6, s5
	s_add_i32 m0, s24, 0xc000
	ds_read_b128 v[168:171], v150
	global_load_lds_dwordx4 v138, s[8:9]
	ds_read_b128 v[172:175], v150 offset:1024
	ds_read_b128 v[176:179], v150 offset:2048
	ds_read_b128 v[180:183], v150 offset:3072
	ds_read_b128 v[184:187], v150 offset:4096
	ds_read_b128 v[188:191], v150 offset:5120
	ds_read_b128 v[192:195], v150 offset:6144
	ds_read_b128 v[198:201], v150 offset:7168
	s_add_i32 m0, s24, 0xe000
	s_nop 0
	global_load_lds_dwordx4 v136, s[8:9]
	s_waitcnt lgkmcnt(8)
	s_setprio 1
	s_barrier
	s_waitcnt lgkmcnt(7)
	v_mfma_f32_16x16x32_bf16 v[124:127], v[152:155], v[168:171], v[124:127]
	v_mfma_f32_16x16x32_bf16 v[120:123], v[160:163], v[168:171], v[120:123]
	s_waitcnt lgkmcnt(5)
	v_mfma_f32_16x16x32_bf16 v[108:111], v[152:155], v[176:179], v[108:111]
	v_mfma_f32_16x16x32_bf16 v[104:107], v[160:163], v[176:179], v[104:107]
	s_waitcnt lgkmcnt(3)
	v_mfma_f32_16x16x32_bf16 v[92:95], v[152:155], v[184:187], v[92:95]
	v_mfma_f32_16x16x32_bf16 v[88:91], v[160:163], v[184:187], v[88:91]
	s_waitcnt lgkmcnt(1)
	v_mfma_f32_16x16x32_bf16 v[76:79], v[152:155], v[192:195], v[76:79]
	v_mfma_f32_16x16x32_bf16 v[72:75], v[160:163], v[192:195], v[72:75]
	v_mfma_f32_16x16x32_bf16 v[124:127], v[156:159], v[172:175], v[124:127]
	s_add_i32 s8, s35, s22
	v_mfma_f32_16x16x32_bf16 v[120:123], v[164:167], v[172:175], v[120:123]
	v_lshl_add_u64 v[144:145], s[12:13], 0, v[132:133]
	v_mfma_f32_16x16x32_bf16 v[108:111], v[156:159], v[180:183], v[108:111]
	v_lshl_add_u64 v[218:219], s[12:13], 0, v[128:129]
	v_mfma_f32_16x16x32_bf16 v[104:107], v[164:167], v[180:183], v[104:107]
	v_mfma_f32_16x16x32_bf16 v[92:95], v[156:159], v[188:191], v[92:95]
	v_mfma_f32_16x16x32_bf16 v[88:91], v[164:167], v[188:191], v[88:91]
	s_waitcnt lgkmcnt(0)
	v_mfma_f32_16x16x32_bf16 v[76:79], v[156:159], v[198:201], v[76:79]
	v_mfma_f32_16x16x32_bf16 v[72:75], v[164:167], v[198:201], v[72:75]
	s_barrier
	s_setprio 0
	s_mov_b32 m0, s8
	ds_read_b128 v[202:205], v151
	global_load_lds_dwordx4 v[144:145], off
	ds_read_b128 v[206:209], v151 offset:1024
	ds_read_b128 v[210:213], v151 offset:2048
	ds_read_b128 v[214:217], v151 offset:3072
	s_add_i32 m0, s8, 0x2000
	s_nop 0
	global_load_lds_dwordx4 v[218:219], off
	s_setprio 1
	s_barrier
	s_waitcnt lgkmcnt(3)
	v_mfma_f32_16x16x32_bf16 v[116:119], v[202:205], v[168:171], v[116:119]
	s_waitcnt lgkmcnt(1)
	v_mfma_f32_16x16x32_bf16 v[112:115], v[210:213], v[168:171], v[112:115]
	v_mfma_f32_16x16x32_bf16 v[100:103], v[202:205], v[176:179], v[100:103]
	v_mfma_f32_16x16x32_bf16 v[96:99], v[210:213], v[176:179], v[96:99]
	v_mfma_f32_16x16x32_bf16 v[84:87], v[202:205], v[184:187], v[84:87]
	v_mfma_f32_16x16x32_bf16 v[80:83], v[210:213], v[184:187], v[80:83]
	v_mfma_f32_16x16x32_bf16 v[68:71], v[202:205], v[192:195], v[68:71]
	v_mfma_f32_16x16x32_bf16 v[64:67], v[210:213], v[192:195], v[64:67]
	v_mfma_f32_16x16x32_bf16 v[116:119], v[206:209], v[172:175], v[116:119]
	v_lshl_add_u64 v[222:223], s[14:15], 0, v[130:131]
	s_mov_b32 m0, s24
	s_waitcnt lgkmcnt(0)
	v_mfma_f32_16x16x32_bf16 v[112:115], v[214:217], v[172:175], v[112:115]
	v_lshl_add_u64 v[220:221], s[14:15], 0, v[134:135]
	v_mfma_f32_16x16x32_bf16 v[100:103], v[206:209], v[180:183], v[100:103]
	v_mfma_f32_16x16x32_bf16 v[96:99], v[214:217], v[180:183], v[96:99]
	v_mfma_f32_16x16x32_bf16 v[84:87], v[206:209], v[188:191], v[84:87]
	v_mfma_f32_16x16x32_bf16 v[80:83], v[214:217], v[188:191], v[80:83]
	v_mfma_f32_16x16x32_bf16 v[68:71], v[206:209], v[198:201], v[68:71]
	v_mfma_f32_16x16x32_bf16 v[64:67], v[214:217], v[198:201], v[64:67]
	s_barrier
	s_setprio 0
	ds_read_b128 v[168:171], v150 offset:16384
	global_load_lds_dwordx4 v[220:221], off
	ds_read_b128 v[172:175], v150 offset:17408
	ds_read_b128 v[176:179], v150 offset:18432
	ds_read_b128 v[180:183], v150 offset:19456
	ds_read_b128 v[184:187], v150 offset:20480
	ds_read_b128 v[188:191], v150 offset:21504
	ds_read_b128 v[192:195], v150 offset:22528
	ds_read_b128 v[198:201], v150 offset:23552
	s_mov_b32 m0, s25
	s_nop 0
	global_load_lds_dwordx4 v[222:223], off
	s_waitcnt vmcnt(10)
	s_setprio 1
	s_barrier
	s_waitcnt lgkmcnt(7)
	v_mfma_f32_16x16x32_bf16 v[60:63], v[152:155], v[168:171], v[60:63]
	v_mfma_f32_16x16x32_bf16 v[56:59], v[160:163], v[168:171], v[56:59]
	s_waitcnt lgkmcnt(5)
	v_mfma_f32_16x16x32_bf16 v[44:47], v[152:155], v[176:179], v[44:47]
	v_mfma_f32_16x16x32_bf16 v[40:43], v[160:163], v[176:179], v[40:43]
	s_waitcnt lgkmcnt(3)
	v_mfma_f32_16x16x32_bf16 v[28:31], v[152:155], v[184:187], v[28:31]
	v_mfma_f32_16x16x32_bf16 v[24:27], v[160:163], v[184:187], v[24:27]
	s_waitcnt lgkmcnt(1)
	v_mfma_f32_16x16x32_bf16 v[12:15], v[152:155], v[192:195], v[12:15]
	v_mfma_f32_16x16x32_bf16 v[8:11], v[160:163], v[192:195], v[8:11]
	v_mfma_f32_16x16x32_bf16 v[60:63], v[156:159], v[172:175], v[60:63]
	s_add_u32 s8, s12, 0x160000
	s_addc_u32 s9, s13, 0
	v_mfma_f32_16x16x32_bf16 v[56:59], v[164:167], v[172:175], v[56:59]
	s_add_i32 s39, s36, s22
	v_mfma_f32_16x16x32_bf16 v[44:47], v[156:159], v[180:183], v[44:47]
	v_mfma_f32_16x16x32_bf16 v[40:43], v[164:167], v[180:183], v[40:43]
	v_mfma_f32_16x16x32_bf16 v[28:31], v[156:159], v[188:191], v[28:31]
	v_mfma_f32_16x16x32_bf16 v[24:27], v[164:167], v[188:191], v[24:27]
	s_waitcnt lgkmcnt(0)
	v_mfma_f32_16x16x32_bf16 v[12:15], v[156:159], v[198:201], v[12:15]
	v_mfma_f32_16x16x32_bf16 v[8:11], v[164:167], v[198:201], v[8:11]
	s_barrier
; #define PG8_STAGE(bufoff, gbase, voff) do { _Pragma("unroll") for (int _i = 0; _i < 2; ++_i) \
;         __builtin_amdgcn_global_load_lds((const unsigned*)((const char*)(gbase) + (voff)[_i]), (LAS unsigned*)(lds + (bufoff) + ldsw + _i * 8192), 16, 0, 0); } while (0)
; #define PG8_LDA(dst, b, h) do { _Pragma("unroll") for (int m = 0; m < 4; ++m) _Pragma("unroll") for (int k = 0; k < 2; ++k) dst[m][k] = *(const LAS bf16x8*)(lds + PG8_SA(b, h) + aoff + m * 2048 + k * 1024); } while (0)
; #define PG8_WAIT_V(n) asm volatile("s_waitcnt vmcnt(" #n ")" ::: "memory")
; #define PG8_BAR __builtin_amdgcn_s_barrier()
; template <class Map, class Epi>
; DI void gemm_phase(LAS unsigned char* lds, const Map& MP, const Epi& E, const int nM, const int nN, const int K, const int lda, const int ldb) {
;     ...
;         for (int t = 0; t < nt; t += 2) {
;             const bool last = (t == nt - 2);
;             const char* a1 = cA + (size_t)(t + 1) * kstep;
;             const char* a2 = last ? nA : cA + (size_t)(t + 2) * kstep; const char* b2 = last ? nB : cB + (size_t)(t + 2) * kstep;
;             const char* a3 = a2 + kstep; const char* b3 = b2 + kstep;
;             PG8_LDB(B0, 0, 0); PG8_SCHED; PG8_LDA(At, 0, 0); PG8_STAGE(PG8_SA(1, 1), a1 + hstepA, voffA);
;             PG8_WAIT_L(8); PG8_BAR; PG8_WAIT_L(0); PG8_MMA(0, 0, At, B0); PG8_BAR; PG8_SCHED;
;             PG8_LDB(B1, 0, 1); PG8_STAGE(PG8_SB(0, 0), b2, voffB);
;             PG8_BAR; PG8_WAIT_L(0); PG8_MMA(0, 1, At, B1); PG8_BAR;
;             PG8_LDA(At, 0, 1); PG8_STAGE(PG8_SA(0, 0), a2, voffA);
;             PG8_BAR; PG8_WAIT_L(0); PG8_MMA(1, 0, At, B0); PG8_BAR; PG8_SCHED;
;             PG8_STAGE(PG8_SB(0, 1), b2 + hstepB, voffB);
;             PG8_WAIT_V(6); PG8_BAR; PG8_MMA(1, 1, At, B1); PG8_BAR;
;             PG8_LDB(B0, 1, 0); PG8_SCHED; PG8_LDA(At, 1, 0); PG8_STAGE(PG8_SA(0, 1), a2 + hstepA, voffA);
;             PG8_WAIT_L(8); PG8_BAR; PG8_WAIT_L(0); PG8_MMA(0, 0, At, B0); PG8_BAR; PG8_SCHED;
;             PG8_LDB(B1, 1, 1); PG8_STAGE(PG8_SB(1, 0), b3, voffB);
;             PG8_BAR; PG8_WAIT_L(0); PG8_MMA(0, 1, At, B1); PG8_BAR;
;             PG8_LDA(At, 1, 1); PG8_STAGE(PG8_SA(1, 0), a3, voffA);
;             PG8_BAR; PG8_WAIT_L(0); PG8_MMA(1, 0, At, B0); PG8_BAR; PG8_SCHED;
;             PG8_STAGE(PG8_SB(1, 1), b3 + hstepB, voffB);
;             PG8_WAIT_V(6); PG8_BAR; PG8_MMA(1, 1, At, B1); PG8_BAR;
	s_setprio 0
	s_mov_b32 m0, s39
	s_nop 0
	global_load_lds_dwordx4 v132, s[8:9]
	s_add_i32 m0, s39, 0x2000
	s_nop 0
	global_load_lds_dwordx4 v128, s[8:9]
	s_waitcnt vmcnt(6)
	s_setprio 1
	s_barrier
	v_mfma_f32_16x16x32_bf16 v[52:55], v[202:205], v[168:171], v[52:55]
	v_mfma_f32_16x16x32_bf16 v[48:51], v[210:213], v[168:171], v[48:51]
	s_add_i32 s39, 0, 0x18000
	v_add_u32_e32 v164, s39, v148
	ds_read_b128 v[152:155], v164
	v_mfma_f32_16x16x32_bf16 v[36:39], v[202:205], v[176:179], v[36:39]
	v_mfma_f32_16x16x32_bf16 v[32:35], v[210:213], v[176:179], v[32:35]
	ds_read_b128 v[156:159], v164 offset:1024
	v_mfma_f32_16x16x32_bf16 v[20:23], v[202:205], v[184:187], v[20:23]
	v_mfma_f32_16x16x32_bf16 v[16:19], v[210:213], v[184:187], v[16:19]
	ds_read_b128 v[160:163], v164 offset:2048
	v_mfma_f32_16x16x32_bf16 v[4:7], v[202:205], v[192:195], v[4:7]
	v_mfma_f32_16x16x32_bf16 v[0:3], v[210:213], v[192:195], v[0:3]
	ds_read_b128 v[164:167], v164 offset:3072
	v_mfma_f32_16x16x32_bf16 v[52:55], v[206:209], v[172:175], v[52:55]
	s_add_u32 s8, s14, 0x160000
	s_addc_u32 s9, s15, 0
	v_mfma_f32_16x16x32_bf16 v[48:51], v[214:217], v[172:175], v[48:51]
	v_mfma_f32_16x16x32_bf16 v[36:39], v[206:209], v[180:183], v[36:39]
	v_mfma_f32_16x16x32_bf16 v[32:35], v[214:217], v[180:183], v[32:35]
	v_mfma_f32_16x16x32_bf16 v[20:23], v[206:209], v[188:191], v[20:23]
	v_mfma_f32_16x16x32_bf16 v[16:19], v[214:217], v[188:191], v[16:19]
	v_mfma_f32_16x16x32_bf16 v[4:7], v[206:209], v[198:201], v[4:7]
	v_mfma_f32_16x16x32_bf16 v[0:3], v[214:217], v[198:201], v[0:3]
	s_barrier
	s_setprio 0
	s_mov_b32 m0, s26
	ds_read_b128 v[168:171], v150 offset:32768
	global_load_lds_dwordx4 v134, s[8:9]
	ds_read_b128 v[172:175], v150 offset:33792
	ds_read_b128 v[176:179], v150 offset:34816
	ds_read_b128 v[180:183], v150 offset:35840
	ds_read_b128 v[184:187], v150 offset:36864
	ds_read_b128 v[188:191], v150 offset:37888
	ds_read_b128 v[192:195], v150 offset:38912
	ds_read_b128 v[198:201], v150 offset:39936
	s_mov_b32 m0, s27
	s_nop 0
	global_load_lds_dwordx4 v130, s[8:9]
	s_waitcnt lgkmcnt(8)
	s_setprio 1
	s_barrier
	s_waitcnt lgkmcnt(7)
	v_mfma_f32_16x16x32_bf16 v[124:127], v[152:155], v[168:171], v[124:127]
	v_mfma_f32_16x16x32_bf16 v[120:123], v[160:163], v[168:171], v[120:123]
	s_waitcnt lgkmcnt(5)
	v_mfma_f32_16x16x32_bf16 v[108:111], v[152:155], v[176:179], v[108:111]
	v_mfma_f32_16x16x32_bf16 v[104:107], v[160:163], v[176:179], v[104:107]
	s_waitcnt lgkmcnt(3)
	v_mfma_f32_16x16x32_bf16 v[92:95], v[152:155], v[184:187], v[92:95]
	v_mfma_f32_16x16x32_bf16 v[88:91], v[160:163], v[184:187], v[88:91]
	s_waitcnt lgkmcnt(1)
	v_mfma_f32_16x16x32_bf16 v[76:79], v[152:155], v[192:195], v[76:79]
	v_mfma_f32_16x16x32_bf16 v[72:75], v[160:163], v[192:195], v[72:75]
	v_mfma_f32_16x16x32_bf16 v[124:127], v[156:159], v[172:175], v[124:127]
	s_add_i32 s14, 0, 0x1c000
	v_mfma_f32_16x16x32_bf16 v[120:123], v[164:167], v[172:175], v[120:123]
	s_add_i32 s8, s39, s22
	v_mfma_f32_16x16x32_bf16 v[108:111], v[156:159], v[180:183], v[108:111]
	v_add_u32_e32 v196, s14, v148
	v_mfma_f32_16x16x32_bf16 v[104:107], v[164:167], v[180:183], v[104:107]
	v_lshl_add_u64 v[144:145], v[144:145], 0, s[52:53]
	v_mfma_f32_16x16x32_bf16 v[92:95], v[156:159], v[188:191], v[92:95]
	v_mfma_f32_16x16x32_bf16 v[88:91], v[164:167], v[188:191], v[88:91]
	s_waitcnt lgkmcnt(0)
	v_mfma_f32_16x16x32_bf16 v[76:79], v[156:159], v[198:201], v[76:79]
	v_mfma_f32_16x16x32_bf16 v[72:75], v[164:167], v[198:201], v[72:75]
	s_barrier
	s_setprio 0
	s_mov_b32 m0, s8
	ds_read_b128 v[202:205], v196
	global_load_lds_dwordx4 v[144:145], off
	ds_read_b128 v[206:209], v196 offset:1024
	ds_read_b128 v[210:213], v196 offset:2048
	ds_read_b128 v[214:217], v196 offset:3072
	v_lshl_add_u64 v[144:145], v[218:219], 0, s[52:53]
	s_add_i32 m0, s8, 0x2000
	s_nop 0
	global_load_lds_dwordx4 v[144:145], off
	s_setprio 1
	s_barrier
	s_waitcnt lgkmcnt(3)
	v_mfma_f32_16x16x32_bf16 v[116:119], v[202:205], v[168:171], v[116:119]
	s_waitcnt lgkmcnt(1)
	v_mfma_f32_16x16x32_bf16 v[112:115], v[210:213], v[168:171], v[112:115]
	v_mfma_f32_16x16x32_bf16 v[100:103], v[202:205], v[176:179], v[100:103]
	v_mfma_f32_16x16x32_bf16 v[96:99], v[210:213], v[176:179], v[96:99]
	v_mfma_f32_16x16x32_bf16 v[84:87], v[202:205], v[184:187], v[84:87]
	v_mfma_f32_16x16x32_bf16 v[80:83], v[210:213], v[184:187], v[80:83]
	v_mfma_f32_16x16x32_bf16 v[68:71], v[202:205], v[192:195], v[68:71]
	v_mfma_f32_16x16x32_bf16 v[64:67], v[210:213], v[192:195], v[64:67]
	v_mfma_f32_16x16x32_bf16 v[116:119], v[206:209], v[172:175], v[116:119]
	s_mov_b32 m0, s30
	s_waitcnt lgkmcnt(0)
	v_mfma_f32_16x16x32_bf16 v[112:115], v[214:217], v[172:175], v[112:115]
	v_lshl_add_u64 v[144:145], v[220:221], 0, s[52:53]
	v_mfma_f32_16x16x32_bf16 v[100:103], v[206:209], v[180:183], v[100:103]
	v_mfma_f32_16x16x32_bf16 v[96:99], v[214:217], v[180:183], v[96:99]
	v_mfma_f32_16x16x32_bf16 v[84:87], v[206:209], v[188:191], v[84:87]
	v_mfma_f32_16x16x32_bf16 v[80:83], v[214:217], v[188:191], v[80:83]
	v_mfma_f32_16x16x32_bf16 v[68:71], v[206:209], v[198:201], v[68:71]
	v_mfma_f32_16x16x32_bf16 v[64:67], v[214:217], v[198:201], v[64:67]
	s_barrier
	s_setprio 0
	ds_read_b128 v[168:171], v150 offset:49152
	global_load_lds_dwordx4 v[144:145], off
	ds_read_b128 v[172:175], v150 offset:50176
	ds_read_b128 v[176:179], v150 offset:51200
	ds_read_b128 v[180:183], v150 offset:52224
	ds_read_b128 v[184:187], v150 offset:53248
	ds_read_b128 v[188:191], v150 offset:54272
	ds_read_b128 v[192:195], v150 offset:55296
	ds_read_b128 v[198:201], v150 offset:56320
	v_lshl_add_u64 v[144:145], v[222:223], 0, s[52:53]
	s_mov_b32 m0, s31
	s_nop 0
	global_load_lds_dwordx4 v[144:145], off
	s_waitcnt vmcnt(10)
	s_setprio 1
	s_barrier
; #define PG8_WAIT_V(n) asm volatile("s_waitcnt vmcnt(" #n ")" ::: "memory")
;     DI void operator()(const f32x4 (&acc)[2][2][4][2], const Unit& u, int wr, int wc, int fr, int fq) const {
;         const int row0 = u.pm * BM + wr * 64 + fr, col0 = u.pn * BM + wc * 32 + 8 * fq;
;         f32x4 sc[2][2];
; #pragma unroll
;         for (int bj = 0; bj < 2; ++bj)
; #pragma unroll
;             for (int n = 0; n < 2; ++n) sc[bj][n] = scale ? *(const f32x4*)(scale + col0 + bj * HALF + 4 * n) : (f32x4){1.f, 1.f, 1.f, 1.f};
; #pragma unroll
;         for (int ai = 0; ai < 2; ++ai)
; #pragma unroll
; template <class Map, class Epi>
; DI void gemm_phase(LAS unsigned char* lds, const Map& MP, const Epi& E, const int nM, const int nN, const int K, const int lda, const int ldb) {
;     ...
;         for (int t = 0; t < nt; t += 2) {
;             const bool last = (t == nt - 2);
;             const char* a1 = cA + (size_t)(t + 1) * kstep;
;             const char* a2 = last ? nA : cA + (size_t)(t + 2) * kstep; const char* b2 = last ? nB : cB + (size_t)(t + 2) * kstep;
;             const char* a3 = a2 + kstep; const char* b3 = b2 + kstep;
;             PG8_LDB(B0, 0, 0); PG8_SCHED; PG8_LDA(At, 0, 0); PG8_STAGE(PG8_SA(1, 1), a1 + hstepA, voffA);
;             PG8_WAIT_L(8); PG8_BAR; PG8_WAIT_L(0); PG8_MMA(0, 0, At, B0); PG8_BAR; PG8_SCHED;
;             PG8_LDB(B1, 0, 1); PG8_STAGE(PG8_SB(0, 0), b2, voffB);
;             PG8_BAR; PG8_WAIT_L(0); PG8_MMA(0, 1, At, B1); PG8_BAR;
;             PG8_LDA(At, 0, 1); PG8_STAGE(PG8_SA(0, 0), a2, voffA);
;             PG8_BAR; PG8_WAIT_L(0); PG8_MMA(1, 0, At, B0); PG8_BAR; PG8_SCHED;
;             PG8_STAGE(PG8_SB(0, 1), b2 + hstepB, voffB);
;             PG8_WAIT_V(6); PG8_BAR; PG8_MMA(1, 1, At, B1); PG8_BAR;
;             PG8_LDB(B0, 1, 0); PG8_SCHED; PG8_LDA(At, 1, 0); PG8_STAGE(PG8_SA(0, 1), a2 + hstepA, voffA);
;             PG8_WAIT_L(8); PG8_BAR; PG8_WAIT_L(0); PG8_MMA(0, 0, At, B0); PG8_BAR; PG8_SCHED;
;             PG8_LDB(B1, 1, 1); PG8_STAGE(PG8_SB(1, 0), b3, voffB);
;             PG8_BAR; PG8_WAIT_L(0); PG8_MMA(0, 1, At, B1); PG8_BAR;
;             PG8_LDA(At, 1, 1); PG8_STAGE(PG8_SA(1, 0), a3, voffA);
;             PG8_BAR; PG8_WAIT_L(0); PG8_MMA(1, 0, At, B0); PG8_BAR; PG8_SCHED;
;             PG8_STAGE(PG8_SB(1, 1), b3 + hstepB, voffB);
;             PG8_WAIT_V(6); PG8_BAR; PG8_MMA(1, 1, At, B1); PG8_BAR;
	s_waitcnt lgkmcnt(7)
	v_mfma_f32_16x16x32_bf16 v[60:63], v[152:155], v[168:171], v[60:63]
	v_mfma_f32_16x16x32_bf16 v[56:59], v[160:163], v[168:171], v[56:59]
	s_waitcnt lgkmcnt(5)
	v_mfma_f32_16x16x32_bf16 v[44:47], v[152:155], v[176:179], v[44:47]
	v_mfma_f32_16x16x32_bf16 v[40:43], v[160:163], v[176:179], v[40:43]
	s_waitcnt lgkmcnt(3)
	v_mfma_f32_16x16x32_bf16 v[28:31], v[152:155], v[184:187], v[28:31]
	v_mfma_f32_16x16x32_bf16 v[24:27], v[160:163], v[184:187], v[24:27]
	s_waitcnt lgkmcnt(1)
	v_mfma_f32_16x16x32_bf16 v[12:15], v[152:155], v[192:195], v[12:15]
	v_mfma_f32_16x16x32_bf16 v[8:11], v[160:163], v[192:195], v[8:11]
	v_mfma_f32_16x16x32_bf16 v[60:63], v[156:159], v[172:175], v[60:63]
	s_add_u32 s8, s12, 0x160080
	s_addc_u32 s9, s13, 0
	v_mfma_f32_16x16x32_bf16 v[56:59], v[164:167], v[172:175], v[56:59]
	s_add_i32 s12, s14, s22
	v_mfma_f32_16x16x32_bf16 v[44:47], v[156:159], v[180:183], v[44:47]
	v_mfma_f32_16x16x32_bf16 v[40:43], v[164:167], v[180:183], v[40:43]
	v_mfma_f32_16x16x32_bf16 v[28:31], v[156:159], v[188:191], v[28:31]
	v_mfma_f32_16x16x32_bf16 v[24:27], v[164:167], v[188:191], v[24:27]
	s_waitcnt lgkmcnt(0)
	v_mfma_f32_16x16x32_bf16 v[12:15], v[156:159], v[198:201], v[12:15]
	v_mfma_f32_16x16x32_bf16 v[8:11], v[164:167], v[198:201], v[8:11]
	s_barrier
	s_setprio 0
	s_mov_b32 m0, s12
	s_nop 0
	global_load_lds_dwordx4 v132, s[8:9]
	s_add_i32 m0, s12, 0x2000
	s_nop 0
	global_load_lds_dwordx4 v128, s[8:9]
	s_waitcnt vmcnt(6)
	s_setprio 1
	s_barrier
	v_mfma_f32_16x16x32_bf16 v[52:55], v[202:205], v[168:171], v[52:55]
	v_mfma_f32_16x16x32_bf16 v[48:51], v[210:213], v[168:171], v[48:51]
	ds_read_b128 v[152:155], v149
	v_mfma_f32_16x16x32_bf16 v[36:39], v[202:205], v[176:179], v[36:39]
	v_mfma_f32_16x16x32_bf16 v[32:35], v[210:213], v[176:179], v[32:35]
	ds_read_b128 v[156:159], v149 offset:1024
	v_mfma_f32_16x16x32_bf16 v[20:23], v[202:205], v[184:187], v[20:23]
	v_mfma_f32_16x16x32_bf16 v[16:19], v[210:213], v[184:187], v[16:19]
	ds_read_b128 v[160:163], v149 offset:2048
	v_mfma_f32_16x16x32_bf16 v[4:7], v[202:205], v[192:195], v[4:7]
	v_mfma_f32_16x16x32_bf16 v[0:3], v[210:213], v[192:195], v[0:3]
	ds_read_b128 v[164:167], v149 offset:3072
	v_mfma_f32_16x16x32_bf16 v[52:55], v[206:209], v[172:175], v[52:55]
	s_add_i32 s3, s3, 2
	v_mfma_f32_16x16x32_bf16 v[48:51], v[214:217], v[172:175], v[48:51]
	s_add_u32 s5, s5, 0x100
	s_addc_u32 s38, s38, 0
	v_mfma_f32_16x16x32_bf16 v[36:39], v[206:209], v[180:183], v[36:39]
	s_cmpk_gt_u32 s3, 0x55
	v_mfma_f32_16x16x32_bf16 v[32:35], v[214:217], v[180:183], v[32:35]
	s_mov_b64 s[8:9], s[10:11]
	v_mfma_f32_16x16x32_bf16 v[20:23], v[206:209], v[188:191], v[20:23]
	v_mfma_f32_16x16x32_bf16 v[16:19], v[214:217], v[188:191], v[16:19]
	v_mfma_f32_16x16x32_bf16 v[4:7], v[206:209], v[198:201], v[4:7]
	v_mfma_f32_16x16x32_bf16 v[0:3], v[214:217], v[198:201], v[0:3]
	s_barrier
	s_setprio 0
	s_cbranch_scc0 .LBB1_1239
	s_waitcnt lgkmcnt(0)
	v_mov_b32_e32 v152, v147
	v_mov_b32_e32 v144, v146
	s_lshl_b32 s2, s2, 8
	s_add_i32 s2, s2, s29
	s_lshl_b32 s3, s4, 8
	v_add_u32_e32 v152, s2, v152
	s_or_b32 s3, s3, s54
	v_ashrrev_i32_e32 v153, 31, v152
	v_lshl_add_u32 v144, v144, 3, s3
	v_lshlrev_b64 v[152:153], 12, v[152:153]
	v_ashrrev_i32_e32 v145, 31, v144
	v_lshl_add_u64 v[152:153], s[46:47], 0, v[152:153]
	v_lshl_add_u64 v[144:145], v[144:145], 1, v[152:153]
	global_load_dwordx4 v[160:163], v[144:145], off
	global_load_dwordx4 v[164:167], v[144:145], off offset:256
	s_mov_b64 s[98:99], 0x10000
	v_lshl_add_u64 v[154:155], v[144:145], 0, s[98:99]
	global_load_dwordx4 v[168:171], v[154:155], off
	global_load_dwordx4 v[172:175], v[154:155], off offset:256
	s_mov_b64 s[98:99], 0x20000
	v_lshl_add_u64 v[154:155], v[144:145], 0, s[98:99]
	global_load_dwordx4 v[176:179], v[154:155], off
	global_load_dwordx4 v[180:183], v[154:155], off offset:256
	s_mov_b64 s[98:99], 0x30000
	v_lshl_add_u64 v[154:155], v[144:145], 0, s[98:99]
	global_load_dwordx4 v[184:187], v[154:155], off
	global_load_dwordx4 v[188:191], v[154:155], off offset:256
	s_mov_b64 s[98:99], 0x80000
	v_lshl_add_u64 v[154:155], v[144:145], 0, s[98:99]
	global_load_dwordx4 v[192:195], v[154:155], off
	global_load_dwordx4 v[198:201], v[154:155], off offset:256
	s_mov_b64 s[98:99], 0x90000
	v_lshl_add_u64 v[154:155], v[144:145], 0, s[98:99]
	global_load_dwordx4 v[202:205], v[154:155], off
	global_load_dwordx4 v[206:209], v[154:155], off offset:256
	s_mov_b64 s[98:99], 0xa0000
	v_lshl_add_u64 v[154:155], v[144:145], 0, s[98:99]
	global_load_dwordx4 v[210:213], v[154:155], off
	global_load_dwordx4 v[214:217], v[154:155], off offset:256
	s_mov_b64 s[98:99], 0xb0000
	v_lshl_add_u64 v[154:155], v[144:145], 0, s[98:99]
	global_load_dwordx4 v[248:251], v[154:155], off
	global_load_dwordx4 v[252:255], v[154:155], off offset:256
	s_waitcnt vmcnt(15)
	s_nop 1
	v_mov_b32_e32 v152, v160
	v_mov_b32_e32 v153, v161
	v_mov_b32_e32 v154, v162
	v_mov_b32_e32 v155, v163
	s_mov_b64 s[2:3], 0x10000
	s_mov_b32 s4, s37
	s_mov_b64 s[10:11], s[6:7]
	s_mov_b64 s[8:9], s[42:43]
	s_waitcnt lgkmcnt(0)
	v_lshlrev_b32_e32 v156, 16, v152
	v_and_b32_e32 v157, 0xffff0000, v152
	v_lshlrev_b32_e32 v152, 16, v153
	v_and_b32_e32 v153, 0xffff0000, v153
	v_lshlrev_b32_e32 v158, 16, v154
	v_and_b32_e32 v159, 0xffff0000, v154
	v_lshlrev_b32_e32 v154, 16, v155
	v_and_b32_e32 v155, 0xffff0000, v155
	v_pk_add_f32 v[126:127], v[126:127], v[152:153]
	v_pk_add_f32 v[124:125], v[124:125], v[156:157]
	v_pk_add_f32 v[152:153], v[122:123], v[154:155]
	v_pk_add_f32 v[122:123], v[120:121], v[158:159]
	v_cvt_pk_bf16_f32 v120, v124, v125
	v_cvt_pk_bf16_f32 v121, v126, v127
	v_cvt_pk_bf16_f32 v122, v122, v123
	v_cvt_pk_bf16_f32 v123, v152, v153
	global_store_dwordx4 v[144:145], v[120:123], off
	s_waitcnt vmcnt(15)
; DI unsigned pack2(float a, float b) { f32x2 v = {a, b}; hwbf16x2 r = __builtin_convertvector(v, hwbf16x2); return __builtin_bit_cast(unsigned, r); }
; DI float bflo(unsigned w) { return __uint_as_float(w << 16); }
; DI float bfhi(unsigned w) { return __uint_as_float(w & 0xffff0000u); }
;     DI void operator()(const f32x4 (&acc)[2][2][4][2], const Unit& u, int wr, int wc, int fr, int fq) const {
;     ...
;         for (int ai = 0; ai < 2; ++ai)
; #pragma unroll
;             for (int m = 0; m < 4; ++m) { const size_t ro = (size_t)(row0 + ai * HALF + m * 16) * D + col0;
; #pragma unroll
;                 for (int bj = 0; bj < 2; ++bj) {
;                     f32x4 x0, x1;
;                     if constexpr (IB) { const u32x4 w = *(const u32x4*)((const bf16_t*)Xin + ro + bj * HALF);
;                         x0 = (f32x4){bflo(w[0]), bfhi(w[0]), bflo(w[1]), bfhi(w[1])}; x1 = (f32x4){bflo(w[2]), bfhi(w[2]), bflo(w[3]), bfhi(w[3])}; }
;                     else { x0 = *(const f32x4*)((const float*)Xin + ro + bj * HALF); x1 = *(const f32x4*)((const float*)Xin + ro + bj * HALF + 4); }
;                     x0 += acc[ai][bj][m][0] * sc[bj][0]; x1 += acc[ai][bj][m][1] * sc[bj][1];
;                     if constexpr (OB) { u32x4 o; o[0] = pack2(x0[0], x0[1]); o[1] = pack2(x0[2], x0[3]); o[2] = pack2(x1[0], x1[1]); o[3] = pack2(x1[2], x1[3]);
;                         *(u32x4*)((bf16_t*)Xout + ro + bj * HALF) = o; }
;                     else { *(f32x4*)((float*)Xout + ro + bj * HALF) = x0; *(f32x4*)((float*)Xout + ro + bj * HALF + 4) = x1; } } }
	s_nop 1
	v_mov_b32_e32 v120, v164
	v_mov_b32_e32 v121, v165
	v_mov_b32_e32 v122, v166
	v_mov_b32_e32 v123, v167
	s_waitcnt lgkmcnt(0)
	v_lshlrev_b32_e32 v124, 16, v120
	v_and_b32_e32 v125, 0xffff0000, v120
	v_lshlrev_b32_e32 v120, 16, v121
	v_and_b32_e32 v121, 0xffff0000, v121
	v_lshlrev_b32_e32 v126, 16, v122
	v_and_b32_e32 v127, 0xffff0000, v122
	v_lshlrev_b32_e32 v122, 16, v123
	v_and_b32_e32 v123, 0xffff0000, v123
	v_pk_add_f32 v[116:117], v[116:117], v[124:125]
	v_pk_add_f32 v[118:119], v[118:119], v[120:121]
	v_pk_add_f32 v[120:121], v[114:115], v[122:123]
	v_pk_add_f32 v[114:115], v[112:113], v[126:127]
	v_cvt_pk_bf16_f32 v112, v116, v117
	v_lshl_add_u64 v[116:117], v[144:145], 0, s[2:3]
	s_mov_b32 s2, 0x10000
	v_cvt_pk_bf16_f32 v113, v118, v119
	v_add_co_u32_e32 v118, vcc, s2, v144
	v_cvt_pk_bf16_f32 v114, v114, v115
	v_cvt_pk_bf16_f32 v115, v120, v121
	v_addc_co_u32_e32 v119, vcc, 0, v145, vcc
	global_store_dwordx4 v[144:145], v[112:115], off offset:256
	s_waitcnt vmcnt(15)
	s_nop 1
	v_mov_b32_e32 v112, v168
	v_mov_b32_e32 v113, v169
	v_mov_b32_e32 v114, v170
	v_mov_b32_e32 v115, v171
	s_mov_b64 s[2:3], 0x20000
	s_waitcnt lgkmcnt(0)
	v_lshlrev_b32_e32 v120, 16, v112
	v_and_b32_e32 v121, 0xffff0000, v112
	v_lshlrev_b32_e32 v112, 16, v113
	v_and_b32_e32 v113, 0xffff0000, v113
	v_lshlrev_b32_e32 v122, 16, v114
	v_and_b32_e32 v123, 0xffff0000, v114
	v_lshlrev_b32_e32 v114, 16, v115
	v_and_b32_e32 v115, 0xffff0000, v115
	v_pk_add_f32 v[110:111], v[110:111], v[112:113]
	v_pk_add_f32 v[108:109], v[108:109], v[120:121]
	v_pk_add_f32 v[112:113], v[106:107], v[114:115]
	v_pk_add_f32 v[106:107], v[104:105], v[122:123]
	v_cvt_pk_bf16_f32 v104, v108, v109
	v_cvt_pk_bf16_f32 v105, v110, v111
	v_cvt_pk_bf16_f32 v106, v106, v107
	v_cvt_pk_bf16_f32 v107, v112, v113
	global_store_dwordx4 v[118:119], v[104:107], off
	s_waitcnt vmcnt(15)
	s_nop 1
	v_mov_b32_e32 v104, v172
	v_mov_b32_e32 v105, v173
	v_mov_b32_e32 v106, v174
	v_mov_b32_e32 v107, v175
	s_waitcnt lgkmcnt(0)
	v_lshlrev_b32_e32 v108, 16, v104
	v_and_b32_e32 v109, 0xffff0000, v104
	v_lshlrev_b32_e32 v104, 16, v105
	v_and_b32_e32 v105, 0xffff0000, v105
	v_lshlrev_b32_e32 v110, 16, v106
	v_and_b32_e32 v111, 0xffff0000, v106
	v_lshlrev_b32_e32 v106, 16, v107
	v_and_b32_e32 v107, 0xffff0000, v107
	v_pk_add_f32 v[100:101], v[100:101], v[108:109]
	v_pk_add_f32 v[102:103], v[102:103], v[104:105]
	v_pk_add_f32 v[104:105], v[98:99], v[106:107]
	v_pk_add_f32 v[98:99], v[96:97], v[110:111]
	v_cvt_pk_bf16_f32 v96, v100, v101
	v_lshl_add_u64 v[100:101], v[144:145], 0, s[2:3]
	s_mov_b32 s2, 0x20000
	v_cvt_pk_bf16_f32 v97, v102, v103
	v_add_co_u32_e32 v102, vcc, s2, v144
	v_cvt_pk_bf16_f32 v98, v98, v99
	v_cvt_pk_bf16_f32 v99, v104, v105
	v_addc_co_u32_e32 v103, vcc, 0, v145, vcc
	global_store_dwordx4 v[116:117], v[96:99], off offset:256
	s_waitcnt vmcnt(15)
	s_nop 1
	v_mov_b32_e32 v96, v176
	v_mov_b32_e32 v97, v177
	v_mov_b32_e32 v98, v178
	v_mov_b32_e32 v99, v179
	s_mov_b64 s[2:3], 0x30000
	s_waitcnt lgkmcnt(0)
	v_lshlrev_b32_e32 v104, 16, v96
	v_and_b32_e32 v105, 0xffff0000, v96
	v_lshlrev_b32_e32 v96, 16, v97
	v_and_b32_e32 v97, 0xffff0000, v97
	v_lshlrev_b32_e32 v106, 16, v98
	v_and_b32_e32 v107, 0xffff0000, v98
	v_lshlrev_b32_e32 v98, 16, v99
	v_and_b32_e32 v99, 0xffff0000, v99
	v_pk_add_f32 v[94:95], v[94:95], v[96:97]
	v_pk_add_f32 v[92:93], v[92:93], v[104:105]
	v_pk_add_f32 v[96:97], v[90:91], v[98:99]
	v_pk_add_f32 v[90:91], v[88:89], v[106:107]
	v_cvt_pk_bf16_f32 v88, v92, v93
	v_cvt_pk_bf16_f32 v89, v94, v95
	v_cvt_pk_bf16_f32 v90, v90, v91
	v_cvt_pk_bf16_f32 v91, v96, v97
	global_store_dwordx4 v[102:103], v[88:91], off
	s_waitcnt vmcnt(15)
	s_nop 1
	v_mov_b32_e32 v88, v180
	v_mov_b32_e32 v89, v181
	v_mov_b32_e32 v90, v182
	v_mov_b32_e32 v91, v183
	s_waitcnt lgkmcnt(0)
	v_lshlrev_b32_e32 v92, 16, v88
	v_and_b32_e32 v93, 0xffff0000, v88
	v_lshlrev_b32_e32 v88, 16, v89
	v_and_b32_e32 v89, 0xffff0000, v89
	v_lshlrev_b32_e32 v94, 16, v90
	v_and_b32_e32 v95, 0xffff0000, v90
	v_lshlrev_b32_e32 v90, 16, v91
	v_and_b32_e32 v91, 0xffff0000, v91
	v_pk_add_f32 v[86:87], v[86:87], v[88:89]
	v_pk_add_f32 v[84:85], v[84:85], v[92:93]
	v_pk_add_f32 v[88:89], v[82:83], v[90:91]
	v_pk_add_f32 v[82:83], v[80:81], v[94:95]
	v_cvt_pk_bf16_f32 v80, v84, v85
	v_cvt_pk_bf16_f32 v81, v86, v87
	v_cvt_pk_bf16_f32 v82, v82, v83
	v_cvt_pk_bf16_f32 v83, v88, v89
	global_store_dwordx4 v[100:101], v[80:83], off offset:256
	s_nop 1
	v_lshl_add_u64 v[80:81], v[144:145], 0, s[2:3]
	s_mov_b32 s2, 0x30000
	v_add_co_u32_e32 v86, vcc, s2, v144
	s_mov_b64 s[2:3], 0x80000
	s_nop 0
	v_addc_co_u32_e32 v87, vcc, 0, v145, vcc
	s_waitcnt vmcnt(15)
	s_nop 1
	v_mov_b32_e32 v82, v184
	v_mov_b32_e32 v83, v185
	v_mov_b32_e32 v84, v186
	v_mov_b32_e32 v85, v187
	s_waitcnt lgkmcnt(0)
	v_lshlrev_b32_e32 v88, 16, v82
	v_and_b32_e32 v89, 0xffff0000, v82
	v_lshlrev_b32_e32 v82, 16, v83
	v_and_b32_e32 v83, 0xffff0000, v83
	v_lshlrev_b32_e32 v90, 16, v84
	v_and_b32_e32 v91, 0xffff0000, v84
	v_lshlrev_b32_e32 v84, 16, v85
	v_and_b32_e32 v85, 0xffff0000, v85
	v_pk_add_f32 v[78:79], v[78:79], v[82:83]
	v_pk_add_f32 v[76:77], v[76:77], v[88:89]
	v_pk_add_f32 v[82:83], v[74:75], v[84:85]
	v_pk_add_f32 v[74:75], v[72:73], v[90:91]
	v_cvt_pk_bf16_f32 v72, v76, v77
	v_cvt_pk_bf16_f32 v73, v78, v79
	v_cvt_pk_bf16_f32 v74, v74, v75
	v_cvt_pk_bf16_f32 v75, v82, v83
	global_store_dwordx4 v[86:87], v[72:75], off
	s_waitcnt vmcnt(15)
	s_nop 1
	v_mov_b32_e32 v72, v188
	v_mov_b32_e32 v73, v189
	v_mov_b32_e32 v74, v190
	v_mov_b32_e32 v75, v191
	s_waitcnt lgkmcnt(0)
; DI unsigned pack2(float a, float b) { f32x2 v = {a, b}; hwbf16x2 r = __builtin_convertvector(v, hwbf16x2); return __builtin_bit_cast(unsigned, r); }
; DI float bflo(unsigned w) { return __uint_as_float(w << 16); }
; DI float bfhi(unsigned w) { return __uint_as_float(w & 0xffff0000u); }
;     DI void operator()(const f32x4 (&acc)[2][2][4][2], const Unit& u, int wr, int wc, int fr, int fq) const {
;     ...
;         for (int ai = 0; ai < 2; ++ai)
; #pragma unroll
;             for (int m = 0; m < 4; ++m) { const size_t ro = (size_t)(row0 + ai * HALF + m * 16) * D + col0;
; #pragma unroll
;                 for (int bj = 0; bj < 2; ++bj) {
;                     f32x4 x0, x1;
;                     if constexpr (IB) { const u32x4 w = *(const u32x4*)((const bf16_t*)Xin + ro + bj * HALF);
;                         x0 = (f32x4){bflo(w[0]), bfhi(w[0]), bflo(w[1]), bfhi(w[1])}; x1 = (f32x4){bflo(w[2]), bfhi(w[2]), bflo(w[3]), bfhi(w[3])}; }
;                     else { x0 = *(const f32x4*)((const float*)Xin + ro + bj * HALF); x1 = *(const f32x4*)((const float*)Xin + ro + bj * HALF + 4); }
;                     x0 += acc[ai][bj][m][0] * sc[bj][0]; x1 += acc[ai][bj][m][1] * sc[bj][1];
;                     if constexpr (OB) { u32x4 o; o[0] = pack2(x0[0], x0[1]); o[1] = pack2(x0[2], x0[3]); o[2] = pack2(x1[0], x1[1]); o[3] = pack2(x1[2], x1[3]);
;                         *(u32x4*)((bf16_t*)Xout + ro + bj * HALF) = o; }
;                     else { *(f32x4*)((float*)Xout + ro + bj * HALF) = x0; *(f32x4*)((float*)Xout + ro + bj * HALF + 4) = x1; } } }
	v_lshlrev_b32_e32 v76, 16, v72
	v_and_b32_e32 v77, 0xffff0000, v72
	v_lshlrev_b32_e32 v72, 16, v73
	v_and_b32_e32 v73, 0xffff0000, v73
	v_lshlrev_b32_e32 v78, 16, v74
	v_and_b32_e32 v79, 0xffff0000, v74
	v_lshlrev_b32_e32 v74, 16, v75
	v_and_b32_e32 v75, 0xffff0000, v75
	v_pk_add_f32 v[70:71], v[70:71], v[72:73]
	v_pk_add_f32 v[68:69], v[68:69], v[76:77]
	v_pk_add_f32 v[72:73], v[66:67], v[74:75]
	v_pk_add_f32 v[66:67], v[64:65], v[78:79]
	v_cvt_pk_bf16_f32 v64, v68, v69
	v_cvt_pk_bf16_f32 v65, v70, v71
	v_cvt_pk_bf16_f32 v66, v66, v67
	v_cvt_pk_bf16_f32 v67, v72, v73
	global_store_dwordx4 v[80:81], v[64:67], off offset:256
	s_nop 1
	v_lshl_add_u64 v[64:65], v[144:145], 0, s[2:3]
	s_mov_b32 s2, 0x80000
	v_add_co_u32_e32 v70, vcc, s2, v144
	s_mov_b64 s[2:3], 0x90000
	s_nop 0
	v_addc_co_u32_e32 v71, vcc, 0, v145, vcc
	s_waitcnt vmcnt(15)
	s_nop 1
	v_mov_b32_e32 v66, v192
	v_mov_b32_e32 v67, v193
	v_mov_b32_e32 v68, v194
	v_mov_b32_e32 v69, v195
	s_waitcnt lgkmcnt(0)
	v_lshlrev_b32_e32 v72, 16, v66
	v_and_b32_e32 v73, 0xffff0000, v66
	v_lshlrev_b32_e32 v66, 16, v67
	v_and_b32_e32 v67, 0xffff0000, v67
	v_lshlrev_b32_e32 v74, 16, v68
	v_and_b32_e32 v75, 0xffff0000, v68
	v_lshlrev_b32_e32 v68, 16, v69
	v_and_b32_e32 v69, 0xffff0000, v69
	v_pk_add_f32 v[62:63], v[62:63], v[66:67]
	v_pk_add_f32 v[60:61], v[60:61], v[72:73]
	v_pk_add_f32 v[66:67], v[58:59], v[68:69]
	v_pk_add_f32 v[58:59], v[56:57], v[74:75]
	v_cvt_pk_bf16_f32 v56, v60, v61
	v_cvt_pk_bf16_f32 v57, v62, v63
	v_cvt_pk_bf16_f32 v58, v58, v59
	v_cvt_pk_bf16_f32 v59, v66, v67
	global_store_dwordx4 v[70:71], v[56:59], off
	s_waitcnt vmcnt(15)
	s_nop 1
	v_mov_b32_e32 v56, v198
	v_mov_b32_e32 v57, v199
	v_mov_b32_e32 v58, v200
	v_mov_b32_e32 v59, v201
	s_waitcnt lgkmcnt(0)
	v_lshlrev_b32_e32 v60, 16, v56
	v_and_b32_e32 v61, 0xffff0000, v56
	v_lshlrev_b32_e32 v56, 16, v57
	v_and_b32_e32 v57, 0xffff0000, v57
	v_lshlrev_b32_e32 v62, 16, v58
	v_and_b32_e32 v63, 0xffff0000, v58
	v_lshlrev_b32_e32 v58, 16, v59
	v_and_b32_e32 v59, 0xffff0000, v59
	v_pk_add_f32 v[54:55], v[54:55], v[56:57]
	v_pk_add_f32 v[52:53], v[52:53], v[60:61]
	v_pk_add_f32 v[56:57], v[50:51], v[58:59]
	v_pk_add_f32 v[50:51], v[48:49], v[62:63]
	v_cvt_pk_bf16_f32 v48, v52, v53
	v_cvt_pk_bf16_f32 v49, v54, v55
	v_cvt_pk_bf16_f32 v50, v50, v51
	v_cvt_pk_bf16_f32 v51, v56, v57
	global_store_dwordx4 v[64:65], v[48:51], off offset:256
	s_nop 1
	v_lshl_add_u64 v[48:49], v[144:145], 0, s[2:3]
	s_mov_b32 s2, 0x90000
	v_add_co_u32_e32 v54, vcc, s2, v144
	s_mov_b64 s[2:3], 0xa0000
	s_nop 0
	v_addc_co_u32_e32 v55, vcc, 0, v145, vcc
	s_waitcnt vmcnt(15)
	s_nop 1
	v_mov_b32_e32 v50, v202
	v_mov_b32_e32 v51, v203
	v_mov_b32_e32 v52, v204
	v_mov_b32_e32 v53, v205
	s_waitcnt lgkmcnt(0)
	v_lshlrev_b32_e32 v56, 16, v50
	v_and_b32_e32 v57, 0xffff0000, v50
	v_lshlrev_b32_e32 v50, 16, v51
	v_and_b32_e32 v51, 0xffff0000, v51
	v_lshlrev_b32_e32 v58, 16, v52
	v_and_b32_e32 v59, 0xffff0000, v52
	v_lshlrev_b32_e32 v52, 16, v53
	v_and_b32_e32 v53, 0xffff0000, v53
	v_pk_add_f32 v[46:47], v[46:47], v[50:51]
	v_pk_add_f32 v[44:45], v[44:45], v[56:57]
	v_pk_add_f32 v[50:51], v[42:43], v[52:53]
	v_pk_add_f32 v[42:43], v[40:41], v[58:59]
	v_cvt_pk_bf16_f32 v40, v44, v45
	v_cvt_pk_bf16_f32 v41, v46, v47
	v_cvt_pk_bf16_f32 v42, v42, v43
	v_cvt_pk_bf16_f32 v43, v50, v51
	global_store_dwordx4 v[54:55], v[40:43], off
	s_waitcnt vmcnt(15)
	s_nop 1
	v_mov_b32_e32 v40, v206
	v_mov_b32_e32 v41, v207
	v_mov_b32_e32 v42, v208
	v_mov_b32_e32 v43, v209
	s_waitcnt lgkmcnt(0)
; DI unsigned pack2(float a, float b) { f32x2 v = {a, b}; hwbf16x2 r = __builtin_convertvector(v, hwbf16x2); return __builtin_bit_cast(unsigned, r); }
; DI float bflo(unsigned w) { return __uint_as_float(w << 16); }
; DI float bfhi(unsigned w) { return __uint_as_float(w & 0xffff0000u); }
;     DI const char* a(const Unit& u) const { return (const char*)(A + (size_t)u.pm * BM * lda); }
;     DI const char* a(const Unit& u) const { return (const char*)(A + (size_t)u.pm * BM * 2048 + (u.pn >> 1) * 512); }
;     DI const char* a(const Unit& u) const { return (const char*)((u.pn < 12 ? A1 : A2) + (size_t)u.pm * BM * 512); }
; #define PG8_BAR __builtin_amdgcn_s_barrier()
;     DI void operator()(const f32x4 (&acc)[2][2][4][2], const Unit& u, int wr, int wc, int fr, int fq) const {
;     ...
;                 for (int bj = 0; bj < 2; ++bj) {
;                     f32x4 x0, x1;
;                     if constexpr (IB) { const u32x4 w = *(const u32x4*)((const bf16_t*)Xin + ro + bj * HALF);
;                         x0 = (f32x4){bflo(w[0]), bfhi(w[0]), bflo(w[1]), bfhi(w[1])}; x1 = (f32x4){bflo(w[2]), bfhi(w[2]), bflo(w[3]), bfhi(w[3])}; }
;                     else { x0 = *(const f32x4*)((const float*)Xin + ro + bj * HALF); x1 = *(const f32x4*)((const float*)Xin + ro + bj * HALF + 4); }
;                     x0 += acc[ai][bj][m][0] * sc[bj][0]; x1 += acc[ai][bj][m][1] * sc[bj][1];
;                     if constexpr (OB) { u32x4 o; o[0] = pack2(x0[0], x0[1]); o[1] = pack2(x0[2], x0[3]); o[2] = pack2(x1[0], x1[1]); o[3] = pack2(x1[2], x1[3]);
;                         *(u32x4*)((bf16_t*)Xout + ro + bj * HALF) = o; }
;                     else { *(f32x4*)((float*)Xout + ro + bj * HALF) = x0; *(f32x4*)((float*)Xout + ro + bj * HALF + 4) = x1; } } }
; template <class Map, class Epi>
; DI void gemm_phase(LAS unsigned char* lds, const Map& MP, const Epi& E, const int nM, const int nN, const int K, const int lda, const int ldb) {
;     ...
;         if (!has_next) break;
; #pragma unroll
;         for (int a = 0; a < 2; ++a)
; #pragma unroll
;             for (int b = 0; b < 2; ++b)
; #pragma unroll
;                 for (int m = 0; m < 4; ++m)
; #pragma unroll
;                     for (int n = 0; n < 2; ++n) acc[a][b][m][n] = (f32x4){0.f, 0.f, 0.f, 0.f};
;         cur = nxt; cA = nA; cB = nB; ++ui;
;     }
;     PG8_WAIT_V(0);
;     if (wr == 0) PG8_BAR;
;     PG8_BAR;
	v_lshlrev_b32_e32 v44, 16, v40
	v_and_b32_e32 v45, 0xffff0000, v40
	v_lshlrev_b32_e32 v40, 16, v41
	v_and_b32_e32 v41, 0xffff0000, v41
	v_lshlrev_b32_e32 v46, 16, v42
	v_and_b32_e32 v47, 0xffff0000, v42
	v_lshlrev_b32_e32 v42, 16, v43
	v_and_b32_e32 v43, 0xffff0000, v43
	v_pk_add_f32 v[38:39], v[38:39], v[40:41]
	v_pk_add_f32 v[36:37], v[36:37], v[44:45]
	v_pk_add_f32 v[40:41], v[34:35], v[42:43]
	v_pk_add_f32 v[34:35], v[32:33], v[46:47]
	v_cvt_pk_bf16_f32 v32, v36, v37
	v_cvt_pk_bf16_f32 v33, v38, v39
	v_cvt_pk_bf16_f32 v34, v34, v35
	v_cvt_pk_bf16_f32 v35, v40, v41
	global_store_dwordx4 v[48:49], v[32:35], off offset:256
	s_nop 1
	v_lshl_add_u64 v[32:33], v[144:145], 0, s[2:3]
	s_mov_b32 s2, 0xa0000
	v_add_co_u32_e32 v38, vcc, s2, v144
	s_mov_b64 s[2:3], 0xb0000
	s_nop 0
	v_addc_co_u32_e32 v39, vcc, 0, v145, vcc
	s_waitcnt vmcnt(15)
	s_nop 1
	v_mov_b32_e32 v34, v210
	v_mov_b32_e32 v35, v211
	v_mov_b32_e32 v36, v212
	v_mov_b32_e32 v37, v213
	s_waitcnt lgkmcnt(0)
	v_lshlrev_b32_e32 v40, 16, v34
	v_and_b32_e32 v41, 0xffff0000, v34
	v_lshlrev_b32_e32 v34, 16, v35
	v_and_b32_e32 v35, 0xffff0000, v35
	v_lshlrev_b32_e32 v42, 16, v36
	v_and_b32_e32 v43, 0xffff0000, v36
	v_lshlrev_b32_e32 v36, 16, v37
	v_and_b32_e32 v37, 0xffff0000, v37
	v_pk_add_f32 v[30:31], v[30:31], v[34:35]
	v_pk_add_f32 v[28:29], v[28:29], v[40:41]
	v_pk_add_f32 v[34:35], v[26:27], v[36:37]
	v_pk_add_f32 v[26:27], v[24:25], v[42:43]
	v_cvt_pk_bf16_f32 v24, v28, v29
	v_cvt_pk_bf16_f32 v25, v30, v31
	v_cvt_pk_bf16_f32 v26, v26, v27
	v_cvt_pk_bf16_f32 v27, v34, v35
	global_store_dwordx4 v[38:39], v[24:27], off
	s_waitcnt vmcnt(15)
	s_nop 1
	v_mov_b32_e32 v24, v214
	v_mov_b32_e32 v25, v215
	v_mov_b32_e32 v26, v216
	v_mov_b32_e32 v27, v217
	s_waitcnt lgkmcnt(0)
	v_lshlrev_b32_e32 v28, 16, v24
	v_and_b32_e32 v29, 0xffff0000, v24
	v_lshlrev_b32_e32 v24, 16, v25
	v_and_b32_e32 v25, 0xffff0000, v25
	v_lshlrev_b32_e32 v30, 16, v26
	v_and_b32_e32 v31, 0xffff0000, v26
	v_lshlrev_b32_e32 v26, 16, v27
	v_and_b32_e32 v27, 0xffff0000, v27
	v_pk_add_f32 v[22:23], v[22:23], v[24:25]
	v_pk_add_f32 v[20:21], v[20:21], v[28:29]
	v_pk_add_f32 v[24:25], v[18:19], v[26:27]
	v_pk_add_f32 v[18:19], v[16:17], v[30:31]
	v_cvt_pk_bf16_f32 v16, v20, v21
	v_cvt_pk_bf16_f32 v17, v22, v23
	v_cvt_pk_bf16_f32 v18, v18, v19
	v_cvt_pk_bf16_f32 v19, v24, v25
	global_store_dwordx4 v[32:33], v[16:19], off offset:256
	s_nop 1
	v_lshl_add_u64 v[16:17], v[144:145], 0, s[2:3]
	s_mov_b32 s2, 0xb0000
	v_add_co_u32_e32 v22, vcc, s2, v144
	s_mov_b32 s2, s55
	s_nop 0
	v_addc_co_u32_e32 v23, vcc, 0, v145, vcc
	s_waitcnt vmcnt(15)
	s_nop 1
	v_mov_b32_e32 v18, v248
	v_mov_b32_e32 v19, v249
	v_mov_b32_e32 v20, v250
	v_mov_b32_e32 v21, v251
	s_and_b64 vcc, exec, s[40:41]
	s_waitcnt lgkmcnt(0)
	v_lshlrev_b32_e32 v24, 16, v18
	v_and_b32_e32 v25, 0xffff0000, v18
	v_lshlrev_b32_e32 v18, 16, v19
	v_and_b32_e32 v19, 0xffff0000, v19
	v_lshlrev_b32_e32 v26, 16, v20
	v_and_b32_e32 v27, 0xffff0000, v20
	v_lshlrev_b32_e32 v20, 16, v21
	v_and_b32_e32 v21, 0xffff0000, v21
	v_pk_add_f32 v[14:15], v[14:15], v[18:19]
	v_pk_add_f32 v[12:13], v[12:13], v[24:25]
	v_pk_add_f32 v[18:19], v[10:11], v[20:21]
	v_pk_add_f32 v[10:11], v[8:9], v[26:27]
	v_cvt_pk_bf16_f32 v8, v12, v13
	v_cvt_pk_bf16_f32 v9, v14, v15
	v_cvt_pk_bf16_f32 v10, v10, v11
	v_cvt_pk_bf16_f32 v11, v18, v19
	global_store_dwordx4 v[22:23], v[8:11], off
	s_waitcnt vmcnt(15)
	s_nop 1
	v_mov_b32_e32 v8, v252
	v_mov_b32_e32 v9, v253
	v_mov_b32_e32 v10, v254
	v_mov_b32_e32 v11, v255
	s_waitcnt lgkmcnt(0)
	v_lshlrev_b32_e32 v12, 16, v8
	v_and_b32_e32 v13, 0xffff0000, v8
	v_lshlrev_b32_e32 v8, 16, v9
	v_and_b32_e32 v9, 0xffff0000, v9
	v_lshlrev_b32_e32 v14, 16, v10
	v_and_b32_e32 v15, 0xffff0000, v10
	v_lshlrev_b32_e32 v10, 16, v11
	v_and_b32_e32 v11, 0xffff0000, v11
	v_pk_add_f32 v[6:7], v[6:7], v[8:9]
	v_pk_add_f32 v[4:5], v[4:5], v[12:13]
	v_pk_add_f32 v[8:9], v[2:3], v[10:11]
	v_pk_add_f32 v[2:3], v[0:1], v[14:15]
	v_cvt_pk_bf16_f32 v0, v4, v5
	v_cvt_pk_bf16_f32 v1, v6, v7
	v_cvt_pk_bf16_f32 v2, v2, v3
	v_cvt_pk_bf16_f32 v3, v8, v9
	global_store_dwordx4 v[16:17], v[0:3], off offset:256
	s_cbranch_vccz .LBB1_1232
	s_waitcnt vmcnt(0)
	s_cmpk_gt_u32 s17, 0xff
	s_cbranch_scc1 .LBB1_1243
	s_barrier

; #define PG8_STAGE(bufoff, gbase, voff) do { _Pragma("unroll") for (int _i = 0; _i < 2; ++_i) \
;         __builtin_amdgcn_global_load_lds((const unsigned*)((const char*)(gbase) + (voff)[_i]), (LAS unsigned*)(lds + (bufoff) + ldsw + _i * 8192), 16, 0, 0); } while (0)
; #define PG8_LDA(dst, b, h) do { _Pragma("unroll") for (int m = 0; m < 4; ++m) _Pragma("unroll") for (int k = 0; k < 2; ++k) dst[m][k] = *(const LAS bf16x8*)(lds + PG8_SA(b, h) + aoff + m * 2048 + k * 1024); } while (0)
; #define PG8_WAIT_V(n) asm volatile("s_waitcnt vmcnt(" #n ")" ::: "memory")
; #define PG8_BAR __builtin_amdgcn_s_barrier()
; template <class Map, class Epi>
; DI void gemm_phase(LAS unsigned char* lds, const Map& MP, const Epi& E, const int nM, const int nN, const int K, const int lda, const int ldb) {
;     ...
;         for (int t = 0; t < nt; t += 2) {
;             const bool last = (t == nt - 2);
;             const char* a1 = cA + (size_t)(t + 1) * kstep;
;             const char* a2 = last ? nA : cA + (size_t)(t + 2) * kstep; const char* b2 = last ? nB : cB + (size_t)(t + 2) * kstep;
;             const char* a3 = a2 + kstep; const char* b3 = b2 + kstep;
;             PG8_LDB(B0, 0, 0); PG8_SCHED; PG8_LDA(At, 0, 0); PG8_STAGE(PG8_SA(1, 1), a1 + hstepA, voffA);
;             PG8_WAIT_L(8); PG8_BAR; PG8_WAIT_L(0); PG8_MMA(0, 0, At, B0); PG8_BAR; PG8_SCHED;
;             PG8_LDB(B1, 0, 1); PG8_STAGE(PG8_SB(0, 0), b2, voffB);
;             PG8_BAR; PG8_WAIT_L(0); PG8_MMA(0, 1, At, B1); PG8_BAR;
;             PG8_LDA(At, 0, 1); PG8_STAGE(PG8_SA(0, 0), a2, voffA);
;             PG8_BAR; PG8_WAIT_L(0); PG8_MMA(1, 0, At, B0); PG8_BAR; PG8_SCHED;
;             PG8_STAGE(PG8_SB(0, 1), b2 + hstepB, voffB);
;             PG8_WAIT_V(6); PG8_BAR; PG8_MMA(1, 1, At, B1); PG8_BAR;
;             PG8_LDB(B0, 1, 0); PG8_SCHED; PG8_LDA(At, 1, 0); PG8_STAGE(PG8_SA(0, 1), a2 + hstepA, voffA);
;             PG8_WAIT_L(8); PG8_BAR; PG8_WAIT_L(0); PG8_MMA(0, 0, At, B0); PG8_BAR; PG8_SCHED;
;             PG8_LDB(B1, 1, 1); PG8_STAGE(PG8_SB(1, 0), b3, voffB);
;             PG8_BAR; PG8_WAIT_L(0); PG8_MMA(0, 1, At, B1); PG8_BAR;
;             PG8_LDA(At, 1, 1); PG8_STAGE(PG8_SA(1, 0), a3, voffA);
;             PG8_BAR; PG8_WAIT_L(0); PG8_MMA(1, 0, At, B0); PG8_BAR; PG8_SCHED;
;             PG8_STAGE(PG8_SB(1, 1), b3 + hstepB, voffB);
;             PG8_WAIT_V(6); PG8_BAR; PG8_MMA(1, 1, At, B1); PG8_BAR;
.LBB1_1382:
	s_add_u32 s22, s20, 0xfff80080
	s_addc_u32 s23, s21, -1
	s_cmp_eq_u32 s3, 28
	s_cselect_b32 s25, s15, s23
	s_cselect_b32 s24, s48, s22
	s_cselect_b32 s23, s13, s53
	s_cselect_b32 s22, s49, s52
	s_add_i32 m0, s31, 0xc000
	ds_read_b128 v[166:169], v148
	global_load_lds_dwordx4 v138, s[20:21]
	ds_read_b128 v[170:173], v148 offset:1024
	ds_read_b128 v[174:177], v148 offset:2048
	ds_read_b128 v[178:181], v148 offset:3072
	ds_read_b128 v[182:185], v148 offset:4096
	ds_read_b128 v[186:189], v148 offset:5120
	ds_read_b128 v[190:193], v148 offset:6144
	ds_read_b128 v[198:201], v148 offset:7168
	s_add_i32 m0, s31, 0xe000
	s_nop 0
	global_load_lds_dwordx4 v136, s[20:21]
	s_waitcnt lgkmcnt(8)
	s_setprio 1
	s_barrier
	s_waitcnt lgkmcnt(7)
	v_mfma_f32_16x16x32_bf16 v[124:127], v[150:153], v[166:169], v[124:127]
	v_mfma_f32_16x16x32_bf16 v[120:123], v[158:161], v[166:169], v[120:123]
	s_waitcnt lgkmcnt(5)
	v_mfma_f32_16x16x32_bf16 v[116:119], v[150:153], v[174:177], v[116:119]
	v_mfma_f32_16x16x32_bf16 v[112:115], v[158:161], v[174:177], v[112:115]
	s_waitcnt lgkmcnt(3)
	v_mfma_f32_16x16x32_bf16 v[100:103], v[150:153], v[182:185], v[100:103]
	v_mfma_f32_16x16x32_bf16 v[96:99], v[158:161], v[182:185], v[96:99]
	s_waitcnt lgkmcnt(1)
	v_mfma_f32_16x16x32_bf16 v[84:87], v[150:153], v[190:193], v[84:87]
	v_mfma_f32_16x16x32_bf16 v[80:83], v[158:161], v[190:193], v[80:83]
	v_mfma_f32_16x16x32_bf16 v[124:127], v[154:157], v[170:173], v[124:127]
	s_add_i32 s54, s44, s29
	v_mfma_f32_16x16x32_bf16 v[120:123], v[162:165], v[170:173], v[120:123]
	v_lshl_add_u64 v[194:195], s[22:23], 0, v[132:133]
	v_mfma_f32_16x16x32_bf16 v[116:119], v[154:157], v[178:181], v[116:119]
	v_lshl_add_u64 v[218:219], s[22:23], 0, v[128:129]
	v_mfma_f32_16x16x32_bf16 v[112:115], v[162:165], v[178:181], v[112:115]
	v_mfma_f32_16x16x32_bf16 v[100:103], v[154:157], v[186:189], v[100:103]
	v_mfma_f32_16x16x32_bf16 v[96:99], v[162:165], v[186:189], v[96:99]
	s_waitcnt lgkmcnt(0)
	v_mfma_f32_16x16x32_bf16 v[84:87], v[154:157], v[198:201], v[84:87]
	v_mfma_f32_16x16x32_bf16 v[80:83], v[162:165], v[198:201], v[80:83]
	s_barrier
	s_setprio 0
	s_mov_b32 m0, s54
	ds_read_b128 v[202:205], v149
	global_load_lds_dwordx4 v[194:195], off
	ds_read_b128 v[206:209], v149 offset:1024
	ds_read_b128 v[210:213], v149 offset:2048
	ds_read_b128 v[214:217], v149 offset:3072
	s_add_i32 m0, s54, 0x2000
	s_nop 0
	global_load_lds_dwordx4 v[218:219], off
	s_setprio 1
	s_barrier
	s_waitcnt lgkmcnt(3)
	v_mfma_f32_16x16x32_bf16 v[108:111], v[202:205], v[166:169], v[108:111]
	s_waitcnt lgkmcnt(1)
	v_mfma_f32_16x16x32_bf16 v[104:107], v[210:213], v[166:169], v[104:107]
	v_mfma_f32_16x16x32_bf16 v[92:95], v[202:205], v[174:177], v[92:95]
	v_mfma_f32_16x16x32_bf16 v[88:91], v[210:213], v[174:177], v[88:91]
	v_mfma_f32_16x16x32_bf16 v[76:79], v[202:205], v[182:185], v[76:79]
	v_mfma_f32_16x16x32_bf16 v[72:75], v[210:213], v[182:185], v[72:75]
	v_mfma_f32_16x16x32_bf16 v[68:71], v[202:205], v[190:193], v[68:71]
	v_mfma_f32_16x16x32_bf16 v[64:67], v[210:213], v[190:193], v[64:67]
	v_mfma_f32_16x16x32_bf16 v[108:111], v[206:209], v[170:173], v[108:111]
	v_lshl_add_u64 v[222:223], s[24:25], 0, v[130:131]
	s_mov_b32 m0, s31
	s_waitcnt lgkmcnt(0)
	v_mfma_f32_16x16x32_bf16 v[104:107], v[214:217], v[170:173], v[104:107]
	v_lshl_add_u64 v[220:221], s[24:25], 0, v[134:135]
	v_mfma_f32_16x16x32_bf16 v[92:95], v[206:209], v[178:181], v[92:95]
	v_mfma_f32_16x16x32_bf16 v[88:91], v[214:217], v[178:181], v[88:91]
	v_mfma_f32_16x16x32_bf16 v[76:79], v[206:209], v[186:189], v[76:79]
	v_mfma_f32_16x16x32_bf16 v[72:75], v[214:217], v[186:189], v[72:75]
	v_mfma_f32_16x16x32_bf16 v[68:71], v[206:209], v[198:201], v[68:71]
	v_mfma_f32_16x16x32_bf16 v[64:67], v[214:217], v[198:201], v[64:67]
	s_barrier
	s_setprio 0
	ds_read_b128 v[166:169], v148 offset:16384
	global_load_lds_dwordx4 v[220:221], off
	ds_read_b128 v[170:173], v148 offset:17408
	ds_read_b128 v[174:177], v148 offset:18432
	ds_read_b128 v[178:181], v148 offset:19456
	ds_read_b128 v[182:185], v148 offset:20480
	ds_read_b128 v[186:189], v148 offset:21504
	ds_read_b128 v[190:193], v148 offset:22528
	ds_read_b128 v[198:201], v148 offset:23552
	s_mov_b32 m0, s11
	s_nop 0
	global_load_lds_dwordx4 v[222:223], off
	s_waitcnt vmcnt(10)
	s_setprio 1
	s_barrier
	s_waitcnt lgkmcnt(7)
	v_mfma_f32_16x16x32_bf16 v[60:63], v[150:153], v[166:169], v[60:63]
	v_mfma_f32_16x16x32_bf16 v[56:59], v[158:161], v[166:169], v[56:59]
	s_waitcnt lgkmcnt(5)
	v_mfma_f32_16x16x32_bf16 v[52:55], v[150:153], v[174:177], v[52:55]
	v_mfma_f32_16x16x32_bf16 v[48:51], v[158:161], v[174:177], v[48:51]
	s_waitcnt lgkmcnt(3)
	v_mfma_f32_16x16x32_bf16 v[36:39], v[150:153], v[182:185], v[36:39]
	v_mfma_f32_16x16x32_bf16 v[32:35], v[158:161], v[182:185], v[32:35]
	s_waitcnt lgkmcnt(1)
	v_mfma_f32_16x16x32_bf16 v[20:23], v[150:153], v[190:193], v[20:23]
	v_mfma_f32_16x16x32_bf16 v[16:19], v[158:161], v[190:193], v[16:19]
	v_mfma_f32_16x16x32_bf16 v[60:63], v[154:157], v[170:173], v[60:63]
	s_add_u32 s54, s22, 0x80000
	s_addc_u32 s55, s23, 0
	v_mfma_f32_16x16x32_bf16 v[56:59], v[162:165], v[170:173], v[56:59]
	s_add_i32 s56, s45, s29
	v_mfma_f32_16x16x32_bf16 v[52:55], v[154:157], v[178:181], v[52:55]
	v_mfma_f32_16x16x32_bf16 v[48:51], v[162:165], v[178:181], v[48:51]
	v_mfma_f32_16x16x32_bf16 v[36:39], v[154:157], v[186:189], v[36:39]
	v_mfma_f32_16x16x32_bf16 v[32:35], v[162:165], v[186:189], v[32:35]
	s_waitcnt lgkmcnt(0)
	v_mfma_f32_16x16x32_bf16 v[20:23], v[154:157], v[198:201], v[20:23]
	v_mfma_f32_16x16x32_bf16 v[16:19], v[162:165], v[198:201], v[16:19]
	s_barrier
; #define PG8_STAGE(bufoff, gbase, voff) do { _Pragma("unroll") for (int _i = 0; _i < 2; ++_i) \
;         __builtin_amdgcn_global_load_lds((const unsigned*)((const char*)(gbase) + (voff)[_i]), (LAS unsigned*)(lds + (bufoff) + ldsw + _i * 8192), 16, 0, 0); } while (0)
; #define PG8_LDA(dst, b, h) do { _Pragma("unroll") for (int m = 0; m < 4; ++m) _Pragma("unroll") for (int k = 0; k < 2; ++k) dst[m][k] = *(const LAS bf16x8*)(lds + PG8_SA(b, h) + aoff + m * 2048 + k * 1024); } while (0)
; #define PG8_WAIT_V(n) asm volatile("s_waitcnt vmcnt(" #n ")" ::: "memory")
; #define PG8_BAR __builtin_amdgcn_s_barrier()
; template <class Map, class Epi>
; DI void gemm_phase(LAS unsigned char* lds, const Map& MP, const Epi& E, const int nM, const int nN, const int K, const int lda, const int ldb) {
;     ...
;         for (int t = 0; t < nt; t += 2) {
;             const bool last = (t == nt - 2);
;             const char* a1 = cA + (size_t)(t + 1) * kstep;
;             const char* a2 = last ? nA : cA + (size_t)(t + 2) * kstep; const char* b2 = last ? nB : cB + (size_t)(t + 2) * kstep;
;             const char* a3 = a2 + kstep; const char* b3 = b2 + kstep;
;             PG8_LDB(B0, 0, 0); PG8_SCHED; PG8_LDA(At, 0, 0); PG8_STAGE(PG8_SA(1, 1), a1 + hstepA, voffA);
;             PG8_WAIT_L(8); PG8_BAR; PG8_WAIT_L(0); PG8_MMA(0, 0, At, B0); PG8_BAR; PG8_SCHED;
;             PG8_LDB(B1, 0, 1); PG8_STAGE(PG8_SB(0, 0), b2, voffB);
;             PG8_BAR; PG8_WAIT_L(0); PG8_MMA(0, 1, At, B1); PG8_BAR;
;             PG8_LDA(At, 0, 1); PG8_STAGE(PG8_SA(0, 0), a2, voffA);
;             PG8_BAR; PG8_WAIT_L(0); PG8_MMA(1, 0, At, B0); PG8_BAR; PG8_SCHED;
;             PG8_STAGE(PG8_SB(0, 1), b2 + hstepB, voffB);
;             PG8_WAIT_V(6); PG8_BAR; PG8_MMA(1, 1, At, B1); PG8_BAR;
;             PG8_LDB(B0, 1, 0); PG8_SCHED; PG8_LDA(At, 1, 0); PG8_STAGE(PG8_SA(0, 1), a2 + hstepA, voffA);
;             PG8_WAIT_L(8); PG8_BAR; PG8_WAIT_L(0); PG8_MMA(0, 0, At, B0); PG8_BAR; PG8_SCHED;
;             PG8_LDB(B1, 1, 1); PG8_STAGE(PG8_SB(1, 0), b3, voffB);
;             PG8_BAR; PG8_WAIT_L(0); PG8_MMA(0, 1, At, B1); PG8_BAR;
;             PG8_LDA(At, 1, 1); PG8_STAGE(PG8_SA(1, 0), a3, voffA);
;             PG8_BAR; PG8_WAIT_L(0); PG8_MMA(1, 0, At, B0); PG8_BAR; PG8_SCHED;
;             PG8_STAGE(PG8_SB(1, 1), b3 + hstepB, voffB);
;             PG8_WAIT_V(6); PG8_BAR; PG8_MMA(1, 1, At, B1); PG8_BAR;
	s_setprio 0
	s_mov_b32 m0, s56
	s_nop 0
	global_load_lds_dwordx4 v132, s[54:55]
	s_add_i32 m0, s56, 0x2000
	s_nop 0
	global_load_lds_dwordx4 v128, s[54:55]
	s_waitcnt vmcnt(6)
	s_setprio 1
	s_barrier
	v_mfma_f32_16x16x32_bf16 v[44:47], v[202:205], v[166:169], v[44:47]
	v_mfma_f32_16x16x32_bf16 v[40:43], v[210:213], v[166:169], v[40:43]
	s_add_i32 s54, 0, 0x18000
	v_add_u32_e32 v162, s54, v146
	ds_read_b128 v[150:153], v162
	v_mfma_f32_16x16x32_bf16 v[28:31], v[202:205], v[174:177], v[28:31]
	v_mfma_f32_16x16x32_bf16 v[24:27], v[210:213], v[174:177], v[24:27]
	ds_read_b128 v[154:157], v162 offset:1024
	v_mfma_f32_16x16x32_bf16 v[12:15], v[202:205], v[182:185], v[12:15]
	v_mfma_f32_16x16x32_bf16 v[8:11], v[210:213], v[182:185], v[8:11]
	ds_read_b128 v[158:161], v162 offset:2048
	v_mfma_f32_16x16x32_bf16 v[4:7], v[202:205], v[190:193], v[4:7]
	v_mfma_f32_16x16x32_bf16 v[0:3], v[210:213], v[190:193], v[0:3]
	ds_read_b128 v[162:165], v162 offset:3072
	v_mfma_f32_16x16x32_bf16 v[44:47], v[206:209], v[170:173], v[44:47]
	s_add_u32 s24, s24, 0x80000
	s_addc_u32 s25, s25, 0
	v_mfma_f32_16x16x32_bf16 v[40:43], v[214:217], v[170:173], v[40:43]
	v_mfma_f32_16x16x32_bf16 v[28:31], v[206:209], v[178:181], v[28:31]
	v_mfma_f32_16x16x32_bf16 v[24:27], v[214:217], v[178:181], v[24:27]
	v_mfma_f32_16x16x32_bf16 v[12:15], v[206:209], v[186:189], v[12:15]
	v_mfma_f32_16x16x32_bf16 v[8:11], v[214:217], v[186:189], v[8:11]
	v_mfma_f32_16x16x32_bf16 v[4:7], v[206:209], v[198:201], v[4:7]
	v_mfma_f32_16x16x32_bf16 v[0:3], v[214:217], v[198:201], v[0:3]
	s_barrier
	s_setprio 0
	s_mov_b32 m0, s34
	ds_read_b128 v[166:169], v148 offset:32768
	global_load_lds_dwordx4 v134, s[24:25]
	ds_read_b128 v[170:173], v148 offset:33792
	ds_read_b128 v[174:177], v148 offset:34816
	ds_read_b128 v[178:181], v148 offset:35840
	ds_read_b128 v[182:185], v148 offset:36864
	ds_read_b128 v[186:189], v148 offset:37888
	ds_read_b128 v[190:193], v148 offset:38912
	ds_read_b128 v[198:201], v148 offset:39936
	s_mov_b32 m0, s35
	s_nop 0
	global_load_lds_dwordx4 v130, s[24:25]
	s_waitcnt lgkmcnt(8)
	s_setprio 1
	s_barrier
	s_waitcnt lgkmcnt(7)
	v_mfma_f32_16x16x32_bf16 v[124:127], v[150:153], v[166:169], v[124:127]
	v_mfma_f32_16x16x32_bf16 v[120:123], v[158:161], v[166:169], v[120:123]
	s_waitcnt lgkmcnt(5)
	v_mfma_f32_16x16x32_bf16 v[116:119], v[150:153], v[174:177], v[116:119]
	v_mfma_f32_16x16x32_bf16 v[112:115], v[158:161], v[174:177], v[112:115]
	s_waitcnt lgkmcnt(3)
	v_mfma_f32_16x16x32_bf16 v[100:103], v[150:153], v[182:185], v[100:103]
	v_mfma_f32_16x16x32_bf16 v[96:99], v[158:161], v[182:185], v[96:99]
	s_waitcnt lgkmcnt(1)
	v_mfma_f32_16x16x32_bf16 v[84:87], v[150:153], v[190:193], v[84:87]
	v_mfma_f32_16x16x32_bf16 v[80:83], v[158:161], v[190:193], v[80:83]
	v_mfma_f32_16x16x32_bf16 v[124:127], v[154:157], v[170:173], v[124:127]
	s_add_i32 s24, 0, 0x1c000
	v_mfma_f32_16x16x32_bf16 v[120:123], v[162:165], v[170:173], v[120:123]
	s_add_i32 s25, s54, s29
	v_mfma_f32_16x16x32_bf16 v[116:119], v[154:157], v[178:181], v[116:119]
	v_add_u32_e32 v196, s24, v146
	v_mfma_f32_16x16x32_bf16 v[112:115], v[162:165], v[178:181], v[112:115]
	v_lshl_add_u64 v[194:195], v[194:195], 0, s[8:9]
	v_mfma_f32_16x16x32_bf16 v[100:103], v[154:157], v[186:189], v[100:103]
	v_mfma_f32_16x16x32_bf16 v[96:99], v[162:165], v[186:189], v[96:99]
	s_waitcnt lgkmcnt(0)
	v_mfma_f32_16x16x32_bf16 v[84:87], v[154:157], v[198:201], v[84:87]
	v_mfma_f32_16x16x32_bf16 v[80:83], v[162:165], v[198:201], v[80:83]
	s_barrier
	s_setprio 0
	s_mov_b32 m0, s25
	ds_read_b128 v[202:205], v196
	global_load_lds_dwordx4 v[194:195], off
	ds_read_b128 v[206:209], v196 offset:1024
	ds_read_b128 v[210:213], v196 offset:2048
	ds_read_b128 v[214:217], v196 offset:3072
	v_lshl_add_u64 v[194:195], v[218:219], 0, s[8:9]
	s_add_i32 m0, s25, 0x2000
	s_nop 0
	global_load_lds_dwordx4 v[194:195], off
	s_setprio 1
	s_barrier
	s_waitcnt lgkmcnt(3)
	v_mfma_f32_16x16x32_bf16 v[108:111], v[202:205], v[166:169], v[108:111]
	s_waitcnt lgkmcnt(1)
	v_mfma_f32_16x16x32_bf16 v[104:107], v[210:213], v[166:169], v[104:107]
	v_mfma_f32_16x16x32_bf16 v[92:95], v[202:205], v[174:177], v[92:95]
	v_mfma_f32_16x16x32_bf16 v[88:91], v[210:213], v[174:177], v[88:91]
	v_mfma_f32_16x16x32_bf16 v[76:79], v[202:205], v[182:185], v[76:79]
	v_mfma_f32_16x16x32_bf16 v[72:75], v[210:213], v[182:185], v[72:75]
	v_mfma_f32_16x16x32_bf16 v[68:71], v[202:205], v[190:193], v[68:71]
	v_mfma_f32_16x16x32_bf16 v[64:67], v[210:213], v[190:193], v[64:67]
	v_mfma_f32_16x16x32_bf16 v[108:111], v[206:209], v[170:173], v[108:111]
	s_mov_b32 m0, s39
	s_waitcnt lgkmcnt(0)
	v_mfma_f32_16x16x32_bf16 v[104:107], v[214:217], v[170:173], v[104:107]
	v_lshl_add_u64 v[194:195], v[220:221], 0, s[8:9]
	v_mfma_f32_16x16x32_bf16 v[92:95], v[206:209], v[178:181], v[92:95]
	v_mfma_f32_16x16x32_bf16 v[88:91], v[214:217], v[178:181], v[88:91]
	v_mfma_f32_16x16x32_bf16 v[76:79], v[206:209], v[186:189], v[76:79]
	v_mfma_f32_16x16x32_bf16 v[72:75], v[214:217], v[186:189], v[72:75]
	v_mfma_f32_16x16x32_bf16 v[68:71], v[206:209], v[198:201], v[68:71]
	v_mfma_f32_16x16x32_bf16 v[64:67], v[214:217], v[198:201], v[64:67]
	s_barrier
	s_setprio 0
	ds_read_b128 v[166:169], v148 offset:49152
	global_load_lds_dwordx4 v[194:195], off
	ds_read_b128 v[170:173], v148 offset:50176
	ds_read_b128 v[174:177], v148 offset:51200
	ds_read_b128 v[178:181], v148 offset:52224
	ds_read_b128 v[182:185], v148 offset:53248
	ds_read_b128 v[186:189], v148 offset:54272
	ds_read_b128 v[190:193], v148 offset:55296
	ds_read_b128 v[198:201], v148 offset:56320
	v_lshl_add_u64 v[194:195], v[222:223], 0, s[8:9]
	s_mov_b32 m0, s42
	s_nop 0
	global_load_lds_dwordx4 v[194:195], off
	s_waitcnt vmcnt(10)
	s_setprio 1
	s_barrier
; #define PG8_STAGE(bufoff, gbase, voff) do { _Pragma("unroll") for (int _i = 0; _i < 2; ++_i) \
;         __builtin_amdgcn_global_load_lds((const unsigned*)((const char*)(gbase) + (voff)[_i]), (LAS unsigned*)(lds + (bufoff) + ldsw + _i * 8192), 16, 0, 0); } while (0)
; #define PG8_LDA(dst, b, h) do { _Pragma("unroll") for (int m = 0; m < 4; ++m) _Pragma("unroll") for (int k = 0; k < 2; ++k) dst[m][k] = *(const LAS bf16x8*)(lds + PG8_SA(b, h) + aoff + m * 2048 + k * 1024); } while (0)
; #define PG8_LDB(dst, b, h) do { _Pragma("unroll") for (int n = 0; n < 2; ++n) _Pragma("unroll") for (int k = 0; k < 2; ++k) dst[n][k] = *(const LAS bf16x8*)(lds + PG8_SB(b, h) + boff + n * 2048 + k * 1024); } while (0)
; #define PG8_MMA(ai, bj, At, Bt) do { __builtin_amdgcn_s_setprio(1); _Pragma("unroll") for (int m = 0; m < 4; ++m) _Pragma("unroll") for (int n = 0; n < 2; ++n) _Pragma("unroll") for (int k = 0; k < 2; ++k) \
;         acc[ai][bj][m][n] = __builtin_amdgcn_mfma_f32_16x16x32_bf16(Bt[n][k], At[m][k], acc[ai][bj][m][n], 0, 0, 0); __builtin_amdgcn_s_setprio(0); } while (0)
; #define PG8_WAIT_V(n) asm volatile("s_waitcnt vmcnt(" #n ")" ::: "memory")
; #define PG8_WAIT_L(n) asm volatile("s_waitcnt lgkmcnt(" #n ")" ::: "memory")
; #define PG8_BAR __builtin_amdgcn_s_barrier()
; #define PG8_SCHED __builtin_amdgcn_sched_barrier(0)
; template <class Map, class Epi>
; DI void gemm_phase(LAS unsigned char* lds, const Map& MP, const Epi& E, const int nM, const int nN, const int K, const int lda, const int ldb) {
;     ...
;             PG8_WAIT_V(6); PG8_BAR; PG8_MMA(1, 1, At, B1); PG8_BAR;
;             PG8_LDB(B0, 1, 0); PG8_SCHED; PG8_LDA(At, 1, 0); PG8_STAGE(PG8_SA(0, 1), a2 + hstepA, voffA);
;             PG8_WAIT_L(8); PG8_BAR; PG8_WAIT_L(0); PG8_MMA(0, 0, At, B0); PG8_BAR; PG8_SCHED;
;             PG8_LDB(B1, 1, 1); PG8_STAGE(PG8_SB(1, 0), b3, voffB);
;             PG8_BAR; PG8_WAIT_L(0); PG8_MMA(0, 1, At, B1); PG8_BAR;
;             PG8_LDA(At, 1, 1); PG8_STAGE(PG8_SA(1, 0), a3, voffA);
;             PG8_BAR; PG8_WAIT_L(0); PG8_MMA(1, 0, At, B0); PG8_BAR; PG8_SCHED;
;             PG8_STAGE(PG8_SB(1, 1), b3 + hstepB, voffB);
;             PG8_WAIT_V(6); PG8_BAR; PG8_MMA(1, 1, At, B1); PG8_BAR;
	s_waitcnt lgkmcnt(7)
	v_mfma_f32_16x16x32_bf16 v[60:63], v[150:153], v[166:169], v[60:63]
	v_mfma_f32_16x16x32_bf16 v[56:59], v[158:161], v[166:169], v[56:59]
	s_waitcnt lgkmcnt(5)
	v_mfma_f32_16x16x32_bf16 v[52:55], v[150:153], v[174:177], v[52:55]
	v_mfma_f32_16x16x32_bf16 v[48:51], v[158:161], v[174:177], v[48:51]
	s_waitcnt lgkmcnt(3)
	v_mfma_f32_16x16x32_bf16 v[36:39], v[150:153], v[182:185], v[36:39]
	v_mfma_f32_16x16x32_bf16 v[32:35], v[158:161], v[182:185], v[32:35]
	s_waitcnt lgkmcnt(1)
	v_mfma_f32_16x16x32_bf16 v[20:23], v[150:153], v[190:193], v[20:23]
	v_mfma_f32_16x16x32_bf16 v[16:19], v[158:161], v[190:193], v[16:19]
	v_mfma_f32_16x16x32_bf16 v[60:63], v[154:157], v[170:173], v[60:63]
	s_add_u32 s22, s22, 0x80080
	s_addc_u32 s23, s23, 0
	v_mfma_f32_16x16x32_bf16 v[56:59], v[162:165], v[170:173], v[56:59]
	s_add_i32 s24, s24, s29
	v_mfma_f32_16x16x32_bf16 v[52:55], v[154:157], v[178:181], v[52:55]
	v_mfma_f32_16x16x32_bf16 v[48:51], v[162:165], v[178:181], v[48:51]
	v_mfma_f32_16x16x32_bf16 v[36:39], v[154:157], v[186:189], v[36:39]
	v_mfma_f32_16x16x32_bf16 v[32:35], v[162:165], v[186:189], v[32:35]
	s_waitcnt lgkmcnt(0)
	v_mfma_f32_16x16x32_bf16 v[20:23], v[154:157], v[198:201], v[20:23]
	v_mfma_f32_16x16x32_bf16 v[16:19], v[162:165], v[198:201], v[16:19]
	s_barrier
	s_setprio 0
	s_mov_b32 m0, s24
	s_nop 0
	global_load_lds_dwordx4 v132, s[22:23]
	s_add_i32 m0, s24, 0x2000
	s_nop 0
	global_load_lds_dwordx4 v128, s[22:23]
	s_waitcnt vmcnt(6)
	s_setprio 1
	s_barrier
	v_mfma_f32_16x16x32_bf16 v[44:47], v[202:205], v[166:169], v[44:47]
	v_mfma_f32_16x16x32_bf16 v[40:43], v[210:213], v[166:169], v[40:43]
	ds_read_b128 v[150:153], v147
	v_mfma_f32_16x16x32_bf16 v[28:31], v[202:205], v[174:177], v[28:31]
	v_mfma_f32_16x16x32_bf16 v[24:27], v[210:213], v[174:177], v[24:27]
	ds_read_b128 v[154:157], v147 offset:1024
	v_mfma_f32_16x16x32_bf16 v[12:15], v[202:205], v[182:185], v[12:15]
	v_mfma_f32_16x16x32_bf16 v[8:11], v[210:213], v[182:185], v[8:11]
	ds_read_b128 v[158:161], v147 offset:2048
	v_mfma_f32_16x16x32_bf16 v[4:7], v[202:205], v[190:193], v[4:7]
	v_mfma_f32_16x16x32_bf16 v[0:3], v[210:213], v[190:193], v[0:3]
	ds_read_b128 v[162:165], v147 offset:3072
	v_mfma_f32_16x16x32_bf16 v[44:47], v[206:209], v[170:173], v[44:47]
	s_add_i32 s3, s3, 2
	v_mfma_f32_16x16x32_bf16 v[40:43], v[214:217], v[170:173], v[40:43]
	s_add_u32 s52, s52, 0x100
	s_addc_u32 s53, s53, 0
	v_mfma_f32_16x16x32_bf16 v[28:31], v[206:209], v[178:181], v[28:31]
	s_add_u32 s20, s20, 0x100
	s_addc_u32 s21, s21, 0
	v_mfma_f32_16x16x32_bf16 v[24:27], v[214:217], v[178:181], v[24:27]
	s_cmp_gt_u32 s3, 29
	v_mfma_f32_16x16x32_bf16 v[12:15], v[206:209], v[186:189], v[12:15]
	v_mfma_f32_16x16x32_bf16 v[8:11], v[214:217], v[186:189], v[8:11]
	v_mfma_f32_16x16x32_bf16 v[4:7], v[206:209], v[198:201], v[4:7]
	v_mfma_f32_16x16x32_bf16 v[0:3], v[214:217], v[198:201], v[0:3]
	s_barrier
	s_setprio 0
	s_cbranch_scc0 .LBB1_1382
; DI unsigned pack2(float a, float b) { f32x2 v = {a, b}; hwbf16x2 r = __builtin_convertvector(v, hwbf16x2); return __builtin_bit_cast(unsigned, r); }
;     DI const char* a(const Unit& u) const { return (const char*)(A + (size_t)u.pm * BM * lda); }
;     DI const char* a(const Unit& u) const { return (const char*)(A + (size_t)u.pm * BM * 2048 + (u.pn >> 1) * 512); }
;     DI const char* a(const Unit& u) const { return (const char*)((u.pn < 12 ? A1 : A2) + (size_t)u.pm * BM * 512); }
; #define PG8_WAIT_V(n) asm volatile("s_waitcnt vmcnt(" #n ")" ::: "memory")
; #define PG8_BAR __builtin_amdgcn_s_barrier()
;     DI void operator()(const f32x4 (&acc)[2][2][4][2], const Unit& u, int wr, int wc, int fr, int fq) const {
;         bf16_t* O = O1; int ldc = ldc1, pn = u.pn; if (pn >= split) { O = O2; ldc = ldc2; pn -= split; }
;         const int row0 = u.pm * BM + wr * 64 + fr, col0 = pn * BM + wc * 32 + 8 * fq;
; #pragma unroll
;         for (int ai = 0; ai < 2; ++ai)
; #pragma unroll
;             for (int m = 0; m < 4; ++m) { bf16_t* rowp = O + (size_t)(row0 + ai * HALF + m * 16) * ldc + col0;
; #pragma unroll
;                 for (int bj = 0; bj < 2; ++bj) { const f32x4 v0 = acc[ai][bj][m][0], v1 = acc[ai][bj][m][1];
;                     u32x4 o; o[0] = pack2(v0[0], v0[1]); o[1] = pack2(v0[2], v0[3]); o[2] = pack2(v1[0], v1[1]); o[3] = pack2(v1[2], v1[3]);
;                     *(u32x4*)(rowp + bj * HALF) = o; } }
;     }
; template <class Map, class Epi>
; DI void gemm_phase(LAS unsigned char* lds, const Map& MP, const Epi& E, const int nM, const int nN, const int K, const int lda, const int ldb) {
;     ...
;         if (!has_next) break;
; #pragma unroll
;         for (int a = 0; a < 2; ++a)
; #pragma unroll
;             for (int b = 0; b < 2; ++b)
; #pragma unroll
;                 for (int m = 0; m < 4; ++m)
; #pragma unroll
;                     for (int n = 0; n < 2; ++n) acc[a][b][m][n] = (f32x4){0.f, 0.f, 0.f, 0.f};
;         cur = nxt; cA = nA; cB = nB; ++ui;
;     }
;     PG8_WAIT_V(0);
;     if (wr == 0) PG8_BAR;
;     PG8_BAR;
	s_waitcnt lgkmcnt(0)
	s_lshl_b32 s3, s10, 8
	v_mov_b32_e32 v150, v144
	v_mov_b32_e32 v151, v145
	s_add_i32 s3, s3, s37
	v_cvt_pk_bf16_f32 v68, v68, v69
	v_add_u32_e32 v154, s3, v150
	s_lshl_b32 s3, s47, 8
	s_or_b32 s3, s3, s38
	v_lshl_add_u32 v150, v151, 3, s3
	v_ashrrev_i32_e32 v151, 31, v150
	v_lshl_add_u64 v[150:151], v[150:151], 1, s[6:7]
	v_cvt_pk_bf16_f32 v69, v70, v71
	v_cvt_pk_bf16_f32 v70, v64, v65
	v_add_u32_e32 v64, 0x80, v154
	v_mad_i64_i32 v[152:153], s[20:21], v154, s46, v[150:151]
	v_cvt_pk_bf16_f32 v108, v108, v109
	v_cvt_pk_bf16_f32 v109, v110, v111
	v_cvt_pk_bf16_f32 v110, v104, v105
	v_cvt_pk_bf16_f32 v111, v106, v107
	v_add_u32_e32 v104, 16, v154
	v_mad_i64_i32 v[64:65], s[20:21], v64, s46, v[150:151]
	v_cvt_pk_bf16_f32 v44, v44, v45
	v_cvt_pk_bf16_f32 v45, v46, v47
	v_cvt_pk_bf16_f32 v46, v40, v41
	v_cvt_pk_bf16_f32 v47, v42, v43
	v_add_u32_e32 v40, 0x90, v154
	global_store_dwordx4 v[152:153], v[108:111], off offset:256
	v_cvt_pk_bf16_f32 v92, v92, v93
	v_cvt_pk_bf16_f32 v93, v94, v95
	v_mad_i64_i32 v[108:109], s[20:21], v104, s46, v[150:151]
	v_cvt_pk_bf16_f32 v94, v88, v89
	v_cvt_pk_bf16_f32 v95, v90, v91
	v_add_u32_e32 v88, 32, v154
	global_store_dwordx4 v[64:65], v[44:47], off offset:256
	v_cvt_pk_bf16_f32 v28, v28, v29
	v_cvt_pk_bf16_f32 v29, v30, v31
	v_mad_i64_i32 v[44:45], s[20:21], v40, s46, v[150:151]
	v_cvt_pk_bf16_f32 v30, v24, v25
	v_cvt_pk_bf16_f32 v31, v26, v27
	v_add_u32_e32 v24, 0xa0, v154
	global_store_dwordx4 v[108:109], v[92:95], off offset:256
	v_cvt_pk_bf16_f32 v76, v76, v77
	v_cvt_pk_bf16_f32 v77, v78, v79
	v_mad_i64_i32 v[92:93], s[20:21], v88, s46, v[150:151]
	v_cvt_pk_bf16_f32 v78, v72, v73
	v_cvt_pk_bf16_f32 v79, v74, v75
	v_add_u32_e32 v72, 48, v154
	global_store_dwordx4 v[44:45], v[28:31], off offset:256
	v_cvt_pk_bf16_f32 v12, v12, v13
	v_cvt_pk_bf16_f32 v13, v14, v15
	v_mad_i64_i32 v[28:29], s[20:21], v24, s46, v[150:151]
	v_cvt_pk_bf16_f32 v14, v8, v9
	v_cvt_pk_bf16_f32 v15, v10, v11
	v_add_u32_e32 v8, 0xb0, v154
	global_store_dwordx4 v[92:93], v[76:79], off offset:256
	global_store_dwordx4 v[28:29], v[12:15], off offset:256
	v_cvt_pk_bf16_f32 v124, v124, v125
	v_mad_i64_i32 v[76:77], s[20:21], v72, s46, v[150:151]
	v_mad_i64_i32 v[12:13], s[20:21], v8, s46, v[150:151]
	v_cvt_pk_bf16_f32 v125, v126, v127
	v_cvt_pk_bf16_f32 v126, v120, v121
	v_cvt_pk_bf16_f32 v127, v122, v123
	v_cvt_pk_bf16_f32 v104, v116, v117
	v_cvt_pk_bf16_f32 v105, v118, v119
	v_cvt_pk_bf16_f32 v106, v112, v113
	v_cvt_pk_bf16_f32 v107, v114, v115
	v_cvt_pk_bf16_f32 v88, v100, v101
	v_cvt_pk_bf16_f32 v89, v102, v103
	v_cvt_pk_bf16_f32 v90, v96, v97
	v_cvt_pk_bf16_f32 v91, v98, v99
	v_cvt_pk_bf16_f32 v72, v84, v85
	v_cvt_pk_bf16_f32 v73, v86, v87
	v_cvt_pk_bf16_f32 v74, v80, v81
	v_cvt_pk_bf16_f32 v75, v82, v83
	v_cvt_pk_bf16_f32 v71, v66, v67
	v_cvt_pk_bf16_f32 v60, v60, v61
	v_cvt_pk_bf16_f32 v61, v62, v63
	v_cvt_pk_bf16_f32 v62, v56, v57
	v_cvt_pk_bf16_f32 v63, v58, v59
	v_cvt_pk_bf16_f32 v40, v52, v53
	v_cvt_pk_bf16_f32 v41, v54, v55
	v_cvt_pk_bf16_f32 v42, v48, v49
	v_cvt_pk_bf16_f32 v43, v50, v51
	v_cvt_pk_bf16_f32 v24, v36, v37
	v_cvt_pk_bf16_f32 v25, v38, v39
	v_cvt_pk_bf16_f32 v26, v32, v33
	v_cvt_pk_bf16_f32 v27, v34, v35
	v_cvt_pk_bf16_f32 v8, v20, v21
	v_cvt_pk_bf16_f32 v9, v22, v23
	v_cvt_pk_bf16_f32 v10, v16, v17
	v_cvt_pk_bf16_f32 v11, v18, v19
	v_cvt_pk_bf16_f32 v4, v4, v5
	v_cvt_pk_bf16_f32 v5, v6, v7
	v_cvt_pk_bf16_f32 v6, v0, v1
	v_cvt_pk_bf16_f32 v7, v2, v3
	s_and_b64 vcc, exec, s[40:41]
	s_mov_b32 s47, s12
	s_mov_b32 s10, s14
	s_mov_b64 s[20:21], s[18:19]
	s_mov_b64 s[22:23], s[16:17]
	global_store_dwordx4 v[152:153], v[124:127], off
	global_store_dwordx4 v[108:109], v[104:107], off
	global_store_dwordx4 v[92:93], v[88:91], off
	global_store_dwordx4 v[76:77], v[72:75], off
	global_store_dwordx4 v[76:77], v[68:71], off offset:256
	global_store_dwordx4 v[64:65], v[60:63], off
	global_store_dwordx4 v[44:45], v[40:43], off
	global_store_dwordx4 v[28:29], v[24:27], off
	global_store_dwordx4 v[12:13], v[8:11], off
	global_store_dwordx4 v[12:13], v[4:7], off offset:256
	s_cbranch_vccz .LBB1_1379
	s_waitcnt vmcnt(0)
	s_cmpk_gt_u32 s4, 0xff
	s_cbranch_scc1 .LBB1_1386
	s_barrier

; #define PG8_STAGE(bufoff, gbase, voff) do { _Pragma("unroll") for (int _i = 0; _i < 2; ++_i) \
;         __builtin_amdgcn_global_load_lds((const unsigned*)((const char*)(gbase) + (voff)[_i]), (LAS unsigned*)(lds + (bufoff) + ldsw + _i * 8192), 16, 0, 0); } while (0)
; #define PG8_LDA(dst, b, h) do { _Pragma("unroll") for (int m = 0; m < 4; ++m) _Pragma("unroll") for (int k = 0; k < 2; ++k) dst[m][k] = *(const LAS bf16x8*)(lds + PG8_SA(b, h) + aoff + m * 2048 + k * 1024); } while (0)
; #define PG8_WAIT_V(n) asm volatile("s_waitcnt vmcnt(" #n ")" ::: "memory")
; #define PG8_BAR __builtin_amdgcn_s_barrier()
; template <class Map, class Epi>
; DI void gemm_phase(LAS unsigned char* lds, const Map& MP, const Epi& E, const int nM, const int nN, const int K, const int lda, const int ldb) {
;     ...
;         for (int t = 0; t < nt; t += 2) {
;             const bool last = (t == nt - 2);
;             const char* a1 = cA + (size_t)(t + 1) * kstep;
;             const char* a2 = last ? nA : cA + (size_t)(t + 2) * kstep; const char* b2 = last ? nB : cB + (size_t)(t + 2) * kstep;
;             const char* a3 = a2 + kstep; const char* b3 = b2 + kstep;
;             PG8_LDB(B0, 0, 0); PG8_SCHED; PG8_LDA(At, 0, 0); PG8_STAGE(PG8_SA(1, 1), a1 + hstepA, voffA);
;             PG8_WAIT_L(8); PG8_BAR; PG8_WAIT_L(0); PG8_MMA(0, 0, At, B0); PG8_BAR; PG8_SCHED;
;             PG8_LDB(B1, 0, 1); PG8_STAGE(PG8_SB(0, 0), b2, voffB);
;             PG8_BAR; PG8_WAIT_L(0); PG8_MMA(0, 1, At, B1); PG8_BAR;
;             PG8_LDA(At, 0, 1); PG8_STAGE(PG8_SA(0, 0), a2, voffA);
;             PG8_BAR; PG8_WAIT_L(0); PG8_MMA(1, 0, At, B0); PG8_BAR; PG8_SCHED;
;             PG8_STAGE(PG8_SB(0, 1), b2 + hstepB, voffB);
;             PG8_WAIT_V(6); PG8_BAR; PG8_MMA(1, 1, At, B1); PG8_BAR;
;             PG8_LDB(B0, 1, 0); PG8_SCHED; PG8_LDA(At, 1, 0); PG8_STAGE(PG8_SA(0, 1), a2 + hstepA, voffA);
;             PG8_WAIT_L(8); PG8_BAR; PG8_WAIT_L(0); PG8_MMA(0, 0, At, B0); PG8_BAR; PG8_SCHED;
;             PG8_LDB(B1, 1, 1); PG8_STAGE(PG8_SB(1, 0), b3, voffB);
;             PG8_BAR; PG8_WAIT_L(0); PG8_MMA(0, 1, At, B1); PG8_BAR;
;             PG8_LDA(At, 1, 1); PG8_STAGE(PG8_SA(1, 0), a3, voffA);
;             PG8_BAR; PG8_WAIT_L(0); PG8_MMA(1, 0, At, B0); PG8_BAR; PG8_SCHED;
;             PG8_STAGE(PG8_SB(1, 1), b3 + hstepB, voffB);
;             PG8_WAIT_V(6); PG8_BAR; PG8_MMA(1, 1, At, B1); PG8_BAR;
.LBB1_1529:
	s_add_u32 s20, s18, 0xfffe0080
	s_addc_u32 s21, s19, -1
	s_cmp_eq_u32 s3, 4
	s_cselect_b32 s23, s13, s21
	s_cselect_b32 s22, s52, s20
	s_cselect_b32 s21, s53, s56
	s_cselect_b32 s20, s54, s55
	s_add_i32 m0, s11, 0xc000
	ds_read_b128 v[166:169], v148
	global_load_lds_dwordx4 v138, s[18:19]
	ds_read_b128 v[170:173], v148 offset:1024
	ds_read_b128 v[174:177], v148 offset:2048
	ds_read_b128 v[178:181], v148 offset:3072
	ds_read_b128 v[182:185], v148 offset:4096
	ds_read_b128 v[186:189], v148 offset:5120
	ds_read_b128 v[190:193], v148 offset:6144
	ds_read_b128 v[198:201], v148 offset:7168
	s_add_i32 m0, s11, 0xe000
	s_nop 0
	global_load_lds_dwordx4 v136, s[18:19]
	s_waitcnt lgkmcnt(8)
	s_setprio 1
	s_barrier
	s_waitcnt lgkmcnt(7)
	v_mfma_f32_16x16x32_bf16 v[124:127], v[150:153], v[166:169], v[124:127]
	v_mfma_f32_16x16x32_bf16 v[120:123], v[158:161], v[166:169], v[120:123]
	s_waitcnt lgkmcnt(5)
	v_mfma_f32_16x16x32_bf16 v[116:119], v[150:153], v[174:177], v[116:119]
	v_mfma_f32_16x16x32_bf16 v[112:115], v[158:161], v[174:177], v[112:115]
	s_waitcnt lgkmcnt(3)
	v_mfma_f32_16x16x32_bf16 v[100:103], v[150:153], v[182:185], v[100:103]
	v_mfma_f32_16x16x32_bf16 v[96:99], v[158:161], v[182:185], v[96:99]
	s_waitcnt lgkmcnt(1)
	v_mfma_f32_16x16x32_bf16 v[84:87], v[150:153], v[190:193], v[84:87]
	v_mfma_f32_16x16x32_bf16 v[80:83], v[158:161], v[190:193], v[80:83]
	v_mfma_f32_16x16x32_bf16 v[124:127], v[154:157], v[170:173], v[124:127]
	s_add_i32 s57, s47, s31
	v_mfma_f32_16x16x32_bf16 v[120:123], v[162:165], v[170:173], v[120:123]
	v_lshl_add_u64 v[194:195], s[20:21], 0, v[132:133]
	v_mfma_f32_16x16x32_bf16 v[116:119], v[154:157], v[178:181], v[116:119]
	v_lshl_add_u64 v[218:219], s[20:21], 0, v[128:129]
	v_mfma_f32_16x16x32_bf16 v[112:115], v[162:165], v[178:181], v[112:115]
	v_mfma_f32_16x16x32_bf16 v[100:103], v[154:157], v[186:189], v[100:103]
	v_mfma_f32_16x16x32_bf16 v[96:99], v[162:165], v[186:189], v[96:99]
	s_waitcnt lgkmcnt(0)
	v_mfma_f32_16x16x32_bf16 v[84:87], v[154:157], v[198:201], v[84:87]
	v_mfma_f32_16x16x32_bf16 v[80:83], v[162:165], v[198:201], v[80:83]
	s_barrier
	s_setprio 0
	s_mov_b32 m0, s57
	ds_read_b128 v[202:205], v149
	global_load_lds_dwordx4 v[194:195], off
	ds_read_b128 v[206:209], v149 offset:1024
	ds_read_b128 v[210:213], v149 offset:2048
	ds_read_b128 v[214:217], v149 offset:3072
	s_add_i32 m0, s57, 0x2000
	s_nop 0
	global_load_lds_dwordx4 v[218:219], off
	s_setprio 1
	s_barrier
	s_waitcnt lgkmcnt(3)
	v_mfma_f32_16x16x32_bf16 v[108:111], v[202:205], v[166:169], v[108:111]
	s_waitcnt lgkmcnt(1)
	v_mfma_f32_16x16x32_bf16 v[104:107], v[210:213], v[166:169], v[104:107]
	v_mfma_f32_16x16x32_bf16 v[92:95], v[202:205], v[174:177], v[92:95]
	v_mfma_f32_16x16x32_bf16 v[88:91], v[210:213], v[174:177], v[88:91]
	v_mfma_f32_16x16x32_bf16 v[76:79], v[202:205], v[182:185], v[76:79]
	v_mfma_f32_16x16x32_bf16 v[72:75], v[210:213], v[182:185], v[72:75]
	v_mfma_f32_16x16x32_bf16 v[68:71], v[202:205], v[190:193], v[68:71]
	v_mfma_f32_16x16x32_bf16 v[64:67], v[210:213], v[190:193], v[64:67]
	v_mfma_f32_16x16x32_bf16 v[108:111], v[206:209], v[170:173], v[108:111]
	v_lshl_add_u64 v[222:223], s[22:23], 0, v[130:131]
	s_mov_b32 m0, s11
	s_waitcnt lgkmcnt(0)
	v_mfma_f32_16x16x32_bf16 v[104:107], v[214:217], v[170:173], v[104:107]
	v_lshl_add_u64 v[220:221], s[22:23], 0, v[134:135]
	v_mfma_f32_16x16x32_bf16 v[92:95], v[206:209], v[178:181], v[92:95]
	v_mfma_f32_16x16x32_bf16 v[88:91], v[214:217], v[178:181], v[88:91]
	v_mfma_f32_16x16x32_bf16 v[76:79], v[206:209], v[186:189], v[76:79]
	v_mfma_f32_16x16x32_bf16 v[72:75], v[214:217], v[186:189], v[72:75]
	v_mfma_f32_16x16x32_bf16 v[68:71], v[206:209], v[198:201], v[68:71]
	v_mfma_f32_16x16x32_bf16 v[64:67], v[214:217], v[198:201], v[64:67]
	s_barrier
	s_setprio 0
	ds_read_b128 v[166:169], v148 offset:16384
	global_load_lds_dwordx4 v[220:221], off
	ds_read_b128 v[170:173], v148 offset:17408
	ds_read_b128 v[174:177], v148 offset:18432
	ds_read_b128 v[178:181], v148 offset:19456
	ds_read_b128 v[182:185], v148 offset:20480
	ds_read_b128 v[186:189], v148 offset:21504
	ds_read_b128 v[190:193], v148 offset:22528
	ds_read_b128 v[198:201], v148 offset:23552
	s_mov_b32 m0, s35
	s_nop 0
	global_load_lds_dwordx4 v[222:223], off
	s_waitcnt vmcnt(10)
	s_setprio 1
	s_barrier
	s_waitcnt lgkmcnt(7)
	v_mfma_f32_16x16x32_bf16 v[60:63], v[150:153], v[166:169], v[60:63]
	v_mfma_f32_16x16x32_bf16 v[56:59], v[158:161], v[166:169], v[56:59]
	s_waitcnt lgkmcnt(5)
	v_mfma_f32_16x16x32_bf16 v[52:55], v[150:153], v[174:177], v[52:55]
	v_mfma_f32_16x16x32_bf16 v[48:51], v[158:161], v[174:177], v[48:51]
	s_waitcnt lgkmcnt(3)
	v_mfma_f32_16x16x32_bf16 v[36:39], v[150:153], v[182:185], v[36:39]
	v_mfma_f32_16x16x32_bf16 v[32:35], v[158:161], v[182:185], v[32:35]
	s_waitcnt lgkmcnt(1)
	v_mfma_f32_16x16x32_bf16 v[20:23], v[150:153], v[190:193], v[20:23]
	v_mfma_f32_16x16x32_bf16 v[16:19], v[158:161], v[190:193], v[16:19]
	v_mfma_f32_16x16x32_bf16 v[60:63], v[154:157], v[170:173], v[60:63]
	s_add_u32 s58, s20, 0x20000
	s_addc_u32 s59, s21, 0
	v_mfma_f32_16x16x32_bf16 v[56:59], v[162:165], v[170:173], v[56:59]
	s_add_i32 s57, s48, s31
	v_mfma_f32_16x16x32_bf16 v[52:55], v[154:157], v[178:181], v[52:55]
	v_mfma_f32_16x16x32_bf16 v[48:51], v[162:165], v[178:181], v[48:51]
	v_mfma_f32_16x16x32_bf16 v[36:39], v[154:157], v[186:189], v[36:39]
	v_mfma_f32_16x16x32_bf16 v[32:35], v[162:165], v[186:189], v[32:35]
	s_waitcnt lgkmcnt(0)
	v_mfma_f32_16x16x32_bf16 v[20:23], v[154:157], v[198:201], v[20:23]
	v_mfma_f32_16x16x32_bf16 v[16:19], v[162:165], v[198:201], v[16:19]
	s_barrier
; #define PG8_STAGE(bufoff, gbase, voff) do { _Pragma("unroll") for (int _i = 0; _i < 2; ++_i) \
;         __builtin_amdgcn_global_load_lds((const unsigned*)((const char*)(gbase) + (voff)[_i]), (LAS unsigned*)(lds + (bufoff) + ldsw + _i * 8192), 16, 0, 0); } while (0)
; #define PG8_LDA(dst, b, h) do { _Pragma("unroll") for (int m = 0; m < 4; ++m) _Pragma("unroll") for (int k = 0; k < 2; ++k) dst[m][k] = *(const LAS bf16x8*)(lds + PG8_SA(b, h) + aoff + m * 2048 + k * 1024); } while (0)
; #define PG8_WAIT_V(n) asm volatile("s_waitcnt vmcnt(" #n ")" ::: "memory")
; #define PG8_BAR __builtin_amdgcn_s_barrier()
; template <class Map, class Epi>
; DI void gemm_phase(LAS unsigned char* lds, const Map& MP, const Epi& E, const int nM, const int nN, const int K, const int lda, const int ldb) {
;     ...
;         for (int t = 0; t < nt; t += 2) {
;             const bool last = (t == nt - 2);
;             const char* a1 = cA + (size_t)(t + 1) * kstep;
;             const char* a2 = last ? nA : cA + (size_t)(t + 2) * kstep; const char* b2 = last ? nB : cB + (size_t)(t + 2) * kstep;
;             const char* a3 = a2 + kstep; const char* b3 = b2 + kstep;
;             PG8_LDB(B0, 0, 0); PG8_SCHED; PG8_LDA(At, 0, 0); PG8_STAGE(PG8_SA(1, 1), a1 + hstepA, voffA);
;             PG8_WAIT_L(8); PG8_BAR; PG8_WAIT_L(0); PG8_MMA(0, 0, At, B0); PG8_BAR; PG8_SCHED;
;             PG8_LDB(B1, 0, 1); PG8_STAGE(PG8_SB(0, 0), b2, voffB);
;             PG8_BAR; PG8_WAIT_L(0); PG8_MMA(0, 1, At, B1); PG8_BAR;
;             PG8_LDA(At, 0, 1); PG8_STAGE(PG8_SA(0, 0), a2, voffA);
;             PG8_BAR; PG8_WAIT_L(0); PG8_MMA(1, 0, At, B0); PG8_BAR; PG8_SCHED;
;             PG8_STAGE(PG8_SB(0, 1), b2 + hstepB, voffB);
;             PG8_WAIT_V(6); PG8_BAR; PG8_MMA(1, 1, At, B1); PG8_BAR;
;             PG8_LDB(B0, 1, 0); PG8_SCHED; PG8_LDA(At, 1, 0); PG8_STAGE(PG8_SA(0, 1), a2 + hstepA, voffA);
;             PG8_WAIT_L(8); PG8_BAR; PG8_WAIT_L(0); PG8_MMA(0, 0, At, B0); PG8_BAR; PG8_SCHED;
;             PG8_LDB(B1, 1, 1); PG8_STAGE(PG8_SB(1, 0), b3, voffB);
;             PG8_BAR; PG8_WAIT_L(0); PG8_MMA(0, 1, At, B1); PG8_BAR;
;             PG8_LDA(At, 1, 1); PG8_STAGE(PG8_SA(1, 0), a3, voffA);
;             PG8_BAR; PG8_WAIT_L(0); PG8_MMA(1, 0, At, B0); PG8_BAR; PG8_SCHED;
;             PG8_STAGE(PG8_SB(1, 1), b3 + hstepB, voffB);
;             PG8_WAIT_V(6); PG8_BAR; PG8_MMA(1, 1, At, B1); PG8_BAR;
	s_setprio 0
	s_mov_b32 m0, s57
	s_nop 0
	global_load_lds_dwordx4 v132, s[58:59]
	s_add_i32 m0, s57, 0x2000
	s_nop 0
	global_load_lds_dwordx4 v128, s[58:59]
	s_waitcnt vmcnt(6)
	s_setprio 1
	s_barrier
	v_mfma_f32_16x16x32_bf16 v[44:47], v[202:205], v[166:169], v[44:47]
	v_mfma_f32_16x16x32_bf16 v[40:43], v[210:213], v[166:169], v[40:43]
	s_add_i32 s57, 0, 0x18000
	v_add_u32_e32 v162, s57, v146
	ds_read_b128 v[150:153], v162
	v_mfma_f32_16x16x32_bf16 v[28:31], v[202:205], v[174:177], v[28:31]
	v_mfma_f32_16x16x32_bf16 v[24:27], v[210:213], v[174:177], v[24:27]
	ds_read_b128 v[154:157], v162 offset:1024
	v_mfma_f32_16x16x32_bf16 v[12:15], v[202:205], v[182:185], v[12:15]
	v_mfma_f32_16x16x32_bf16 v[8:11], v[210:213], v[182:185], v[8:11]
	ds_read_b128 v[158:161], v162 offset:2048
	v_mfma_f32_16x16x32_bf16 v[4:7], v[202:205], v[190:193], v[4:7]
	v_mfma_f32_16x16x32_bf16 v[0:3], v[210:213], v[190:193], v[0:3]
	ds_read_b128 v[162:165], v162 offset:3072
	v_mfma_f32_16x16x32_bf16 v[44:47], v[206:209], v[170:173], v[44:47]
	s_add_u32 s22, s22, 0x20000
	s_addc_u32 s23, s23, 0
	v_mfma_f32_16x16x32_bf16 v[40:43], v[214:217], v[170:173], v[40:43]
	v_mfma_f32_16x16x32_bf16 v[28:31], v[206:209], v[178:181], v[28:31]
	v_mfma_f32_16x16x32_bf16 v[24:27], v[214:217], v[178:181], v[24:27]
	v_mfma_f32_16x16x32_bf16 v[12:15], v[206:209], v[186:189], v[12:15]
	v_mfma_f32_16x16x32_bf16 v[8:11], v[214:217], v[186:189], v[8:11]
	v_mfma_f32_16x16x32_bf16 v[4:7], v[206:209], v[198:201], v[4:7]
	v_mfma_f32_16x16x32_bf16 v[0:3], v[214:217], v[198:201], v[0:3]
	s_barrier
	s_setprio 0
	s_mov_b32 m0, s36
	ds_read_b128 v[166:169], v148 offset:32768
	global_load_lds_dwordx4 v134, s[22:23]
	ds_read_b128 v[170:173], v148 offset:33792
	ds_read_b128 v[174:177], v148 offset:34816
	ds_read_b128 v[178:181], v148 offset:35840
	ds_read_b128 v[182:185], v148 offset:36864
	ds_read_b128 v[186:189], v148 offset:37888
	ds_read_b128 v[190:193], v148 offset:38912
	ds_read_b128 v[198:201], v148 offset:39936
	s_mov_b32 m0, s37
	s_nop 0
	global_load_lds_dwordx4 v130, s[22:23]
	s_waitcnt lgkmcnt(8)
	s_setprio 1
	s_barrier
	s_waitcnt lgkmcnt(7)
	v_mfma_f32_16x16x32_bf16 v[124:127], v[150:153], v[166:169], v[124:127]
	v_mfma_f32_16x16x32_bf16 v[120:123], v[158:161], v[166:169], v[120:123]
	s_waitcnt lgkmcnt(5)
	v_mfma_f32_16x16x32_bf16 v[116:119], v[150:153], v[174:177], v[116:119]
	v_mfma_f32_16x16x32_bf16 v[112:115], v[158:161], v[174:177], v[112:115]
	s_waitcnt lgkmcnt(3)
	v_mfma_f32_16x16x32_bf16 v[100:103], v[150:153], v[182:185], v[100:103]
	v_mfma_f32_16x16x32_bf16 v[96:99], v[158:161], v[182:185], v[96:99]
	s_waitcnt lgkmcnt(1)
	v_mfma_f32_16x16x32_bf16 v[84:87], v[150:153], v[190:193], v[84:87]
	v_mfma_f32_16x16x32_bf16 v[80:83], v[158:161], v[190:193], v[80:83]
	v_mfma_f32_16x16x32_bf16 v[124:127], v[154:157], v[170:173], v[124:127]
	s_add_i32 s22, 0, 0x1c000
	v_mfma_f32_16x16x32_bf16 v[120:123], v[162:165], v[170:173], v[120:123]
	s_add_i32 s23, s57, s31
	v_mfma_f32_16x16x32_bf16 v[116:119], v[154:157], v[178:181], v[116:119]
	v_add_u32_e32 v196, s22, v146
	v_mfma_f32_16x16x32_bf16 v[112:115], v[162:165], v[178:181], v[112:115]
	v_lshl_add_u64 v[194:195], v[194:195], 0, s[8:9]
	v_mfma_f32_16x16x32_bf16 v[100:103], v[154:157], v[186:189], v[100:103]
	v_mfma_f32_16x16x32_bf16 v[96:99], v[162:165], v[186:189], v[96:99]
	s_waitcnt lgkmcnt(0)
	v_mfma_f32_16x16x32_bf16 v[84:87], v[154:157], v[198:201], v[84:87]
	v_mfma_f32_16x16x32_bf16 v[80:83], v[162:165], v[198:201], v[80:83]
	s_barrier
	s_setprio 0
	s_mov_b32 m0, s23
	ds_read_b128 v[202:205], v196
	global_load_lds_dwordx4 v[194:195], off
	ds_read_b128 v[206:209], v196 offset:1024
	ds_read_b128 v[210:213], v196 offset:2048
	ds_read_b128 v[214:217], v196 offset:3072
	v_lshl_add_u64 v[194:195], v[218:219], 0, s[8:9]
	s_add_i32 m0, s23, 0x2000
	s_nop 0
	global_load_lds_dwordx4 v[194:195], off
	s_setprio 1
	s_barrier
	s_waitcnt lgkmcnt(3)
	v_mfma_f32_16x16x32_bf16 v[108:111], v[202:205], v[166:169], v[108:111]
	s_waitcnt lgkmcnt(1)
	v_mfma_f32_16x16x32_bf16 v[104:107], v[210:213], v[166:169], v[104:107]
	v_mfma_f32_16x16x32_bf16 v[92:95], v[202:205], v[174:177], v[92:95]
	v_mfma_f32_16x16x32_bf16 v[88:91], v[210:213], v[174:177], v[88:91]
	v_mfma_f32_16x16x32_bf16 v[76:79], v[202:205], v[182:185], v[76:79]
	v_mfma_f32_16x16x32_bf16 v[72:75], v[210:213], v[182:185], v[72:75]
	v_mfma_f32_16x16x32_bf16 v[68:71], v[202:205], v[190:193], v[68:71]
	v_mfma_f32_16x16x32_bf16 v[64:67], v[210:213], v[190:193], v[64:67]
	v_mfma_f32_16x16x32_bf16 v[108:111], v[206:209], v[170:173], v[108:111]
	s_mov_b32 m0, s43
	s_waitcnt lgkmcnt(0)
	v_mfma_f32_16x16x32_bf16 v[104:107], v[214:217], v[170:173], v[104:107]
	v_lshl_add_u64 v[194:195], v[220:221], 0, s[8:9]
	v_mfma_f32_16x16x32_bf16 v[92:95], v[206:209], v[178:181], v[92:95]
	v_mfma_f32_16x16x32_bf16 v[88:91], v[214:217], v[178:181], v[88:91]
	v_mfma_f32_16x16x32_bf16 v[76:79], v[206:209], v[186:189], v[76:79]
	v_mfma_f32_16x16x32_bf16 v[72:75], v[214:217], v[186:189], v[72:75]
	v_mfma_f32_16x16x32_bf16 v[68:71], v[206:209], v[198:201], v[68:71]
	v_mfma_f32_16x16x32_bf16 v[64:67], v[214:217], v[198:201], v[64:67]
	s_barrier
	s_setprio 0
	ds_read_b128 v[166:169], v148 offset:49152
	global_load_lds_dwordx4 v[194:195], off
	ds_read_b128 v[170:173], v148 offset:50176
	ds_read_b128 v[174:177], v148 offset:51200
	ds_read_b128 v[178:181], v148 offset:52224
	ds_read_b128 v[182:185], v148 offset:53248
	ds_read_b128 v[186:189], v148 offset:54272
	ds_read_b128 v[190:193], v148 offset:55296
	ds_read_b128 v[198:201], v148 offset:56320
	v_lshl_add_u64 v[194:195], v[222:223], 0, s[8:9]
	s_mov_b32 m0, s44
	s_nop 0
	global_load_lds_dwordx4 v[194:195], off
	s_waitcnt vmcnt(10)
	s_setprio 1
	s_barrier
; #define PG8_STAGE(bufoff, gbase, voff) do { _Pragma("unroll") for (int _i = 0; _i < 2; ++_i) \
;         __builtin_amdgcn_global_load_lds((const unsigned*)((const char*)(gbase) + (voff)[_i]), (LAS unsigned*)(lds + (bufoff) + ldsw + _i * 8192), 16, 0, 0); } while (0)
; #define PG8_LDA(dst, b, h) do { _Pragma("unroll") for (int m = 0; m < 4; ++m) _Pragma("unroll") for (int k = 0; k < 2; ++k) dst[m][k] = *(const LAS bf16x8*)(lds + PG8_SA(b, h) + aoff + m * 2048 + k * 1024); } while (0)
; #define PG8_LDB(dst, b, h) do { _Pragma("unroll") for (int n = 0; n < 2; ++n) _Pragma("unroll") for (int k = 0; k < 2; ++k) dst[n][k] = *(const LAS bf16x8*)(lds + PG8_SB(b, h) + boff + n * 2048 + k * 1024); } while (0)
; #define PG8_MMA(ai, bj, At, Bt) do { __builtin_amdgcn_s_setprio(1); _Pragma("unroll") for (int m = 0; m < 4; ++m) _Pragma("unroll") for (int n = 0; n < 2; ++n) _Pragma("unroll") for (int k = 0; k < 2; ++k) \
;         acc[ai][bj][m][n] = __builtin_amdgcn_mfma_f32_16x16x32_bf16(Bt[n][k], At[m][k], acc[ai][bj][m][n], 0, 0, 0); __builtin_amdgcn_s_setprio(0); } while (0)
; #define PG8_WAIT_V(n) asm volatile("s_waitcnt vmcnt(" #n ")" ::: "memory")
; #define PG8_WAIT_L(n) asm volatile("s_waitcnt lgkmcnt(" #n ")" ::: "memory")
; #define PG8_BAR __builtin_amdgcn_s_barrier()
; #define PG8_SCHED __builtin_amdgcn_sched_barrier(0)
; template <class Map, class Epi>
; DI void gemm_phase(LAS unsigned char* lds, const Map& MP, const Epi& E, const int nM, const int nN, const int K, const int lda, const int ldb) {
;     ...
;             PG8_WAIT_V(6); PG8_BAR; PG8_MMA(1, 1, At, B1); PG8_BAR;
;             PG8_LDB(B0, 1, 0); PG8_SCHED; PG8_LDA(At, 1, 0); PG8_STAGE(PG8_SA(0, 1), a2 + hstepA, voffA);
;             PG8_WAIT_L(8); PG8_BAR; PG8_WAIT_L(0); PG8_MMA(0, 0, At, B0); PG8_BAR; PG8_SCHED;
;             PG8_LDB(B1, 1, 1); PG8_STAGE(PG8_SB(1, 0), b3, voffB);
;             PG8_BAR; PG8_WAIT_L(0); PG8_MMA(0, 1, At, B1); PG8_BAR;
;             PG8_LDA(At, 1, 1); PG8_STAGE(PG8_SA(1, 0), a3, voffA);
;             PG8_BAR; PG8_WAIT_L(0); PG8_MMA(1, 0, At, B0); PG8_BAR; PG8_SCHED;
;             PG8_STAGE(PG8_SB(1, 1), b3 + hstepB, voffB);
;             PG8_WAIT_V(6); PG8_BAR; PG8_MMA(1, 1, At, B1); PG8_BAR;
	s_waitcnt lgkmcnt(7)
	v_mfma_f32_16x16x32_bf16 v[60:63], v[150:153], v[166:169], v[60:63]
	v_mfma_f32_16x16x32_bf16 v[56:59], v[158:161], v[166:169], v[56:59]
	s_waitcnt lgkmcnt(5)
	v_mfma_f32_16x16x32_bf16 v[52:55], v[150:153], v[174:177], v[52:55]
	v_mfma_f32_16x16x32_bf16 v[48:51], v[158:161], v[174:177], v[48:51]
	s_waitcnt lgkmcnt(3)
	v_mfma_f32_16x16x32_bf16 v[36:39], v[150:153], v[182:185], v[36:39]
	v_mfma_f32_16x16x32_bf16 v[32:35], v[158:161], v[182:185], v[32:35]
	s_waitcnt lgkmcnt(1)
	v_mfma_f32_16x16x32_bf16 v[20:23], v[150:153], v[190:193], v[20:23]
	v_mfma_f32_16x16x32_bf16 v[16:19], v[158:161], v[190:193], v[16:19]
	v_mfma_f32_16x16x32_bf16 v[60:63], v[154:157], v[170:173], v[60:63]
	s_add_u32 s20, s20, 0x20080
	s_addc_u32 s21, s21, 0
	v_mfma_f32_16x16x32_bf16 v[56:59], v[162:165], v[170:173], v[56:59]
	s_add_i32 s22, s22, s31
	v_mfma_f32_16x16x32_bf16 v[52:55], v[154:157], v[178:181], v[52:55]
	v_mfma_f32_16x16x32_bf16 v[48:51], v[162:165], v[178:181], v[48:51]
	v_mfma_f32_16x16x32_bf16 v[36:39], v[154:157], v[186:189], v[36:39]
	v_mfma_f32_16x16x32_bf16 v[32:35], v[162:165], v[186:189], v[32:35]
	s_waitcnt lgkmcnt(0)
	v_mfma_f32_16x16x32_bf16 v[20:23], v[154:157], v[198:201], v[20:23]
	v_mfma_f32_16x16x32_bf16 v[16:19], v[162:165], v[198:201], v[16:19]
	s_barrier
	s_setprio 0
	s_mov_b32 m0, s22
	s_nop 0
	global_load_lds_dwordx4 v132, s[20:21]
	s_add_i32 m0, s22, 0x2000
	s_nop 0
	global_load_lds_dwordx4 v128, s[20:21]
	s_waitcnt vmcnt(6)
	s_setprio 1
	s_barrier
	v_mfma_f32_16x16x32_bf16 v[44:47], v[202:205], v[166:169], v[44:47]
	v_mfma_f32_16x16x32_bf16 v[40:43], v[210:213], v[166:169], v[40:43]
	ds_read_b128 v[150:153], v147
	v_mfma_f32_16x16x32_bf16 v[28:31], v[202:205], v[174:177], v[28:31]
	v_mfma_f32_16x16x32_bf16 v[24:27], v[210:213], v[174:177], v[24:27]
	ds_read_b128 v[154:157], v147 offset:1024
	v_mfma_f32_16x16x32_bf16 v[12:15], v[202:205], v[182:185], v[12:15]
	v_mfma_f32_16x16x32_bf16 v[8:11], v[210:213], v[182:185], v[8:11]
	ds_read_b128 v[158:161], v147 offset:2048
	v_mfma_f32_16x16x32_bf16 v[4:7], v[202:205], v[190:193], v[4:7]
	v_mfma_f32_16x16x32_bf16 v[0:3], v[210:213], v[190:193], v[0:3]
	ds_read_b128 v[162:165], v147 offset:3072
	v_mfma_f32_16x16x32_bf16 v[44:47], v[206:209], v[170:173], v[44:47]
	s_add_i32 s3, s3, 2
	v_mfma_f32_16x16x32_bf16 v[40:43], v[214:217], v[170:173], v[40:43]
	s_add_u32 s55, s55, 0x100
	s_addc_u32 s56, s56, 0
	v_mfma_f32_16x16x32_bf16 v[28:31], v[206:209], v[178:181], v[28:31]
	s_add_u32 s18, s18, 0x100
	s_addc_u32 s19, s19, 0
	v_mfma_f32_16x16x32_bf16 v[24:27], v[214:217], v[178:181], v[24:27]
	s_cmp_gt_u32 s3, 5
	v_mfma_f32_16x16x32_bf16 v[12:15], v[206:209], v[186:189], v[12:15]
	v_mfma_f32_16x16x32_bf16 v[8:11], v[214:217], v[186:189], v[8:11]
	v_mfma_f32_16x16x32_bf16 v[4:7], v[206:209], v[198:201], v[4:7]
	v_mfma_f32_16x16x32_bf16 v[0:3], v[214:217], v[198:201], v[0:3]
	s_barrier
	s_setprio 0
	s_cbranch_scc0 .LBB1_1529
; DI unsigned pack2(float a, float b) { f32x2 v = {a, b}; hwbf16x2 r = __builtin_convertvector(v, hwbf16x2); return __builtin_bit_cast(unsigned, r); }
;     DI void operator()(const f32x4 (&acc)[2][2][4][2], const Unit& u, int wr, int wc, int fr, int fq) const {
;         bf16_t* O = O1; int ldc = ldc1, pn = u.pn; if (pn >= split) { O = O2; ldc = ldc2; pn -= split; }
;         const int row0 = u.pm * BM + wr * 64 + fr, col0 = pn * BM + wc * 32 + 8 * fq;
; #pragma unroll
;         for (int ai = 0; ai < 2; ++ai)
; #pragma unroll
;             for (int m = 0; m < 4; ++m) { bf16_t* rowp = O + (size_t)(row0 + ai * HALF + m * 16) * ldc + col0;
; #pragma unroll
;                 for (int bj = 0; bj < 2; ++bj) { const f32x4 v0 = acc[ai][bj][m][0], v1 = acc[ai][bj][m][1];
;                     u32x4 o; o[0] = pack2(v0[0], v0[1]); o[1] = pack2(v0[2], v0[3]); o[2] = pack2(v1[0], v1[1]); o[3] = pack2(v1[2], v1[3]);
;                     *(u32x4*)(rowp + bj * HALF) = o; } }
;     }
	s_waitcnt lgkmcnt(0)
	s_cmp_lt_i32 s45, 12
	s_cselect_b32 s3, 0, -12
	s_mov_b32 s13, 0x1e510000
	s_movk_i32 s18, 0xc00
	s_cselect_b32 s13, s13, 0x2a510000
	s_cselect_b32 s20, s18, 0x1000
	s_add_i32 s3, s3, s45
	s_add_u32 s18, s6, s13
	v_mov_b32_e32 v150, v144
	v_mov_b32_e32 v151, v145
	s_addc_u32 s19, s7, 0
	s_lshl_b32 s10, s10, 8
	s_lshl_b32 s3, s3, 8
	s_add_i32 s10, s10, s39
	s_or_b32 s3, s3, s42
	v_add_u32_e32 v154, s10, v150
	v_lshl_add_u32 v150, v151, 3, s3
	v_ashrrev_i32_e32 v151, 31, v150
	v_lshl_add_u64 v[150:151], v[150:151], 1, s[18:19]
	v_mad_i64_i32 v[152:153], s[18:19], s20, v154, 0
	v_cvt_pk_bf16_f32 v108, v108, v109
	v_cvt_pk_bf16_f32 v109, v110, v111
	v_cvt_pk_bf16_f32 v110, v104, v105
	v_add_u32_e32 v104, 16, v154
	v_lshl_add_u64 v[152:153], v[152:153], 1, v[150:151]
	v_cvt_pk_bf16_f32 v111, v106, v107
	v_mad_i64_i32 v[104:105], s[18:19], s20, v104, 0
	v_cvt_pk_bf16_f32 v92, v92, v93
	v_cvt_pk_bf16_f32 v93, v94, v95
	v_cvt_pk_bf16_f32 v94, v88, v89
	v_add_u32_e32 v88, 32, v154
	v_cvt_pk_bf16_f32 v124, v124, v125
	v_cvt_pk_bf16_f32 v125, v126, v127
	v_cvt_pk_bf16_f32 v126, v120, v121
	v_cvt_pk_bf16_f32 v127, v122, v123
	global_store_dwordx4 v[152:153], v[108:111], off offset:256
	v_cvt_pk_bf16_f32 v95, v90, v91
	v_mad_i64_i32 v[88:89], s[18:19], s20, v88, 0
	v_lshl_add_u64 v[108:109], v[104:105], 1, v[150:151]
	v_cvt_pk_bf16_f32 v76, v76, v77
	v_cvt_pk_bf16_f32 v77, v78, v79
	v_cvt_pk_bf16_f32 v78, v72, v73
	v_add_u32_e32 v72, 48, v154
	v_cvt_pk_bf16_f32 v68, v68, v69
	v_cvt_pk_bf16_f32 v69, v70, v71
	v_cvt_pk_bf16_f32 v70, v64, v65
	v_add_u32_e32 v64, 0x80, v154
	global_store_dwordx4 v[152:153], v[124:127], off
	v_cvt_pk_bf16_f32 v104, v116, v117
	v_cvt_pk_bf16_f32 v105, v118, v119
	v_cvt_pk_bf16_f32 v106, v112, v113
	v_cvt_pk_bf16_f32 v107, v114, v115
	global_store_dwordx4 v[108:109], v[92:95], off offset:256
	v_cvt_pk_bf16_f32 v79, v74, v75
	v_mad_i64_i32 v[72:73], s[18:19], s20, v72, 0
	v_lshl_add_u64 v[92:93], v[88:89], 1, v[150:151]
	v_mad_i64_i32 v[64:65], s[18:19], s20, v64, 0
	v_cvt_pk_bf16_f32 v44, v44, v45
	v_cvt_pk_bf16_f32 v45, v46, v47
	v_cvt_pk_bf16_f32 v46, v40, v41
	v_add_u32_e32 v40, 0x90, v154
	global_store_dwordx4 v[108:109], v[104:107], off
	v_cvt_pk_bf16_f32 v88, v100, v101
	v_cvt_pk_bf16_f32 v89, v102, v103
	v_cvt_pk_bf16_f32 v90, v96, v97
	v_cvt_pk_bf16_f32 v91, v98, v99
	global_store_dwordx4 v[92:93], v[76:79], off offset:256
	v_cvt_pk_bf16_f32 v74, v80, v81
	v_cvt_pk_bf16_f32 v75, v82, v83
	v_lshl_add_u64 v[76:77], v[72:73], 1, v[150:151]
	v_cvt_pk_bf16_f32 v72, v84, v85
	v_cvt_pk_bf16_f32 v73, v86, v87
	v_cvt_pk_bf16_f32 v71, v66, v67
	v_lshl_add_u64 v[64:65], v[64:65], 1, v[150:151]
	v_cvt_pk_bf16_f32 v47, v42, v43
	v_mad_i64_i32 v[40:41], s[18:19], s20, v40, 0
	v_cvt_pk_bf16_f32 v28, v28, v29
	v_cvt_pk_bf16_f32 v29, v30, v31
	v_cvt_pk_bf16_f32 v30, v24, v25
	v_add_u32_e32 v24, 0xa0, v154
	global_store_dwordx4 v[92:93], v[88:91], off
	global_store_dwordx4 v[76:77], v[72:75], off
	global_store_dwordx4 v[76:77], v[68:71], off offset:256
	v_cvt_pk_bf16_f32 v60, v60, v61
	v_cvt_pk_bf16_f32 v61, v62, v63
	v_cvt_pk_bf16_f32 v62, v56, v57
	v_cvt_pk_bf16_f32 v63, v58, v59
	global_store_dwordx4 v[64:65], v[44:47], off offset:256
	v_cvt_pk_bf16_f32 v31, v26, v27
	v_mad_i64_i32 v[24:25], s[18:19], s20, v24, 0
	v_lshl_add_u64 v[44:45], v[40:41], 1, v[150:151]
	v_cvt_pk_bf16_f32 v12, v12, v13
	v_cvt_pk_bf16_f32 v13, v14, v15
	v_cvt_pk_bf16_f32 v14, v8, v9
	v_add_u32_e32 v8, 0xb0, v154
	global_store_dwordx4 v[64:65], v[60:63], off
	v_cvt_pk_bf16_f32 v40, v52, v53
	v_cvt_pk_bf16_f32 v41, v54, v55
	v_cvt_pk_bf16_f32 v42, v48, v49
	v_cvt_pk_bf16_f32 v43, v50, v51
	global_store_dwordx4 v[44:45], v[28:31], off offset:256
	v_cvt_pk_bf16_f32 v15, v10, v11
	v_mad_i64_i32 v[8:9], s[18:19], s20, v8, 0
	v_lshl_add_u64 v[28:29], v[24:25], 1, v[150:151]
	global_store_dwordx4 v[44:45], v[40:43], off
	v_cvt_pk_bf16_f32 v24, v36, v37
	v_cvt_pk_bf16_f32 v25, v38, v39
	v_cvt_pk_bf16_f32 v26, v32, v33
	v_cvt_pk_bf16_f32 v27, v34, v35
	global_store_dwordx4 v[28:29], v[12:15], off offset:256
	v_cvt_pk_bf16_f32 v10, v16, v17
	v_cvt_pk_bf16_f32 v11, v18, v19
	v_lshl_add_u64 v[12:13], v[8:9], 1, v[150:151]
	v_cvt_pk_bf16_f32 v8, v20, v21
	v_cvt_pk_bf16_f32 v9, v22, v23
	v_cvt_pk_bf16_f32 v4, v4, v5
	v_cvt_pk_bf16_f32 v5, v6, v7
	v_cvt_pk_bf16_f32 v6, v0, v1
	v_cvt_pk_bf16_f32 v7, v2, v3
	s_and_b64 vcc, exec, s[40:41]
	s_mov_b32 s45, s49
	s_mov_b32 s10, s12
	s_mov_b64 s[18:19], s[16:17]
	s_mov_b64 s[20:21], s[14:15]
	global_store_dwordx4 v[28:29], v[24:27], off
	global_store_dwordx4 v[12:13], v[8:11], off
	global_store_dwordx4 v[12:13], v[4:7], off offset:256
	s_cbranch_vccz .LBB1_1526
	s_waitcnt vmcnt(0)
	s_cmpk_gt_u32 s4, 0xff
	s_cbranch_scc1 .LBB1_1533
	s_barrier

; #define PG8_STAGE(bufoff, gbase, voff) do { _Pragma("unroll") for (int _i = 0; _i < 2; ++_i) \
;         __builtin_amdgcn_global_load_lds((const unsigned*)((const char*)(gbase) + (voff)[_i]), (LAS unsigned*)(lds + (bufoff) + ldsw + _i * 8192), 16, 0, 0); } while (0)
; #define PG8_LDA(dst, b, h) do { _Pragma("unroll") for (int m = 0; m < 4; ++m) _Pragma("unroll") for (int k = 0; k < 2; ++k) dst[m][k] = *(const LAS bf16x8*)(lds + PG8_SA(b, h) + aoff + m * 2048 + k * 1024); } while (0)
; #define PG8_WAIT_V(n) asm volatile("s_waitcnt vmcnt(" #n ")" ::: "memory")
; #define PG8_BAR __builtin_amdgcn_s_barrier()
; template <class Map, class Epi>
; DI void gemm_phase(LAS unsigned char* lds, const Map& MP, const Epi& E, const int nM, const int nN, const int K, const int lda, const int ldb) {
;     ...
;         for (int t = 0; t < nt; t += 2) {
;             const bool last = (t == nt - 2);
;             const char* a1 = cA + (size_t)(t + 1) * kstep;
;             const char* a2 = last ? nA : cA + (size_t)(t + 2) * kstep; const char* b2 = last ? nB : cB + (size_t)(t + 2) * kstep;
;             const char* a3 = a2 + kstep; const char* b3 = b2 + kstep;
;             PG8_LDB(B0, 0, 0); PG8_SCHED; PG8_LDA(At, 0, 0); PG8_STAGE(PG8_SA(1, 1), a1 + hstepA, voffA);
;             PG8_WAIT_L(8); PG8_BAR; PG8_WAIT_L(0); PG8_MMA(0, 0, At, B0); PG8_BAR; PG8_SCHED;
;             PG8_LDB(B1, 0, 1); PG8_STAGE(PG8_SB(0, 0), b2, voffB);
;             PG8_BAR; PG8_WAIT_L(0); PG8_MMA(0, 1, At, B1); PG8_BAR;
;             PG8_LDA(At, 0, 1); PG8_STAGE(PG8_SA(0, 0), a2, voffA);
;             PG8_BAR; PG8_WAIT_L(0); PG8_MMA(1, 0, At, B0); PG8_BAR; PG8_SCHED;
;             PG8_STAGE(PG8_SB(0, 1), b2 + hstepB, voffB);
;             PG8_WAIT_V(6); PG8_BAR; PG8_MMA(1, 1, At, B1); PG8_BAR;
;             PG8_LDB(B0, 1, 0); PG8_SCHED; PG8_LDA(At, 1, 0); PG8_STAGE(PG8_SA(0, 1), a2 + hstepA, voffA);
;             PG8_WAIT_L(8); PG8_BAR; PG8_WAIT_L(0); PG8_MMA(0, 0, At, B0); PG8_BAR; PG8_SCHED;
;             PG8_LDB(B1, 1, 1); PG8_STAGE(PG8_SB(1, 0), b3, voffB);
;             PG8_BAR; PG8_WAIT_L(0); PG8_MMA(0, 1, At, B1); PG8_BAR;
;             PG8_LDA(At, 1, 1); PG8_STAGE(PG8_SA(1, 0), a3, voffA);
;             PG8_BAR; PG8_WAIT_L(0); PG8_MMA(1, 0, At, B0); PG8_BAR; PG8_SCHED;
;             PG8_STAGE(PG8_SB(1, 1), b3 + hstepB, voffB);
;             PG8_WAIT_V(6); PG8_BAR; PG8_MMA(1, 1, At, B1); PG8_BAR;
.LBB1_1764:
	s_add_u32 s12, s10, 0xfff80080
	s_addc_u32 s13, s11, -1
	s_cmp_eq_u32 s3, 28
	s_cselect_b32 s15, s37, s13
	s_cselect_b32 s14, s38, s12
	s_cselect_b32 s13, s39, s48
	s_cselect_b32 s12, s45, s47
	s_add_i32 m0, s24, 0xc000
	ds_read_b128 v[168:171], v150
	global_load_lds_dwordx4 v138, s[10:11]
	ds_read_b128 v[172:175], v150 offset:1024
	ds_read_b128 v[176:179], v150 offset:2048
	ds_read_b128 v[180:183], v150 offset:3072
	ds_read_b128 v[184:187], v150 offset:4096
	ds_read_b128 v[188:191], v150 offset:5120
	ds_read_b128 v[192:195], v150 offset:6144
	ds_read_b128 v[198:201], v150 offset:7168
	s_add_i32 m0, s24, 0xe000
	s_nop 0
	global_load_lds_dwordx4 v136, s[10:11]
	s_waitcnt lgkmcnt(8)
	s_setprio 1
	s_barrier
	s_waitcnt lgkmcnt(7)
	v_mfma_f32_16x16x32_bf16 v[124:127], v[152:155], v[168:171], v[124:127]
	v_mfma_f32_16x16x32_bf16 v[120:123], v[160:163], v[168:171], v[120:123]
	s_waitcnt lgkmcnt(5)
	v_mfma_f32_16x16x32_bf16 v[108:111], v[152:155], v[176:179], v[108:111]
	v_mfma_f32_16x16x32_bf16 v[104:107], v[160:163], v[176:179], v[104:107]
	s_waitcnt lgkmcnt(3)
	v_mfma_f32_16x16x32_bf16 v[92:95], v[152:155], v[184:187], v[92:95]
	v_mfma_f32_16x16x32_bf16 v[88:91], v[160:163], v[184:187], v[88:91]
	s_waitcnt lgkmcnt(1)
	v_mfma_f32_16x16x32_bf16 v[76:79], v[152:155], v[192:195], v[76:79]
	v_mfma_f32_16x16x32_bf16 v[72:75], v[160:163], v[192:195], v[72:75]
	v_mfma_f32_16x16x32_bf16 v[124:127], v[156:159], v[172:175], v[124:127]
	s_add_i32 s49, s35, s22
	v_mfma_f32_16x16x32_bf16 v[120:123], v[164:167], v[172:175], v[120:123]
	v_lshl_add_u64 v[144:145], s[12:13], 0, v[132:133]
	v_mfma_f32_16x16x32_bf16 v[108:111], v[156:159], v[180:183], v[108:111]
	v_lshl_add_u64 v[218:219], s[12:13], 0, v[128:129]
	v_mfma_f32_16x16x32_bf16 v[104:107], v[164:167], v[180:183], v[104:107]
	v_mfma_f32_16x16x32_bf16 v[92:95], v[156:159], v[188:191], v[92:95]
	v_mfma_f32_16x16x32_bf16 v[88:91], v[164:167], v[188:191], v[88:91]
	s_waitcnt lgkmcnt(0)
	v_mfma_f32_16x16x32_bf16 v[76:79], v[156:159], v[198:201], v[76:79]
	v_mfma_f32_16x16x32_bf16 v[72:75], v[164:167], v[198:201], v[72:75]
	s_barrier
	s_setprio 0
	s_mov_b32 m0, s49
	ds_read_b128 v[202:205], v151
	global_load_lds_dwordx4 v[144:145], off
	ds_read_b128 v[206:209], v151 offset:1024
	ds_read_b128 v[210:213], v151 offset:2048
	ds_read_b128 v[214:217], v151 offset:3072
	s_add_i32 m0, s49, 0x2000
	s_nop 0
	global_load_lds_dwordx4 v[218:219], off
	s_setprio 1
	s_barrier
	s_waitcnt lgkmcnt(3)
	v_mfma_f32_16x16x32_bf16 v[116:119], v[202:205], v[168:171], v[116:119]
	s_waitcnt lgkmcnt(1)
	v_mfma_f32_16x16x32_bf16 v[112:115], v[210:213], v[168:171], v[112:115]
	v_mfma_f32_16x16x32_bf16 v[100:103], v[202:205], v[176:179], v[100:103]
	v_mfma_f32_16x16x32_bf16 v[96:99], v[210:213], v[176:179], v[96:99]
	v_mfma_f32_16x16x32_bf16 v[84:87], v[202:205], v[184:187], v[84:87]
	v_mfma_f32_16x16x32_bf16 v[80:83], v[210:213], v[184:187], v[80:83]
	v_mfma_f32_16x16x32_bf16 v[68:71], v[202:205], v[192:195], v[68:71]
	v_mfma_f32_16x16x32_bf16 v[64:67], v[210:213], v[192:195], v[64:67]
	v_mfma_f32_16x16x32_bf16 v[116:119], v[206:209], v[172:175], v[116:119]
	v_lshl_add_u64 v[222:223], s[14:15], 0, v[130:131]
	s_mov_b32 m0, s24
	s_waitcnt lgkmcnt(0)
	v_mfma_f32_16x16x32_bf16 v[112:115], v[214:217], v[172:175], v[112:115]
	v_lshl_add_u64 v[220:221], s[14:15], 0, v[134:135]
	v_mfma_f32_16x16x32_bf16 v[100:103], v[206:209], v[180:183], v[100:103]
	v_mfma_f32_16x16x32_bf16 v[96:99], v[214:217], v[180:183], v[96:99]
	v_mfma_f32_16x16x32_bf16 v[84:87], v[206:209], v[188:191], v[84:87]
	v_mfma_f32_16x16x32_bf16 v[80:83], v[214:217], v[188:191], v[80:83]
	v_mfma_f32_16x16x32_bf16 v[68:71], v[206:209], v[198:201], v[68:71]
	v_mfma_f32_16x16x32_bf16 v[64:67], v[214:217], v[198:201], v[64:67]
	s_barrier
	s_setprio 0
	ds_read_b128 v[168:171], v150 offset:16384
	global_load_lds_dwordx4 v[220:221], off
	ds_read_b128 v[172:175], v150 offset:17408
	ds_read_b128 v[176:179], v150 offset:18432
	ds_read_b128 v[180:183], v150 offset:19456
	ds_read_b128 v[184:187], v150 offset:20480
	ds_read_b128 v[188:191], v150 offset:21504
	ds_read_b128 v[192:195], v150 offset:22528
	ds_read_b128 v[198:201], v150 offset:23552
	s_mov_b32 m0, s9
	s_nop 0
	global_load_lds_dwordx4 v[222:223], off
	s_waitcnt vmcnt(10)
	s_setprio 1
	s_barrier
	s_waitcnt lgkmcnt(7)
	v_mfma_f32_16x16x32_bf16 v[60:63], v[152:155], v[168:171], v[60:63]
	v_mfma_f32_16x16x32_bf16 v[56:59], v[160:163], v[168:171], v[56:59]
	s_waitcnt lgkmcnt(5)
	v_mfma_f32_16x16x32_bf16 v[44:47], v[152:155], v[176:179], v[44:47]
	v_mfma_f32_16x16x32_bf16 v[40:43], v[160:163], v[176:179], v[40:43]
	s_waitcnt lgkmcnt(3)
	v_mfma_f32_16x16x32_bf16 v[28:31], v[152:155], v[184:187], v[28:31]
	v_mfma_f32_16x16x32_bf16 v[24:27], v[160:163], v[184:187], v[24:27]
	s_waitcnt lgkmcnt(1)
	v_mfma_f32_16x16x32_bf16 v[12:15], v[152:155], v[192:195], v[12:15]
	v_mfma_f32_16x16x32_bf16 v[8:11], v[160:163], v[192:195], v[8:11]
	v_mfma_f32_16x16x32_bf16 v[60:63], v[156:159], v[172:175], v[60:63]
	s_add_u32 s54, s12, 0x80000
	s_addc_u32 s55, s13, 0
	v_mfma_f32_16x16x32_bf16 v[56:59], v[164:167], v[172:175], v[56:59]
	s_add_i32 s49, s36, s22
	v_mfma_f32_16x16x32_bf16 v[44:47], v[156:159], v[180:183], v[44:47]
	v_mfma_f32_16x16x32_bf16 v[40:43], v[164:167], v[180:183], v[40:43]
	v_mfma_f32_16x16x32_bf16 v[28:31], v[156:159], v[188:191], v[28:31]
	v_mfma_f32_16x16x32_bf16 v[24:27], v[164:167], v[188:191], v[24:27]
	s_waitcnt lgkmcnt(0)
	v_mfma_f32_16x16x32_bf16 v[12:15], v[156:159], v[198:201], v[12:15]
	v_mfma_f32_16x16x32_bf16 v[8:11], v[164:167], v[198:201], v[8:11]
	s_barrier
; #define PG8_STAGE(bufoff, gbase, voff) do { _Pragma("unroll") for (int _i = 0; _i < 2; ++_i) \
;         __builtin_amdgcn_global_load_lds((const unsigned*)((const char*)(gbase) + (voff)[_i]), (LAS unsigned*)(lds + (bufoff) + ldsw + _i * 8192), 16, 0, 0); } while (0)
; #define PG8_LDA(dst, b, h) do { _Pragma("unroll") for (int m = 0; m < 4; ++m) _Pragma("unroll") for (int k = 0; k < 2; ++k) dst[m][k] = *(const LAS bf16x8*)(lds + PG8_SA(b, h) + aoff + m * 2048 + k * 1024); } while (0)
; #define PG8_WAIT_V(n) asm volatile("s_waitcnt vmcnt(" #n ")" ::: "memory")
; #define PG8_BAR __builtin_amdgcn_s_barrier()
; template <class Map, class Epi>
; DI void gemm_phase(LAS unsigned char* lds, const Map& MP, const Epi& E, const int nM, const int nN, const int K, const int lda, const int ldb) {
;     ...
;         for (int t = 0; t < nt; t += 2) {
;             const bool last = (t == nt - 2);
;             const char* a1 = cA + (size_t)(t + 1) * kstep;
;             const char* a2 = last ? nA : cA + (size_t)(t + 2) * kstep; const char* b2 = last ? nB : cB + (size_t)(t + 2) * kstep;
;             const char* a3 = a2 + kstep; const char* b3 = b2 + kstep;
;             PG8_LDB(B0, 0, 0); PG8_SCHED; PG8_LDA(At, 0, 0); PG8_STAGE(PG8_SA(1, 1), a1 + hstepA, voffA);
;             PG8_WAIT_L(8); PG8_BAR; PG8_WAIT_L(0); PG8_MMA(0, 0, At, B0); PG8_BAR; PG8_SCHED;
;             PG8_LDB(B1, 0, 1); PG8_STAGE(PG8_SB(0, 0), b2, voffB);
;             PG8_BAR; PG8_WAIT_L(0); PG8_MMA(0, 1, At, B1); PG8_BAR;
;             PG8_LDA(At, 0, 1); PG8_STAGE(PG8_SA(0, 0), a2, voffA);
;             PG8_BAR; PG8_WAIT_L(0); PG8_MMA(1, 0, At, B0); PG8_BAR; PG8_SCHED;
;             PG8_STAGE(PG8_SB(0, 1), b2 + hstepB, voffB);
;             PG8_WAIT_V(6); PG8_BAR; PG8_MMA(1, 1, At, B1); PG8_BAR;
;             PG8_LDB(B0, 1, 0); PG8_SCHED; PG8_LDA(At, 1, 0); PG8_STAGE(PG8_SA(0, 1), a2 + hstepA, voffA);
;             PG8_WAIT_L(8); PG8_BAR; PG8_WAIT_L(0); PG8_MMA(0, 0, At, B0); PG8_BAR; PG8_SCHED;
;             PG8_LDB(B1, 1, 1); PG8_STAGE(PG8_SB(1, 0), b3, voffB);
;             PG8_BAR; PG8_WAIT_L(0); PG8_MMA(0, 1, At, B1); PG8_BAR;
;             PG8_LDA(At, 1, 1); PG8_STAGE(PG8_SA(1, 0), a3, voffA);
;             PG8_BAR; PG8_WAIT_L(0); PG8_MMA(1, 0, At, B0); PG8_BAR; PG8_SCHED;
;             PG8_STAGE(PG8_SB(1, 1), b3 + hstepB, voffB);
;             PG8_WAIT_V(6); PG8_BAR; PG8_MMA(1, 1, At, B1); PG8_BAR;
	s_setprio 0
	s_mov_b32 m0, s49
	s_nop 0
	global_load_lds_dwordx4 v132, s[54:55]
	s_add_i32 m0, s49, 0x2000
	s_nop 0
	global_load_lds_dwordx4 v128, s[54:55]
	s_waitcnt vmcnt(6)
	s_setprio 1
	s_barrier
	v_mfma_f32_16x16x32_bf16 v[52:55], v[202:205], v[168:171], v[52:55]
	v_mfma_f32_16x16x32_bf16 v[48:51], v[210:213], v[168:171], v[48:51]
	s_add_i32 s49, 0, 0x18000
	v_add_u32_e32 v164, s49, v148
	ds_read_b128 v[152:155], v164
	v_mfma_f32_16x16x32_bf16 v[36:39], v[202:205], v[176:179], v[36:39]
	v_mfma_f32_16x16x32_bf16 v[32:35], v[210:213], v[176:179], v[32:35]
	ds_read_b128 v[156:159], v164 offset:1024
	v_mfma_f32_16x16x32_bf16 v[20:23], v[202:205], v[184:187], v[20:23]
	v_mfma_f32_16x16x32_bf16 v[16:19], v[210:213], v[184:187], v[16:19]
	ds_read_b128 v[160:163], v164 offset:2048
	v_mfma_f32_16x16x32_bf16 v[4:7], v[202:205], v[192:195], v[4:7]
	v_mfma_f32_16x16x32_bf16 v[0:3], v[210:213], v[192:195], v[0:3]
	ds_read_b128 v[164:167], v164 offset:3072
	v_mfma_f32_16x16x32_bf16 v[52:55], v[206:209], v[172:175], v[52:55]
	s_add_u32 s14, s14, 0x80000
	s_addc_u32 s15, s15, 0
	v_mfma_f32_16x16x32_bf16 v[48:51], v[214:217], v[172:175], v[48:51]
	v_mfma_f32_16x16x32_bf16 v[36:39], v[206:209], v[180:183], v[36:39]
	v_mfma_f32_16x16x32_bf16 v[32:35], v[214:217], v[180:183], v[32:35]
	v_mfma_f32_16x16x32_bf16 v[20:23], v[206:209], v[188:191], v[20:23]
	v_mfma_f32_16x16x32_bf16 v[16:19], v[214:217], v[188:191], v[16:19]
	v_mfma_f32_16x16x32_bf16 v[4:7], v[206:209], v[198:201], v[4:7]
	v_mfma_f32_16x16x32_bf16 v[0:3], v[214:217], v[198:201], v[0:3]
	s_barrier
	s_setprio 0
	s_mov_b32 m0, s25
	ds_read_b128 v[168:171], v150 offset:32768
	global_load_lds_dwordx4 v134, s[14:15]
	ds_read_b128 v[172:175], v150 offset:33792
	ds_read_b128 v[176:179], v150 offset:34816
	ds_read_b128 v[180:183], v150 offset:35840
	ds_read_b128 v[184:187], v150 offset:36864
	ds_read_b128 v[188:191], v150 offset:37888
	ds_read_b128 v[192:195], v150 offset:38912
	ds_read_b128 v[198:201], v150 offset:39936
	s_mov_b32 m0, s26
	s_nop 0
	global_load_lds_dwordx4 v130, s[14:15]
	s_waitcnt lgkmcnt(8)
	s_setprio 1
	s_barrier
	s_waitcnt lgkmcnt(7)
	v_mfma_f32_16x16x32_bf16 v[124:127], v[152:155], v[168:171], v[124:127]
	v_mfma_f32_16x16x32_bf16 v[120:123], v[160:163], v[168:171], v[120:123]
	s_waitcnt lgkmcnt(5)
	v_mfma_f32_16x16x32_bf16 v[108:111], v[152:155], v[176:179], v[108:111]
	v_mfma_f32_16x16x32_bf16 v[104:107], v[160:163], v[176:179], v[104:107]
	s_waitcnt lgkmcnt(3)
	v_mfma_f32_16x16x32_bf16 v[92:95], v[152:155], v[184:187], v[92:95]
	v_mfma_f32_16x16x32_bf16 v[88:91], v[160:163], v[184:187], v[88:91]
	s_waitcnt lgkmcnt(1)
	v_mfma_f32_16x16x32_bf16 v[76:79], v[152:155], v[192:195], v[76:79]
	v_mfma_f32_16x16x32_bf16 v[72:75], v[160:163], v[192:195], v[72:75]
	v_mfma_f32_16x16x32_bf16 v[124:127], v[156:159], v[172:175], v[124:127]
	s_add_i32 s14, 0, 0x1c000
	v_mfma_f32_16x16x32_bf16 v[120:123], v[164:167], v[172:175], v[120:123]
	s_add_i32 s15, s49, s22
	v_mfma_f32_16x16x32_bf16 v[108:111], v[156:159], v[180:183], v[108:111]
	v_add_u32_e32 v196, s14, v148
	v_mfma_f32_16x16x32_bf16 v[104:107], v[164:167], v[180:183], v[104:107]
	v_lshl_add_u64 v[144:145], v[144:145], 0, s[42:43]
	v_mfma_f32_16x16x32_bf16 v[92:95], v[156:159], v[188:191], v[92:95]
	v_mfma_f32_16x16x32_bf16 v[88:91], v[164:167], v[188:191], v[88:91]
	s_waitcnt lgkmcnt(0)
	v_mfma_f32_16x16x32_bf16 v[76:79], v[156:159], v[198:201], v[76:79]
	v_mfma_f32_16x16x32_bf16 v[72:75], v[164:167], v[198:201], v[72:75]
	s_barrier
	s_setprio 0
	s_mov_b32 m0, s15
	ds_read_b128 v[202:205], v196
	global_load_lds_dwordx4 v[144:145], off
	ds_read_b128 v[206:209], v196 offset:1024
	ds_read_b128 v[210:213], v196 offset:2048
	ds_read_b128 v[214:217], v196 offset:3072
	v_lshl_add_u64 v[144:145], v[218:219], 0, s[42:43]
	s_add_i32 m0, s15, 0x2000
	s_nop 0
	global_load_lds_dwordx4 v[144:145], off
	s_setprio 1
	s_barrier
	s_waitcnt lgkmcnt(3)
	v_mfma_f32_16x16x32_bf16 v[116:119], v[202:205], v[168:171], v[116:119]
	s_waitcnt lgkmcnt(1)
	v_mfma_f32_16x16x32_bf16 v[112:115], v[210:213], v[168:171], v[112:115]
	v_mfma_f32_16x16x32_bf16 v[100:103], v[202:205], v[176:179], v[100:103]
	v_mfma_f32_16x16x32_bf16 v[96:99], v[210:213], v[176:179], v[96:99]
	v_mfma_f32_16x16x32_bf16 v[84:87], v[202:205], v[184:187], v[84:87]
	v_mfma_f32_16x16x32_bf16 v[80:83], v[210:213], v[184:187], v[80:83]
	v_mfma_f32_16x16x32_bf16 v[68:71], v[202:205], v[192:195], v[68:71]
	v_mfma_f32_16x16x32_bf16 v[64:67], v[210:213], v[192:195], v[64:67]
	v_mfma_f32_16x16x32_bf16 v[116:119], v[206:209], v[172:175], v[116:119]
	s_mov_b32 m0, s30
	s_waitcnt lgkmcnt(0)
	v_mfma_f32_16x16x32_bf16 v[112:115], v[214:217], v[172:175], v[112:115]
	v_lshl_add_u64 v[144:145], v[220:221], 0, s[42:43]
	v_mfma_f32_16x16x32_bf16 v[100:103], v[206:209], v[180:183], v[100:103]
	v_mfma_f32_16x16x32_bf16 v[96:99], v[214:217], v[180:183], v[96:99]
	v_mfma_f32_16x16x32_bf16 v[84:87], v[206:209], v[188:191], v[84:87]
	v_mfma_f32_16x16x32_bf16 v[80:83], v[214:217], v[188:191], v[80:83]
	v_mfma_f32_16x16x32_bf16 v[68:71], v[206:209], v[198:201], v[68:71]
	v_mfma_f32_16x16x32_bf16 v[64:67], v[214:217], v[198:201], v[64:67]
	s_barrier
	s_setprio 0
	ds_read_b128 v[168:171], v150 offset:49152
	global_load_lds_dwordx4 v[144:145], off
	ds_read_b128 v[172:175], v150 offset:50176
	ds_read_b128 v[176:179], v150 offset:51200
	ds_read_b128 v[180:183], v150 offset:52224
	ds_read_b128 v[184:187], v150 offset:53248
	ds_read_b128 v[188:191], v150 offset:54272
	ds_read_b128 v[192:195], v150 offset:55296
	ds_read_b128 v[198:201], v150 offset:56320
	v_lshl_add_u64 v[144:145], v[222:223], 0, s[42:43]
	s_mov_b32 m0, s31
	s_nop 0
	global_load_lds_dwordx4 v[144:145], off
	s_waitcnt vmcnt(10)
	s_setprio 1
	s_barrier
; DI unsigned pack2(float a, float b) { f32x2 v = {a, b}; hwbf16x2 r = __builtin_convertvector(v, hwbf16x2); return __builtin_bit_cast(unsigned, r); }
; DI float bflo(unsigned w) { return __uint_as_float(w << 16); }
;     DI void operator()(const f32x4 (&acc)[2][2][4][2], const Unit& u, int wr, int wc, int fr, int fq) const {
;     ...
;         for (int ai = 0; ai < 2; ++ai)
; #pragma unroll
;             for (int m = 0; m < 4; ++m) { const size_t ro = (size_t)(row0 + ai * HALF + m * 16) * D + col0;
; #pragma unroll
;                 for (int bj = 0; bj < 2; ++bj) {
;                     f32x4 x0, x1;
;                     if constexpr (IB) { const u32x4 w = *(const u32x4*)((const bf16_t*)Xin + ro + bj * HALF);
;                         x0 = (f32x4){bflo(w[0]), bfhi(w[0]), bflo(w[1]), bfhi(w[1])}; x1 = (f32x4){bflo(w[2]), bfhi(w[2]), bflo(w[3]), bfhi(w[3])}; }
;                     else { x0 = *(const f32x4*)((const float*)Xin + ro + bj * HALF); x1 = *(const f32x4*)((const float*)Xin + ro + bj * HALF + 4); }
;                     x0 += acc[ai][bj][m][0] * sc[bj][0]; x1 += acc[ai][bj][m][1] * sc[bj][1];
;                     if constexpr (OB) { u32x4 o; o[0] = pack2(x0[0], x0[1]); o[1] = pack2(x0[2], x0[3]); o[2] = pack2(x1[0], x1[1]); o[3] = pack2(x1[2], x1[3]);
;                         *(u32x4*)((bf16_t*)Xout + ro + bj * HALF) = o; }
;                     else { *(f32x4*)((float*)Xout + ro + bj * HALF) = x0; *(f32x4*)((float*)Xout + ro + bj * HALF + 4) = x1; } } }
; template <class Map, class Epi>
; DI void gemm_phase(LAS unsigned char* lds, const Map& MP, const Epi& E, const int nM, const int nN, const int K, const int lda, const int ldb) {
;     ...
;             PG8_WAIT_V(6); PG8_BAR; PG8_MMA(1, 1, At, B1); PG8_BAR;
;             PG8_LDB(B0, 1, 0); PG8_SCHED; PG8_LDA(At, 1, 0); PG8_STAGE(PG8_SA(0, 1), a2 + hstepA, voffA);
;             PG8_WAIT_L(8); PG8_BAR; PG8_WAIT_L(0); PG8_MMA(0, 0, At, B0); PG8_BAR; PG8_SCHED;
;             PG8_LDB(B1, 1, 1); PG8_STAGE(PG8_SB(1, 0), b3, voffB);
;             PG8_BAR; PG8_WAIT_L(0); PG8_MMA(0, 1, At, B1); PG8_BAR;
;             PG8_LDA(At, 1, 1); PG8_STAGE(PG8_SA(1, 0), a3, voffA);
;             PG8_BAR; PG8_WAIT_L(0); PG8_MMA(1, 0, At, B0); PG8_BAR; PG8_SCHED;
;             PG8_STAGE(PG8_SB(1, 1), b3 + hstepB, voffB);
;             PG8_WAIT_V(6); PG8_BAR; PG8_MMA(1, 1, At, B1); PG8_BAR;
	s_waitcnt lgkmcnt(7)
	v_mfma_f32_16x16x32_bf16 v[60:63], v[152:155], v[168:171], v[60:63]
	v_mfma_f32_16x16x32_bf16 v[56:59], v[160:163], v[168:171], v[56:59]
	s_waitcnt lgkmcnt(5)
	v_mfma_f32_16x16x32_bf16 v[44:47], v[152:155], v[176:179], v[44:47]
	v_mfma_f32_16x16x32_bf16 v[40:43], v[160:163], v[176:179], v[40:43]
	s_waitcnt lgkmcnt(3)
	v_mfma_f32_16x16x32_bf16 v[28:31], v[152:155], v[184:187], v[28:31]
	v_mfma_f32_16x16x32_bf16 v[24:27], v[160:163], v[184:187], v[24:27]
	s_waitcnt lgkmcnt(1)
	v_mfma_f32_16x16x32_bf16 v[12:15], v[152:155], v[192:195], v[12:15]
	v_mfma_f32_16x16x32_bf16 v[8:11], v[160:163], v[192:195], v[8:11]
	v_mfma_f32_16x16x32_bf16 v[60:63], v[156:159], v[172:175], v[60:63]
	s_add_u32 s12, s12, 0x80080
	s_addc_u32 s13, s13, 0
	v_mfma_f32_16x16x32_bf16 v[56:59], v[164:167], v[172:175], v[56:59]
	s_add_i32 s14, s14, s22
	v_mfma_f32_16x16x32_bf16 v[44:47], v[156:159], v[180:183], v[44:47]
	v_mfma_f32_16x16x32_bf16 v[40:43], v[164:167], v[180:183], v[40:43]
	v_mfma_f32_16x16x32_bf16 v[28:31], v[156:159], v[188:191], v[28:31]
	v_mfma_f32_16x16x32_bf16 v[24:27], v[164:167], v[188:191], v[24:27]
	s_waitcnt lgkmcnt(0)
	v_mfma_f32_16x16x32_bf16 v[12:15], v[156:159], v[198:201], v[12:15]
	v_mfma_f32_16x16x32_bf16 v[8:11], v[164:167], v[198:201], v[8:11]
	s_barrier
	s_setprio 0
	s_mov_b32 m0, s14
	s_nop 0
	global_load_lds_dwordx4 v132, s[12:13]
	s_add_i32 m0, s14, 0x2000
	s_nop 0
	global_load_lds_dwordx4 v128, s[12:13]
	s_waitcnt vmcnt(6)
	s_setprio 1
	s_barrier
	v_mfma_f32_16x16x32_bf16 v[52:55], v[202:205], v[168:171], v[52:55]
	v_mfma_f32_16x16x32_bf16 v[48:51], v[210:213], v[168:171], v[48:51]
	ds_read_b128 v[152:155], v149
	v_mfma_f32_16x16x32_bf16 v[36:39], v[202:205], v[176:179], v[36:39]
	v_mfma_f32_16x16x32_bf16 v[32:35], v[210:213], v[176:179], v[32:35]
	ds_read_b128 v[156:159], v149 offset:1024
	v_mfma_f32_16x16x32_bf16 v[20:23], v[202:205], v[184:187], v[20:23]
	v_mfma_f32_16x16x32_bf16 v[16:19], v[210:213], v[184:187], v[16:19]
	ds_read_b128 v[160:163], v149 offset:2048
	v_mfma_f32_16x16x32_bf16 v[4:7], v[202:205], v[192:195], v[4:7]
	v_mfma_f32_16x16x32_bf16 v[0:3], v[210:213], v[192:195], v[0:3]
	ds_read_b128 v[164:167], v149 offset:3072
	v_mfma_f32_16x16x32_bf16 v[52:55], v[206:209], v[172:175], v[52:55]
	s_add_i32 s3, s3, 2
	v_mfma_f32_16x16x32_bf16 v[48:51], v[214:217], v[172:175], v[48:51]
	s_add_u32 s47, s47, 0x100
	s_addc_u32 s48, s48, 0
	v_mfma_f32_16x16x32_bf16 v[36:39], v[206:209], v[180:183], v[36:39]
	s_add_u32 s10, s10, 0x100
	s_addc_u32 s11, s11, 0
	v_mfma_f32_16x16x32_bf16 v[32:35], v[214:217], v[180:183], v[32:35]
	s_cmp_gt_u32 s3, 29
	v_mfma_f32_16x16x32_bf16 v[20:23], v[206:209], v[188:191], v[20:23]
	v_mfma_f32_16x16x32_bf16 v[16:19], v[214:217], v[188:191], v[16:19]
	v_mfma_f32_16x16x32_bf16 v[4:7], v[206:209], v[198:201], v[4:7]
	v_mfma_f32_16x16x32_bf16 v[0:3], v[214:217], v[198:201], v[0:3]
	s_barrier
	s_setprio 0
	s_cbranch_scc0 .LBB1_1764
	s_waitcnt lgkmcnt(0)
	v_mov_b32_e32 v152, v147
	v_mov_b32_e32 v144, v146
	s_lshl_b32 s2, s2, 8
	s_or_b32 s2, s2, s29
	v_lshl_add_u32 v144, v144, 3, s2
	s_lshl_b32 s2, s8, 8
	s_add_i32 s2, s2, s28
	v_add_u32_e32 v152, s2, v152
	v_ashrrev_i32_e32 v153, 31, v152
	v_lshlrev_b64 v[152:153], 12, v[152:153]
	v_ashrrev_i32_e32 v145, 31, v144
	v_lshl_add_u64 v[152:153], s[4:5], 0, v[152:153]
	v_lshl_add_u64 v[144:145], v[144:145], 1, v[152:153]
	global_load_dwordx4 v[160:163], v[144:145], off
	global_load_dwordx4 v[164:167], v[144:145], off offset:256
	s_mov_b64 s[98:99], 0x10000
	v_lshl_add_u64 v[154:155], v[144:145], 0, s[98:99]
	global_load_dwordx4 v[168:171], v[154:155], off
	global_load_dwordx4 v[172:175], v[154:155], off offset:256
	s_mov_b64 s[98:99], 0x20000
	v_lshl_add_u64 v[154:155], v[144:145], 0, s[98:99]
	global_load_dwordx4 v[176:179], v[154:155], off
	global_load_dwordx4 v[180:183], v[154:155], off offset:256
	s_mov_b64 s[98:99], 0x30000
	v_lshl_add_u64 v[154:155], v[144:145], 0, s[98:99]
	global_load_dwordx4 v[184:187], v[154:155], off
	global_load_dwordx4 v[188:191], v[154:155], off offset:256
	s_mov_b64 s[98:99], 0x80000
	v_lshl_add_u64 v[154:155], v[144:145], 0, s[98:99]
	global_load_dwordx4 v[192:195], v[154:155], off
	global_load_dwordx4 v[198:201], v[154:155], off offset:256
	s_mov_b64 s[98:99], 0x90000
	v_lshl_add_u64 v[154:155], v[144:145], 0, s[98:99]
	global_load_dwordx4 v[202:205], v[154:155], off
	global_load_dwordx4 v[206:209], v[154:155], off offset:256
	s_mov_b64 s[98:99], 0xa0000
	v_lshl_add_u64 v[154:155], v[144:145], 0, s[98:99]
	global_load_dwordx4 v[210:213], v[154:155], off
	global_load_dwordx4 v[214:217], v[154:155], off offset:256
	s_mov_b64 s[98:99], 0xb0000
	v_lshl_add_u64 v[154:155], v[144:145], 0, s[98:99]
	global_load_dwordx4 v[248:251], v[154:155], off
	global_load_dwordx4 v[252:255], v[154:155], off offset:256
	s_waitcnt vmcnt(15)
	s_nop 1
	v_mov_b32_e32 v152, v160
	v_mov_b32_e32 v153, v161
	v_mov_b32_e32 v154, v162
	v_mov_b32_e32 v155, v163
	s_mov_b64 s[2:3], 0x10000
	s_mov_b32 s8, s46
	s_mov_b64 s[10:11], s[6:7]
	s_mov_b64 s[12:13], s[52:53]
	s_waitcnt lgkmcnt(0)
	v_lshlrev_b32_e32 v156, 16, v152
	v_and_b32_e32 v157, 0xffff0000, v152
	v_lshlrev_b32_e32 v152, 16, v153
	v_and_b32_e32 v153, 0xffff0000, v153
	v_lshlrev_b32_e32 v158, 16, v154
	v_and_b32_e32 v159, 0xffff0000, v154
	v_lshlrev_b32_e32 v154, 16, v155
	v_and_b32_e32 v155, 0xffff0000, v155
	v_pk_add_f32 v[126:127], v[126:127], v[152:153]
	v_pk_add_f32 v[124:125], v[124:125], v[156:157]
	v_pk_add_f32 v[152:153], v[122:123], v[154:155]
	v_pk_add_f32 v[122:123], v[120:121], v[158:159]
	v_cvt_pk_bf16_f32 v120, v124, v125
	v_cvt_pk_bf16_f32 v121, v126, v127
	v_cvt_pk_bf16_f32 v122, v122, v123
	v_cvt_pk_bf16_f32 v123, v152, v153
	global_store_dwordx4 v[144:145], v[120:123], off
	s_waitcnt vmcnt(15)
; DI unsigned pack2(float a, float b) { f32x2 v = {a, b}; hwbf16x2 r = __builtin_convertvector(v, hwbf16x2); return __builtin_bit_cast(unsigned, r); }
; DI float bflo(unsigned w) { return __uint_as_float(w << 16); }
; DI float bfhi(unsigned w) { return __uint_as_float(w & 0xffff0000u); }
;     DI void operator()(const f32x4 (&acc)[2][2][4][2], const Unit& u, int wr, int wc, int fr, int fq) const {
;     ...
;         for (int ai = 0; ai < 2; ++ai)
; #pragma unroll
;             for (int m = 0; m < 4; ++m) { const size_t ro = (size_t)(row0 + ai * HALF + m * 16) * D + col0;
; #pragma unroll
;                 for (int bj = 0; bj < 2; ++bj) {
;                     f32x4 x0, x1;
;                     if constexpr (IB) { const u32x4 w = *(const u32x4*)((const bf16_t*)Xin + ro + bj * HALF);
;                         x0 = (f32x4){bflo(w[0]), bfhi(w[0]), bflo(w[1]), bfhi(w[1])}; x1 = (f32x4){bflo(w[2]), bfhi(w[2]), bflo(w[3]), bfhi(w[3])}; }
;                     else { x0 = *(const f32x4*)((const float*)Xin + ro + bj * HALF); x1 = *(const f32x4*)((const float*)Xin + ro + bj * HALF + 4); }
;                     x0 += acc[ai][bj][m][0] * sc[bj][0]; x1 += acc[ai][bj][m][1] * sc[bj][1];
;                     if constexpr (OB) { u32x4 o; o[0] = pack2(x0[0], x0[1]); o[1] = pack2(x0[2], x0[3]); o[2] = pack2(x1[0], x1[1]); o[3] = pack2(x1[2], x1[3]);
;                         *(u32x4*)((bf16_t*)Xout + ro + bj * HALF) = o; }
;                     else { *(f32x4*)((float*)Xout + ro + bj * HALF) = x0; *(f32x4*)((float*)Xout + ro + bj * HALF + 4) = x1; } } }
	s_nop 1
	v_mov_b32_e32 v120, v164
	v_mov_b32_e32 v121, v165
	v_mov_b32_e32 v122, v166
	v_mov_b32_e32 v123, v167
	s_waitcnt lgkmcnt(0)
	v_lshlrev_b32_e32 v124, 16, v120
	v_and_b32_e32 v125, 0xffff0000, v120
	v_lshlrev_b32_e32 v120, 16, v121
	v_and_b32_e32 v121, 0xffff0000, v121
	v_lshlrev_b32_e32 v126, 16, v122
	v_and_b32_e32 v127, 0xffff0000, v122
	v_lshlrev_b32_e32 v122, 16, v123
	v_and_b32_e32 v123, 0xffff0000, v123
	v_pk_add_f32 v[116:117], v[116:117], v[124:125]
	v_pk_add_f32 v[118:119], v[118:119], v[120:121]
	v_pk_add_f32 v[120:121], v[114:115], v[122:123]
	v_pk_add_f32 v[114:115], v[112:113], v[126:127]
	v_cvt_pk_bf16_f32 v112, v116, v117
	v_lshl_add_u64 v[116:117], v[144:145], 0, s[2:3]
	s_mov_b32 s2, 0x10000
	v_cvt_pk_bf16_f32 v113, v118, v119
	v_add_co_u32_e32 v118, vcc, s2, v144
	v_cvt_pk_bf16_f32 v114, v114, v115
	v_cvt_pk_bf16_f32 v115, v120, v121
	v_addc_co_u32_e32 v119, vcc, 0, v145, vcc
	global_store_dwordx4 v[144:145], v[112:115], off offset:256
	s_waitcnt vmcnt(15)
	s_nop 1
	v_mov_b32_e32 v112, v168
	v_mov_b32_e32 v113, v169
	v_mov_b32_e32 v114, v170
	v_mov_b32_e32 v115, v171
	s_mov_b64 s[2:3], 0x20000
	s_waitcnt lgkmcnt(0)
	v_lshlrev_b32_e32 v120, 16, v112
	v_and_b32_e32 v121, 0xffff0000, v112
	v_lshlrev_b32_e32 v112, 16, v113
	v_and_b32_e32 v113, 0xffff0000, v113
	v_lshlrev_b32_e32 v122, 16, v114
	v_and_b32_e32 v123, 0xffff0000, v114
	v_lshlrev_b32_e32 v114, 16, v115
	v_and_b32_e32 v115, 0xffff0000, v115
	v_pk_add_f32 v[110:111], v[110:111], v[112:113]
	v_pk_add_f32 v[108:109], v[108:109], v[120:121]
	v_pk_add_f32 v[112:113], v[106:107], v[114:115]
	v_pk_add_f32 v[106:107], v[104:105], v[122:123]
	v_cvt_pk_bf16_f32 v104, v108, v109
	v_cvt_pk_bf16_f32 v105, v110, v111
	v_cvt_pk_bf16_f32 v106, v106, v107
	v_cvt_pk_bf16_f32 v107, v112, v113
	global_store_dwordx4 v[118:119], v[104:107], off
	s_waitcnt vmcnt(15)
	s_nop 1
	v_mov_b32_e32 v104, v172
	v_mov_b32_e32 v105, v173
	v_mov_b32_e32 v106, v174
	v_mov_b32_e32 v107, v175
	s_waitcnt lgkmcnt(0)
	v_lshlrev_b32_e32 v108, 16, v104
	v_and_b32_e32 v109, 0xffff0000, v104
	v_lshlrev_b32_e32 v104, 16, v105
	v_and_b32_e32 v105, 0xffff0000, v105
	v_lshlrev_b32_e32 v110, 16, v106
	v_and_b32_e32 v111, 0xffff0000, v106
	v_lshlrev_b32_e32 v106, 16, v107
	v_and_b32_e32 v107, 0xffff0000, v107
	v_pk_add_f32 v[100:101], v[100:101], v[108:109]
	v_pk_add_f32 v[102:103], v[102:103], v[104:105]
	v_pk_add_f32 v[104:105], v[98:99], v[106:107]
	v_pk_add_f32 v[98:99], v[96:97], v[110:111]
	v_cvt_pk_bf16_f32 v96, v100, v101
	v_lshl_add_u64 v[100:101], v[144:145], 0, s[2:3]
	s_mov_b32 s2, 0x20000
	v_cvt_pk_bf16_f32 v97, v102, v103
	v_add_co_u32_e32 v102, vcc, s2, v144
	v_cvt_pk_bf16_f32 v98, v98, v99
	v_cvt_pk_bf16_f32 v99, v104, v105
	v_addc_co_u32_e32 v103, vcc, 0, v145, vcc
	global_store_dwordx4 v[116:117], v[96:99], off offset:256
	s_waitcnt vmcnt(15)
	s_nop 1
	v_mov_b32_e32 v96, v176
	v_mov_b32_e32 v97, v177
	v_mov_b32_e32 v98, v178
	v_mov_b32_e32 v99, v179
	s_mov_b64 s[2:3], 0x30000
	s_waitcnt lgkmcnt(0)
	v_lshlrev_b32_e32 v104, 16, v96
	v_and_b32_e32 v105, 0xffff0000, v96
	v_lshlrev_b32_e32 v96, 16, v97
	v_and_b32_e32 v97, 0xffff0000, v97
	v_lshlrev_b32_e32 v106, 16, v98
	v_and_b32_e32 v107, 0xffff0000, v98
	v_lshlrev_b32_e32 v98, 16, v99
	v_and_b32_e32 v99, 0xffff0000, v99
	v_pk_add_f32 v[94:95], v[94:95], v[96:97]
	v_pk_add_f32 v[92:93], v[92:93], v[104:105]
	v_pk_add_f32 v[96:97], v[90:91], v[98:99]
	v_pk_add_f32 v[90:91], v[88:89], v[106:107]
	v_cvt_pk_bf16_f32 v88, v92, v93
	v_cvt_pk_bf16_f32 v89, v94, v95
	v_cvt_pk_bf16_f32 v90, v90, v91
	v_cvt_pk_bf16_f32 v91, v96, v97
	global_store_dwordx4 v[102:103], v[88:91], off
	s_waitcnt vmcnt(15)
	s_nop 1
	v_mov_b32_e32 v88, v180
	v_mov_b32_e32 v89, v181
	v_mov_b32_e32 v90, v182
	v_mov_b32_e32 v91, v183
	s_waitcnt lgkmcnt(0)
	v_lshlrev_b32_e32 v92, 16, v88
	v_and_b32_e32 v93, 0xffff0000, v88
	v_lshlrev_b32_e32 v88, 16, v89
	v_and_b32_e32 v89, 0xffff0000, v89
	v_lshlrev_b32_e32 v94, 16, v90
	v_and_b32_e32 v95, 0xffff0000, v90
	v_lshlrev_b32_e32 v90, 16, v91
	v_and_b32_e32 v91, 0xffff0000, v91
	v_pk_add_f32 v[86:87], v[86:87], v[88:89]
	v_pk_add_f32 v[84:85], v[84:85], v[92:93]
	v_pk_add_f32 v[88:89], v[82:83], v[90:91]
	v_pk_add_f32 v[82:83], v[80:81], v[94:95]
	v_cvt_pk_bf16_f32 v80, v84, v85
	v_cvt_pk_bf16_f32 v81, v86, v87
	v_cvt_pk_bf16_f32 v82, v82, v83
	v_cvt_pk_bf16_f32 v83, v88, v89
	global_store_dwordx4 v[100:101], v[80:83], off offset:256
	s_nop 1
	v_lshl_add_u64 v[80:81], v[144:145], 0, s[2:3]
	s_mov_b32 s2, 0x30000
	v_add_co_u32_e32 v86, vcc, s2, v144
	s_mov_b64 s[2:3], 0x80000
	s_nop 0
	v_addc_co_u32_e32 v87, vcc, 0, v145, vcc
	s_waitcnt vmcnt(15)
	s_nop 1
	v_mov_b32_e32 v82, v184
	v_mov_b32_e32 v83, v185
	v_mov_b32_e32 v84, v186
	v_mov_b32_e32 v85, v187
	s_waitcnt lgkmcnt(0)
	v_lshlrev_b32_e32 v88, 16, v82
	v_and_b32_e32 v89, 0xffff0000, v82
	v_lshlrev_b32_e32 v82, 16, v83
	v_and_b32_e32 v83, 0xffff0000, v83
	v_lshlrev_b32_e32 v90, 16, v84
	v_and_b32_e32 v91, 0xffff0000, v84
	v_lshlrev_b32_e32 v84, 16, v85
	v_and_b32_e32 v85, 0xffff0000, v85
	v_pk_add_f32 v[78:79], v[78:79], v[82:83]
	v_pk_add_f32 v[76:77], v[76:77], v[88:89]
	v_pk_add_f32 v[82:83], v[74:75], v[84:85]
	v_pk_add_f32 v[74:75], v[72:73], v[90:91]
	v_cvt_pk_bf16_f32 v72, v76, v77
	v_cvt_pk_bf16_f32 v73, v78, v79
	v_cvt_pk_bf16_f32 v74, v74, v75
	v_cvt_pk_bf16_f32 v75, v82, v83
	global_store_dwordx4 v[86:87], v[72:75], off
	s_waitcnt vmcnt(15)
	s_nop 1
	v_mov_b32_e32 v72, v188
	v_mov_b32_e32 v73, v189
	v_mov_b32_e32 v74, v190
	v_mov_b32_e32 v75, v191
	s_waitcnt lgkmcnt(0)
; DI unsigned pack2(float a, float b) { f32x2 v = {a, b}; hwbf16x2 r = __builtin_convertvector(v, hwbf16x2); return __builtin_bit_cast(unsigned, r); }
; DI float bflo(unsigned w) { return __uint_as_float(w << 16); }
; DI float bfhi(unsigned w) { return __uint_as_float(w & 0xffff0000u); }
;     DI void operator()(const f32x4 (&acc)[2][2][4][2], const Unit& u, int wr, int wc, int fr, int fq) const {
;     ...
;         for (int ai = 0; ai < 2; ++ai)
; #pragma unroll
;             for (int m = 0; m < 4; ++m) { const size_t ro = (size_t)(row0 + ai * HALF + m * 16) * D + col0;
; #pragma unroll
;                 for (int bj = 0; bj < 2; ++bj) {
;                     f32x4 x0, x1;
;                     if constexpr (IB) { const u32x4 w = *(const u32x4*)((const bf16_t*)Xin + ro + bj * HALF);
;                         x0 = (f32x4){bflo(w[0]), bfhi(w[0]), bflo(w[1]), bfhi(w[1])}; x1 = (f32x4){bflo(w[2]), bfhi(w[2]), bflo(w[3]), bfhi(w[3])}; }
;                     else { x0 = *(const f32x4*)((const float*)Xin + ro + bj * HALF); x1 = *(const f32x4*)((const float*)Xin + ro + bj * HALF + 4); }
;                     x0 += acc[ai][bj][m][0] * sc[bj][0]; x1 += acc[ai][bj][m][1] * sc[bj][1];
;                     if constexpr (OB) { u32x4 o; o[0] = pack2(x0[0], x0[1]); o[1] = pack2(x0[2], x0[3]); o[2] = pack2(x1[0], x1[1]); o[3] = pack2(x1[2], x1[3]);
;                         *(u32x4*)((bf16_t*)Xout + ro + bj * HALF) = o; }
;                     else { *(f32x4*)((float*)Xout + ro + bj * HALF) = x0; *(f32x4*)((float*)Xout + ro + bj * HALF + 4) = x1; } } }
	v_lshlrev_b32_e32 v76, 16, v72
	v_and_b32_e32 v77, 0xffff0000, v72
	v_lshlrev_b32_e32 v72, 16, v73
	v_and_b32_e32 v73, 0xffff0000, v73
	v_lshlrev_b32_e32 v78, 16, v74
	v_and_b32_e32 v79, 0xffff0000, v74
	v_lshlrev_b32_e32 v74, 16, v75
	v_and_b32_e32 v75, 0xffff0000, v75
	v_pk_add_f32 v[70:71], v[70:71], v[72:73]
	v_pk_add_f32 v[68:69], v[68:69], v[76:77]
	v_pk_add_f32 v[72:73], v[66:67], v[74:75]
	v_pk_add_f32 v[66:67], v[64:65], v[78:79]
	v_cvt_pk_bf16_f32 v64, v68, v69
	v_cvt_pk_bf16_f32 v65, v70, v71
	v_cvt_pk_bf16_f32 v66, v66, v67
	v_cvt_pk_bf16_f32 v67, v72, v73
	global_store_dwordx4 v[80:81], v[64:67], off offset:256
	s_nop 1
	v_lshl_add_u64 v[64:65], v[144:145], 0, s[2:3]
	s_mov_b32 s2, 0x80000
	v_add_co_u32_e32 v70, vcc, s2, v144
	s_mov_b64 s[2:3], 0x90000
	s_nop 0
	v_addc_co_u32_e32 v71, vcc, 0, v145, vcc
	s_waitcnt vmcnt(15)
	s_nop 1
	v_mov_b32_e32 v66, v192
	v_mov_b32_e32 v67, v193
	v_mov_b32_e32 v68, v194
	v_mov_b32_e32 v69, v195
	s_waitcnt lgkmcnt(0)
	v_lshlrev_b32_e32 v72, 16, v66
	v_and_b32_e32 v73, 0xffff0000, v66
	v_lshlrev_b32_e32 v66, 16, v67
	v_and_b32_e32 v67, 0xffff0000, v67
	v_lshlrev_b32_e32 v74, 16, v68
	v_and_b32_e32 v75, 0xffff0000, v68
	v_lshlrev_b32_e32 v68, 16, v69
	v_and_b32_e32 v69, 0xffff0000, v69
	v_pk_add_f32 v[62:63], v[62:63], v[66:67]
	v_pk_add_f32 v[60:61], v[60:61], v[72:73]
	v_pk_add_f32 v[66:67], v[58:59], v[68:69]
	v_pk_add_f32 v[58:59], v[56:57], v[74:75]
	v_cvt_pk_bf16_f32 v56, v60, v61
	v_cvt_pk_bf16_f32 v57, v62, v63
	v_cvt_pk_bf16_f32 v58, v58, v59
	v_cvt_pk_bf16_f32 v59, v66, v67
	global_store_dwordx4 v[70:71], v[56:59], off
	s_waitcnt vmcnt(15)
	s_nop 1
	v_mov_b32_e32 v56, v198
	v_mov_b32_e32 v57, v199
	v_mov_b32_e32 v58, v200
	v_mov_b32_e32 v59, v201
	s_waitcnt lgkmcnt(0)
	v_lshlrev_b32_e32 v60, 16, v56
	v_and_b32_e32 v61, 0xffff0000, v56
	v_lshlrev_b32_e32 v56, 16, v57
	v_and_b32_e32 v57, 0xffff0000, v57
	v_lshlrev_b32_e32 v62, 16, v58
	v_and_b32_e32 v63, 0xffff0000, v58
	v_lshlrev_b32_e32 v58, 16, v59
	v_and_b32_e32 v59, 0xffff0000, v59
	v_pk_add_f32 v[54:55], v[54:55], v[56:57]
	v_pk_add_f32 v[52:53], v[52:53], v[60:61]
	v_pk_add_f32 v[56:57], v[50:51], v[58:59]
	v_pk_add_f32 v[50:51], v[48:49], v[62:63]
	v_cvt_pk_bf16_f32 v48, v52, v53
	v_cvt_pk_bf16_f32 v49, v54, v55
	v_cvt_pk_bf16_f32 v50, v50, v51
	v_cvt_pk_bf16_f32 v51, v56, v57
	global_store_dwordx4 v[64:65], v[48:51], off offset:256
	s_nop 1
	v_lshl_add_u64 v[48:49], v[144:145], 0, s[2:3]
	s_mov_b32 s2, 0x90000
	v_add_co_u32_e32 v54, vcc, s2, v144
	s_mov_b64 s[2:3], 0xa0000
	s_nop 0
	v_addc_co_u32_e32 v55, vcc, 0, v145, vcc
	s_waitcnt vmcnt(15)
	s_nop 1
	v_mov_b32_e32 v50, v202
	v_mov_b32_e32 v51, v203
	v_mov_b32_e32 v52, v204
	v_mov_b32_e32 v53, v205
	s_waitcnt lgkmcnt(0)
	v_lshlrev_b32_e32 v56, 16, v50
	v_and_b32_e32 v57, 0xffff0000, v50
	v_lshlrev_b32_e32 v50, 16, v51
	v_and_b32_e32 v51, 0xffff0000, v51
	v_lshlrev_b32_e32 v58, 16, v52
	v_and_b32_e32 v59, 0xffff0000, v52
	v_lshlrev_b32_e32 v52, 16, v53
	v_and_b32_e32 v53, 0xffff0000, v53
	v_pk_add_f32 v[46:47], v[46:47], v[50:51]
	v_pk_add_f32 v[44:45], v[44:45], v[56:57]
	v_pk_add_f32 v[50:51], v[42:43], v[52:53]
	v_pk_add_f32 v[42:43], v[40:41], v[58:59]
	v_cvt_pk_bf16_f32 v40, v44, v45
	v_cvt_pk_bf16_f32 v41, v46, v47
	v_cvt_pk_bf16_f32 v42, v42, v43
	v_cvt_pk_bf16_f32 v43, v50, v51
	global_store_dwordx4 v[54:55], v[40:43], off
	s_waitcnt vmcnt(15)
	s_nop 1
	v_mov_b32_e32 v40, v206
	v_mov_b32_e32 v41, v207
	v_mov_b32_e32 v42, v208
	v_mov_b32_e32 v43, v209
	s_waitcnt lgkmcnt(0)
; DI unsigned pack2(float a, float b) { f32x2 v = {a, b}; hwbf16x2 r = __builtin_convertvector(v, hwbf16x2); return __builtin_bit_cast(unsigned, r); }
; DI float bflo(unsigned w) { return __uint_as_float(w << 16); }
; DI float bfhi(unsigned w) { return __uint_as_float(w & 0xffff0000u); }
;     DI const char* a(const Unit& u) const { return (const char*)(A + (size_t)u.pm * BM * lda); }
;     DI const char* a(const Unit& u) const { return (const char*)(A + (size_t)u.pm * BM * 2048 + (u.pn >> 1) * 512); }
;     DI const char* a(const Unit& u) const { return (const char*)((u.pn < 12 ? A1 : A2) + (size_t)u.pm * BM * 512); }
; #define PG8_BAR __builtin_amdgcn_s_barrier()
;     DI void operator()(const f32x4 (&acc)[2][2][4][2], const Unit& u, int wr, int wc, int fr, int fq) const {
;     ...
;                 for (int bj = 0; bj < 2; ++bj) {
;                     f32x4 x0, x1;
;                     if constexpr (IB) { const u32x4 w = *(const u32x4*)((const bf16_t*)Xin + ro + bj * HALF);
;                         x0 = (f32x4){bflo(w[0]), bfhi(w[0]), bflo(w[1]), bfhi(w[1])}; x1 = (f32x4){bflo(w[2]), bfhi(w[2]), bflo(w[3]), bfhi(w[3])}; }
;                     else { x0 = *(const f32x4*)((const float*)Xin + ro + bj * HALF); x1 = *(const f32x4*)((const float*)Xin + ro + bj * HALF + 4); }
;                     x0 += acc[ai][bj][m][0] * sc[bj][0]; x1 += acc[ai][bj][m][1] * sc[bj][1];
;                     if constexpr (OB) { u32x4 o; o[0] = pack2(x0[0], x0[1]); o[1] = pack2(x0[2], x0[3]); o[2] = pack2(x1[0], x1[1]); o[3] = pack2(x1[2], x1[3]);
;                         *(u32x4*)((bf16_t*)Xout + ro + bj * HALF) = o; }
;                     else { *(f32x4*)((float*)Xout + ro + bj * HALF) = x0; *(f32x4*)((float*)Xout + ro + bj * HALF + 4) = x1; } } }
; template <class Map, class Epi>
; DI void gemm_phase(LAS unsigned char* lds, const Map& MP, const Epi& E, const int nM, const int nN, const int K, const int lda, const int ldb) {
;     ...
;         if (!has_next) break;
; #pragma unroll
;         for (int a = 0; a < 2; ++a)
; #pragma unroll
;             for (int b = 0; b < 2; ++b)
; #pragma unroll
;                 for (int m = 0; m < 4; ++m)
; #pragma unroll
;                     for (int n = 0; n < 2; ++n) acc[a][b][m][n] = (f32x4){0.f, 0.f, 0.f, 0.f};
;         cur = nxt; cA = nA; cB = nB; ++ui;
;     }
;     PG8_WAIT_V(0);
;     if (wr == 0) PG8_BAR;
;     PG8_BAR;
	v_lshlrev_b32_e32 v44, 16, v40
	v_and_b32_e32 v45, 0xffff0000, v40
	v_lshlrev_b32_e32 v40, 16, v41
	v_and_b32_e32 v41, 0xffff0000, v41
	v_lshlrev_b32_e32 v46, 16, v42
	v_and_b32_e32 v47, 0xffff0000, v42
	v_lshlrev_b32_e32 v42, 16, v43
	v_and_b32_e32 v43, 0xffff0000, v43
	v_pk_add_f32 v[38:39], v[38:39], v[40:41]
	v_pk_add_f32 v[36:37], v[36:37], v[44:45]
	v_pk_add_f32 v[40:41], v[34:35], v[42:43]
	v_pk_add_f32 v[34:35], v[32:33], v[46:47]
	v_cvt_pk_bf16_f32 v32, v36, v37
	v_cvt_pk_bf16_f32 v33, v38, v39
	v_cvt_pk_bf16_f32 v34, v34, v35
	v_cvt_pk_bf16_f32 v35, v40, v41
	global_store_dwordx4 v[48:49], v[32:35], off offset:256
	s_nop 1
	v_lshl_add_u64 v[32:33], v[144:145], 0, s[2:3]
	s_mov_b32 s2, 0xa0000
	v_add_co_u32_e32 v38, vcc, s2, v144
	s_mov_b64 s[2:3], 0xb0000
	s_nop 0
	v_addc_co_u32_e32 v39, vcc, 0, v145, vcc
	s_waitcnt vmcnt(15)
	s_nop 1
	v_mov_b32_e32 v34, v210
	v_mov_b32_e32 v35, v211
	v_mov_b32_e32 v36, v212
	v_mov_b32_e32 v37, v213
	s_waitcnt lgkmcnt(0)
	v_lshlrev_b32_e32 v40, 16, v34
	v_and_b32_e32 v41, 0xffff0000, v34
	v_lshlrev_b32_e32 v34, 16, v35
	v_and_b32_e32 v35, 0xffff0000, v35
	v_lshlrev_b32_e32 v42, 16, v36
	v_and_b32_e32 v43, 0xffff0000, v36
	v_lshlrev_b32_e32 v36, 16, v37
	v_and_b32_e32 v37, 0xffff0000, v37
	v_pk_add_f32 v[30:31], v[30:31], v[34:35]
	v_pk_add_f32 v[28:29], v[28:29], v[40:41]
	v_pk_add_f32 v[34:35], v[26:27], v[36:37]
	v_pk_add_f32 v[26:27], v[24:25], v[42:43]
	v_cvt_pk_bf16_f32 v24, v28, v29
	v_cvt_pk_bf16_f32 v25, v30, v31
	v_cvt_pk_bf16_f32 v26, v26, v27
	v_cvt_pk_bf16_f32 v27, v34, v35
	global_store_dwordx4 v[38:39], v[24:27], off
	s_waitcnt vmcnt(15)
	s_nop 1
	v_mov_b32_e32 v24, v214
	v_mov_b32_e32 v25, v215
	v_mov_b32_e32 v26, v216
	v_mov_b32_e32 v27, v217
	s_waitcnt lgkmcnt(0)
	v_lshlrev_b32_e32 v28, 16, v24
	v_and_b32_e32 v29, 0xffff0000, v24
	v_lshlrev_b32_e32 v24, 16, v25
	v_and_b32_e32 v25, 0xffff0000, v25
	v_lshlrev_b32_e32 v30, 16, v26
	v_and_b32_e32 v31, 0xffff0000, v26
	v_lshlrev_b32_e32 v26, 16, v27
	v_and_b32_e32 v27, 0xffff0000, v27
	v_pk_add_f32 v[22:23], v[22:23], v[24:25]
	v_pk_add_f32 v[20:21], v[20:21], v[28:29]
	v_pk_add_f32 v[24:25], v[18:19], v[26:27]
	v_pk_add_f32 v[18:19], v[16:17], v[30:31]
	v_cvt_pk_bf16_f32 v16, v20, v21
	v_cvt_pk_bf16_f32 v17, v22, v23
	v_cvt_pk_bf16_f32 v18, v18, v19
	v_cvt_pk_bf16_f32 v19, v24, v25
	global_store_dwordx4 v[32:33], v[16:19], off offset:256
	s_nop 1
	v_lshl_add_u64 v[16:17], v[144:145], 0, s[2:3]
	s_mov_b32 s2, 0xb0000
	v_add_co_u32_e32 v22, vcc, s2, v144
	s_mov_b32 s2, s44
	s_nop 0
	v_addc_co_u32_e32 v23, vcc, 0, v145, vcc
	s_waitcnt vmcnt(15)
	s_nop 1
	v_mov_b32_e32 v18, v248
	v_mov_b32_e32 v19, v249
	v_mov_b32_e32 v20, v250
	v_mov_b32_e32 v21, v251
	s_and_b64 vcc, exec, s[40:41]
	s_waitcnt lgkmcnt(0)
	v_lshlrev_b32_e32 v24, 16, v18
	v_and_b32_e32 v25, 0xffff0000, v18
	v_lshlrev_b32_e32 v18, 16, v19
	v_and_b32_e32 v19, 0xffff0000, v19
	v_lshlrev_b32_e32 v26, 16, v20
	v_and_b32_e32 v27, 0xffff0000, v20
	v_lshlrev_b32_e32 v20, 16, v21
	v_and_b32_e32 v21, 0xffff0000, v21
	v_pk_add_f32 v[14:15], v[14:15], v[18:19]
	v_pk_add_f32 v[12:13], v[12:13], v[24:25]
	v_pk_add_f32 v[18:19], v[10:11], v[20:21]
	v_pk_add_f32 v[10:11], v[8:9], v[26:27]
	v_cvt_pk_bf16_f32 v8, v12, v13
	v_cvt_pk_bf16_f32 v9, v14, v15
	v_cvt_pk_bf16_f32 v10, v10, v11
	v_cvt_pk_bf16_f32 v11, v18, v19
	global_store_dwordx4 v[22:23], v[8:11], off
	s_waitcnt vmcnt(15)
	s_nop 1
	v_mov_b32_e32 v8, v252
	v_mov_b32_e32 v9, v253
	v_mov_b32_e32 v10, v254
	v_mov_b32_e32 v11, v255
	s_waitcnt lgkmcnt(0)
	v_lshlrev_b32_e32 v12, 16, v8
	v_and_b32_e32 v13, 0xffff0000, v8
	v_lshlrev_b32_e32 v8, 16, v9
	v_and_b32_e32 v9, 0xffff0000, v9
	v_lshlrev_b32_e32 v14, 16, v10
	v_and_b32_e32 v15, 0xffff0000, v10
	v_lshlrev_b32_e32 v10, 16, v11
	v_and_b32_e32 v11, 0xffff0000, v11
	v_pk_add_f32 v[6:7], v[6:7], v[8:9]
	v_pk_add_f32 v[4:5], v[4:5], v[12:13]
	v_pk_add_f32 v[8:9], v[2:3], v[10:11]
	v_pk_add_f32 v[2:3], v[0:1], v[14:15]
	v_cvt_pk_bf16_f32 v0, v4, v5
	v_cvt_pk_bf16_f32 v1, v6, v7
	v_cvt_pk_bf16_f32 v2, v2, v3
	v_cvt_pk_bf16_f32 v3, v8, v9
	global_store_dwordx4 v[16:17], v[0:3], off offset:256
	s_cbranch_vccz .LBB1_1761
	s_waitcnt vmcnt(0)
	s_cmpk_gt_u32 s17, 0xff
	s_cbranch_scc1 .LBB1_1768
	s_barrier

; #define PG8_STAGE(bufoff, gbase, voff) do { _Pragma("unroll") for (int _i = 0; _i < 2; ++_i) \
;         __builtin_amdgcn_global_load_lds((const unsigned*)((const char*)(gbase) + (voff)[_i]), (LAS unsigned*)(lds + (bufoff) + ldsw + _i * 8192), 16, 0, 0); } while (0)
; #define PG8_LDA(dst, b, h) do { _Pragma("unroll") for (int m = 0; m < 4; ++m) _Pragma("unroll") for (int k = 0; k < 2; ++k) dst[m][k] = *(const LAS bf16x8*)(lds + PG8_SA(b, h) + aoff + m * 2048 + k * 1024); } while (0)
; #define PG8_WAIT_V(n) asm volatile("s_waitcnt vmcnt(" #n ")" ::: "memory")
; #define PG8_BAR __builtin_amdgcn_s_barrier()
; template <class Map, class Epi>
; DI void gemm_phase(LAS unsigned char* lds, const Map& MP, const Epi& E, const int nM, const int nN, const int K, const int lda, const int ldb) {
;     ...
;         for (int t = 0; t < nt; t += 2) {
;             const bool last = (t == nt - 2);
;             const char* a1 = cA + (size_t)(t + 1) * kstep;
;             const char* a2 = last ? nA : cA + (size_t)(t + 2) * kstep; const char* b2 = last ? nB : cB + (size_t)(t + 2) * kstep;
;             const char* a3 = a2 + kstep; const char* b3 = b2 + kstep;
;             PG8_LDB(B0, 0, 0); PG8_SCHED; PG8_LDA(At, 0, 0); PG8_STAGE(PG8_SA(1, 1), a1 + hstepA, voffA);
;             PG8_WAIT_L(8); PG8_BAR; PG8_WAIT_L(0); PG8_MMA(0, 0, At, B0); PG8_BAR; PG8_SCHED;
;             PG8_LDB(B1, 0, 1); PG8_STAGE(PG8_SB(0, 0), b2, voffB);
;             PG8_BAR; PG8_WAIT_L(0); PG8_MMA(0, 1, At, B1); PG8_BAR;
;             PG8_LDA(At, 0, 1); PG8_STAGE(PG8_SA(0, 0), a2, voffA);
;             PG8_BAR; PG8_WAIT_L(0); PG8_MMA(1, 0, At, B0); PG8_BAR; PG8_SCHED;
;             PG8_STAGE(PG8_SB(0, 1), b2 + hstepB, voffB);
;             PG8_WAIT_V(6); PG8_BAR; PG8_MMA(1, 1, At, B1); PG8_BAR;
;             PG8_LDB(B0, 1, 0); PG8_SCHED; PG8_LDA(At, 1, 0); PG8_STAGE(PG8_SA(0, 1), a2 + hstepA, voffA);
;             PG8_WAIT_L(8); PG8_BAR; PG8_WAIT_L(0); PG8_MMA(0, 0, At, B0); PG8_BAR; PG8_SCHED;
;             PG8_LDB(B1, 1, 1); PG8_STAGE(PG8_SB(1, 0), b3, voffB);
;             PG8_BAR; PG8_WAIT_L(0); PG8_MMA(0, 1, At, B1); PG8_BAR;
;             PG8_LDA(At, 1, 1); PG8_STAGE(PG8_SA(1, 0), a3, voffA);
;             PG8_BAR; PG8_WAIT_L(0); PG8_MMA(1, 0, At, B0); PG8_BAR; PG8_SCHED;
;             PG8_STAGE(PG8_SB(1, 1), b3 + hstepB, voffB);
;             PG8_WAIT_V(6); PG8_BAR; PG8_MMA(1, 1, At, B1); PG8_BAR;
.LBB1_1908:
	s_add_u32 s28, s42, 0xfff80080
	s_addc_u32 s29, s43, -1
	s_cmp_eq_u32 s3, 28
	s_cselect_b32 s47, s23, s29
	s_cselect_b32 s46, s58, s28
	s_cselect_b32 s29, s21, vcc_hi
	s_cselect_b32 s28, s59, vcc_lo
	s_add_i32 m0, s38, 0xc000
	ds_read_b128 v[96:99], v190
	global_load_lds_dwordx4 v178, s[42:43]
	ds_read_b128 v[100:103], v190 offset:1024
	ds_read_b128 v[108:111], v190 offset:2048
	ds_read_b128 v[112:115], v190 offset:3072
	ds_read_b128 v[160:163], v190 offset:4096
	ds_read_b128 v[164:167], v190 offset:5120
	ds_read_b128 v[198:201], v190 offset:6144
	ds_read_b128 v[202:205], v190 offset:7168
	s_add_i32 m0, s38, 0xe000
	s_nop 0
	global_load_lds_dwordx4 v176, s[42:43]
	s_waitcnt lgkmcnt(8)
	s_setprio 1
	s_barrier
	s_waitcnt lgkmcnt(7)
	v_mfma_f32_16x16x32_bf16 v[148:151], v[80:83], v[96:99], v[148:151]
	v_mfma_f32_16x16x32_bf16 v[144:147], v[88:91], v[96:99], v[144:147]
	s_waitcnt lgkmcnt(5)
	v_mfma_f32_16x16x32_bf16 v[136:139], v[80:83], v[108:111], v[136:139]
	v_mfma_f32_16x16x32_bf16 v[128:131], v[88:91], v[108:111], v[128:131]
	s_waitcnt lgkmcnt(3)
	v_mfma_f32_16x16x32_bf16 v[120:123], v[80:83], v[160:163], v[120:123]
	v_mfma_f32_16x16x32_bf16 v[104:107], v[88:91], v[160:163], v[104:107]
	s_waitcnt lgkmcnt(1)
	v_mfma_f32_16x16x32_bf16 v[76:79], v[80:83], v[198:201], v[76:79]
	v_mfma_f32_16x16x32_bf16 v[72:75], v[88:91], v[198:201], v[72:75]
	v_mfma_f32_16x16x32_bf16 v[148:151], v[84:87], v[100:103], v[148:151]
	s_add_i32 s68, s2, s54
	v_mfma_f32_16x16x32_bf16 v[144:147], v[92:95], v[100:103], v[144:147]
	v_lshl_add_u64 v[184:185], s[28:29], 0, v[172:173]
	v_mfma_f32_16x16x32_bf16 v[136:139], v[84:87], v[112:115], v[136:139]
	v_lshl_add_u64 v[194:195], s[28:29], 0, v[168:169]
	v_mfma_f32_16x16x32_bf16 v[128:131], v[92:95], v[112:115], v[128:131]
	v_mfma_f32_16x16x32_bf16 v[120:123], v[84:87], v[164:167], v[120:123]
	v_mfma_f32_16x16x32_bf16 v[104:107], v[92:95], v[164:167], v[104:107]
	s_waitcnt lgkmcnt(0)
	v_mfma_f32_16x16x32_bf16 v[76:79], v[84:87], v[202:205], v[76:79]
	v_mfma_f32_16x16x32_bf16 v[72:75], v[92:95], v[202:205], v[72:75]
	s_barrier
	s_setprio 0
	s_mov_b32 m0, s68
	ds_read_b128 v[206:209], v191
	global_load_lds_dwordx4 v[184:185], off
	ds_read_b128 v[210:213], v191 offset:1024
	ds_read_b128 v[214:217], v191 offset:2048
	ds_read_b128 v[218:221], v191 offset:3072
	s_add_i32 m0, s68, 0x2000
	s_nop 0
	global_load_lds_dwordx4 v[194:195], off
	s_setprio 1
	s_barrier
	s_waitcnt lgkmcnt(3)
	v_mfma_f32_16x16x32_bf16 v[156:159], v[206:209], v[96:99], v[156:159]
	s_waitcnt lgkmcnt(1)
	v_mfma_f32_16x16x32_bf16 v[96:99], v[214:217], v[96:99], v[152:155]
	v_mfma_f32_16x16x32_bf16 v[156:159], v[210:213], v[100:103], v[156:159]
	s_waitcnt lgkmcnt(0)
	v_mfma_f32_16x16x32_bf16 v[96:99], v[218:221], v[100:103], v[96:99]
	v_mfma_f32_16x16x32_bf16 v[100:103], v[206:209], v[108:111], v[140:143]
	v_mfma_f32_16x16x32_bf16 v[108:111], v[214:217], v[108:111], v[132:135]
	v_mfma_f32_16x16x32_bf16 v[116:119], v[214:217], v[160:163], v[116:119]
	v_mfma_f32_16x16x32_bf16 v[68:71], v[206:209], v[198:201], v[68:71]
	v_mfma_f32_16x16x32_bf16 v[64:67], v[214:217], v[198:201], v[64:67]
	v_lshl_add_u64 v[234:235], s[46:47], 0, v[170:171]
	s_mov_b32 m0, s38
	v_mfma_f32_16x16x32_bf16 v[100:103], v[210:213], v[112:115], v[100:103]
	v_lshl_add_u64 v[226:227], s[46:47], 0, v[174:175]
	v_mfma_f32_16x16x32_bf16 v[108:111], v[218:221], v[112:115], v[108:111]
	v_mfma_f32_16x16x32_bf16 v[112:115], v[206:209], v[160:163], v[124:127]
	v_mfma_f32_16x16x32_bf16 v[116:119], v[218:221], v[164:167], v[116:119]
	v_mfma_f32_16x16x32_bf16 v[68:71], v[210:213], v[202:205], v[68:71]
	v_mfma_f32_16x16x32_bf16 v[64:67], v[218:221], v[202:205], v[64:67]
	v_mfma_f32_16x16x32_bf16 v[112:115], v[210:213], v[164:167], v[112:115]
	s_barrier
	s_setprio 0
	ds_read_b128 v[124:127], v190 offset:16384
	global_load_lds_dwordx4 v[226:227], off
	ds_read_b128 v[132:135], v190 offset:17408
	ds_read_b128 v[140:143], v190 offset:18432
	ds_read_b128 v[152:155], v190 offset:19456
	ds_read_b128 v[160:163], v190 offset:20480
	ds_read_b128 v[164:167], v190 offset:21504
	ds_read_b128 v[198:201], v190 offset:22528
	ds_read_b128 v[202:205], v190 offset:23552
	s_mov_b32 m0, s39
	s_nop 0
	global_load_lds_dwordx4 v[234:235], off
	s_waitcnt vmcnt(10)
	s_setprio 1
	s_barrier
	s_waitcnt lgkmcnt(7)
	v_mfma_f32_16x16x32_bf16 v[60:63], v[80:83], v[124:127], v[60:63]
	v_mfma_f32_16x16x32_bf16 v[48:51], v[88:91], v[124:127], v[48:51]
	s_waitcnt lgkmcnt(5)
	v_mfma_f32_16x16x32_bf16 v[40:43], v[80:83], v[140:143], v[40:43]
	v_mfma_f32_16x16x32_bf16 v[32:35], v[88:91], v[140:143], v[32:35]
	s_waitcnt lgkmcnt(3)
	v_mfma_f32_16x16x32_bf16 v[24:27], v[80:83], v[160:163], v[24:27]
	v_mfma_f32_16x16x32_bf16 v[16:19], v[88:91], v[160:163], v[16:19]
	s_waitcnt lgkmcnt(1)
	v_mfma_f32_16x16x32_bf16 v[12:15], v[80:83], v[198:201], v[12:15]
	v_mfma_f32_16x16x32_bf16 v[8:11], v[88:91], v[198:201], v[8:11]
	v_mfma_f32_16x16x32_bf16 v[60:63], v[84:87], v[132:135], v[60:63]
	s_add_u32 s68, s28, 0x80000
	s_addc_u32 s69, s29, 0
	v_mfma_f32_16x16x32_bf16 v[48:51], v[92:95], v[132:135], v[48:51]
	s_add_i32 s70, s31, s54
	v_mfma_f32_16x16x32_bf16 v[40:43], v[84:87], v[152:155], v[40:43]
	v_mfma_f32_16x16x32_bf16 v[32:35], v[92:95], v[152:155], v[32:35]
	v_mfma_f32_16x16x32_bf16 v[24:27], v[84:87], v[164:167], v[24:27]
	v_mfma_f32_16x16x32_bf16 v[16:19], v[92:95], v[164:167], v[16:19]
	s_waitcnt lgkmcnt(0)
	v_mfma_f32_16x16x32_bf16 v[12:15], v[84:87], v[202:205], v[12:15]
	v_mfma_f32_16x16x32_bf16 v[8:11], v[92:95], v[202:205], v[8:11]
	s_barrier
; #define PG8_STAGE(bufoff, gbase, voff) do { _Pragma("unroll") for (int _i = 0; _i < 2; ++_i) \
;         __builtin_amdgcn_global_load_lds((const unsigned*)((const char*)(gbase) + (voff)[_i]), (LAS unsigned*)(lds + (bufoff) + ldsw + _i * 8192), 16, 0, 0); } while (0)
; #define PG8_LDA(dst, b, h) do { _Pragma("unroll") for (int m = 0; m < 4; ++m) _Pragma("unroll") for (int k = 0; k < 2; ++k) dst[m][k] = *(const LAS bf16x8*)(lds + PG8_SA(b, h) + aoff + m * 2048 + k * 1024); } while (0)
; #define PG8_WAIT_V(n) asm volatile("s_waitcnt vmcnt(" #n ")" ::: "memory")
; #define PG8_BAR __builtin_amdgcn_s_barrier()
; template <class Map, class Epi>
; DI void gemm_phase(LAS unsigned char* lds, const Map& MP, const Epi& E, const int nM, const int nN, const int K, const int lda, const int ldb) {
;     ...
;         for (int t = 0; t < nt; t += 2) {
;             const bool last = (t == nt - 2);
;             const char* a1 = cA + (size_t)(t + 1) * kstep;
;             const char* a2 = last ? nA : cA + (size_t)(t + 2) * kstep; const char* b2 = last ? nB : cB + (size_t)(t + 2) * kstep;
;             const char* a3 = a2 + kstep; const char* b3 = b2 + kstep;
;             PG8_LDB(B0, 0, 0); PG8_SCHED; PG8_LDA(At, 0, 0); PG8_STAGE(PG8_SA(1, 1), a1 + hstepA, voffA);
;             PG8_WAIT_L(8); PG8_BAR; PG8_WAIT_L(0); PG8_MMA(0, 0, At, B0); PG8_BAR; PG8_SCHED;
;             PG8_LDB(B1, 0, 1); PG8_STAGE(PG8_SB(0, 0), b2, voffB);
;             PG8_BAR; PG8_WAIT_L(0); PG8_MMA(0, 1, At, B1); PG8_BAR;
;             PG8_LDA(At, 0, 1); PG8_STAGE(PG8_SA(0, 0), a2, voffA);
;             PG8_BAR; PG8_WAIT_L(0); PG8_MMA(1, 0, At, B0); PG8_BAR; PG8_SCHED;
;             PG8_STAGE(PG8_SB(0, 1), b2 + hstepB, voffB);
;             PG8_WAIT_V(6); PG8_BAR; PG8_MMA(1, 1, At, B1); PG8_BAR;
;             PG8_LDB(B0, 1, 0); PG8_SCHED; PG8_LDA(At, 1, 0); PG8_STAGE(PG8_SA(0, 1), a2 + hstepA, voffA);
;             PG8_WAIT_L(8); PG8_BAR; PG8_WAIT_L(0); PG8_MMA(0, 0, At, B0); PG8_BAR; PG8_SCHED;
;             PG8_LDB(B1, 1, 1); PG8_STAGE(PG8_SB(1, 0), b3, voffB);
;             PG8_BAR; PG8_WAIT_L(0); PG8_MMA(0, 1, At, B1); PG8_BAR;
;             PG8_LDA(At, 1, 1); PG8_STAGE(PG8_SA(1, 0), a3, voffA);
;             PG8_BAR; PG8_WAIT_L(0); PG8_MMA(1, 0, At, B0); PG8_BAR; PG8_SCHED;
;             PG8_STAGE(PG8_SB(1, 1), b3 + hstepB, voffB);
;             PG8_WAIT_V(6); PG8_BAR; PG8_MMA(1, 1, At, B1); PG8_BAR;
	s_setprio 0
	s_mov_b32 m0, s70
	s_nop 0
	global_load_lds_dwordx4 v172, s[68:69]
	s_add_i32 m0, s70, 0x2000
	s_nop 0
	global_load_lds_dwordx4 v168, s[68:69]
	s_waitcnt vmcnt(6)
	s_setprio 1
	s_barrier
	v_mfma_f32_16x16x32_bf16 v[56:59], v[206:209], v[124:127], v[56:59]
	v_mfma_f32_16x16x32_bf16 v[52:55], v[214:217], v[124:127], v[52:55]
	s_add_i32 s68, 0, 0x18000
	v_add_u32_e32 v92, s68, v188
	ds_read_b128 v[80:83], v92
	v_mfma_f32_16x16x32_bf16 v[44:47], v[206:209], v[140:143], v[44:47]
	v_mfma_f32_16x16x32_bf16 v[36:39], v[214:217], v[140:143], v[36:39]
	ds_read_b128 v[84:87], v92 offset:1024
	v_mfma_f32_16x16x32_bf16 v[28:31], v[206:209], v[160:163], v[28:31]
	v_mfma_f32_16x16x32_bf16 v[20:23], v[214:217], v[160:163], v[20:23]
	ds_read_b128 v[88:91], v92 offset:2048
	v_mfma_f32_16x16x32_bf16 v[4:7], v[206:209], v[198:201], v[4:7]
	v_mfma_f32_16x16x32_bf16 v[0:3], v[214:217], v[198:201], v[0:3]
	ds_read_b128 v[92:95], v92 offset:3072
	v_mfma_f32_16x16x32_bf16 v[56:59], v[210:213], v[132:135], v[56:59]
	s_add_u32 s46, s46, 0x80000
	s_addc_u32 s47, s47, 0
	v_mfma_f32_16x16x32_bf16 v[52:55], v[218:221], v[132:135], v[52:55]
	v_mfma_f32_16x16x32_bf16 v[44:47], v[210:213], v[152:155], v[44:47]
	v_mfma_f32_16x16x32_bf16 v[36:39], v[218:221], v[152:155], v[36:39]
	v_mfma_f32_16x16x32_bf16 v[28:31], v[210:213], v[164:167], v[28:31]
	v_mfma_f32_16x16x32_bf16 v[20:23], v[218:221], v[164:167], v[20:23]
	v_mfma_f32_16x16x32_bf16 v[4:7], v[210:213], v[202:205], v[4:7]
	v_mfma_f32_16x16x32_bf16 v[0:3], v[218:221], v[202:205], v[0:3]
	s_barrier
	s_setprio 0
	s_mov_b32 m0, s56
	ds_read_b128 v[124:127], v190 offset:32768
	global_load_lds_dwordx4 v174, s[46:47]
	ds_read_b128 v[132:135], v190 offset:33792
	ds_read_b128 v[160:163], v190 offset:34816
	ds_read_b128 v[164:167], v190 offset:35840
	ds_read_b128 v[198:201], v190 offset:36864
	ds_read_b128 v[202:205], v190 offset:37888
	ds_read_b128 v[206:209], v190 offset:38912
	ds_read_b128 v[210:213], v190 offset:39936
	s_mov_b32 m0, s57
	s_nop 0
	global_load_lds_dwordx4 v170, s[46:47]
	s_waitcnt lgkmcnt(8)
	s_setprio 1
	s_barrier
	s_waitcnt lgkmcnt(7)
	v_mfma_f32_16x16x32_bf16 v[140:143], v[80:83], v[124:127], v[148:151]
	s_waitcnt lgkmcnt(6)
	v_mfma_f32_16x16x32_bf16 v[148:151], v[84:87], v[132:135], v[140:143]
	v_mfma_f32_16x16x32_bf16 v[140:143], v[88:91], v[124:127], v[144:147]
	s_waitcnt lgkmcnt(5)
	v_mfma_f32_16x16x32_bf16 v[136:139], v[80:83], v[160:163], v[136:139]
	v_mfma_f32_16x16x32_bf16 v[128:131], v[88:91], v[160:163], v[128:131]
	s_waitcnt lgkmcnt(3)
	v_mfma_f32_16x16x32_bf16 v[120:123], v[80:83], v[198:201], v[120:123]
	v_mfma_f32_16x16x32_bf16 v[104:107], v[88:91], v[198:201], v[104:107]
	s_waitcnt lgkmcnt(1)
	v_mfma_f32_16x16x32_bf16 v[76:79], v[80:83], v[206:209], v[76:79]
	v_mfma_f32_16x16x32_bf16 v[72:75], v[88:91], v[206:209], v[72:75]
	s_add_i32 s46, 0, 0x1c000
	v_mfma_f32_16x16x32_bf16 v[144:147], v[92:95], v[132:135], v[140:143]
	v_add_u32_e32 v140, s46, v188
	v_mfma_f32_16x16x32_bf16 v[136:139], v[84:87], v[164:167], v[136:139]
	s_add_i32 s47, s68, s54
	v_mfma_f32_16x16x32_bf16 v[128:131], v[92:95], v[164:167], v[128:131]
	v_mfma_f32_16x16x32_bf16 v[120:123], v[84:87], v[202:205], v[120:123]
	v_mfma_f32_16x16x32_bf16 v[104:107], v[92:95], v[202:205], v[104:107]
	s_waitcnt lgkmcnt(0)
	v_mfma_f32_16x16x32_bf16 v[76:79], v[84:87], v[210:213], v[76:79]
	v_mfma_f32_16x16x32_bf16 v[72:75], v[92:95], v[210:213], v[72:75]
	s_barrier
	s_setprio 0
	ds_read_b128 v[214:217], v140
	ds_read_b128 v[218:221], v140 offset:1024
	ds_read_b128 v[222:225], v140 offset:2048
	ds_read_b128 v[230:233], v140 offset:3072
	v_lshl_add_u64 v[140:141], v[184:185], 0, s[14:15]
	s_mov_b32 m0, s47
	s_nop 0
	global_load_lds_dwordx4 v[140:141], off
	v_lshl_add_u64 v[140:141], v[194:195], 0, s[14:15]
	s_add_i32 m0, s47, 0x2000
	s_nop 0
	global_load_lds_dwordx4 v[140:141], off
	s_setprio 1
	s_barrier
	s_waitcnt lgkmcnt(1)
	v_mfma_f32_16x16x32_bf16 v[96:99], v[222:225], v[124:127], v[96:99]
	v_mfma_f32_16x16x32_bf16 v[140:143], v[214:217], v[124:127], v[156:159]
	s_waitcnt lgkmcnt(0)
	v_mfma_f32_16x16x32_bf16 v[152:155], v[230:233], v[132:135], v[96:99]
	v_mfma_f32_16x16x32_bf16 v[96:99], v[214:217], v[160:163], v[100:103]
	v_mfma_f32_16x16x32_bf16 v[156:159], v[218:221], v[132:135], v[140:143]
	v_mfma_f32_16x16x32_bf16 v[140:143], v[218:221], v[164:167], v[96:99]
	v_mfma_f32_16x16x32_bf16 v[96:99], v[222:225], v[160:163], v[108:111]
	v_mfma_f32_16x16x32_bf16 v[132:135], v[230:233], v[164:167], v[96:99]
	v_mfma_f32_16x16x32_bf16 v[96:99], v[214:217], v[198:201], v[112:115]
	s_mov_b32 m0, s63
	v_mfma_f32_16x16x32_bf16 v[124:127], v[218:221], v[202:205], v[96:99]
	v_lshl_add_u64 v[184:185], v[226:227], 0, s[14:15]
	v_mfma_f32_16x16x32_bf16 v[96:99], v[222:225], v[198:201], v[116:119]
	v_mfma_f32_16x16x32_bf16 v[68:71], v[214:217], v[206:209], v[68:71]
	v_mfma_f32_16x16x32_bf16 v[64:67], v[222:225], v[206:209], v[64:67]
	v_mfma_f32_16x16x32_bf16 v[116:119], v[230:233], v[202:205], v[96:99]
	v_mfma_f32_16x16x32_bf16 v[68:71], v[218:221], v[210:213], v[68:71]
	v_mfma_f32_16x16x32_bf16 v[64:67], v[230:233], v[210:213], v[64:67]
	s_barrier
	s_setprio 0
	ds_read_b128 v[96:99], v190 offset:49152
	global_load_lds_dwordx4 v[184:185], off
	ds_read_b128 v[100:103], v190 offset:50176
	ds_read_b128 v[108:111], v190 offset:51200
	ds_read_b128 v[112:115], v190 offset:52224
	ds_read_b128 v[160:163], v190 offset:53248
	ds_read_b128 v[164:167], v190 offset:54272
	ds_read_b128 v[198:201], v190 offset:55296
	ds_read_b128 v[202:205], v190 offset:56320
	v_lshl_add_u64 v[184:185], v[234:235], 0, s[14:15]
	s_mov_b32 m0, s66
	s_nop 0
	global_load_lds_dwordx4 v[184:185], off
	s_waitcnt vmcnt(10)
	s_setprio 1
	s_barrier
; #define PG8_STAGE(bufoff, gbase, voff) do { _Pragma("unroll") for (int _i = 0; _i < 2; ++_i) \
;         __builtin_amdgcn_global_load_lds((const unsigned*)((const char*)(gbase) + (voff)[_i]), (LAS unsigned*)(lds + (bufoff) + ldsw + _i * 8192), 16, 0, 0); } while (0)
; #define PG8_LDA(dst, b, h) do { _Pragma("unroll") for (int m = 0; m < 4; ++m) _Pragma("unroll") for (int k = 0; k < 2; ++k) dst[m][k] = *(const LAS bf16x8*)(lds + PG8_SA(b, h) + aoff + m * 2048 + k * 1024); } while (0)
; #define PG8_LDB(dst, b, h) do { _Pragma("unroll") for (int n = 0; n < 2; ++n) _Pragma("unroll") for (int k = 0; k < 2; ++k) dst[n][k] = *(const LAS bf16x8*)(lds + PG8_SB(b, h) + boff + n * 2048 + k * 1024); } while (0)
; #define PG8_MMA(ai, bj, At, Bt) do { __builtin_amdgcn_s_setprio(1); _Pragma("unroll") for (int m = 0; m < 4; ++m) _Pragma("unroll") for (int n = 0; n < 2; ++n) _Pragma("unroll") for (int k = 0; k < 2; ++k) \
;         acc[ai][bj][m][n] = __builtin_amdgcn_mfma_f32_16x16x32_bf16(Bt[n][k], At[m][k], acc[ai][bj][m][n], 0, 0, 0); __builtin_amdgcn_s_setprio(0); } while (0)
; #define PG8_WAIT_V(n) asm volatile("s_waitcnt vmcnt(" #n ")" ::: "memory")
; #define PG8_WAIT_L(n) asm volatile("s_waitcnt lgkmcnt(" #n ")" ::: "memory")
; #define PG8_BAR __builtin_amdgcn_s_barrier()
; #define PG8_SCHED __builtin_amdgcn_sched_barrier(0)
; template <class Map, class Epi>
; DI void gemm_phase(LAS unsigned char* lds, const Map& MP, const Epi& E, const int nM, const int nN, const int K, const int lda, const int ldb) {
;     ...
;             PG8_WAIT_V(6); PG8_BAR; PG8_MMA(1, 1, At, B1); PG8_BAR;
;             PG8_LDB(B0, 1, 0); PG8_SCHED; PG8_LDA(At, 1, 0); PG8_STAGE(PG8_SA(0, 1), a2 + hstepA, voffA);
;             PG8_WAIT_L(8); PG8_BAR; PG8_WAIT_L(0); PG8_MMA(0, 0, At, B0); PG8_BAR; PG8_SCHED;
;             PG8_LDB(B1, 1, 1); PG8_STAGE(PG8_SB(1, 0), b3, voffB);
;             PG8_BAR; PG8_WAIT_L(0); PG8_MMA(0, 1, At, B1); PG8_BAR;
;             PG8_LDA(At, 1, 1); PG8_STAGE(PG8_SA(1, 0), a3, voffA);
;             PG8_BAR; PG8_WAIT_L(0); PG8_MMA(1, 0, At, B0); PG8_BAR; PG8_SCHED;
;             PG8_STAGE(PG8_SB(1, 1), b3 + hstepB, voffB);
;             PG8_WAIT_V(6); PG8_BAR; PG8_MMA(1, 1, At, B1); PG8_BAR;
	s_waitcnt lgkmcnt(7)
	v_mfma_f32_16x16x32_bf16 v[60:63], v[80:83], v[96:99], v[60:63]
	v_mfma_f32_16x16x32_bf16 v[48:51], v[88:91], v[96:99], v[48:51]
	s_waitcnt lgkmcnt(5)
	v_mfma_f32_16x16x32_bf16 v[40:43], v[80:83], v[108:111], v[40:43]
	v_mfma_f32_16x16x32_bf16 v[32:35], v[88:91], v[108:111], v[32:35]
	s_waitcnt lgkmcnt(3)
	v_mfma_f32_16x16x32_bf16 v[24:27], v[80:83], v[160:163], v[24:27]
	v_mfma_f32_16x16x32_bf16 v[16:19], v[88:91], v[160:163], v[16:19]
	s_waitcnt lgkmcnt(1)
	v_mfma_f32_16x16x32_bf16 v[12:15], v[80:83], v[198:201], v[12:15]
	v_mfma_f32_16x16x32_bf16 v[8:11], v[88:91], v[198:201], v[8:11]
	v_mfma_f32_16x16x32_bf16 v[60:63], v[84:87], v[100:103], v[60:63]
	s_add_u32 s28, s28, 0x80080
	s_addc_u32 s29, s29, 0
	v_mfma_f32_16x16x32_bf16 v[48:51], v[92:95], v[100:103], v[48:51]
	s_add_i32 s46, s46, s54
	v_mfma_f32_16x16x32_bf16 v[40:43], v[84:87], v[112:115], v[40:43]
	v_mfma_f32_16x16x32_bf16 v[32:35], v[92:95], v[112:115], v[32:35]
	v_mfma_f32_16x16x32_bf16 v[24:27], v[84:87], v[164:167], v[24:27]
	v_mfma_f32_16x16x32_bf16 v[16:19], v[92:95], v[164:167], v[16:19]
	s_waitcnt lgkmcnt(0)
	v_mfma_f32_16x16x32_bf16 v[12:15], v[84:87], v[202:205], v[12:15]
	v_mfma_f32_16x16x32_bf16 v[8:11], v[92:95], v[202:205], v[8:11]
	s_barrier
	s_setprio 0
	s_mov_b32 m0, s46
	s_nop 0
	global_load_lds_dwordx4 v172, s[28:29]
	s_add_i32 m0, s46, 0x2000
	s_nop 0
	global_load_lds_dwordx4 v168, s[28:29]
	s_waitcnt vmcnt(6)
	s_setprio 1
	s_barrier
	v_mfma_f32_16x16x32_bf16 v[56:59], v[214:217], v[96:99], v[56:59]
	v_mfma_f32_16x16x32_bf16 v[52:55], v[222:225], v[96:99], v[52:55]
	ds_read_b128 v[80:83], v189
	v_mfma_f32_16x16x32_bf16 v[44:47], v[214:217], v[108:111], v[44:47]
	v_mfma_f32_16x16x32_bf16 v[36:39], v[222:225], v[108:111], v[36:39]
	ds_read_b128 v[84:87], v189 offset:1024
	v_mfma_f32_16x16x32_bf16 v[28:31], v[214:217], v[160:163], v[28:31]
	v_mfma_f32_16x16x32_bf16 v[20:23], v[222:225], v[160:163], v[20:23]
	ds_read_b128 v[88:91], v189 offset:2048
	v_mfma_f32_16x16x32_bf16 v[4:7], v[214:217], v[198:201], v[4:7]
	v_mfma_f32_16x16x32_bf16 v[0:3], v[222:225], v[198:201], v[0:3]
	ds_read_b128 v[92:95], v189 offset:3072
	v_mfma_f32_16x16x32_bf16 v[56:59], v[218:221], v[100:103], v[56:59]
	s_add_i32 s3, s3, 2
	v_mfma_f32_16x16x32_bf16 v[52:55], v[230:233], v[100:103], v[52:55]
	s_add_u32 vcc_lo, vcc_lo, 0x100
	s_addc_u32 vcc_hi, vcc_hi, 0
	v_mfma_f32_16x16x32_bf16 v[44:47], v[218:221], v[112:115], v[44:47]
	s_add_u32 s42, s42, 0x100
	s_addc_u32 s43, s43, 0
	v_mfma_f32_16x16x32_bf16 v[36:39], v[230:233], v[112:115], v[36:39]
	s_cmp_gt_u32 s3, 29
	v_mfma_f32_16x16x32_bf16 v[28:31], v[218:221], v[164:167], v[28:31]
	v_mfma_f32_16x16x32_bf16 v[20:23], v[230:233], v[164:167], v[20:23]
	v_mfma_f32_16x16x32_bf16 v[4:7], v[218:221], v[202:205], v[4:7]
	v_mfma_f32_16x16x32_bf16 v[0:3], v[230:233], v[202:205], v[0:3]
	s_barrier
	s_setprio 0
	s_cbranch_scc0 .LBB1_1908
; DI float silu_mul(float g, float v) { return g * v * __builtin_amdgcn_rcpf(1.0f + __builtin_amdgcn_exp2f(-LOG2E * g)); }
;     DI void operator()(const f32x4 (&acc)[2][2][4][2], const Unit& u, int wr, int wc, int fr, int fq) const {
;         const int row0 = u.pm * BM + wr * 64 + fr, ch0 = u.pn * 128 + wc * 32 + 8 * fq;
;         f32x4 w0[2], w1[2], w2[2], bb[2];
; #pragma unroll
;         for (int n = 0; n < 2; ++n) { w0[n] = *(const f32x4*)(cw + ch0 + 4 * n); w1[n] = *(const f32x4*)(cw + DFF + ch0 + 4 * n); w2[n] = *(const f32x4*)(cw + 2 * DFF + ch0 + 4 * n); bb[n] = *(const f32x4*)(cb + ch0 + 4 * n); }
; #pragma unroll
;         for (int ai = 0; ai < 2; ++ai)
; #pragma unroll
;             for (int m = 0; m < 4; ++m) {
;                 const bool efirst = (m == 0) && (fr == 0), elast = (m == 3) && (fr == 15);
;                 const int row = row0 + ai * HALF + m * 16;
;                 f32x4 gc[2];
; #pragma unroll
;                 for (int n = 0; n < 2; ++n) {
;                     const f32x4 g = acc[ai][0][m][n];
;                     const f32x4 gprev = acc[ai][0][m > 0 ? m - 1 : 0][n], gnext = acc[ai][0][m < 3 ? m + 1 : 3][n];
;                     f32x4 up, dn;
; #pragma unroll
;                     for (int e = 0; e < 4; ++e) {
;                         const float pu = (m > 0 && fr == 15) ? gprev[e] : g[e];
;                         const float pd = (m < 3 && fr == 0) ? gnext[e] : g[e];
;                         up[e] = dpp_ror1(pu); dn[e] = dpp_ror15(pd);
;                     }
;                     if (efirst) up = (f32x4){0.f, 0.f, 0.f, 0.f};
;                     if (elast) dn = (f32x4){0.f, 0.f, 0.f, 0.f};
;                     gc[n] = w0[n] * up + w1[n] * g + w2[n] * dn + bb[n];
;                 }
;                 if (efirst || elast) {
;                     const size_t eo = (size_t)((row >> 6) * 2 + (elast ? 1 : 0)) * DFF + ch0;
; #pragma unroll
;                     for (int n = 0; n < 2; ++n) { *(f32x4*)(EP + eo + 4 * n) = gc[n]; *(f32x4*)(ER + eo + 4 * n) = acc[ai][0][m][n]; *(f32x4*)(EV + eo + 4 * n) = acc[ai][1][m][n]; }
;                 } else {
;                     const f32x4 v0 = acc[ai][1][m][0], v1 = acc[ai][1][m][1];
;                     u32x4 o;
;                     o[0] = pack2(silu_mul(gc[0][0], v0[0]), silu_mul(gc[0][1], v0[1])); o[1] = pack2(silu_mul(gc[0][2], v0[2]), silu_mul(gc[0][3], v0[3]));
	s_waitcnt lgkmcnt(0)
	s_lshl_b32 s21, s45, 7
	v_mov_b32_e32 v194, v186
	v_mov_b32_e32 v80, v187
	s_or_b32 s21, s21, s62
	v_lshl_add_u32 v184, v80, 3, s21
	v_ashrrev_i32_e32 v185, 31, v184
	v_lshlrev_b64 v[80:81], 2, v[184:185]
	v_lshl_add_u64 v[84:85], s[4:5], 0, v[80:81]
	v_lshl_add_u64 v[88:89], s[16:17], 0, v[80:81]
	v_lshl_add_u64 v[92:93], s[18:19], 0, v[80:81]
	v_lshl_add_u64 v[112:113], s[6:7], 0, v[80:81]
	global_load_dwordx4 v[80:83], v[84:85], off offset:16
	global_load_dwordx4 v[96:99], v[84:85], off
	s_nop 0
	global_load_dwordx4 v[84:87], v[88:89], off offset:16
	global_load_dwordx4 v[100:103], v[88:89], off
	s_nop 0
	global_load_dwordx4 v[88:91], v[92:93], off offset:16
	global_load_dwordx4 v[108:111], v[92:93], off
	s_nop 0
	global_load_dwordx4 v[92:95], v[112:113], off offset:16
	s_nop 0
	global_load_dwordx4 v[112:115], v[112:113], off
	v_cmp_eq_u32_e32 vcc, 0, v194
	s_nop 0
	s_nop 0
	v_cndmask_b32_e32 v161, v148, v136, vcc
	v_cndmask_b32_e32 v162, v149, v137, vcc
	v_cndmask_b32_e32 v163, v150, v138, vcc
	v_mov_b32_dpp v160, v161 row_ror:15 row_mask:0xf bank_mask:0xf
	s_nop 0
	s_nop 0
	v_mov_b32_dpp v161, v162 row_ror:15 row_mask:0xf bank_mask:0xf
	v_mov_b32_dpp v164, v150 row_ror:1 row_mask:0xf bank_mask:0xf
	v_cndmask_b32_e32 v165, v151, v139, vcc
	v_mov_b32_dpp v162, v163 row_ror:15 row_mask:0xf bank_mask:0xf
	v_mov_b32_dpp v195, v151 row_ror:1 row_mask:0xf bank_mask:0xf
	v_mov_b32_dpp v166, v148 row_ror:1 row_mask:0xf bank_mask:0xf
	v_mov_b32_dpp v167, v149 row_ror:1 row_mask:0xf bank_mask:0xf
	v_mov_b32_dpp v163, v165 row_ror:15 row_mask:0xf bank_mask:0xf
	v_cndmask_b32_e64 v165, v195, 0, vcc
	v_cndmask_b32_e64 v164, v164, 0, vcc
	v_cndmask_b32_e64 v167, v167, 0, vcc
	v_cndmask_b32_e64 v166, v166, 0, vcc
	s_nop 0
	s_nop 0
	v_mov_b32_dpp v195, v144 row_ror:1 row_mask:0xf bank_mask:0xf
	v_mov_b32_dpp v196, v145 row_ror:1 row_mask:0xf bank_mask:0xf
	v_mov_b32_dpp v198, v146 row_ror:1 row_mask:0xf bank_mask:0xf
	v_cndmask_b32_e32 v199, v147, v131, vcc
	v_mov_b32_dpp v200, v147 row_ror:1 row_mask:0xf bank_mask:0xf
	v_cndmask_b32_e64 v198, v198, 0, vcc
	v_cndmask_b32_e64 v201, v196, 0, vcc
	s_lshl_b32 s3, s44, 8
	s_add_i32 s3, s3, s49
	v_add_u32_e32 v193, s3, v194
	v_cmp_ne_u32_e64 s[46:47], 0, v194
	s_waitcnt vmcnt(0)
	v_pk_mul_f32 v[164:165], v[98:99], v[164:165]
	v_pk_mul_f32 v[166:167], v[96:97], v[166:167]
	v_pk_fma_f32 v[164:165], v[150:151], v[102:103], v[164:165]
	v_pk_fma_f32 v[166:167], v[148:149], v[100:101], v[166:167]
	v_pk_fma_f32 v[162:163], v[110:111], v[162:163], v[164:165]
	v_cndmask_b32_e32 v165, v144, v128, vcc
	v_pk_fma_f32 v[160:161], v[108:109], v[160:161], v[166:167]
	v_cndmask_b32_e32 v166, v145, v129, vcc
	v_mov_b32_dpp v164, v165 row_ror:15 row_mask:0xf bank_mask:0xf
	v_cndmask_b32_e32 v167, v146, v130, vcc
	v_pk_add_f32 v[162:163], v[114:115], v[162:163]
	v_mov_b32_dpp v165, v166 row_ror:15 row_mask:0xf bank_mask:0xf
	v_pk_add_f32 v[160:161], v[112:113], v[160:161]
	s_nop 0
	v_mov_b32_dpp v166, v167 row_ror:15 row_mask:0xf bank_mask:0xf
	s_nop 1
	v_mov_b32_dpp v167, v199 row_ror:15 row_mask:0xf bank_mask:0xf
	v_cndmask_b32_e64 v199, v200, 0, vcc
	v_cndmask_b32_e64 v200, v195, 0, vcc
	v_pk_mul_f32 v[200:201], v[80:81], v[200:201]
	v_pk_mul_f32 v[198:199], v[82:83], v[198:199]
	v_pk_fma_f32 v[200:201], v[144:145], v[84:85], v[200:201]
	v_pk_fma_f32 v[198:199], v[146:147], v[86:87], v[198:199]
	v_pk_fma_f32 v[164:165], v[88:89], v[164:165], v[200:201]
	v_pk_fma_f32 v[166:167], v[90:91], v[166:167], v[198:199]
	v_pk_add_f32 v[164:165], v[92:93], v[164:165]
	v_pk_add_f32 v[166:167], v[94:95], v[166:167]
	s_and_saveexec_b64 s[28:29], s[46:47]
	s_xor_b64 s[28:29], exec, s[28:29]
	s_cbranch_execz .LBB1_1911
	v_mul_f32_e32 v195, 0xbfb8aa3b, v160
	v_exp_f32_e32 v195, v195
	v_mul_f32_e32 v196, 0xbfb8aa3b, v161
	v_exp_f32_e32 v196, v196
	v_pk_mul_f32 v[160:161], v[156:157], v[160:161]
	v_add_f32_e32 v195, 1.0, v195
	v_rcp_f32_e32 v198, v195
	v_add_f32_e32 v196, 1.0, v196
	v_mul_f32_e32 v195, 0xbfb8aa3b, v162
	v_rcp_f32_e32 v199, v196
	v_exp_f32_e32 v195, v195
	v_mul_f32_e32 v196, 0xbfb8aa3b, v163
	v_exp_f32_e32 v196, v196
	v_pk_mul_f32 v[160:161], v[160:161], v[198:199]
	v_add_f32_e32 v195, 1.0, v195
	v_rcp_f32_e32 v200, v195
	v_add_f32_e32 v195, 1.0, v196
	v_rcp_f32_e32 v201, v195
	v_cvt_pk_bf16_f32 v160, v160, v161
	v_mul_f32_e32 v161, 0xbfb8aa3b, v164
	v_exp_f32_e32 v195, v161
	v_mul_f32_e32 v161, 0xbfb8aa3b, v165
	v_exp_f32_e32 v196, v161
	v_pk_mul_f32 v[162:163], v[158:159], v[162:163]
	v_pk_mul_f32 v[164:165], v[152:153], v[164:165]
	v_pk_mul_f32 v[162:163], v[162:163], v[200:201]
	s_nop 0
	v_cvt_pk_bf16_f32 v161, v162, v163
	v_add_f32_e32 v162, 1.0, v195
	v_mul_f32_e32 v195, 0xbfb8aa3b, v166
	v_add_f32_e32 v163, 1.0, v196
	v_exp_f32_e32 v195, v195
	v_mul_f32_e32 v196, 0xbfb8aa3b, v167
	v_exp_f32_e32 v196, v196
	v_rcp_f32_e32 v162, v162
	v_add_f32_e32 v195, 1.0, v195
	v_rcp_f32_e32 v198, v195
	v_add_f32_e32 v195, 1.0, v196
	v_rcp_f32_e32 v163, v163
	v_rcp_f32_e32 v199, v195
	v_pk_mul_f32 v[166:167], v[154:155], v[166:167]
	v_pk_mul_f32 v[162:163], v[164:165], v[162:163]
	v_pk_mul_f32 v[164:165], v[166:167], v[198:199]
	v_cvt_pk_bf16_f32 v162, v162, v163
	v_cvt_pk_bf16_f32 v163, v164, v165
	v_mov_b64_e32 v[164:165], s[52:53]
	v_mad_i64_i32 v[164:165], s[42:43], v193, s60, v[164:165]
	v_lshl_add_u64 v[164:165], v[184:185], 1, v[164:165]
	global_store_dwordx4 v[164:165], v[160:163], off

; #define PG8_STAGE(bufoff, gbase, voff) do { _Pragma("unroll") for (int _i = 0; _i < 2; ++_i) \
;         __builtin_amdgcn_global_load_lds((const unsigned*)((const char*)(gbase) + (voff)[_i]), (LAS unsigned*)(lds + (bufoff) + ldsw + _i * 8192), 16, 0, 0); } while (0)
; #define PG8_LDA(dst, b, h) do { _Pragma("unroll") for (int m = 0; m < 4; ++m) _Pragma("unroll") for (int k = 0; k < 2; ++k) dst[m][k] = *(const LAS bf16x8*)(lds + PG8_SA(b, h) + aoff + m * 2048 + k * 1024); } while (0)
; #define PG8_WAIT_V(n) asm volatile("s_waitcnt vmcnt(" #n ")" ::: "memory")
; #define PG8_BAR __builtin_amdgcn_s_barrier()
; template <class Map, class Epi>
; DI void gemm_phase(LAS unsigned char* lds, const Map& MP, const Epi& E, const int nM, const int nN, const int K, const int lda, const int ldb) {
;     ...
;         for (int t = 0; t < nt; t += 2) {
;             const bool last = (t == nt - 2);
;             const char* a1 = cA + (size_t)(t + 1) * kstep;
;             const char* a2 = last ? nA : cA + (size_t)(t + 2) * kstep; const char* b2 = last ? nB : cB + (size_t)(t + 2) * kstep;
;             const char* a3 = a2 + kstep; const char* b3 = b2 + kstep;
;             PG8_LDB(B0, 0, 0); PG8_SCHED; PG8_LDA(At, 0, 0); PG8_STAGE(PG8_SA(1, 1), a1 + hstepA, voffA);
;             PG8_WAIT_L(8); PG8_BAR; PG8_WAIT_L(0); PG8_MMA(0, 0, At, B0); PG8_BAR; PG8_SCHED;
;             PG8_LDB(B1, 0, 1); PG8_STAGE(PG8_SB(0, 0), b2, voffB);
;             PG8_BAR; PG8_WAIT_L(0); PG8_MMA(0, 1, At, B1); PG8_BAR;
;             PG8_LDA(At, 0, 1); PG8_STAGE(PG8_SA(0, 0), a2, voffA);
;             PG8_BAR; PG8_WAIT_L(0); PG8_MMA(1, 0, At, B0); PG8_BAR; PG8_SCHED;
;             PG8_STAGE(PG8_SB(0, 1), b2 + hstepB, voffB);
;             PG8_WAIT_V(6); PG8_BAR; PG8_MMA(1, 1, At, B1); PG8_BAR;
;             PG8_LDB(B0, 1, 0); PG8_SCHED; PG8_LDA(At, 1, 0); PG8_STAGE(PG8_SA(0, 1), a2 + hstepA, voffA);
;             PG8_WAIT_L(8); PG8_BAR; PG8_WAIT_L(0); PG8_MMA(0, 0, At, B0); PG8_BAR; PG8_SCHED;
;             PG8_LDB(B1, 1, 1); PG8_STAGE(PG8_SB(1, 0), b3, voffB);
;             PG8_BAR; PG8_WAIT_L(0); PG8_MMA(0, 1, At, B1); PG8_BAR;
;             PG8_LDA(At, 1, 1); PG8_STAGE(PG8_SA(1, 0), a3, voffA);
;             PG8_BAR; PG8_WAIT_L(0); PG8_MMA(1, 0, At, B0); PG8_BAR; PG8_SCHED;
;             PG8_STAGE(PG8_SB(1, 1), b3 + hstepB, voffB);
;             PG8_WAIT_V(6); PG8_BAR; PG8_MMA(1, 1, At, B1); PG8_BAR;
.LBB1_2078:
	s_add_u32 s10, s8, 0x100
	s_addc_u32 s11, s9, 0
	s_cmpk_eq_i32 s3, 0x54
	s_cselect_b32 s15, s43, s11
	s_cselect_b32 s14, s42, s10
	s_cselect_b32 s13, s7, s44
	s_cselect_b32 s12, s6, s39
	s_add_i32 m0, s24, 0xc000
	ds_read_b128 v[168:171], v150
	global_load_lds_dwordx4 v138, s[8:9]
	ds_read_b128 v[172:175], v150 offset:1024
	ds_read_b128 v[176:179], v150 offset:2048
	ds_read_b128 v[180:183], v150 offset:3072
	ds_read_b128 v[184:187], v150 offset:4096
	ds_read_b128 v[188:191], v150 offset:5120
	ds_read_b128 v[192:195], v150 offset:6144
	ds_read_b128 v[198:201], v150 offset:7168
	s_add_i32 m0, s24, 0xe000
	s_nop 0
	global_load_lds_dwordx4 v136, s[8:9]
	s_waitcnt lgkmcnt(8)
	s_setprio 1
	s_barrier
	s_waitcnt lgkmcnt(7)
	v_mfma_f32_16x16x32_bf16 v[124:127], v[152:155], v[168:171], v[124:127]
	v_mfma_f32_16x16x32_bf16 v[120:123], v[160:163], v[168:171], v[120:123]
	s_waitcnt lgkmcnt(5)
	v_mfma_f32_16x16x32_bf16 v[108:111], v[152:155], v[176:179], v[108:111]
	v_mfma_f32_16x16x32_bf16 v[104:107], v[160:163], v[176:179], v[104:107]
	s_waitcnt lgkmcnt(3)
	v_mfma_f32_16x16x32_bf16 v[92:95], v[152:155], v[184:187], v[92:95]
	v_mfma_f32_16x16x32_bf16 v[88:91], v[160:163], v[184:187], v[88:91]
	s_waitcnt lgkmcnt(1)
	v_mfma_f32_16x16x32_bf16 v[76:79], v[152:155], v[192:195], v[76:79]
	v_mfma_f32_16x16x32_bf16 v[72:75], v[160:163], v[192:195], v[72:75]
	v_mfma_f32_16x16x32_bf16 v[124:127], v[156:159], v[172:175], v[124:127]
	s_add_i32 s8, s35, s22
	v_mfma_f32_16x16x32_bf16 v[120:123], v[164:167], v[172:175], v[120:123]
	v_lshl_add_u64 v[144:145], s[12:13], 0, v[132:133]
	v_mfma_f32_16x16x32_bf16 v[108:111], v[156:159], v[180:183], v[108:111]
	v_lshl_add_u64 v[218:219], s[12:13], 0, v[128:129]
	v_mfma_f32_16x16x32_bf16 v[104:107], v[164:167], v[180:183], v[104:107]
	v_mfma_f32_16x16x32_bf16 v[92:95], v[156:159], v[188:191], v[92:95]
	v_mfma_f32_16x16x32_bf16 v[88:91], v[164:167], v[188:191], v[88:91]
	s_waitcnt lgkmcnt(0)
	v_mfma_f32_16x16x32_bf16 v[76:79], v[156:159], v[198:201], v[76:79]
	v_mfma_f32_16x16x32_bf16 v[72:75], v[164:167], v[198:201], v[72:75]
	s_barrier
	s_setprio 0
	s_mov_b32 m0, s8
	ds_read_b128 v[202:205], v151
	global_load_lds_dwordx4 v[144:145], off
	ds_read_b128 v[206:209], v151 offset:1024
	ds_read_b128 v[210:213], v151 offset:2048
	ds_read_b128 v[214:217], v151 offset:3072
	s_add_i32 m0, s8, 0x2000
	s_nop 0
	global_load_lds_dwordx4 v[218:219], off
	s_setprio 1
	s_barrier
	s_waitcnt lgkmcnt(3)
	v_mfma_f32_16x16x32_bf16 v[116:119], v[202:205], v[168:171], v[116:119]
	s_waitcnt lgkmcnt(1)
	v_mfma_f32_16x16x32_bf16 v[112:115], v[210:213], v[168:171], v[112:115]
	v_mfma_f32_16x16x32_bf16 v[100:103], v[202:205], v[176:179], v[100:103]
	v_mfma_f32_16x16x32_bf16 v[96:99], v[210:213], v[176:179], v[96:99]
	v_mfma_f32_16x16x32_bf16 v[84:87], v[202:205], v[184:187], v[84:87]
	v_mfma_f32_16x16x32_bf16 v[80:83], v[210:213], v[184:187], v[80:83]
	v_mfma_f32_16x16x32_bf16 v[68:71], v[202:205], v[192:195], v[68:71]
	v_mfma_f32_16x16x32_bf16 v[64:67], v[210:213], v[192:195], v[64:67]
	v_mfma_f32_16x16x32_bf16 v[116:119], v[206:209], v[172:175], v[116:119]
	v_lshl_add_u64 v[222:223], s[14:15], 0, v[130:131]
	s_mov_b32 m0, s24
	s_waitcnt lgkmcnt(0)
	v_mfma_f32_16x16x32_bf16 v[112:115], v[214:217], v[172:175], v[112:115]
	v_lshl_add_u64 v[220:221], s[14:15], 0, v[134:135]
	v_mfma_f32_16x16x32_bf16 v[100:103], v[206:209], v[180:183], v[100:103]
	v_mfma_f32_16x16x32_bf16 v[96:99], v[214:217], v[180:183], v[96:99]
	v_mfma_f32_16x16x32_bf16 v[84:87], v[206:209], v[188:191], v[84:87]
	v_mfma_f32_16x16x32_bf16 v[80:83], v[214:217], v[188:191], v[80:83]
	v_mfma_f32_16x16x32_bf16 v[68:71], v[206:209], v[198:201], v[68:71]
	v_mfma_f32_16x16x32_bf16 v[64:67], v[214:217], v[198:201], v[64:67]
	s_barrier
	s_setprio 0
	ds_read_b128 v[168:171], v150 offset:16384
	global_load_lds_dwordx4 v[220:221], off
	ds_read_b128 v[172:175], v150 offset:17408
	ds_read_b128 v[176:179], v150 offset:18432
	ds_read_b128 v[180:183], v150 offset:19456
	ds_read_b128 v[184:187], v150 offset:20480
	ds_read_b128 v[188:191], v150 offset:21504
	ds_read_b128 v[192:195], v150 offset:22528
	ds_read_b128 v[198:201], v150 offset:23552
	s_mov_b32 m0, s25
	s_nop 0
	global_load_lds_dwordx4 v[222:223], off
	s_waitcnt vmcnt(10)
	s_setprio 1
	s_barrier
	s_waitcnt lgkmcnt(7)
	v_mfma_f32_16x16x32_bf16 v[60:63], v[152:155], v[168:171], v[60:63]
	v_mfma_f32_16x16x32_bf16 v[56:59], v[160:163], v[168:171], v[56:59]
	s_waitcnt lgkmcnt(5)
	v_mfma_f32_16x16x32_bf16 v[44:47], v[152:155], v[176:179], v[44:47]
	v_mfma_f32_16x16x32_bf16 v[40:43], v[160:163], v[176:179], v[40:43]
	s_waitcnt lgkmcnt(3)
	v_mfma_f32_16x16x32_bf16 v[28:31], v[152:155], v[184:187], v[28:31]
	v_mfma_f32_16x16x32_bf16 v[24:27], v[160:163], v[184:187], v[24:27]
	s_waitcnt lgkmcnt(1)
	v_mfma_f32_16x16x32_bf16 v[12:15], v[152:155], v[192:195], v[12:15]
	v_mfma_f32_16x16x32_bf16 v[8:11], v[160:163], v[192:195], v[8:11]
	v_mfma_f32_16x16x32_bf16 v[60:63], v[156:159], v[172:175], v[60:63]
	s_add_u32 s8, s12, 0x160000
	s_addc_u32 s9, s13, 0
	v_mfma_f32_16x16x32_bf16 v[56:59], v[164:167], v[172:175], v[56:59]
	s_add_i32 s45, s36, s22
	v_mfma_f32_16x16x32_bf16 v[44:47], v[156:159], v[180:183], v[44:47]
	v_mfma_f32_16x16x32_bf16 v[40:43], v[164:167], v[180:183], v[40:43]
	v_mfma_f32_16x16x32_bf16 v[28:31], v[156:159], v[188:191], v[28:31]
	v_mfma_f32_16x16x32_bf16 v[24:27], v[164:167], v[188:191], v[24:27]
	s_waitcnt lgkmcnt(0)
	v_mfma_f32_16x16x32_bf16 v[12:15], v[156:159], v[198:201], v[12:15]
	v_mfma_f32_16x16x32_bf16 v[8:11], v[164:167], v[198:201], v[8:11]
	s_barrier
; #define PG8_STAGE(bufoff, gbase, voff) do { _Pragma("unroll") for (int _i = 0; _i < 2; ++_i) \
;         __builtin_amdgcn_global_load_lds((const unsigned*)((const char*)(gbase) + (voff)[_i]), (LAS unsigned*)(lds + (bufoff) + ldsw + _i * 8192), 16, 0, 0); } while (0)
; #define PG8_LDA(dst, b, h) do { _Pragma("unroll") for (int m = 0; m < 4; ++m) _Pragma("unroll") for (int k = 0; k < 2; ++k) dst[m][k] = *(const LAS bf16x8*)(lds + PG8_SA(b, h) + aoff + m * 2048 + k * 1024); } while (0)
; #define PG8_WAIT_V(n) asm volatile("s_waitcnt vmcnt(" #n ")" ::: "memory")
; #define PG8_BAR __builtin_amdgcn_s_barrier()
; template <class Map, class Epi>
; DI void gemm_phase(LAS unsigned char* lds, const Map& MP, const Epi& E, const int nM, const int nN, const int K, const int lda, const int ldb) {
;     ...
;         for (int t = 0; t < nt; t += 2) {
;             const bool last = (t == nt - 2);
;             const char* a1 = cA + (size_t)(t + 1) * kstep;
;             const char* a2 = last ? nA : cA + (size_t)(t + 2) * kstep; const char* b2 = last ? nB : cB + (size_t)(t + 2) * kstep;
;             const char* a3 = a2 + kstep; const char* b3 = b2 + kstep;
;             PG8_LDB(B0, 0, 0); PG8_SCHED; PG8_LDA(At, 0, 0); PG8_STAGE(PG8_SA(1, 1), a1 + hstepA, voffA);
;             PG8_WAIT_L(8); PG8_BAR; PG8_WAIT_L(0); PG8_MMA(0, 0, At, B0); PG8_BAR; PG8_SCHED;
;             PG8_LDB(B1, 0, 1); PG8_STAGE(PG8_SB(0, 0), b2, voffB);
;             PG8_BAR; PG8_WAIT_L(0); PG8_MMA(0, 1, At, B1); PG8_BAR;
;             PG8_LDA(At, 0, 1); PG8_STAGE(PG8_SA(0, 0), a2, voffA);
;             PG8_BAR; PG8_WAIT_L(0); PG8_MMA(1, 0, At, B0); PG8_BAR; PG8_SCHED;
;             PG8_STAGE(PG8_SB(0, 1), b2 + hstepB, voffB);
;             PG8_WAIT_V(6); PG8_BAR; PG8_MMA(1, 1, At, B1); PG8_BAR;
;             PG8_LDB(B0, 1, 0); PG8_SCHED; PG8_LDA(At, 1, 0); PG8_STAGE(PG8_SA(0, 1), a2 + hstepA, voffA);
;             PG8_WAIT_L(8); PG8_BAR; PG8_WAIT_L(0); PG8_MMA(0, 0, At, B0); PG8_BAR; PG8_SCHED;
;             PG8_LDB(B1, 1, 1); PG8_STAGE(PG8_SB(1, 0), b3, voffB);
;             PG8_BAR; PG8_WAIT_L(0); PG8_MMA(0, 1, At, B1); PG8_BAR;
;             PG8_LDA(At, 1, 1); PG8_STAGE(PG8_SA(1, 0), a3, voffA);
;             PG8_BAR; PG8_WAIT_L(0); PG8_MMA(1, 0, At, B0); PG8_BAR; PG8_SCHED;
;             PG8_STAGE(PG8_SB(1, 1), b3 + hstepB, voffB);
;             PG8_WAIT_V(6); PG8_BAR; PG8_MMA(1, 1, At, B1); PG8_BAR;
	s_setprio 0
	s_mov_b32 m0, s45
	s_nop 0
	global_load_lds_dwordx4 v132, s[8:9]
	s_add_i32 m0, s45, 0x2000
	s_nop 0
	global_load_lds_dwordx4 v128, s[8:9]
	s_waitcnt vmcnt(6)
	s_setprio 1
	s_barrier
	v_mfma_f32_16x16x32_bf16 v[52:55], v[202:205], v[168:171], v[52:55]
	v_mfma_f32_16x16x32_bf16 v[48:51], v[210:213], v[168:171], v[48:51]
	s_add_i32 s45, 0, 0x18000
	v_add_u32_e32 v164, s45, v148
	ds_read_b128 v[152:155], v164
	v_mfma_f32_16x16x32_bf16 v[36:39], v[202:205], v[176:179], v[36:39]
	v_mfma_f32_16x16x32_bf16 v[32:35], v[210:213], v[176:179], v[32:35]
	ds_read_b128 v[156:159], v164 offset:1024
	v_mfma_f32_16x16x32_bf16 v[20:23], v[202:205], v[184:187], v[20:23]
	v_mfma_f32_16x16x32_bf16 v[16:19], v[210:213], v[184:187], v[16:19]
	ds_read_b128 v[160:163], v164 offset:2048
	v_mfma_f32_16x16x32_bf16 v[4:7], v[202:205], v[192:195], v[4:7]
	v_mfma_f32_16x16x32_bf16 v[0:3], v[210:213], v[192:195], v[0:3]
	ds_read_b128 v[164:167], v164 offset:3072
	v_mfma_f32_16x16x32_bf16 v[52:55], v[206:209], v[172:175], v[52:55]
	s_add_u32 s8, s14, 0x160000
	s_addc_u32 s9, s15, 0
	v_mfma_f32_16x16x32_bf16 v[48:51], v[214:217], v[172:175], v[48:51]
	v_mfma_f32_16x16x32_bf16 v[36:39], v[206:209], v[180:183], v[36:39]
	v_mfma_f32_16x16x32_bf16 v[32:35], v[214:217], v[180:183], v[32:35]
	v_mfma_f32_16x16x32_bf16 v[20:23], v[206:209], v[188:191], v[20:23]
	v_mfma_f32_16x16x32_bf16 v[16:19], v[214:217], v[188:191], v[16:19]
	v_mfma_f32_16x16x32_bf16 v[4:7], v[206:209], v[198:201], v[4:7]
	v_mfma_f32_16x16x32_bf16 v[0:3], v[214:217], v[198:201], v[0:3]
	s_barrier
	s_setprio 0
	s_mov_b32 m0, s26
	ds_read_b128 v[168:171], v150 offset:32768
	global_load_lds_dwordx4 v134, s[8:9]
	ds_read_b128 v[172:175], v150 offset:33792
	ds_read_b128 v[176:179], v150 offset:34816
	ds_read_b128 v[180:183], v150 offset:35840
	ds_read_b128 v[184:187], v150 offset:36864
	ds_read_b128 v[188:191], v150 offset:37888
	ds_read_b128 v[192:195], v150 offset:38912
	ds_read_b128 v[198:201], v150 offset:39936
	s_mov_b32 m0, s27
	s_nop 0
	global_load_lds_dwordx4 v130, s[8:9]
	s_waitcnt lgkmcnt(8)
	s_setprio 1
	s_barrier
	s_waitcnt lgkmcnt(7)
	v_mfma_f32_16x16x32_bf16 v[124:127], v[152:155], v[168:171], v[124:127]
	v_mfma_f32_16x16x32_bf16 v[120:123], v[160:163], v[168:171], v[120:123]
	s_waitcnt lgkmcnt(5)
	v_mfma_f32_16x16x32_bf16 v[108:111], v[152:155], v[176:179], v[108:111]
	v_mfma_f32_16x16x32_bf16 v[104:107], v[160:163], v[176:179], v[104:107]
	s_waitcnt lgkmcnt(3)
	v_mfma_f32_16x16x32_bf16 v[92:95], v[152:155], v[184:187], v[92:95]
	v_mfma_f32_16x16x32_bf16 v[88:91], v[160:163], v[184:187], v[88:91]
	s_waitcnt lgkmcnt(1)
	v_mfma_f32_16x16x32_bf16 v[76:79], v[152:155], v[192:195], v[76:79]
	v_mfma_f32_16x16x32_bf16 v[72:75], v[160:163], v[192:195], v[72:75]
	v_mfma_f32_16x16x32_bf16 v[124:127], v[156:159], v[172:175], v[124:127]
	s_add_i32 s14, 0, 0x1c000
	v_mfma_f32_16x16x32_bf16 v[120:123], v[164:167], v[172:175], v[120:123]
	s_add_i32 s8, s45, s22
	v_mfma_f32_16x16x32_bf16 v[108:111], v[156:159], v[180:183], v[108:111]
	v_add_u32_e32 v196, s14, v148
	v_mfma_f32_16x16x32_bf16 v[104:107], v[164:167], v[180:183], v[104:107]
	v_lshl_add_u64 v[144:145], v[144:145], 0, s[46:47]
	v_mfma_f32_16x16x32_bf16 v[92:95], v[156:159], v[188:191], v[92:95]
	v_mfma_f32_16x16x32_bf16 v[88:91], v[164:167], v[188:191], v[88:91]
	s_waitcnt lgkmcnt(0)
	v_mfma_f32_16x16x32_bf16 v[76:79], v[156:159], v[198:201], v[76:79]
	v_mfma_f32_16x16x32_bf16 v[72:75], v[164:167], v[198:201], v[72:75]
	s_barrier
	s_setprio 0
	s_mov_b32 m0, s8
	ds_read_b128 v[202:205], v196
	global_load_lds_dwordx4 v[144:145], off
	ds_read_b128 v[206:209], v196 offset:1024
	ds_read_b128 v[210:213], v196 offset:2048
	ds_read_b128 v[214:217], v196 offset:3072
	v_lshl_add_u64 v[144:145], v[218:219], 0, s[46:47]
	s_add_i32 m0, s8, 0x2000
	s_nop 0
	global_load_lds_dwordx4 v[144:145], off
	s_setprio 1
	s_barrier
	s_waitcnt lgkmcnt(3)
	v_mfma_f32_16x16x32_bf16 v[116:119], v[202:205], v[168:171], v[116:119]
	s_waitcnt lgkmcnt(1)
	v_mfma_f32_16x16x32_bf16 v[112:115], v[210:213], v[168:171], v[112:115]
	v_mfma_f32_16x16x32_bf16 v[100:103], v[202:205], v[176:179], v[100:103]
	v_mfma_f32_16x16x32_bf16 v[96:99], v[210:213], v[176:179], v[96:99]
	v_mfma_f32_16x16x32_bf16 v[84:87], v[202:205], v[184:187], v[84:87]
	v_mfma_f32_16x16x32_bf16 v[80:83], v[210:213], v[184:187], v[80:83]
	v_mfma_f32_16x16x32_bf16 v[68:71], v[202:205], v[192:195], v[68:71]
	v_mfma_f32_16x16x32_bf16 v[64:67], v[210:213], v[192:195], v[64:67]
	v_mfma_f32_16x16x32_bf16 v[116:119], v[206:209], v[172:175], v[116:119]
	s_mov_b32 m0, s30
	s_waitcnt lgkmcnt(0)
	v_mfma_f32_16x16x32_bf16 v[112:115], v[214:217], v[172:175], v[112:115]
	v_lshl_add_u64 v[144:145], v[220:221], 0, s[46:47]
	v_mfma_f32_16x16x32_bf16 v[100:103], v[206:209], v[180:183], v[100:103]
	v_mfma_f32_16x16x32_bf16 v[96:99], v[214:217], v[180:183], v[96:99]
	v_mfma_f32_16x16x32_bf16 v[84:87], v[206:209], v[188:191], v[84:87]
	v_mfma_f32_16x16x32_bf16 v[80:83], v[214:217], v[188:191], v[80:83]
	v_mfma_f32_16x16x32_bf16 v[68:71], v[206:209], v[198:201], v[68:71]
	v_mfma_f32_16x16x32_bf16 v[64:67], v[214:217], v[198:201], v[64:67]
	s_barrier
	s_setprio 0
	ds_read_b128 v[168:171], v150 offset:49152
	global_load_lds_dwordx4 v[144:145], off
	ds_read_b128 v[172:175], v150 offset:50176
	ds_read_b128 v[176:179], v150 offset:51200
	ds_read_b128 v[180:183], v150 offset:52224
	ds_read_b128 v[184:187], v150 offset:53248
	ds_read_b128 v[188:191], v150 offset:54272
	ds_read_b128 v[192:195], v150 offset:55296
	ds_read_b128 v[198:201], v150 offset:56320
	v_lshl_add_u64 v[144:145], v[222:223], 0, s[46:47]
	s_mov_b32 m0, s31
	s_nop 0
	global_load_lds_dwordx4 v[144:145], off
	s_waitcnt vmcnt(10)
	s_setprio 1
	s_barrier
; DI unsigned pack2(float a, float b) { f32x2 v = {a, b}; hwbf16x2 r = __builtin_convertvector(v, hwbf16x2); return __builtin_bit_cast(unsigned, r); }
; DI float bflo(unsigned w) { return __uint_as_float(w << 16); }
;     DI void operator()(const f32x4 (&acc)[2][2][4][2], const Unit& u, int wr, int wc, int fr, int fq) const {
;     ...
;         for (int ai = 0; ai < 2; ++ai)
; #pragma unroll
;             for (int m = 0; m < 4; ++m) { const size_t ro = (size_t)(row0 + ai * HALF + m * 16) * D + col0;
; #pragma unroll
;                 for (int bj = 0; bj < 2; ++bj) {
;                     f32x4 x0, x1;
;                     if constexpr (IB) { const u32x4 w = *(const u32x4*)((const bf16_t*)Xin + ro + bj * HALF);
;                         x0 = (f32x4){bflo(w[0]), bfhi(w[0]), bflo(w[1]), bfhi(w[1])}; x1 = (f32x4){bflo(w[2]), bfhi(w[2]), bflo(w[3]), bfhi(w[3])}; }
;                     else { x0 = *(const f32x4*)((const float*)Xin + ro + bj * HALF); x1 = *(const f32x4*)((const float*)Xin + ro + bj * HALF + 4); }
;                     x0 += acc[ai][bj][m][0] * sc[bj][0]; x1 += acc[ai][bj][m][1] * sc[bj][1];
;                     if constexpr (OB) { u32x4 o; o[0] = pack2(x0[0], x0[1]); o[1] = pack2(x0[2], x0[3]); o[2] = pack2(x1[0], x1[1]); o[3] = pack2(x1[2], x1[3]);
;                         *(u32x4*)((bf16_t*)Xout + ro + bj * HALF) = o; }
;                     else { *(f32x4*)((float*)Xout + ro + bj * HALF) = x0; *(f32x4*)((float*)Xout + ro + bj * HALF + 4) = x1; } } }
; template <class Map, class Epi>
; DI void gemm_phase(LAS unsigned char* lds, const Map& MP, const Epi& E, const int nM, const int nN, const int K, const int lda, const int ldb) {
;     ...
;             PG8_WAIT_V(6); PG8_BAR; PG8_MMA(1, 1, At, B1); PG8_BAR;
;             PG8_LDB(B0, 1, 0); PG8_SCHED; PG8_LDA(At, 1, 0); PG8_STAGE(PG8_SA(0, 1), a2 + hstepA, voffA);
;             PG8_WAIT_L(8); PG8_BAR; PG8_WAIT_L(0); PG8_MMA(0, 0, At, B0); PG8_BAR; PG8_SCHED;
;             PG8_LDB(B1, 1, 1); PG8_STAGE(PG8_SB(1, 0), b3, voffB);
;             PG8_BAR; PG8_WAIT_L(0); PG8_MMA(0, 1, At, B1); PG8_BAR;
;             PG8_LDA(At, 1, 1); PG8_STAGE(PG8_SA(1, 0), a3, voffA);
;             PG8_BAR; PG8_WAIT_L(0); PG8_MMA(1, 0, At, B0); PG8_BAR; PG8_SCHED;
;             PG8_STAGE(PG8_SB(1, 1), b3 + hstepB, voffB);
;             PG8_WAIT_V(6); PG8_BAR; PG8_MMA(1, 1, At, B1); PG8_BAR;
	s_waitcnt lgkmcnt(7)
	v_mfma_f32_16x16x32_bf16 v[60:63], v[152:155], v[168:171], v[60:63]
	v_mfma_f32_16x16x32_bf16 v[56:59], v[160:163], v[168:171], v[56:59]
	s_waitcnt lgkmcnt(5)
	v_mfma_f32_16x16x32_bf16 v[44:47], v[152:155], v[176:179], v[44:47]
	v_mfma_f32_16x16x32_bf16 v[40:43], v[160:163], v[176:179], v[40:43]
	s_waitcnt lgkmcnt(3)
	v_mfma_f32_16x16x32_bf16 v[28:31], v[152:155], v[184:187], v[28:31]
	v_mfma_f32_16x16x32_bf16 v[24:27], v[160:163], v[184:187], v[24:27]
	s_waitcnt lgkmcnt(1)
	v_mfma_f32_16x16x32_bf16 v[12:15], v[152:155], v[192:195], v[12:15]
	v_mfma_f32_16x16x32_bf16 v[8:11], v[160:163], v[192:195], v[8:11]
	v_mfma_f32_16x16x32_bf16 v[60:63], v[156:159], v[172:175], v[60:63]
	s_add_u32 s8, s12, 0x160080
	s_addc_u32 s9, s13, 0
	v_mfma_f32_16x16x32_bf16 v[56:59], v[164:167], v[172:175], v[56:59]
	s_add_i32 s12, s14, s22
	v_mfma_f32_16x16x32_bf16 v[44:47], v[156:159], v[180:183], v[44:47]
	v_mfma_f32_16x16x32_bf16 v[40:43], v[164:167], v[180:183], v[40:43]
	v_mfma_f32_16x16x32_bf16 v[28:31], v[156:159], v[188:191], v[28:31]
	v_mfma_f32_16x16x32_bf16 v[24:27], v[164:167], v[188:191], v[24:27]
	s_waitcnt lgkmcnt(0)
	v_mfma_f32_16x16x32_bf16 v[12:15], v[156:159], v[198:201], v[12:15]
	v_mfma_f32_16x16x32_bf16 v[8:11], v[164:167], v[198:201], v[8:11]
	s_barrier
	s_setprio 0
	s_mov_b32 m0, s12
	s_nop 0
	global_load_lds_dwordx4 v132, s[8:9]
	s_add_i32 m0, s12, 0x2000
	s_nop 0
	global_load_lds_dwordx4 v128, s[8:9]
	s_waitcnt vmcnt(6)
	s_setprio 1
	s_barrier
	v_mfma_f32_16x16x32_bf16 v[52:55], v[202:205], v[168:171], v[52:55]
	v_mfma_f32_16x16x32_bf16 v[48:51], v[210:213], v[168:171], v[48:51]
	ds_read_b128 v[152:155], v149
	v_mfma_f32_16x16x32_bf16 v[36:39], v[202:205], v[176:179], v[36:39]
	v_mfma_f32_16x16x32_bf16 v[32:35], v[210:213], v[176:179], v[32:35]
	ds_read_b128 v[156:159], v149 offset:1024
	v_mfma_f32_16x16x32_bf16 v[20:23], v[202:205], v[184:187], v[20:23]
	v_mfma_f32_16x16x32_bf16 v[16:19], v[210:213], v[184:187], v[16:19]
	ds_read_b128 v[160:163], v149 offset:2048
	v_mfma_f32_16x16x32_bf16 v[4:7], v[202:205], v[192:195], v[4:7]
	v_mfma_f32_16x16x32_bf16 v[0:3], v[210:213], v[192:195], v[0:3]
	ds_read_b128 v[164:167], v149 offset:3072
	v_mfma_f32_16x16x32_bf16 v[52:55], v[206:209], v[172:175], v[52:55]
	s_add_i32 s3, s3, 2
	v_mfma_f32_16x16x32_bf16 v[48:51], v[214:217], v[172:175], v[48:51]
	s_add_u32 s39, s39, 0x100
	s_addc_u32 s44, s44, 0
	v_mfma_f32_16x16x32_bf16 v[36:39], v[206:209], v[180:183], v[36:39]
	s_cmpk_gt_u32 s3, 0x55
	v_mfma_f32_16x16x32_bf16 v[32:35], v[214:217], v[180:183], v[32:35]
	s_mov_b64 s[8:9], s[10:11]
	v_mfma_f32_16x16x32_bf16 v[20:23], v[206:209], v[188:191], v[20:23]
	v_mfma_f32_16x16x32_bf16 v[16:19], v[214:217], v[188:191], v[16:19]
	v_mfma_f32_16x16x32_bf16 v[4:7], v[206:209], v[198:201], v[4:7]
	v_mfma_f32_16x16x32_bf16 v[0:3], v[214:217], v[198:201], v[0:3]
	s_barrier
	s_setprio 0
	s_cbranch_scc0 .LBB1_2078
	s_waitcnt lgkmcnt(0)
	v_mov_b32_e32 v152, v147
	v_mov_b32_e32 v144, v146
	s_lshl_b32 s2, s2, 8
	s_add_i32 s2, s2, s29
	s_lshl_b32 s3, s38, 8
	v_add_u32_e32 v152, s2, v152
	s_or_b32 s3, s3, s52
	v_ashrrev_i32_e32 v153, 31, v152
	v_lshl_add_u32 v144, v144, 3, s3
	v_lshlrev_b64 v[152:153], 12, v[152:153]
	v_ashrrev_i32_e32 v145, 31, v144
	v_lshl_add_u64 v[152:153], s[4:5], 0, v[152:153]
	v_lshl_add_u64 v[144:145], v[144:145], 1, v[152:153]
	global_load_dwordx4 v[160:163], v[144:145], off
	global_load_dwordx4 v[164:167], v[144:145], off offset:256
	s_mov_b64 s[98:99], 0x10000
	v_lshl_add_u64 v[154:155], v[144:145], 0, s[98:99]
	global_load_dwordx4 v[168:171], v[154:155], off
	global_load_dwordx4 v[172:175], v[154:155], off offset:256
	s_mov_b64 s[98:99], 0x20000
	v_lshl_add_u64 v[154:155], v[144:145], 0, s[98:99]
	global_load_dwordx4 v[176:179], v[154:155], off
	global_load_dwordx4 v[180:183], v[154:155], off offset:256
	s_mov_b64 s[98:99], 0x30000
	v_lshl_add_u64 v[154:155], v[144:145], 0, s[98:99]
	global_load_dwordx4 v[184:187], v[154:155], off
	global_load_dwordx4 v[188:191], v[154:155], off offset:256
	s_mov_b64 s[98:99], 0x80000
	v_lshl_add_u64 v[154:155], v[144:145], 0, s[98:99]
	global_load_dwordx4 v[192:195], v[154:155], off
	global_load_dwordx4 v[198:201], v[154:155], off offset:256
	s_mov_b64 s[98:99], 0x90000
	v_lshl_add_u64 v[154:155], v[144:145], 0, s[98:99]
	global_load_dwordx4 v[202:205], v[154:155], off
	global_load_dwordx4 v[206:209], v[154:155], off offset:256
	s_mov_b64 s[98:99], 0xa0000
	v_lshl_add_u64 v[154:155], v[144:145], 0, s[98:99]
	global_load_dwordx4 v[210:213], v[154:155], off
	global_load_dwordx4 v[214:217], v[154:155], off offset:256
	s_mov_b64 s[98:99], 0xb0000
	v_lshl_add_u64 v[154:155], v[144:145], 0, s[98:99]
	global_load_dwordx4 v[248:251], v[154:155], off
	global_load_dwordx4 v[252:255], v[154:155], off offset:256
	s_waitcnt vmcnt(15)
	s_nop 1
	v_mov_b32_e32 v152, v160
	v_mov_b32_e32 v153, v161
	v_mov_b32_e32 v154, v162
	v_mov_b32_e32 v155, v163
	s_mov_b64 s[2:3], 0x10000
	s_mov_b32 s38, s37
	s_mov_b64 s[10:11], s[6:7]
	s_mov_b64 s[8:9], s[42:43]
	s_waitcnt lgkmcnt(0)
	v_lshlrev_b32_e32 v156, 16, v152
	v_and_b32_e32 v157, 0xffff0000, v152
	v_lshlrev_b32_e32 v152, 16, v153
	v_and_b32_e32 v153, 0xffff0000, v153
	v_lshlrev_b32_e32 v158, 16, v154
	v_and_b32_e32 v159, 0xffff0000, v154
	v_lshlrev_b32_e32 v154, 16, v155
	v_and_b32_e32 v155, 0xffff0000, v155
	v_pk_add_f32 v[126:127], v[126:127], v[152:153]
	v_pk_add_f32 v[124:125], v[124:125], v[156:157]
	v_pk_add_f32 v[152:153], v[122:123], v[154:155]
	v_pk_add_f32 v[122:123], v[120:121], v[158:159]
	v_cvt_pk_bf16_f32 v120, v124, v125
	v_cvt_pk_bf16_f32 v121, v126, v127
	v_cvt_pk_bf16_f32 v122, v122, v123
	v_cvt_pk_bf16_f32 v123, v152, v153
	global_store_dwordx4 v[144:145], v[120:123], off
	s_waitcnt vmcnt(15)
; DI unsigned pack2(float a, float b) { f32x2 v = {a, b}; hwbf16x2 r = __builtin_convertvector(v, hwbf16x2); return __builtin_bit_cast(unsigned, r); }
; DI float bflo(unsigned w) { return __uint_as_float(w << 16); }
; DI float bfhi(unsigned w) { return __uint_as_float(w & 0xffff0000u); }
;     DI void operator()(const f32x4 (&acc)[2][2][4][2], const Unit& u, int wr, int wc, int fr, int fq) const {
;     ...
;             for (int m = 0; m < 4; ++m) { const size_t ro = (size_t)(row0 + ai * HALF + m * 16) * D + col0;
; #pragma unroll
;                 for (int bj = 0; bj < 2; ++bj) {
;                     f32x4 x0, x1;
;                     if constexpr (IB) { const u32x4 w = *(const u32x4*)((const bf16_t*)Xin + ro + bj * HALF);
;                         x0 = (f32x4){bflo(w[0]), bfhi(w[0]), bflo(w[1]), bfhi(w[1])}; x1 = (f32x4){bflo(w[2]), bfhi(w[2]), bflo(w[3]), bfhi(w[3])}; }
;                     else { x0 = *(const f32x4*)((const float*)Xin + ro + bj * HALF); x1 = *(const f32x4*)((const float*)Xin + ro + bj * HALF + 4); }
;                     x0 += acc[ai][bj][m][0] * sc[bj][0]; x1 += acc[ai][bj][m][1] * sc[bj][1];
;                     if constexpr (OB) { u32x4 o; o[0] = pack2(x0[0], x0[1]); o[1] = pack2(x0[2], x0[3]); o[2] = pack2(x1[0], x1[1]); o[3] = pack2(x1[2], x1[3]);
;                         *(u32x4*)((bf16_t*)Xout + ro + bj * HALF) = o; }
;                     else { *(f32x4*)((float*)Xout + ro + bj * HALF) = x0; *(f32x4*)((float*)Xout + ro + bj * HALF + 4) = x1; } } }
	s_nop 1
	v_mov_b32_e32 v120, v164
	v_mov_b32_e32 v121, v165
	v_mov_b32_e32 v122, v166
	v_mov_b32_e32 v123, v167
	s_waitcnt lgkmcnt(0)
	v_lshlrev_b32_e32 v124, 16, v120
	v_and_b32_e32 v125, 0xffff0000, v120
	v_lshlrev_b32_e32 v120, 16, v121
	v_and_b32_e32 v121, 0xffff0000, v121
	v_lshlrev_b32_e32 v126, 16, v122
	v_and_b32_e32 v127, 0xffff0000, v122
	v_lshlrev_b32_e32 v122, 16, v123
	v_and_b32_e32 v123, 0xffff0000, v123
	v_pk_add_f32 v[116:117], v[116:117], v[124:125]
	v_pk_add_f32 v[118:119], v[118:119], v[120:121]
	v_pk_add_f32 v[120:121], v[114:115], v[122:123]
	v_pk_add_f32 v[114:115], v[112:113], v[126:127]
	v_cvt_pk_bf16_f32 v112, v116, v117
	v_lshl_add_u64 v[116:117], v[144:145], 0, s[2:3]
	s_mov_b32 s2, 0x10000
	v_cvt_pk_bf16_f32 v113, v118, v119
	v_add_co_u32_e32 v118, vcc, s2, v144
	v_cvt_pk_bf16_f32 v114, v114, v115
	v_cvt_pk_bf16_f32 v115, v120, v121
	v_addc_co_u32_e32 v119, vcc, 0, v145, vcc
	global_store_dwordx4 v[144:145], v[112:115], off offset:256
	s_waitcnt vmcnt(15)
	s_nop 1
	v_mov_b32_e32 v112, v168
	v_mov_b32_e32 v113, v169
	v_mov_b32_e32 v114, v170
	v_mov_b32_e32 v115, v171
	s_mov_b64 s[2:3], 0x20000
	s_waitcnt lgkmcnt(0)
	v_lshlrev_b32_e32 v120, 16, v112
	v_and_b32_e32 v121, 0xffff0000, v112
	v_lshlrev_b32_e32 v112, 16, v113
	v_and_b32_e32 v113, 0xffff0000, v113
	v_lshlrev_b32_e32 v122, 16, v114
	v_and_b32_e32 v123, 0xffff0000, v114
	v_lshlrev_b32_e32 v114, 16, v115
	v_and_b32_e32 v115, 0xffff0000, v115
	v_pk_add_f32 v[110:111], v[110:111], v[112:113]
	v_pk_add_f32 v[108:109], v[108:109], v[120:121]
	v_pk_add_f32 v[112:113], v[106:107], v[114:115]
	v_pk_add_f32 v[106:107], v[104:105], v[122:123]
	v_cvt_pk_bf16_f32 v104, v108, v109
	v_cvt_pk_bf16_f32 v105, v110, v111
	v_cvt_pk_bf16_f32 v106, v106, v107
	v_cvt_pk_bf16_f32 v107, v112, v113
	global_store_dwordx4 v[118:119], v[104:107], off
	s_waitcnt vmcnt(15)
	s_nop 1
	v_mov_b32_e32 v104, v172
	v_mov_b32_e32 v105, v173
	v_mov_b32_e32 v106, v174
	v_mov_b32_e32 v107, v175
	s_waitcnt lgkmcnt(0)
	v_lshlrev_b32_e32 v108, 16, v104
	v_and_b32_e32 v109, 0xffff0000, v104
	v_lshlrev_b32_e32 v104, 16, v105
	v_and_b32_e32 v105, 0xffff0000, v105
	v_lshlrev_b32_e32 v110, 16, v106
	v_and_b32_e32 v111, 0xffff0000, v106
	v_lshlrev_b32_e32 v106, 16, v107
	v_and_b32_e32 v107, 0xffff0000, v107
	v_pk_add_f32 v[100:101], v[100:101], v[108:109]
	v_pk_add_f32 v[102:103], v[102:103], v[104:105]
	v_pk_add_f32 v[104:105], v[98:99], v[106:107]
	v_pk_add_f32 v[98:99], v[96:97], v[110:111]
	v_cvt_pk_bf16_f32 v96, v100, v101
	v_lshl_add_u64 v[100:101], v[144:145], 0, s[2:3]
	s_mov_b32 s2, 0x20000
	v_cvt_pk_bf16_f32 v97, v102, v103
	v_add_co_u32_e32 v102, vcc, s2, v144
	v_cvt_pk_bf16_f32 v98, v98, v99
	v_cvt_pk_bf16_f32 v99, v104, v105
	v_addc_co_u32_e32 v103, vcc, 0, v145, vcc
	global_store_dwordx4 v[116:117], v[96:99], off offset:256
	s_waitcnt vmcnt(15)
	s_nop 1
	v_mov_b32_e32 v96, v176
	v_mov_b32_e32 v97, v177
	v_mov_b32_e32 v98, v178
	v_mov_b32_e32 v99, v179
	s_mov_b64 s[2:3], 0x30000
	s_waitcnt lgkmcnt(0)
	v_lshlrev_b32_e32 v104, 16, v96
	v_and_b32_e32 v105, 0xffff0000, v96
	v_lshlrev_b32_e32 v96, 16, v97
	v_and_b32_e32 v97, 0xffff0000, v97
	v_lshlrev_b32_e32 v106, 16, v98
	v_and_b32_e32 v107, 0xffff0000, v98
	v_lshlrev_b32_e32 v98, 16, v99
	v_and_b32_e32 v99, 0xffff0000, v99
	v_pk_add_f32 v[94:95], v[94:95], v[96:97]
	v_pk_add_f32 v[92:93], v[92:93], v[104:105]
	v_pk_add_f32 v[96:97], v[90:91], v[98:99]
	v_pk_add_f32 v[90:91], v[88:89], v[106:107]
	v_cvt_pk_bf16_f32 v88, v92, v93
	v_cvt_pk_bf16_f32 v89, v94, v95
	v_cvt_pk_bf16_f32 v90, v90, v91
	v_cvt_pk_bf16_f32 v91, v96, v97
	global_store_dwordx4 v[102:103], v[88:91], off
	s_waitcnt vmcnt(15)
	s_nop 1
	v_mov_b32_e32 v88, v180
	v_mov_b32_e32 v89, v181
	v_mov_b32_e32 v90, v182
	v_mov_b32_e32 v91, v183
	s_waitcnt lgkmcnt(0)
	v_lshlrev_b32_e32 v92, 16, v88
	v_and_b32_e32 v93, 0xffff0000, v88
	v_lshlrev_b32_e32 v88, 16, v89
	v_and_b32_e32 v89, 0xffff0000, v89
	v_lshlrev_b32_e32 v94, 16, v90
	v_and_b32_e32 v95, 0xffff0000, v90
	v_lshlrev_b32_e32 v90, 16, v91
	v_and_b32_e32 v91, 0xffff0000, v91
	v_pk_add_f32 v[86:87], v[86:87], v[88:89]
	v_pk_add_f32 v[84:85], v[84:85], v[92:93]
	v_pk_add_f32 v[88:89], v[82:83], v[90:91]
	v_pk_add_f32 v[82:83], v[80:81], v[94:95]
	v_cvt_pk_bf16_f32 v80, v84, v85
	v_cvt_pk_bf16_f32 v81, v86, v87
	v_cvt_pk_bf16_f32 v82, v82, v83
	v_cvt_pk_bf16_f32 v83, v88, v89
	global_store_dwordx4 v[100:101], v[80:83], off offset:256
	s_nop 1
	v_lshl_add_u64 v[80:81], v[144:145], 0, s[2:3]
	s_mov_b32 s2, 0x30000
	v_add_co_u32_e32 v86, vcc, s2, v144
	s_mov_b64 s[2:3], 0x80000
	s_nop 0
	v_addc_co_u32_e32 v87, vcc, 0, v145, vcc
	s_waitcnt vmcnt(15)
	s_nop 1
	v_mov_b32_e32 v82, v184
	v_mov_b32_e32 v83, v185
	v_mov_b32_e32 v84, v186
	v_mov_b32_e32 v85, v187
	s_waitcnt lgkmcnt(0)
	v_lshlrev_b32_e32 v88, 16, v82
	v_and_b32_e32 v89, 0xffff0000, v82
	v_lshlrev_b32_e32 v82, 16, v83
	v_and_b32_e32 v83, 0xffff0000, v83
	v_lshlrev_b32_e32 v90, 16, v84
	v_and_b32_e32 v91, 0xffff0000, v84
	v_lshlrev_b32_e32 v84, 16, v85
	v_and_b32_e32 v85, 0xffff0000, v85
	v_pk_add_f32 v[78:79], v[78:79], v[82:83]
	v_pk_add_f32 v[76:77], v[76:77], v[88:89]
	v_pk_add_f32 v[82:83], v[74:75], v[84:85]
	v_pk_add_f32 v[74:75], v[72:73], v[90:91]
	v_cvt_pk_bf16_f32 v72, v76, v77
	v_cvt_pk_bf16_f32 v73, v78, v79
	v_cvt_pk_bf16_f32 v74, v74, v75
	v_cvt_pk_bf16_f32 v75, v82, v83
	global_store_dwordx4 v[86:87], v[72:75], off
	s_waitcnt vmcnt(15)
	s_nop 1
	v_mov_b32_e32 v72, v188
	v_mov_b32_e32 v73, v189
	v_mov_b32_e32 v74, v190
	v_mov_b32_e32 v75, v191
	s_waitcnt lgkmcnt(0)
; DI unsigned pack2(float a, float b) { f32x2 v = {a, b}; hwbf16x2 r = __builtin_convertvector(v, hwbf16x2); return __builtin_bit_cast(unsigned, r); }
; DI float bflo(unsigned w) { return __uint_as_float(w << 16); }
; DI float bfhi(unsigned w) { return __uint_as_float(w & 0xffff0000u); }
;     DI void operator()(const f32x4 (&acc)[2][2][4][2], const Unit& u, int wr, int wc, int fr, int fq) const {
;     ...
;             for (int m = 0; m < 4; ++m) { const size_t ro = (size_t)(row0 + ai * HALF + m * 16) * D + col0;
; #pragma unroll
;                 for (int bj = 0; bj < 2; ++bj) {
;                     f32x4 x0, x1;
;                     if constexpr (IB) { const u32x4 w = *(const u32x4*)((const bf16_t*)Xin + ro + bj * HALF);
;                         x0 = (f32x4){bflo(w[0]), bfhi(w[0]), bflo(w[1]), bfhi(w[1])}; x1 = (f32x4){bflo(w[2]), bfhi(w[2]), bflo(w[3]), bfhi(w[3])}; }
;                     else { x0 = *(const f32x4*)((const float*)Xin + ro + bj * HALF); x1 = *(const f32x4*)((const float*)Xin + ro + bj * HALF + 4); }
;                     x0 += acc[ai][bj][m][0] * sc[bj][0]; x1 += acc[ai][bj][m][1] * sc[bj][1];
;                     if constexpr (OB) { u32x4 o; o[0] = pack2(x0[0], x0[1]); o[1] = pack2(x0[2], x0[3]); o[2] = pack2(x1[0], x1[1]); o[3] = pack2(x1[2], x1[3]);
;                         *(u32x4*)((bf16_t*)Xout + ro + bj * HALF) = o; }
;                     else { *(f32x4*)((float*)Xout + ro + bj * HALF) = x0; *(f32x4*)((float*)Xout + ro + bj * HALF + 4) = x1; } } }
	v_lshlrev_b32_e32 v76, 16, v72
	v_and_b32_e32 v77, 0xffff0000, v72
	v_lshlrev_b32_e32 v72, 16, v73
	v_and_b32_e32 v73, 0xffff0000, v73
	v_lshlrev_b32_e32 v78, 16, v74
	v_and_b32_e32 v79, 0xffff0000, v74
	v_lshlrev_b32_e32 v74, 16, v75
	v_and_b32_e32 v75, 0xffff0000, v75
	v_pk_add_f32 v[70:71], v[70:71], v[72:73]
	v_pk_add_f32 v[68:69], v[68:69], v[76:77]
	v_pk_add_f32 v[72:73], v[66:67], v[74:75]
	v_pk_add_f32 v[66:67], v[64:65], v[78:79]
	v_cvt_pk_bf16_f32 v64, v68, v69
	v_cvt_pk_bf16_f32 v65, v70, v71
	v_cvt_pk_bf16_f32 v66, v66, v67
	v_cvt_pk_bf16_f32 v67, v72, v73
	global_store_dwordx4 v[80:81], v[64:67], off offset:256
	s_nop 1
	v_lshl_add_u64 v[64:65], v[144:145], 0, s[2:3]
	s_mov_b32 s2, 0x80000
	v_add_co_u32_e32 v70, vcc, s2, v144
	s_mov_b64 s[2:3], 0x90000
	s_nop 0
	v_addc_co_u32_e32 v71, vcc, 0, v145, vcc
	s_waitcnt vmcnt(15)
	s_nop 1
	v_mov_b32_e32 v66, v192
	v_mov_b32_e32 v67, v193
	v_mov_b32_e32 v68, v194
	v_mov_b32_e32 v69, v195
	s_waitcnt lgkmcnt(0)
	v_lshlrev_b32_e32 v72, 16, v66
	v_and_b32_e32 v73, 0xffff0000, v66
	v_lshlrev_b32_e32 v66, 16, v67
	v_and_b32_e32 v67, 0xffff0000, v67
	v_lshlrev_b32_e32 v74, 16, v68
	v_and_b32_e32 v75, 0xffff0000, v68
	v_lshlrev_b32_e32 v68, 16, v69
	v_and_b32_e32 v69, 0xffff0000, v69
	v_pk_add_f32 v[62:63], v[62:63], v[66:67]
	v_pk_add_f32 v[60:61], v[60:61], v[72:73]
	v_pk_add_f32 v[66:67], v[58:59], v[68:69]
	v_pk_add_f32 v[58:59], v[56:57], v[74:75]
	v_cvt_pk_bf16_f32 v56, v60, v61
	v_cvt_pk_bf16_f32 v57, v62, v63
	v_cvt_pk_bf16_f32 v58, v58, v59
	v_cvt_pk_bf16_f32 v59, v66, v67
	global_store_dwordx4 v[70:71], v[56:59], off
	s_waitcnt vmcnt(15)
	s_nop 1
	v_mov_b32_e32 v56, v198
	v_mov_b32_e32 v57, v199
	v_mov_b32_e32 v58, v200
	v_mov_b32_e32 v59, v201
	s_waitcnt lgkmcnt(0)
	v_lshlrev_b32_e32 v60, 16, v56
	v_and_b32_e32 v61, 0xffff0000, v56
	v_lshlrev_b32_e32 v56, 16, v57
	v_and_b32_e32 v57, 0xffff0000, v57
	v_lshlrev_b32_e32 v62, 16, v58
	v_and_b32_e32 v63, 0xffff0000, v58
	v_lshlrev_b32_e32 v58, 16, v59
	v_and_b32_e32 v59, 0xffff0000, v59
	v_pk_add_f32 v[54:55], v[54:55], v[56:57]
	v_pk_add_f32 v[52:53], v[52:53], v[60:61]
	v_pk_add_f32 v[56:57], v[50:51], v[58:59]
	v_pk_add_f32 v[50:51], v[48:49], v[62:63]
	v_cvt_pk_bf16_f32 v48, v52, v53
	v_cvt_pk_bf16_f32 v49, v54, v55
	v_cvt_pk_bf16_f32 v50, v50, v51
	v_cvt_pk_bf16_f32 v51, v56, v57
	global_store_dwordx4 v[64:65], v[48:51], off offset:256
	s_nop 1
	v_lshl_add_u64 v[48:49], v[144:145], 0, s[2:3]
	s_mov_b32 s2, 0x90000
	v_add_co_u32_e32 v54, vcc, s2, v144
	s_mov_b64 s[2:3], 0xa0000
	s_nop 0
	v_addc_co_u32_e32 v55, vcc, 0, v145, vcc
	s_waitcnt vmcnt(15)
	s_nop 1
	v_mov_b32_e32 v50, v202
	v_mov_b32_e32 v51, v203
	v_mov_b32_e32 v52, v204
	v_mov_b32_e32 v53, v205
	s_waitcnt lgkmcnt(0)
	v_lshlrev_b32_e32 v56, 16, v50
	v_and_b32_e32 v57, 0xffff0000, v50
	v_lshlrev_b32_e32 v50, 16, v51
	v_and_b32_e32 v51, 0xffff0000, v51
	v_lshlrev_b32_e32 v58, 16, v52
	v_and_b32_e32 v59, 0xffff0000, v52
	v_lshlrev_b32_e32 v52, 16, v53
	v_and_b32_e32 v53, 0xffff0000, v53
	v_pk_add_f32 v[46:47], v[46:47], v[50:51]
	v_pk_add_f32 v[44:45], v[44:45], v[56:57]
	v_pk_add_f32 v[50:51], v[42:43], v[52:53]
	v_pk_add_f32 v[42:43], v[40:41], v[58:59]
	v_cvt_pk_bf16_f32 v40, v44, v45
	v_cvt_pk_bf16_f32 v41, v46, v47
	v_cvt_pk_bf16_f32 v42, v42, v43
	v_cvt_pk_bf16_f32 v43, v50, v51
	global_store_dwordx4 v[54:55], v[40:43], off
	s_waitcnt vmcnt(15)
	s_nop 1
	v_mov_b32_e32 v40, v206
	v_mov_b32_e32 v41, v207
	v_mov_b32_e32 v42, v208
	v_mov_b32_e32 v43, v209
	s_waitcnt lgkmcnt(0)
; DI unsigned pack2(float a, float b) { f32x2 v = {a, b}; hwbf16x2 r = __builtin_convertvector(v, hwbf16x2); return __builtin_bit_cast(unsigned, r); }
; DI float bflo(unsigned w) { return __uint_as_float(w << 16); }
; DI float bfhi(unsigned w) { return __uint_as_float(w & 0xffff0000u); }
;     DI const char* a(const Unit& u) const { return (const char*)(A + (size_t)u.pm * BM * lda); }
; #define PG8_BAR __builtin_amdgcn_s_barrier()
;     DI void operator()(const f32x4 (&acc)[2][2][4][2], const Unit& u, int wr, int wc, int fr, int fq) const {
;     ...
;             for (int m = 0; m < 4; ++m) { const size_t ro = (size_t)(row0 + ai * HALF + m * 16) * D + col0;
; #pragma unroll
;                 for (int bj = 0; bj < 2; ++bj) {
;                     f32x4 x0, x1;
;                     if constexpr (IB) { const u32x4 w = *(const u32x4*)((const bf16_t*)Xin + ro + bj * HALF);
;                         x0 = (f32x4){bflo(w[0]), bfhi(w[0]), bflo(w[1]), bfhi(w[1])}; x1 = (f32x4){bflo(w[2]), bfhi(w[2]), bflo(w[3]), bfhi(w[3])}; }
;                     else { x0 = *(const f32x4*)((const float*)Xin + ro + bj * HALF); x1 = *(const f32x4*)((const float*)Xin + ro + bj * HALF + 4); }
;                     x0 += acc[ai][bj][m][0] * sc[bj][0]; x1 += acc[ai][bj][m][1] * sc[bj][1];
;                     if constexpr (OB) { u32x4 o; o[0] = pack2(x0[0], x0[1]); o[1] = pack2(x0[2], x0[3]); o[2] = pack2(x1[0], x1[1]); o[3] = pack2(x1[2], x1[3]);
;                         *(u32x4*)((bf16_t*)Xout + ro + bj * HALF) = o; }
;                     else { *(f32x4*)((float*)Xout + ro + bj * HALF) = x0; *(f32x4*)((float*)Xout + ro + bj * HALF + 4) = x1; } } }
; template <class Map, class Epi>
; DI void gemm_phase(LAS unsigned char* lds, const Map& MP, const Epi& E, const int nM, const int nN, const int K, const int lda, const int ldb) {
;     ...
;         { int frr = fr, fqq = fq; asm volatile("" : "+v"(frr), "+v"(fqq)); E(acc, cur, wr, wc, frr, fqq); }
;         if (!has_next) break;
; #pragma unroll
;         for (int a = 0; a < 2; ++a)
; #pragma unroll
;             for (int b = 0; b < 2; ++b)
; #pragma unroll
;                 for (int m = 0; m < 4; ++m)
; #pragma unroll
;                     for (int n = 0; n < 2; ++n) acc[a][b][m][n] = (f32x4){0.f, 0.f, 0.f, 0.f};
;         cur = nxt; cA = nA; cB = nB; ++ui;
;     }
;     PG8_WAIT_V(0);
;     if (wr == 0) PG8_BAR;
;     PG8_BAR;
	v_lshlrev_b32_e32 v44, 16, v40
	v_and_b32_e32 v45, 0xffff0000, v40
	v_lshlrev_b32_e32 v40, 16, v41
	v_and_b32_e32 v41, 0xffff0000, v41
	v_lshlrev_b32_e32 v46, 16, v42
	v_and_b32_e32 v47, 0xffff0000, v42
	v_lshlrev_b32_e32 v42, 16, v43
	v_and_b32_e32 v43, 0xffff0000, v43
	v_pk_add_f32 v[38:39], v[38:39], v[40:41]
	v_pk_add_f32 v[36:37], v[36:37], v[44:45]
	v_pk_add_f32 v[40:41], v[34:35], v[42:43]
	v_pk_add_f32 v[34:35], v[32:33], v[46:47]
	v_cvt_pk_bf16_f32 v32, v36, v37
	v_cvt_pk_bf16_f32 v33, v38, v39
	v_cvt_pk_bf16_f32 v34, v34, v35
	v_cvt_pk_bf16_f32 v35, v40, v41
	global_store_dwordx4 v[48:49], v[32:35], off offset:256
	s_nop 1
	v_lshl_add_u64 v[32:33], v[144:145], 0, s[2:3]
	s_mov_b32 s2, 0xa0000
	v_add_co_u32_e32 v38, vcc, s2, v144
	s_mov_b64 s[2:3], 0xb0000
	s_nop 0
	v_addc_co_u32_e32 v39, vcc, 0, v145, vcc
	s_waitcnt vmcnt(15)
	s_nop 1
	v_mov_b32_e32 v34, v210
	v_mov_b32_e32 v35, v211
	v_mov_b32_e32 v36, v212
	v_mov_b32_e32 v37, v213
	s_waitcnt lgkmcnt(0)
	v_lshlrev_b32_e32 v40, 16, v34
	v_and_b32_e32 v41, 0xffff0000, v34
	v_lshlrev_b32_e32 v34, 16, v35
	v_and_b32_e32 v35, 0xffff0000, v35
	v_lshlrev_b32_e32 v42, 16, v36
	v_and_b32_e32 v43, 0xffff0000, v36
	v_lshlrev_b32_e32 v36, 16, v37
	v_and_b32_e32 v37, 0xffff0000, v37
	v_pk_add_f32 v[30:31], v[30:31], v[34:35]
	v_pk_add_f32 v[28:29], v[28:29], v[40:41]
	v_pk_add_f32 v[34:35], v[26:27], v[36:37]
	v_pk_add_f32 v[26:27], v[24:25], v[42:43]
	v_cvt_pk_bf16_f32 v24, v28, v29
	v_cvt_pk_bf16_f32 v25, v30, v31
	v_cvt_pk_bf16_f32 v26, v26, v27
	v_cvt_pk_bf16_f32 v27, v34, v35
	global_store_dwordx4 v[38:39], v[24:27], off
	s_waitcnt vmcnt(15)
	s_nop 1
	v_mov_b32_e32 v24, v214
	v_mov_b32_e32 v25, v215
	v_mov_b32_e32 v26, v216
	v_mov_b32_e32 v27, v217
	s_waitcnt lgkmcnt(0)
	v_lshlrev_b32_e32 v28, 16, v24
	v_and_b32_e32 v29, 0xffff0000, v24
	v_lshlrev_b32_e32 v24, 16, v25
	v_and_b32_e32 v25, 0xffff0000, v25
	v_lshlrev_b32_e32 v30, 16, v26
	v_and_b32_e32 v31, 0xffff0000, v26
	v_lshlrev_b32_e32 v26, 16, v27
	v_and_b32_e32 v27, 0xffff0000, v27
	v_pk_add_f32 v[22:23], v[22:23], v[24:25]
	v_pk_add_f32 v[20:21], v[20:21], v[28:29]
	v_pk_add_f32 v[24:25], v[18:19], v[26:27]
	v_pk_add_f32 v[18:19], v[16:17], v[30:31]
	v_cvt_pk_bf16_f32 v16, v20, v21
	v_cvt_pk_bf16_f32 v17, v22, v23
	v_cvt_pk_bf16_f32 v18, v18, v19
	v_cvt_pk_bf16_f32 v19, v24, v25
	global_store_dwordx4 v[32:33], v[16:19], off offset:256
	s_nop 1
	v_lshl_add_u64 v[16:17], v[144:145], 0, s[2:3]
	s_mov_b32 s2, 0xb0000
	v_add_co_u32_e32 v22, vcc, s2, v144
	s_mov_b32 s2, s53
	s_nop 0
	v_addc_co_u32_e32 v23, vcc, 0, v145, vcc
	s_waitcnt vmcnt(15)
	s_nop 1
	v_mov_b32_e32 v18, v248
	v_mov_b32_e32 v19, v249
	v_mov_b32_e32 v20, v250
	v_mov_b32_e32 v21, v251
	s_and_b64 vcc, exec, s[40:41]
	s_waitcnt lgkmcnt(0)
	v_lshlrev_b32_e32 v24, 16, v18
	v_and_b32_e32 v25, 0xffff0000, v18
	v_lshlrev_b32_e32 v18, 16, v19
	v_and_b32_e32 v19, 0xffff0000, v19
	v_lshlrev_b32_e32 v26, 16, v20
	v_and_b32_e32 v27, 0xffff0000, v20
	v_lshlrev_b32_e32 v20, 16, v21
	v_and_b32_e32 v21, 0xffff0000, v21
	v_pk_add_f32 v[14:15], v[14:15], v[18:19]
	v_pk_add_f32 v[12:13], v[12:13], v[24:25]
	v_pk_add_f32 v[18:19], v[10:11], v[20:21]
	v_pk_add_f32 v[10:11], v[8:9], v[26:27]
	v_cvt_pk_bf16_f32 v8, v12, v13
	v_cvt_pk_bf16_f32 v9, v14, v15
	v_cvt_pk_bf16_f32 v10, v10, v11
	v_cvt_pk_bf16_f32 v11, v18, v19
	global_store_dwordx4 v[22:23], v[8:11], off
	s_waitcnt vmcnt(15)
	s_nop 1
	v_mov_b32_e32 v8, v252
	v_mov_b32_e32 v9, v253
	v_mov_b32_e32 v10, v254
	v_mov_b32_e32 v11, v255
	s_waitcnt lgkmcnt(0)
	v_lshlrev_b32_e32 v12, 16, v8
	v_and_b32_e32 v13, 0xffff0000, v8
	v_lshlrev_b32_e32 v8, 16, v9
	v_and_b32_e32 v9, 0xffff0000, v9
	v_lshlrev_b32_e32 v14, 16, v10
	v_and_b32_e32 v15, 0xffff0000, v10
	v_lshlrev_b32_e32 v10, 16, v11
	v_and_b32_e32 v11, 0xffff0000, v11
	v_pk_add_f32 v[6:7], v[6:7], v[8:9]
	v_pk_add_f32 v[4:5], v[4:5], v[12:13]
	v_pk_add_f32 v[8:9], v[2:3], v[10:11]
	v_pk_add_f32 v[2:3], v[0:1], v[14:15]
	v_cvt_pk_bf16_f32 v0, v4, v5
	v_cvt_pk_bf16_f32 v1, v6, v7
	v_cvt_pk_bf16_f32 v2, v2, v3
	v_cvt_pk_bf16_f32 v3, v8, v9
	global_store_dwordx4 v[16:17], v[0:3], off offset:256
	s_cbranch_vccz .LBB1_2071
	s_waitcnt vmcnt(0)
	s_cmpk_gt_u32 s17, 0xff
	s_cbranch_scc1 .LBB1_2082
	s_barrier

; #define PG8_STAGE(bufoff, gbase, voff) do { _Pragma("unroll") for (int _i = 0; _i < 2; ++_i) \
;         __builtin_amdgcn_global_load_lds((const unsigned*)((const char*)(gbase) + (voff)[_i]), (LAS unsigned*)(lds + (bufoff) + ldsw + _i * 8192), 16, 0, 0); } while (0)
; #define PG8_LDA(dst, b, h) do { _Pragma("unroll") for (int m = 0; m < 4; ++m) _Pragma("unroll") for (int k = 0; k < 2; ++k) dst[m][k] = *(const LAS bf16x8*)(lds + PG8_SA(b, h) + aoff + m * 2048 + k * 1024); } while (0)
; #define PG8_LDB(dst, b, h) do { _Pragma("unroll") for (int n = 0; n < 2; ++n) _Pragma("unroll") for (int k = 0; k < 2; ++k) dst[n][k] = *(const LAS bf16x8*)(lds + PG8_SB(b, h) + boff + n * 2048 + k * 1024); } while (0)
; #define PG8_MMA(ai, bj, At, Bt) do { __builtin_amdgcn_s_setprio(1); _Pragma("unroll") for (int m = 0; m < 4; ++m) _Pragma("unroll") for (int n = 0; n < 2; ++n) _Pragma("unroll") for (int k = 0; k < 2; ++k) \
;         acc[ai][bj][m][n] = __builtin_amdgcn_mfma_f32_16x16x32_bf16(Bt[n][k], At[m][k], acc[ai][bj][m][n], 0, 0, 0); __builtin_amdgcn_s_setprio(0); } while (0)
; #define PG8_WAIT_V(n) asm volatile("s_waitcnt vmcnt(" #n ")" ::: "memory")
; #define PG8_WAIT_L(n) asm volatile("s_waitcnt lgkmcnt(" #n ")" ::: "memory")
; #define PG8_BAR __builtin_amdgcn_s_barrier()
; template <class Map, class Epi>
; DI void gemm_phase(LAS unsigned char* lds, const Map& MP, const Epi& E, const int nM, const int nN, const int K, const int lda, const int ldb) {
;     ...
;             const char* a1 = cA + (size_t)(t + 1) * kstep;
;             const char* a2 = last ? nA : cA + (size_t)(t + 2) * kstep; const char* b2 = last ? nB : cB + (size_t)(t + 2) * kstep;
;             const char* a3 = a2 + kstep; const char* b3 = b2 + kstep;
;             PG8_LDB(B0, 0, 0); PG8_SCHED; PG8_LDA(At, 0, 0); PG8_STAGE(PG8_SA(1, 1), a1 + hstepA, voffA);
;             PG8_WAIT_L(8); PG8_BAR; PG8_WAIT_L(0); PG8_MMA(0, 0, At, B0); PG8_BAR; PG8_SCHED;
;             PG8_LDB(B1, 0, 1); PG8_STAGE(PG8_SB(0, 0), b2, voffB);
;             PG8_BAR; PG8_WAIT_L(0); PG8_MMA(0, 1, At, B1); PG8_BAR;
;             PG8_LDA(At, 0, 1); PG8_STAGE(PG8_SA(0, 0), a2, voffA);
;             PG8_BAR; PG8_WAIT_L(0); PG8_MMA(1, 0, At, B0); PG8_BAR; PG8_SCHED;
;             PG8_STAGE(PG8_SB(0, 1), b2 + hstepB, voffB);
;             PG8_WAIT_V(6); PG8_BAR; PG8_MMA(1, 1, At, B1); PG8_BAR;
.LBB1_2339:
	s_add_u32 s12, s10, 0xfff80080
	s_addc_u32 s13, s11, -1
	s_cmp_eq_u32 s3, 4
	s_cselect_b32 s15, s38, s13
	s_cselect_b32 s14, s39, s12
	s_cselect_b32 s13, s48, s56
	s_cselect_b32 s12, s49, s53
	s_add_i32 m0, s9, 0xc000
	ds_read_b128 v[168:171], v166
	global_load_lds_dwordx4 v154, s[10:11]
	ds_read_b128 v[172:175], v166 offset:1024
	ds_read_b128 v[176:179], v166 offset:2048
	ds_read_b128 v[180:183], v166 offset:3072
	ds_read_b128 v[184:187], v166 offset:4096
	ds_read_b128 v[188:191], v166 offset:5120
	ds_read_b128 v[192:195], v166 offset:6144
	ds_read_b128 v[198:201], v166 offset:7168
	s_add_i32 m0, s9, 0xe000
	s_nop 0
	global_load_lds_dwordx4 v152, s[10:11]
	s_waitcnt lgkmcnt(8)
	s_setprio 1
	s_barrier
	s_waitcnt lgkmcnt(7)
	v_mfma_f32_16x16x32_bf16 v[140:143], v[40:43], v[168:171], v[140:143]
	v_mfma_f32_16x16x32_bf16 v[136:139], v[56:59], v[168:171], v[136:139]
	s_waitcnt lgkmcnt(5)
	v_mfma_f32_16x16x32_bf16 v[124:127], v[40:43], v[176:179], v[124:127]
	v_mfma_f32_16x16x32_bf16 v[120:123], v[56:59], v[176:179], v[120:123]
	s_waitcnt lgkmcnt(3)
	v_mfma_f32_16x16x32_bf16 v[108:111], v[40:43], v[184:187], v[108:111]
	v_mfma_f32_16x16x32_bf16 v[104:107], v[56:59], v[184:187], v[104:107]
	s_waitcnt lgkmcnt(1)
	v_mfma_f32_16x16x32_bf16 v[92:95], v[40:43], v[192:195], v[92:95]
	v_mfma_f32_16x16x32_bf16 v[88:91], v[56:59], v[192:195], v[88:91]
	v_mfma_f32_16x16x32_bf16 v[140:143], v[44:47], v[172:175], v[140:143]
	s_add_i32 s57, s35, s22
	v_mfma_f32_16x16x32_bf16 v[136:139], v[60:63], v[172:175], v[136:139]
	v_lshl_add_u64 v[160:161], s[12:13], 0, v[148:149]
	v_mfma_f32_16x16x32_bf16 v[124:127], v[44:47], v[180:183], v[124:127]
	v_lshl_add_u64 v[218:219], s[12:13], 0, v[144:145]
	v_mfma_f32_16x16x32_bf16 v[120:123], v[60:63], v[180:183], v[120:123]
	v_mfma_f32_16x16x32_bf16 v[108:111], v[44:47], v[188:191], v[108:111]
	v_mfma_f32_16x16x32_bf16 v[104:107], v[60:63], v[188:191], v[104:107]
	s_waitcnt lgkmcnt(0)
	v_mfma_f32_16x16x32_bf16 v[92:95], v[44:47], v[198:201], v[92:95]
	v_mfma_f32_16x16x32_bf16 v[88:91], v[60:63], v[198:201], v[88:91]
	s_barrier
	s_setprio 0
	s_mov_b32 m0, s57
	ds_read_b128 v[202:205], v167
	global_load_lds_dwordx4 v[160:161], off
	ds_read_b128 v[206:209], v167 offset:1024
	ds_read_b128 v[210:213], v167 offset:2048
	ds_read_b128 v[214:217], v167 offset:3072
	s_add_i32 m0, s57, 0x2000
	s_nop 0
	global_load_lds_dwordx4 v[218:219], off
	s_setprio 1
	s_barrier
	s_waitcnt lgkmcnt(3)
	v_mfma_f32_16x16x32_bf16 v[132:135], v[202:205], v[168:171], v[132:135]
	s_waitcnt lgkmcnt(1)
	v_mfma_f32_16x16x32_bf16 v[128:131], v[210:213], v[168:171], v[128:131]
	v_mfma_f32_16x16x32_bf16 v[116:119], v[202:205], v[176:179], v[116:119]
	v_mfma_f32_16x16x32_bf16 v[112:115], v[210:213], v[176:179], v[112:115]
	v_mfma_f32_16x16x32_bf16 v[100:103], v[202:205], v[184:187], v[100:103]
	v_mfma_f32_16x16x32_bf16 v[96:99], v[210:213], v[184:187], v[96:99]
	v_mfma_f32_16x16x32_bf16 v[84:87], v[202:205], v[192:195], v[84:87]
	v_mfma_f32_16x16x32_bf16 v[80:83], v[210:213], v[192:195], v[80:83]
	v_mfma_f32_16x16x32_bf16 v[132:135], v[206:209], v[172:175], v[132:135]
	v_lshl_add_u64 v[222:223], s[14:15], 0, v[146:147]
	s_mov_b32 m0, s9
	s_waitcnt lgkmcnt(0)
	v_mfma_f32_16x16x32_bf16 v[128:131], v[214:217], v[172:175], v[128:131]
	v_lshl_add_u64 v[220:221], s[14:15], 0, v[150:151]
	v_mfma_f32_16x16x32_bf16 v[116:119], v[206:209], v[180:183], v[116:119]
	v_mfma_f32_16x16x32_bf16 v[112:115], v[214:217], v[180:183], v[112:115]
	v_mfma_f32_16x16x32_bf16 v[100:103], v[206:209], v[188:191], v[100:103]
	v_mfma_f32_16x16x32_bf16 v[96:99], v[214:217], v[188:191], v[96:99]
	v_mfma_f32_16x16x32_bf16 v[84:87], v[206:209], v[198:201], v[84:87]
	v_mfma_f32_16x16x32_bf16 v[80:83], v[214:217], v[198:201], v[80:83]
	s_barrier
	s_setprio 0
	ds_read_b128 v[168:171], v166 offset:16384
	global_load_lds_dwordx4 v[220:221], off
	ds_read_b128 v[172:175], v166 offset:17408
	ds_read_b128 v[176:179], v166 offset:18432
	ds_read_b128 v[180:183], v166 offset:19456
	ds_read_b128 v[184:187], v166 offset:20480
	ds_read_b128 v[188:191], v166 offset:21504
	ds_read_b128 v[192:195], v166 offset:22528
	ds_read_b128 v[198:201], v166 offset:23552
	s_mov_b32 m0, s24
	s_nop 0
	global_load_lds_dwordx4 v[222:223], off
	s_waitcnt vmcnt(10)
	s_setprio 1
	s_barrier
	s_waitcnt lgkmcnt(7)
	v_mfma_f32_16x16x32_bf16 v[76:79], v[40:43], v[168:171], v[76:79]
	v_mfma_f32_16x16x32_bf16 v[72:75], v[56:59], v[168:171], v[72:75]
	s_waitcnt lgkmcnt(5)
	v_mfma_f32_16x16x32_bf16 v[52:55], v[40:43], v[176:179], v[52:55]
	v_mfma_f32_16x16x32_bf16 v[48:51], v[56:59], v[176:179], v[48:51]
	s_waitcnt lgkmcnt(3)
	v_mfma_f32_16x16x32_bf16 v[28:31], v[40:43], v[184:187], v[28:31]
	v_mfma_f32_16x16x32_bf16 v[24:27], v[56:59], v[184:187], v[24:27]
	s_waitcnt lgkmcnt(1)
	v_mfma_f32_16x16x32_bf16 v[12:15], v[40:43], v[192:195], v[12:15]
	v_mfma_f32_16x16x32_bf16 v[8:11], v[56:59], v[192:195], v[8:11]
	v_mfma_f32_16x16x32_bf16 v[76:79], v[44:47], v[172:175], v[76:79]
	s_add_u32 s58, s12, 0x20000
	s_addc_u32 s59, s13, 0
	v_mfma_f32_16x16x32_bf16 v[72:75], v[60:63], v[172:175], v[72:75]
	s_add_i32 s57, s36, s22
	v_mfma_f32_16x16x32_bf16 v[52:55], v[44:47], v[180:183], v[52:55]
	v_mfma_f32_16x16x32_bf16 v[48:51], v[60:63], v[180:183], v[48:51]
	v_mfma_f32_16x16x32_bf16 v[28:31], v[44:47], v[188:191], v[28:31]
	v_mfma_f32_16x16x32_bf16 v[24:27], v[60:63], v[188:191], v[24:27]
	s_waitcnt lgkmcnt(0)
	v_mfma_f32_16x16x32_bf16 v[12:15], v[44:47], v[198:201], v[12:15]
	v_mfma_f32_16x16x32_bf16 v[8:11], v[60:63], v[198:201], v[8:11]
	s_barrier
; #define PG8_STAGE(bufoff, gbase, voff) do { _Pragma("unroll") for (int _i = 0; _i < 2; ++_i) \
;         __builtin_amdgcn_global_load_lds((const unsigned*)((const char*)(gbase) + (voff)[_i]), (LAS unsigned*)(lds + (bufoff) + ldsw + _i * 8192), 16, 0, 0); } while (0)
; #define PG8_LDA(dst, b, h) do { _Pragma("unroll") for (int m = 0; m < 4; ++m) _Pragma("unroll") for (int k = 0; k < 2; ++k) dst[m][k] = *(const LAS bf16x8*)(lds + PG8_SA(b, h) + aoff + m * 2048 + k * 1024); } while (0)
; #define PG8_LDB(dst, b, h) do { _Pragma("unroll") for (int n = 0; n < 2; ++n) _Pragma("unroll") for (int k = 0; k < 2; ++k) dst[n][k] = *(const LAS bf16x8*)(lds + PG8_SB(b, h) + boff + n * 2048 + k * 1024); } while (0)
; #define PG8_MMA(ai, bj, At, Bt) do { __builtin_amdgcn_s_setprio(1); _Pragma("unroll") for (int m = 0; m < 4; ++m) _Pragma("unroll") for (int n = 0; n < 2; ++n) _Pragma("unroll") for (int k = 0; k < 2; ++k) \
;         acc[ai][bj][m][n] = __builtin_amdgcn_mfma_f32_16x16x32_bf16(Bt[n][k], At[m][k], acc[ai][bj][m][n], 0, 0, 0); __builtin_amdgcn_s_setprio(0); } while (0)
; #define PG8_WAIT_V(n) asm volatile("s_waitcnt vmcnt(" #n ")" ::: "memory")
; #define PG8_WAIT_L(n) asm volatile("s_waitcnt lgkmcnt(" #n ")" ::: "memory")
; #define PG8_BAR __builtin_amdgcn_s_barrier()
; #define PG8_SCHED __builtin_amdgcn_sched_barrier(0)
; template <class Map, class Epi>
; DI void gemm_phase(LAS unsigned char* lds, const Map& MP, const Epi& E, const int nM, const int nN, const int K, const int lda, const int ldb) {
;     ...
;             PG8_STAGE(PG8_SB(0, 1), b2 + hstepB, voffB);
;             PG8_WAIT_V(6); PG8_BAR; PG8_MMA(1, 1, At, B1); PG8_BAR;
;             PG8_LDB(B0, 1, 0); PG8_SCHED; PG8_LDA(At, 1, 0); PG8_STAGE(PG8_SA(0, 1), a2 + hstepA, voffA);
;             PG8_WAIT_L(8); PG8_BAR; PG8_WAIT_L(0); PG8_MMA(0, 0, At, B0); PG8_BAR; PG8_SCHED;
;             PG8_LDB(B1, 1, 1); PG8_STAGE(PG8_SB(1, 0), b3, voffB);
;             PG8_BAR; PG8_WAIT_L(0); PG8_MMA(0, 1, At, B1); PG8_BAR;
;             PG8_LDA(At, 1, 1); PG8_STAGE(PG8_SA(1, 0), a3, voffA);
;             PG8_BAR; PG8_WAIT_L(0); PG8_MMA(1, 0, At, B0); PG8_BAR; PG8_SCHED;
	s_setprio 0
	s_mov_b32 m0, s57
	s_nop 0
	global_load_lds_dwordx4 v148, s[58:59]
	s_add_i32 m0, s57, 0x2000
	s_nop 0
	global_load_lds_dwordx4 v144, s[58:59]
	s_waitcnt vmcnt(6)
	s_setprio 1
	s_barrier
	v_mfma_f32_16x16x32_bf16 v[36:39], v[202:205], v[176:179], v[36:39]
	v_mfma_f32_16x16x32_bf16 v[32:35], v[210:213], v[176:179], v[32:35]
	v_mfma_f32_16x16x32_bf16 v[20:23], v[202:205], v[184:187], v[20:23]
	v_mfma_f32_16x16x32_bf16 v[16:19], v[210:213], v[184:187], v[16:19]
	v_mfma_f32_16x16x32_bf16 v[4:7], v[202:205], v[192:195], v[4:7]
	v_mfma_f32_16x16x32_bf16 v[0:3], v[210:213], v[192:195], v[0:3]
	v_mfma_f32_16x16x32_bf16 v[40:43], v[202:205], v[168:171], v[68:71]
	s_add_i32 s57, 0, 0x18000
	v_add_u32_e32 v68, s57, v164
	ds_read_b128 v[56:59], v68
	ds_read_b128 v[60:63], v68 offset:1024
	v_mfma_f32_16x16x32_bf16 v[44:47], v[210:213], v[168:171], v[64:67]
	ds_read_b128 v[64:67], v68 offset:2048
	ds_read_b128 v[68:71], v68 offset:3072
	v_mfma_f32_16x16x32_bf16 v[36:39], v[206:209], v[180:183], v[36:39]
	s_add_u32 s14, s14, 0x80000
	s_addc_u32 s15, s15, 0
	v_mfma_f32_16x16x32_bf16 v[32:35], v[214:217], v[180:183], v[32:35]
	v_mfma_f32_16x16x32_bf16 v[20:23], v[206:209], v[188:191], v[20:23]
	v_mfma_f32_16x16x32_bf16 v[16:19], v[214:217], v[188:191], v[16:19]
	v_mfma_f32_16x16x32_bf16 v[4:7], v[206:209], v[198:201], v[4:7]
	v_mfma_f32_16x16x32_bf16 v[0:3], v[214:217], v[198:201], v[0:3]
	v_mfma_f32_16x16x32_bf16 v[40:43], v[206:209], v[172:175], v[40:43]
	v_mfma_f32_16x16x32_bf16 v[44:47], v[214:217], v[172:175], v[44:47]
	s_barrier
	s_setprio 0
	s_mov_b32 m0, s25
	ds_read_b128 v[168:171], v166 offset:32768
	global_load_lds_dwordx4 v150, s[14:15]
	ds_read_b128 v[172:175], v166 offset:33792
	ds_read_b128 v[176:179], v166 offset:34816
	ds_read_b128 v[180:183], v166 offset:35840
	ds_read_b128 v[184:187], v166 offset:36864
	ds_read_b128 v[188:191], v166 offset:37888
	ds_read_b128 v[192:195], v166 offset:38912
	ds_read_b128 v[198:201], v166 offset:39936
	s_mov_b32 m0, s26
	s_nop 0
	global_load_lds_dwordx4 v146, s[14:15]
	s_waitcnt lgkmcnt(8)
	s_setprio 1
	s_barrier
	s_waitcnt lgkmcnt(7)
	v_mfma_f32_16x16x32_bf16 v[140:143], v[56:59], v[168:171], v[140:143]
	v_mfma_f32_16x16x32_bf16 v[136:139], v[64:67], v[168:171], v[136:139]
	s_waitcnt lgkmcnt(5)
	v_mfma_f32_16x16x32_bf16 v[124:127], v[56:59], v[176:179], v[124:127]
	v_mfma_f32_16x16x32_bf16 v[120:123], v[64:67], v[176:179], v[120:123]
	s_waitcnt lgkmcnt(3)
	v_mfma_f32_16x16x32_bf16 v[108:111], v[56:59], v[184:187], v[108:111]
	v_mfma_f32_16x16x32_bf16 v[104:107], v[64:67], v[184:187], v[104:107]
	s_waitcnt lgkmcnt(1)
	v_mfma_f32_16x16x32_bf16 v[92:95], v[56:59], v[192:195], v[92:95]
	v_mfma_f32_16x16x32_bf16 v[88:91], v[64:67], v[192:195], v[88:91]
	v_mfma_f32_16x16x32_bf16 v[140:143], v[60:63], v[172:175], v[140:143]
	s_add_i32 s14, 0, 0x1c000
	v_mfma_f32_16x16x32_bf16 v[136:139], v[68:71], v[172:175], v[136:139]
	s_add_i32 s15, s57, s22
	v_mfma_f32_16x16x32_bf16 v[124:127], v[60:63], v[180:183], v[124:127]
	v_add_u32_e32 v196, s14, v164
	v_mfma_f32_16x16x32_bf16 v[120:123], v[68:71], v[180:183], v[120:123]
	v_lshl_add_u64 v[160:161], v[160:161], 0, s[46:47]
	v_mfma_f32_16x16x32_bf16 v[108:111], v[60:63], v[188:191], v[108:111]
	v_mfma_f32_16x16x32_bf16 v[104:107], v[68:71], v[188:191], v[104:107]
	s_waitcnt lgkmcnt(0)
	v_mfma_f32_16x16x32_bf16 v[92:95], v[60:63], v[198:201], v[92:95]
	v_mfma_f32_16x16x32_bf16 v[88:91], v[68:71], v[198:201], v[88:91]
	s_barrier
	s_setprio 0
	s_mov_b32 m0, s15
	ds_read_b128 v[202:205], v196
	global_load_lds_dwordx4 v[160:161], off
	ds_read_b128 v[206:209], v196 offset:1024
	ds_read_b128 v[210:213], v196 offset:2048
	ds_read_b128 v[214:217], v196 offset:3072
	v_lshl_add_u64 v[160:161], v[218:219], 0, s[46:47]
	s_add_i32 m0, s15, 0x2000
	s_nop 0
	global_load_lds_dwordx4 v[160:161], off
	s_setprio 1
	s_barrier
	s_waitcnt lgkmcnt(3)
	v_mfma_f32_16x16x32_bf16 v[132:135], v[202:205], v[168:171], v[132:135]
	s_waitcnt lgkmcnt(1)
	v_mfma_f32_16x16x32_bf16 v[128:131], v[210:213], v[168:171], v[128:131]
	v_mfma_f32_16x16x32_bf16 v[116:119], v[202:205], v[176:179], v[116:119]
	v_mfma_f32_16x16x32_bf16 v[112:115], v[210:213], v[176:179], v[112:115]
	v_mfma_f32_16x16x32_bf16 v[100:103], v[202:205], v[184:187], v[100:103]
	v_mfma_f32_16x16x32_bf16 v[96:99], v[210:213], v[184:187], v[96:99]
	v_mfma_f32_16x16x32_bf16 v[84:87], v[202:205], v[192:195], v[84:87]
	v_mfma_f32_16x16x32_bf16 v[80:83], v[210:213], v[192:195], v[80:83]
	v_mfma_f32_16x16x32_bf16 v[132:135], v[206:209], v[172:175], v[132:135]
	s_mov_b32 m0, s30
	s_waitcnt lgkmcnt(0)
	v_mfma_f32_16x16x32_bf16 v[128:131], v[214:217], v[172:175], v[128:131]
	v_lshl_add_u64 v[160:161], v[220:221], 0, s[46:47]
	v_mfma_f32_16x16x32_bf16 v[116:119], v[206:209], v[180:183], v[116:119]
	v_mfma_f32_16x16x32_bf16 v[112:115], v[214:217], v[180:183], v[112:115]
	v_mfma_f32_16x16x32_bf16 v[100:103], v[206:209], v[188:191], v[100:103]
	v_mfma_f32_16x16x32_bf16 v[96:99], v[214:217], v[188:191], v[96:99]
	v_mfma_f32_16x16x32_bf16 v[84:87], v[206:209], v[198:201], v[84:87]
	v_mfma_f32_16x16x32_bf16 v[80:83], v[214:217], v[198:201], v[80:83]
	s_barrier
	s_setprio 0
	ds_read_b128 v[168:171], v166 offset:49152
	global_load_lds_dwordx4 v[160:161], off
	ds_read_b128 v[172:175], v166 offset:50176
	ds_read_b128 v[176:179], v166 offset:51200
	ds_read_b128 v[180:183], v166 offset:52224
	ds_read_b128 v[184:187], v166 offset:53248
	ds_read_b128 v[188:191], v166 offset:54272
	ds_read_b128 v[192:195], v166 offset:55296
	ds_read_b128 v[198:201], v166 offset:56320
	v_lshl_add_u64 v[160:161], v[222:223], 0, s[46:47]
	s_mov_b32 m0, s31
	s_nop 0
	global_load_lds_dwordx4 v[160:161], off
	s_waitcnt vmcnt(10)
	s_setprio 1
	s_barrier
; DI unsigned pack2(float a, float b) { f32x2 v = {a, b}; hwbf16x2 r = __builtin_convertvector(v, hwbf16x2); return __builtin_bit_cast(unsigned, r); }
; DI float bflo(unsigned w) { return __uint_as_float(w << 16); }
; DI float bfhi(unsigned w) { return __uint_as_float(w & 0xffff0000u); }
; #define PG8_WAIT_V(n) asm volatile("s_waitcnt vmcnt(" #n ")" ::: "memory")
;     DI void operator()(const f32x4 (&acc)[2][2][4][2], const Unit& u, int wr, int wc, int fr, int fq) const {
;         const int row0 = u.pm * BM + wr * 64 + fr, col0 = u.pn * BM + wc * 32 + 8 * fq;
;         f32x4 sc[2][2];
; #pragma unroll
;         for (int bj = 0; bj < 2; ++bj)
; #pragma unroll
;             for (int n = 0; n < 2; ++n) sc[bj][n] = scale ? *(const f32x4*)(scale + col0 + bj * HALF + 4 * n) : (f32x4){1.f, 1.f, 1.f, 1.f};
; #pragma unroll
;         for (int ai = 0; ai < 2; ++ai)
; #pragma unroll
;             for (int m = 0; m < 4; ++m) { const size_t ro = (size_t)(row0 + ai * HALF + m * 16) * D + col0;
; #pragma unroll
;                 for (int bj = 0; bj < 2; ++bj) {
;                     f32x4 x0, x1;
;                     if constexpr (IB) { const u32x4 w = *(const u32x4*)((const bf16_t*)Xin + ro + bj * HALF);
;                         x0 = (f32x4){bflo(w[0]), bfhi(w[0]), bflo(w[1]), bfhi(w[1])}; x1 = (f32x4){bflo(w[2]), bfhi(w[2]), bflo(w[3]), bfhi(w[3])}; }
;                     else { x0 = *(const f32x4*)((const float*)Xin + ro + bj * HALF); x1 = *(const f32x4*)((const float*)Xin + ro + bj * HALF + 4); }
;                     x0 += acc[ai][bj][m][0] * sc[bj][0]; x1 += acc[ai][bj][m][1] * sc[bj][1];
;                     if constexpr (OB) { u32x4 o; o[0] = pack2(x0[0], x0[1]); o[1] = pack2(x0[2], x0[3]); o[2] = pack2(x1[0], x1[1]); o[3] = pack2(x1[2], x1[3]);
;                         *(u32x4*)((bf16_t*)Xout + ro + bj * HALF) = o; }
;                     else { *(f32x4*)((float*)Xout + ro + bj * HALF) = x0; *(f32x4*)((float*)Xout + ro + bj * HALF + 4) = x1; } } }
; template <class Map, class Epi>
; DI void gemm_phase(LAS unsigned char* lds, const Map& MP, const Epi& E, const int nM, const int nN, const int K, const int lda, const int ldb) {
;     ...
;             PG8_BAR; PG8_WAIT_L(0); PG8_MMA(1, 0, At, B0); PG8_BAR; PG8_SCHED;
;             PG8_STAGE(PG8_SB(1, 1), b3 + hstepB, voffB);
;             PG8_WAIT_V(6); PG8_BAR; PG8_MMA(1, 1, At, B1); PG8_BAR;
	s_waitcnt lgkmcnt(7)
	v_mfma_f32_16x16x32_bf16 v[76:79], v[56:59], v[168:171], v[76:79]
	v_mfma_f32_16x16x32_bf16 v[72:75], v[64:67], v[168:171], v[72:75]
	s_waitcnt lgkmcnt(5)
	v_mfma_f32_16x16x32_bf16 v[52:55], v[56:59], v[176:179], v[52:55]
	v_mfma_f32_16x16x32_bf16 v[48:51], v[64:67], v[176:179], v[48:51]
	s_waitcnt lgkmcnt(3)
	v_mfma_f32_16x16x32_bf16 v[28:31], v[56:59], v[184:187], v[28:31]
	v_mfma_f32_16x16x32_bf16 v[24:27], v[64:67], v[184:187], v[24:27]
	s_waitcnt lgkmcnt(1)
	v_mfma_f32_16x16x32_bf16 v[12:15], v[56:59], v[192:195], v[12:15]
	v_mfma_f32_16x16x32_bf16 v[8:11], v[64:67], v[192:195], v[8:11]
	v_mfma_f32_16x16x32_bf16 v[76:79], v[60:63], v[172:175], v[76:79]
	s_add_u32 s12, s12, 0x20080
	s_addc_u32 s13, s13, 0
	v_mfma_f32_16x16x32_bf16 v[72:75], v[68:71], v[172:175], v[72:75]
	s_add_i32 s14, s14, s22
	v_mfma_f32_16x16x32_bf16 v[52:55], v[60:63], v[180:183], v[52:55]
	v_mfma_f32_16x16x32_bf16 v[48:51], v[68:71], v[180:183], v[48:51]
	v_mfma_f32_16x16x32_bf16 v[28:31], v[60:63], v[188:191], v[28:31]
	v_mfma_f32_16x16x32_bf16 v[24:27], v[68:71], v[188:191], v[24:27]
	s_waitcnt lgkmcnt(0)
	v_mfma_f32_16x16x32_bf16 v[12:15], v[60:63], v[198:201], v[12:15]
	v_mfma_f32_16x16x32_bf16 v[8:11], v[68:71], v[198:201], v[8:11]
	s_barrier
	s_setprio 0
	s_mov_b32 m0, s14
	s_nop 0
	global_load_lds_dwordx4 v148, s[12:13]
	s_add_i32 m0, s14, 0x2000
	s_nop 0
	global_load_lds_dwordx4 v144, s[12:13]
	s_waitcnt vmcnt(6)
	s_setprio 1
	s_barrier
	v_mfma_f32_16x16x32_bf16 v[40:43], v[202:205], v[168:171], v[40:43]
	v_mfma_f32_16x16x32_bf16 v[68:71], v[206:209], v[172:175], v[40:43]
	v_mfma_f32_16x16x32_bf16 v[40:43], v[210:213], v[168:171], v[44:47]
	v_mfma_f32_16x16x32_bf16 v[36:39], v[202:205], v[176:179], v[36:39]
	v_mfma_f32_16x16x32_bf16 v[32:35], v[210:213], v[176:179], v[32:35]
	v_mfma_f32_16x16x32_bf16 v[20:23], v[202:205], v[184:187], v[20:23]
	v_mfma_f32_16x16x32_bf16 v[16:19], v[210:213], v[184:187], v[16:19]
	v_mfma_f32_16x16x32_bf16 v[4:7], v[202:205], v[192:195], v[4:7]
	v_mfma_f32_16x16x32_bf16 v[0:3], v[210:213], v[192:195], v[0:3]
	s_add_i32 s3, s3, 2
	v_mfma_f32_16x16x32_bf16 v[64:67], v[214:217], v[172:175], v[40:43]
	s_add_u32 s53, s53, 0x100
	s_addc_u32 s56, s56, 0
	ds_read_b128 v[40:43], v165
	ds_read_b128 v[44:47], v165 offset:1024
	ds_read_b128 v[56:59], v165 offset:2048
	ds_read_b128 v[60:63], v165 offset:3072
	v_mfma_f32_16x16x32_bf16 v[36:39], v[206:209], v[180:183], v[36:39]
	s_add_u32 s10, s10, 0x100
	s_addc_u32 s11, s11, 0
	v_mfma_f32_16x16x32_bf16 v[32:35], v[214:217], v[180:183], v[32:35]
	s_cmp_gt_u32 s3, 5
	v_mfma_f32_16x16x32_bf16 v[20:23], v[206:209], v[188:191], v[20:23]
	v_mfma_f32_16x16x32_bf16 v[16:19], v[214:217], v[188:191], v[16:19]
	v_mfma_f32_16x16x32_bf16 v[4:7], v[206:209], v[198:201], v[4:7]
	v_mfma_f32_16x16x32_bf16 v[0:3], v[214:217], v[198:201], v[0:3]
	s_barrier
	s_setprio 0
	s_cbranch_scc0 .LBB1_2339
	s_waitcnt lgkmcnt(0)
	s_lshl_b32 s2, s2, 8
	v_mov_b32_e32 v40, v163
	v_mov_b32_e32 v168, v162
	s_or_b32 s2, s2, s29
	s_and_b64 vcc, exec, s[40:41]
	v_lshl_add_u32 v160, v40, 3, s2
	s_lshl_b32 s2, s8, 8
	s_add_i32 s2, s2, s28
	v_add_u32_e32 v168, s2, v168
	v_ashrrev_i32_e32 v169, 31, v168
	v_ashrrev_i32_e32 v161, 31, v160
	v_lshlrev_b64 v[168:169], 11, v[168:169]
	v_lshl_add_u64 v[44:45], v[160:161], 2, s[44:45]
	v_lshl_add_u64 v[160:161], v[168:169], 0, v[160:161]
	v_lshlrev_b64 v[160:161], 1, v[160:161]
	v_lshl_add_u64 v[172:173], s[4:5], 0, v[160:161]
	global_load_dwordx4 v[56:59], v[44:45], off offset:16
	global_load_dwordx4 v[60:63], v[44:45], off
	global_load_dwordx4 v[40:43], v[44:45], off offset:528
	s_nop 0
	global_load_dwordx4 v[44:47], v[44:45], off offset:512
	s_mov_b64 s[2:3], 0x10000
	global_load_dwordx4 v[178:181], v[172:173], off
	global_load_dwordx4 v[182:185], v[172:173], off offset:256
	s_mov_b64 s[98:99], 0x10000
	v_lshl_add_u64 v[170:171], v[172:173], 0, s[98:99]
	global_load_dwordx4 v[186:189], v[170:171], off
	global_load_dwordx4 v[190:193], v[170:171], off offset:256
	s_mov_b64 s[98:99], 0x20000
	v_lshl_add_u64 v[170:171], v[172:173], 0, s[98:99]
	global_load_dwordx4 v[198:201], v[170:171], off
	global_load_dwordx4 v[202:205], v[170:171], off offset:256
	s_mov_b64 s[98:99], 0x30000
	v_lshl_add_u64 v[170:171], v[172:173], 0, s[98:99]
	global_load_dwordx4 v[206:209], v[170:171], off
	global_load_dwordx4 v[210:213], v[170:171], off offset:256
	s_mov_b64 s[98:99], 0x80000
	v_lshl_add_u64 v[170:171], v[172:173], 0, s[98:99]
	global_load_dwordx4 v[214:217], v[170:171], off
	global_load_dwordx4 v[248:251], v[170:171], off offset:256
	s_mov_b64 s[98:99], 0x90000
	v_lshl_add_u64 v[170:171], v[172:173], 0, s[98:99]
	global_load_dwordx4 v[252:255], v[170:171], off
	s_waitcnt vmcnt(10)
	s_nop 1
	v_mov_b32_e32 v168, v178
	v_mov_b32_e32 v169, v179
	v_mov_b32_e32 v170, v180
	v_mov_b32_e32 v171, v181
	s_mov_b32 s8, s52
	s_mov_b64 s[10:11], s[54:55]
	s_mov_b64 s[12:13], s[6:7]
	s_waitcnt lgkmcnt(0)
	v_lshlrev_b32_e32 v174, 16, v168
	v_and_b32_e32 v175, 0xffff0000, v168
	v_lshlrev_b32_e32 v168, 16, v169
	v_and_b32_e32 v169, 0xffff0000, v169
	v_lshlrev_b32_e32 v176, 16, v170
	v_and_b32_e32 v177, 0xffff0000, v170
	v_lshlrev_b32_e32 v170, 16, v171
	v_and_b32_e32 v171, 0xffff0000, v171
	v_pk_fma_f32 v[142:143], v[142:143], v[62:63], v[168:169]
	v_pk_fma_f32 v[140:141], v[140:141], v[60:61], v[174:175]
	v_pk_fma_f32 v[168:169], v[138:139], v[58:59], v[170:171]
	v_pk_fma_f32 v[138:139], v[136:137], v[56:57], v[176:177]
	v_cvt_pk_bf16_f32 v136, v140, v141
	v_cvt_pk_bf16_f32 v137, v142, v143
	v_cvt_pk_bf16_f32 v138, v138, v139
	v_cvt_pk_bf16_f32 v139, v168, v169
	v_lshl_add_u64 v[140:141], s[42:43], 0, v[160:161]
	global_store_dwordx4 v[140:141], v[136:139], off
	s_waitcnt vmcnt(10)
; DI unsigned pack2(float a, float b) { f32x2 v = {a, b}; hwbf16x2 r = __builtin_convertvector(v, hwbf16x2); return __builtin_bit_cast(unsigned, r); }
; DI float bflo(unsigned w) { return __uint_as_float(w << 16); }
; DI float bfhi(unsigned w) { return __uint_as_float(w & 0xffff0000u); }
;     DI void operator()(const f32x4 (&acc)[2][2][4][2], const Unit& u, int wr, int wc, int fr, int fq) const {
;     ...
;             for (int m = 0; m < 4; ++m) { const size_t ro = (size_t)(row0 + ai * HALF + m * 16) * D + col0;
; #pragma unroll
;                 for (int bj = 0; bj < 2; ++bj) {
;                     f32x4 x0, x1;
;                     if constexpr (IB) { const u32x4 w = *(const u32x4*)((const bf16_t*)Xin + ro + bj * HALF);
;                         x0 = (f32x4){bflo(w[0]), bfhi(w[0]), bflo(w[1]), bfhi(w[1])}; x1 = (f32x4){bflo(w[2]), bfhi(w[2]), bflo(w[3]), bfhi(w[3])}; }
;                     else { x0 = *(const f32x4*)((const float*)Xin + ro + bj * HALF); x1 = *(const f32x4*)((const float*)Xin + ro + bj * HALF + 4); }
;                     x0 += acc[ai][bj][m][0] * sc[bj][0]; x1 += acc[ai][bj][m][1] * sc[bj][1];
;                     if constexpr (OB) { u32x4 o; o[0] = pack2(x0[0], x0[1]); o[1] = pack2(x0[2], x0[3]); o[2] = pack2(x1[0], x1[1]); o[3] = pack2(x1[2], x1[3]);
;                         *(u32x4*)((bf16_t*)Xout + ro + bj * HALF) = o; }
;                     else { *(f32x4*)((float*)Xout + ro + bj * HALF) = x0; *(f32x4*)((float*)Xout + ro + bj * HALF + 4) = x1; } } }
	s_nop 1
	v_mov_b32_e32 v136, v182
	v_mov_b32_e32 v137, v183
	v_mov_b32_e32 v138, v184
	v_mov_b32_e32 v139, v185
	s_waitcnt lgkmcnt(0)
	v_lshlrev_b32_e32 v142, 16, v136
	v_and_b32_e32 v143, 0xffff0000, v136
	v_lshlrev_b32_e32 v136, 16, v137
	v_and_b32_e32 v137, 0xffff0000, v137
	v_lshlrev_b32_e32 v168, 16, v138
	v_and_b32_e32 v169, 0xffff0000, v138
	v_lshlrev_b32_e32 v138, 16, v139
	v_and_b32_e32 v139, 0xffff0000, v139
	v_pk_fma_f32 v[134:135], v[134:135], v[46:47], v[136:137]
	v_pk_fma_f32 v[132:133], v[132:133], v[44:45], v[142:143]
	v_pk_fma_f32 v[136:137], v[130:131], v[42:43], v[138:139]
	v_pk_fma_f32 v[130:131], v[128:129], v[40:41], v[168:169]
	v_cvt_pk_bf16_f32 v128, v132, v133
	v_cvt_pk_bf16_f32 v129, v134, v135
	v_cvt_pk_bf16_f32 v130, v130, v131
	v_cvt_pk_bf16_f32 v131, v136, v137
	v_lshl_add_u64 v[132:133], v[160:161], 0, s[2:3]
	global_store_dwordx4 v[140:141], v[128:131], off offset:256
	v_lshl_add_u64 v[134:135], s[4:5], 0, v[132:133]
	s_waitcnt vmcnt(10)
	s_nop 1
	v_mov_b32_e32 v128, v186
	v_mov_b32_e32 v129, v187
	v_mov_b32_e32 v130, v188
	v_mov_b32_e32 v131, v189
	s_mov_b64 s[2:3], 0x20000
	s_waitcnt lgkmcnt(0)
	v_lshlrev_b32_e32 v136, 16, v128
	v_and_b32_e32 v137, 0xffff0000, v128
	v_lshlrev_b32_e32 v128, 16, v129
	v_and_b32_e32 v129, 0xffff0000, v129
	v_lshlrev_b32_e32 v138, 16, v130
	v_and_b32_e32 v139, 0xffff0000, v130
	v_lshlrev_b32_e32 v130, 16, v131
	v_and_b32_e32 v131, 0xffff0000, v131
	v_pk_fma_f32 v[126:127], v[126:127], v[62:63], v[128:129]
	v_pk_fma_f32 v[124:125], v[124:125], v[60:61], v[136:137]
	v_pk_fma_f32 v[128:129], v[122:123], v[58:59], v[130:131]
	v_pk_fma_f32 v[122:123], v[120:121], v[56:57], v[138:139]
	v_cvt_pk_bf16_f32 v120, v124, v125
	v_cvt_pk_bf16_f32 v121, v126, v127
	v_cvt_pk_bf16_f32 v122, v122, v123
	v_cvt_pk_bf16_f32 v123, v128, v129
	v_lshl_add_u64 v[124:125], s[42:43], 0, v[132:133]
	global_store_dwordx4 v[124:125], v[120:123], off
	s_waitcnt vmcnt(10)
	s_nop 1
	v_mov_b32_e32 v120, v190
	v_mov_b32_e32 v121, v191
	v_mov_b32_e32 v122, v192
	v_mov_b32_e32 v123, v193
	s_waitcnt lgkmcnt(0)
	v_lshlrev_b32_e32 v126, 16, v120
	v_and_b32_e32 v127, 0xffff0000, v120
	v_lshlrev_b32_e32 v120, 16, v121
	v_and_b32_e32 v121, 0xffff0000, v121
	v_lshlrev_b32_e32 v128, 16, v122
	v_and_b32_e32 v129, 0xffff0000, v122
	v_lshlrev_b32_e32 v122, 16, v123
	v_and_b32_e32 v123, 0xffff0000, v123
	v_pk_fma_f32 v[118:119], v[118:119], v[46:47], v[120:121]
	v_pk_fma_f32 v[116:117], v[116:117], v[44:45], v[126:127]
	v_pk_fma_f32 v[120:121], v[114:115], v[42:43], v[122:123]
	v_pk_fma_f32 v[114:115], v[112:113], v[40:41], v[128:129]
	v_cvt_pk_bf16_f32 v112, v116, v117
	v_cvt_pk_bf16_f32 v113, v118, v119
	v_cvt_pk_bf16_f32 v114, v114, v115
	v_cvt_pk_bf16_f32 v115, v120, v121
	v_lshl_add_u64 v[116:117], v[160:161], 0, s[2:3]
	global_store_dwordx4 v[124:125], v[112:115], off offset:256
	v_lshl_add_u64 v[118:119], s[4:5], 0, v[116:117]
	s_waitcnt vmcnt(10)
	s_nop 1
	v_mov_b32_e32 v112, v198
	v_mov_b32_e32 v113, v199
	v_mov_b32_e32 v114, v200
	v_mov_b32_e32 v115, v201
	s_mov_b64 s[2:3], 0x30000
	s_waitcnt lgkmcnt(0)
	v_lshlrev_b32_e32 v120, 16, v112
	v_and_b32_e32 v121, 0xffff0000, v112
	v_lshlrev_b32_e32 v112, 16, v113
	v_and_b32_e32 v113, 0xffff0000, v113
	v_lshlrev_b32_e32 v122, 16, v114
	v_and_b32_e32 v123, 0xffff0000, v114
	v_lshlrev_b32_e32 v114, 16, v115
	v_and_b32_e32 v115, 0xffff0000, v115
	v_pk_fma_f32 v[110:111], v[110:111], v[62:63], v[112:113]
	v_pk_fma_f32 v[108:109], v[108:109], v[60:61], v[120:121]
	v_pk_fma_f32 v[112:113], v[106:107], v[58:59], v[114:115]
	v_pk_fma_f32 v[106:107], v[104:105], v[56:57], v[122:123]
	v_cvt_pk_bf16_f32 v104, v108, v109
	v_cvt_pk_bf16_f32 v105, v110, v111
	v_cvt_pk_bf16_f32 v106, v106, v107
	v_cvt_pk_bf16_f32 v107, v112, v113
	v_lshl_add_u64 v[108:109], s[42:43], 0, v[116:117]
	global_store_dwordx4 v[108:109], v[104:107], off
	s_waitcnt vmcnt(10)
	s_nop 1
	v_mov_b32_e32 v104, v202
	v_mov_b32_e32 v105, v203
	v_mov_b32_e32 v106, v204
	v_mov_b32_e32 v107, v205
	s_waitcnt lgkmcnt(0)
	v_lshlrev_b32_e32 v110, 16, v104
	v_and_b32_e32 v111, 0xffff0000, v104
	v_lshlrev_b32_e32 v104, 16, v105
	v_and_b32_e32 v105, 0xffff0000, v105
	v_lshlrev_b32_e32 v112, 16, v106
	v_and_b32_e32 v113, 0xffff0000, v106
	v_lshlrev_b32_e32 v106, 16, v107
	v_and_b32_e32 v107, 0xffff0000, v107
	v_pk_fma_f32 v[102:103], v[102:103], v[46:47], v[104:105]
	v_pk_fma_f32 v[100:101], v[100:101], v[44:45], v[110:111]
	v_pk_fma_f32 v[104:105], v[98:99], v[42:43], v[106:107]
	v_pk_fma_f32 v[98:99], v[96:97], v[40:41], v[112:113]
	v_cvt_pk_bf16_f32 v96, v100, v101
	v_cvt_pk_bf16_f32 v97, v102, v103
	v_cvt_pk_bf16_f32 v98, v98, v99
	v_cvt_pk_bf16_f32 v99, v104, v105
	v_lshl_add_u64 v[100:101], v[160:161], 0, s[2:3]
	global_store_dwordx4 v[108:109], v[96:99], off offset:256
	v_lshl_add_u64 v[102:103], s[4:5], 0, v[100:101]
	s_waitcnt vmcnt(10)
	s_nop 1
	v_mov_b32_e32 v96, v206
	v_mov_b32_e32 v97, v207
	v_mov_b32_e32 v98, v208
	v_mov_b32_e32 v99, v209
	s_mov_b64 s[2:3], 0x80000
	s_waitcnt lgkmcnt(0)
	v_lshlrev_b32_e32 v104, 16, v96
	v_and_b32_e32 v105, 0xffff0000, v96
	v_lshlrev_b32_e32 v96, 16, v97
	v_and_b32_e32 v97, 0xffff0000, v97
	v_lshlrev_b32_e32 v106, 16, v98
	v_and_b32_e32 v107, 0xffff0000, v98
	v_lshlrev_b32_e32 v98, 16, v99
	v_and_b32_e32 v99, 0xffff0000, v99
	v_pk_fma_f32 v[94:95], v[94:95], v[62:63], v[96:97]
	v_pk_fma_f32 v[92:93], v[92:93], v[60:61], v[104:105]
	v_pk_fma_f32 v[96:97], v[90:91], v[58:59], v[98:99]
	v_pk_fma_f32 v[90:91], v[88:89], v[56:57], v[106:107]
	v_cvt_pk_bf16_f32 v88, v92, v93
	v_cvt_pk_bf16_f32 v89, v94, v95
	v_cvt_pk_bf16_f32 v90, v90, v91
	v_cvt_pk_bf16_f32 v91, v96, v97
	v_lshl_add_u64 v[92:93], s[42:43], 0, v[100:101]
	global_store_dwordx4 v[92:93], v[88:91], off
	s_waitcnt vmcnt(10)
; DI unsigned pack2(float a, float b) { f32x2 v = {a, b}; hwbf16x2 r = __builtin_convertvector(v, hwbf16x2); return __builtin_bit_cast(unsigned, r); }
; DI float bflo(unsigned w) { return __uint_as_float(w << 16); }
; DI float bfhi(unsigned w) { return __uint_as_float(w & 0xffff0000u); }
;     DI void operator()(const f32x4 (&acc)[2][2][4][2], const Unit& u, int wr, int wc, int fr, int fq) const {
;     ...
;             for (int m = 0; m < 4; ++m) { const size_t ro = (size_t)(row0 + ai * HALF + m * 16) * D + col0;
; #pragma unroll
;                 for (int bj = 0; bj < 2; ++bj) {
;                     f32x4 x0, x1;
;                     if constexpr (IB) { const u32x4 w = *(const u32x4*)((const bf16_t*)Xin + ro + bj * HALF);
;                         x0 = (f32x4){bflo(w[0]), bfhi(w[0]), bflo(w[1]), bfhi(w[1])}; x1 = (f32x4){bflo(w[2]), bfhi(w[2]), bflo(w[3]), bfhi(w[3])}; }
;                     else { x0 = *(const f32x4*)((const float*)Xin + ro + bj * HALF); x1 = *(const f32x4*)((const float*)Xin + ro + bj * HALF + 4); }
;                     x0 += acc[ai][bj][m][0] * sc[bj][0]; x1 += acc[ai][bj][m][1] * sc[bj][1];
;                     if constexpr (OB) { u32x4 o; o[0] = pack2(x0[0], x0[1]); o[1] = pack2(x0[2], x0[3]); o[2] = pack2(x1[0], x1[1]); o[3] = pack2(x1[2], x1[3]);
;                         *(u32x4*)((bf16_t*)Xout + ro + bj * HALF) = o; }
;                     else { *(f32x4*)((float*)Xout + ro + bj * HALF) = x0; *(f32x4*)((float*)Xout + ro + bj * HALF + 4) = x1; } } }
	s_nop 1
	v_mov_b32_e32 v88, v210
	v_mov_b32_e32 v89, v211
	v_mov_b32_e32 v90, v212
	v_mov_b32_e32 v91, v213
	s_waitcnt lgkmcnt(0)
	v_lshlrev_b32_e32 v94, 16, v88
	v_and_b32_e32 v95, 0xffff0000, v88
	v_lshlrev_b32_e32 v88, 16, v89
	v_and_b32_e32 v89, 0xffff0000, v89
	v_lshlrev_b32_e32 v96, 16, v90
	v_and_b32_e32 v97, 0xffff0000, v90
	v_lshlrev_b32_e32 v90, 16, v91
	v_and_b32_e32 v91, 0xffff0000, v91
	v_pk_fma_f32 v[86:87], v[86:87], v[46:47], v[88:89]
	v_pk_fma_f32 v[84:85], v[84:85], v[44:45], v[94:95]
	v_pk_fma_f32 v[88:89], v[82:83], v[42:43], v[90:91]
	v_pk_fma_f32 v[82:83], v[80:81], v[40:41], v[96:97]
	v_cvt_pk_bf16_f32 v80, v84, v85
	v_cvt_pk_bf16_f32 v81, v86, v87
	v_cvt_pk_bf16_f32 v82, v82, v83
	v_cvt_pk_bf16_f32 v83, v88, v89
	v_lshl_add_u64 v[84:85], v[160:161], 0, s[2:3]
	global_store_dwordx4 v[92:93], v[80:83], off offset:256
	v_lshl_add_u64 v[86:87], s[4:5], 0, v[84:85]
	s_waitcnt vmcnt(10)
	s_nop 1
	v_mov_b32_e32 v80, v214
	v_mov_b32_e32 v81, v215
	v_mov_b32_e32 v82, v216
	v_mov_b32_e32 v83, v217
	s_mov_b64 s[2:3], 0x90000
	s_waitcnt lgkmcnt(0)
	v_lshlrev_b32_e32 v88, 16, v80
	v_and_b32_e32 v89, 0xffff0000, v80
	v_lshlrev_b32_e32 v80, 16, v81
	v_and_b32_e32 v81, 0xffff0000, v81
	v_lshlrev_b32_e32 v90, 16, v82
	v_and_b32_e32 v91, 0xffff0000, v82
	v_lshlrev_b32_e32 v82, 16, v83
	v_and_b32_e32 v83, 0xffff0000, v83
	v_pk_fma_f32 v[78:79], v[78:79], v[62:63], v[80:81]
	v_pk_fma_f32 v[76:77], v[76:77], v[60:61], v[88:89]
	v_pk_fma_f32 v[80:81], v[74:75], v[58:59], v[82:83]
	v_pk_fma_f32 v[74:75], v[72:73], v[56:57], v[90:91]
	v_cvt_pk_bf16_f32 v72, v76, v77
	v_cvt_pk_bf16_f32 v73, v78, v79
	v_cvt_pk_bf16_f32 v74, v74, v75
	v_cvt_pk_bf16_f32 v75, v80, v81
	v_lshl_add_u64 v[76:77], s[42:43], 0, v[84:85]
	global_store_dwordx4 v[76:77], v[72:75], off
	s_waitcnt vmcnt(10)
	s_nop 1
	v_mov_b32_e32 v72, v248
	v_mov_b32_e32 v73, v249
	v_mov_b32_e32 v74, v250
	v_mov_b32_e32 v75, v251
	s_waitcnt lgkmcnt(0)
	v_lshlrev_b32_e32 v78, 16, v72
	v_and_b32_e32 v79, 0xffff0000, v72
	v_lshlrev_b32_e32 v72, 16, v73
	v_and_b32_e32 v73, 0xffff0000, v73
	v_lshlrev_b32_e32 v80, 16, v74
	v_and_b32_e32 v81, 0xffff0000, v74
	v_lshlrev_b32_e32 v74, 16, v75
	v_and_b32_e32 v75, 0xffff0000, v75
	v_pk_fma_f32 v[70:71], v[70:71], v[46:47], v[72:73]
	v_pk_fma_f32 v[68:69], v[68:69], v[44:45], v[78:79]
	v_pk_fma_f32 v[72:73], v[66:67], v[42:43], v[74:75]
	v_pk_fma_f32 v[66:67], v[64:65], v[40:41], v[80:81]
	v_cvt_pk_bf16_f32 v64, v68, v69
	v_cvt_pk_bf16_f32 v65, v70, v71
	v_cvt_pk_bf16_f32 v66, v66, v67
	v_cvt_pk_bf16_f32 v67, v72, v73
	v_lshl_add_u64 v[68:69], v[160:161], 0, s[2:3]
	global_store_dwordx4 v[76:77], v[64:67], off offset:256
	v_lshl_add_u64 v[70:71], s[4:5], 0, v[68:69]
	s_waitcnt vmcnt(10)
	s_nop 1
	v_mov_b32_e32 v64, v252
	v_mov_b32_e32 v65, v253
	v_mov_b32_e32 v66, v254
	v_mov_b32_e32 v67, v255
	s_mov_b64 s[2:3], 0xa0000
	s_waitcnt lgkmcnt(0)
	v_lshlrev_b32_e32 v72, 16, v64
	v_and_b32_e32 v73, 0xffff0000, v64
	v_lshlrev_b32_e32 v64, 16, v65
	v_and_b32_e32 v65, 0xffff0000, v65
	v_lshlrev_b32_e32 v74, 16, v66
	v_and_b32_e32 v75, 0xffff0000, v66
	v_lshlrev_b32_e32 v66, 16, v67
	v_and_b32_e32 v67, 0xffff0000, v67
	v_pk_fma_f32 v[54:55], v[54:55], v[62:63], v[64:65]
	v_pk_fma_f32 v[52:53], v[52:53], v[60:61], v[72:73]
	v_pk_fma_f32 v[64:65], v[50:51], v[58:59], v[66:67]
	v_pk_fma_f32 v[50:51], v[48:49], v[56:57], v[74:75]
	v_cvt_pk_bf16_f32 v48, v52, v53
	v_cvt_pk_bf16_f32 v49, v54, v55
	v_cvt_pk_bf16_f32 v50, v50, v51
	v_cvt_pk_bf16_f32 v51, v64, v65
	v_lshl_add_u64 v[52:53], s[42:43], 0, v[68:69]
	global_store_dwordx4 v[52:53], v[48:51], off
	global_load_dwordx4 v[48:51], v[70:71], off offset:256
	s_waitcnt vmcnt(0) lgkmcnt(0)
; DI unsigned pack2(float a, float b) { f32x2 v = {a, b}; hwbf16x2 r = __builtin_convertvector(v, hwbf16x2); return __builtin_bit_cast(unsigned, r); }
; DI float bflo(unsigned w) { return __uint_as_float(w << 16); }
; DI float bfhi(unsigned w) { return __uint_as_float(w & 0xffff0000u); }
;     DI const char* a(const Unit& u) const { return (const char*)(A + (size_t)u.pm * BM * lda); }
; #define PG8_BAR __builtin_amdgcn_s_barrier()
;     DI void operator()(const f32x4 (&acc)[2][2][4][2], const Unit& u, int wr, int wc, int fr, int fq) const {
;     ...
;             for (int m = 0; m < 4; ++m) { const size_t ro = (size_t)(row0 + ai * HALF + m * 16) * D + col0;
; #pragma unroll
;                 for (int bj = 0; bj < 2; ++bj) {
;                     f32x4 x0, x1;
;                     if constexpr (IB) { const u32x4 w = *(const u32x4*)((const bf16_t*)Xin + ro + bj * HALF);
;                         x0 = (f32x4){bflo(w[0]), bfhi(w[0]), bflo(w[1]), bfhi(w[1])}; x1 = (f32x4){bflo(w[2]), bfhi(w[2]), bflo(w[3]), bfhi(w[3])}; }
;                     else { x0 = *(const f32x4*)((const float*)Xin + ro + bj * HALF); x1 = *(const f32x4*)((const float*)Xin + ro + bj * HALF + 4); }
;                     x0 += acc[ai][bj][m][0] * sc[bj][0]; x1 += acc[ai][bj][m][1] * sc[bj][1];
;                     if constexpr (OB) { u32x4 o; o[0] = pack2(x0[0], x0[1]); o[1] = pack2(x0[2], x0[3]); o[2] = pack2(x1[0], x1[1]); o[3] = pack2(x1[2], x1[3]);
;                         *(u32x4*)((bf16_t*)Xout + ro + bj * HALF) = o; }
;                     else { *(f32x4*)((float*)Xout + ro + bj * HALF) = x0; *(f32x4*)((float*)Xout + ro + bj * HALF + 4) = x1; } } }
; template <class Map, class Epi>
; DI void gemm_phase(LAS unsigned char* lds, const Map& MP, const Epi& E, const int nM, const int nN, const int K, const int lda, const int ldb) {
;     ...
;         { int frr = fr, fqq = fq; asm volatile("" : "+v"(frr), "+v"(fqq)); E(acc, cur, wr, wc, frr, fqq); }
;         if (!has_next) break;
; #pragma unroll
;         for (int a = 0; a < 2; ++a)
; #pragma unroll
;             for (int b = 0; b < 2; ++b)
; #pragma unroll
;                 for (int m = 0; m < 4; ++m)
; #pragma unroll
;                     for (int n = 0; n < 2; ++n) acc[a][b][m][n] = (f32x4){0.f, 0.f, 0.f, 0.f};
;         cur = nxt; cA = nA; cB = nB; ++ui;
;     }
;     PG8_WAIT_V(0);
;     if (wr == 0) PG8_BAR;
;     PG8_BAR;
	v_lshlrev_b32_e32 v54, 16, v48
	v_and_b32_e32 v55, 0xffff0000, v48
	v_lshlrev_b32_e32 v48, 16, v49
	v_and_b32_e32 v49, 0xffff0000, v49
	v_lshlrev_b32_e32 v64, 16, v50
	v_and_b32_e32 v65, 0xffff0000, v50
	v_lshlrev_b32_e32 v50, 16, v51
	v_and_b32_e32 v51, 0xffff0000, v51
	v_pk_fma_f32 v[38:39], v[38:39], v[46:47], v[48:49]
	v_pk_fma_f32 v[36:37], v[36:37], v[44:45], v[54:55]
	v_pk_fma_f32 v[48:49], v[34:35], v[42:43], v[50:51]
	v_pk_fma_f32 v[34:35], v[32:33], v[40:41], v[64:65]
	v_cvt_pk_bf16_f32 v32, v36, v37
	v_cvt_pk_bf16_f32 v33, v38, v39
	v_cvt_pk_bf16_f32 v34, v34, v35
	v_cvt_pk_bf16_f32 v35, v48, v49
	v_lshl_add_u64 v[36:37], v[160:161], 0, s[2:3]
	global_store_dwordx4 v[52:53], v[32:35], off offset:256
	v_lshl_add_u64 v[38:39], s[4:5], 0, v[36:37]
	global_load_dwordx4 v[32:35], v[38:39], off
	s_mov_b64 s[2:3], 0xb0000
	s_waitcnt vmcnt(0) lgkmcnt(0)
	v_lshlrev_b32_e32 v48, 16, v32
	v_and_b32_e32 v49, 0xffff0000, v32
	v_lshlrev_b32_e32 v32, 16, v33
	v_and_b32_e32 v33, 0xffff0000, v33
	v_lshlrev_b32_e32 v50, 16, v34
	v_and_b32_e32 v51, 0xffff0000, v34
	v_lshlrev_b32_e32 v34, 16, v35
	v_and_b32_e32 v35, 0xffff0000, v35
	v_pk_fma_f32 v[30:31], v[30:31], v[62:63], v[32:33]
	v_pk_fma_f32 v[28:29], v[28:29], v[60:61], v[48:49]
	v_pk_fma_f32 v[32:33], v[26:27], v[58:59], v[34:35]
	v_pk_fma_f32 v[26:27], v[24:25], v[56:57], v[50:51]
	v_cvt_pk_bf16_f32 v24, v28, v29
	v_cvt_pk_bf16_f32 v25, v30, v31
	v_cvt_pk_bf16_f32 v26, v26, v27
	v_cvt_pk_bf16_f32 v27, v32, v33
	v_lshl_add_u64 v[28:29], s[42:43], 0, v[36:37]
	global_store_dwordx4 v[28:29], v[24:27], off
	global_load_dwordx4 v[24:27], v[38:39], off offset:256
	s_waitcnt vmcnt(0) lgkmcnt(0)
	v_lshlrev_b32_e32 v30, 16, v24
	v_and_b32_e32 v31, 0xffff0000, v24
	v_lshlrev_b32_e32 v24, 16, v25
	v_and_b32_e32 v25, 0xffff0000, v25
	v_lshlrev_b32_e32 v32, 16, v26
	v_and_b32_e32 v33, 0xffff0000, v26
	v_lshlrev_b32_e32 v26, 16, v27
	v_and_b32_e32 v27, 0xffff0000, v27
	v_pk_fma_f32 v[22:23], v[22:23], v[46:47], v[24:25]
	v_pk_fma_f32 v[20:21], v[20:21], v[44:45], v[30:31]
	v_pk_fma_f32 v[24:25], v[18:19], v[42:43], v[26:27]
	v_pk_fma_f32 v[18:19], v[16:17], v[40:41], v[32:33]
	v_cvt_pk_bf16_f32 v16, v20, v21
	v_cvt_pk_bf16_f32 v17, v22, v23
	v_cvt_pk_bf16_f32 v18, v18, v19
	v_cvt_pk_bf16_f32 v19, v24, v25
	v_lshl_add_u64 v[20:21], v[160:161], 0, s[2:3]
	global_store_dwordx4 v[28:29], v[16:19], off offset:256
	v_lshl_add_u64 v[22:23], s[4:5], 0, v[20:21]
	global_load_dwordx4 v[16:19], v[22:23], off
	s_mov_b32 s2, s37
	s_waitcnt vmcnt(0) lgkmcnt(0)
	v_lshlrev_b32_e32 v24, 16, v16
	v_and_b32_e32 v25, 0xffff0000, v16
	v_lshlrev_b32_e32 v16, 16, v17
	v_and_b32_e32 v17, 0xffff0000, v17
	v_lshlrev_b32_e32 v26, 16, v18
	v_and_b32_e32 v27, 0xffff0000, v18
	v_lshlrev_b32_e32 v18, 16, v19
	v_and_b32_e32 v19, 0xffff0000, v19
	v_pk_fma_f32 v[14:15], v[14:15], v[62:63], v[16:17]
	v_pk_fma_f32 v[12:13], v[12:13], v[60:61], v[24:25]
	v_pk_fma_f32 v[16:17], v[10:11], v[58:59], v[18:19]
	v_pk_fma_f32 v[10:11], v[8:9], v[56:57], v[26:27]
	v_cvt_pk_bf16_f32 v8, v12, v13
	v_cvt_pk_bf16_f32 v9, v14, v15
	v_cvt_pk_bf16_f32 v10, v10, v11
	v_cvt_pk_bf16_f32 v11, v16, v17
	v_lshl_add_u64 v[12:13], s[42:43], 0, v[20:21]
	global_store_dwordx4 v[12:13], v[8:11], off
	global_load_dwordx4 v[8:11], v[22:23], off offset:256
	s_waitcnt vmcnt(0) lgkmcnt(0)
	v_lshlrev_b32_e32 v14, 16, v8
	v_and_b32_e32 v15, 0xffff0000, v8
	v_lshlrev_b32_e32 v8, 16, v9
	v_and_b32_e32 v9, 0xffff0000, v9
	v_lshlrev_b32_e32 v16, 16, v10
	v_and_b32_e32 v17, 0xffff0000, v10
	v_lshlrev_b32_e32 v10, 16, v11
	v_and_b32_e32 v11, 0xffff0000, v11
	v_pk_fma_f32 v[6:7], v[6:7], v[46:47], v[8:9]
	v_pk_fma_f32 v[4:5], v[4:5], v[44:45], v[14:15]
	v_pk_fma_f32 v[8:9], v[2:3], v[42:43], v[10:11]
	v_pk_fma_f32 v[2:3], v[0:1], v[40:41], v[16:17]
	v_cvt_pk_bf16_f32 v0, v4, v5
	v_cvt_pk_bf16_f32 v1, v6, v7
	v_cvt_pk_bf16_f32 v2, v2, v3
	v_cvt_pk_bf16_f32 v3, v8, v9
	global_store_dwordx4 v[12:13], v[0:3], off offset:256
	s_cbranch_vccz .LBB1_2336
	s_waitcnt vmcnt(0)
	s_cmpk_gt_u32 s17, 0xff
	s_cbranch_scc1 .LBB1_2343
	s_barrier

; #define PG8_STAGE(bufoff, gbase, voff) do { _Pragma("unroll") for (int _i = 0; _i < 2; ++_i) \
;         __builtin_amdgcn_global_load_lds((const unsigned*)((const char*)(gbase) + (voff)[_i]), (LAS unsigned*)(lds + (bufoff) + ldsw + _i * 8192), 16, 0, 0); } while (0)
; #define PG8_LDA(dst, b, h) do { _Pragma("unroll") for (int m = 0; m < 4; ++m) _Pragma("unroll") for (int k = 0; k < 2; ++k) dst[m][k] = *(const LAS bf16x8*)(lds + PG8_SA(b, h) + aoff + m * 2048 + k * 1024); } while (0)
; #define PG8_LDB(dst, b, h) do { _Pragma("unroll") for (int n = 0; n < 2; ++n) _Pragma("unroll") for (int k = 0; k < 2; ++k) dst[n][k] = *(const LAS bf16x8*)(lds + PG8_SB(b, h) + boff + n * 2048 + k * 1024); } while (0)
; #define PG8_MMA(ai, bj, At, Bt) do { __builtin_amdgcn_s_setprio(1); _Pragma("unroll") for (int m = 0; m < 4; ++m) _Pragma("unroll") for (int n = 0; n < 2; ++n) _Pragma("unroll") for (int k = 0; k < 2; ++k) \
;         acc[ai][bj][m][n] = __builtin_amdgcn_mfma_f32_16x16x32_bf16(Bt[n][k], At[m][k], acc[ai][bj][m][n], 0, 0, 0); __builtin_amdgcn_s_setprio(0); } while (0)
; #define PG8_WAIT_V(n) asm volatile("s_waitcnt vmcnt(" #n ")" ::: "memory")
; #define PG8_WAIT_L(n) asm volatile("s_waitcnt lgkmcnt(" #n ")" ::: "memory")
; #define PG8_BAR __builtin_amdgcn_s_barrier()
; template <class Map, class Epi>
; DI void gemm_phase(LAS unsigned char* lds, const Map& MP, const Epi& E, const int nM, const int nN, const int K, const int lda, const int ldb) {
;     ...
;             const char* a1 = cA + (size_t)(t + 1) * kstep;
;             const char* a2 = last ? nA : cA + (size_t)(t + 2) * kstep; const char* b2 = last ? nB : cB + (size_t)(t + 2) * kstep;
;             const char* a3 = a2 + kstep; const char* b3 = b2 + kstep;
;             PG8_LDB(B0, 0, 0); PG8_SCHED; PG8_LDA(At, 0, 0); PG8_STAGE(PG8_SA(1, 1), a1 + hstepA, voffA);
;             PG8_WAIT_L(8); PG8_BAR; PG8_WAIT_L(0); PG8_MMA(0, 0, At, B0); PG8_BAR; PG8_SCHED;
;             PG8_LDB(B1, 0, 1); PG8_STAGE(PG8_SB(0, 0), b2, voffB);
;             PG8_BAR; PG8_WAIT_L(0); PG8_MMA(0, 1, At, B1); PG8_BAR;
;             PG8_LDA(At, 0, 1); PG8_STAGE(PG8_SA(0, 0), a2, voffA);
;             PG8_BAR; PG8_WAIT_L(0); PG8_MMA(1, 0, At, B0); PG8_BAR; PG8_SCHED;
;             PG8_STAGE(PG8_SB(0, 1), b2 + hstepB, voffB);
;             PG8_WAIT_V(6); PG8_BAR; PG8_MMA(1, 1, At, B1); PG8_BAR;
.LBB1_2483:
	s_add_u32 s28, s42, 0xfff80080
	s_addc_u32 s29, s43, -1
	s_cmp_eq_u32 s3, 28
	s_cselect_b32 s47, s23, s29
	s_cselect_b32 s46, s58, s28
	s_cselect_b32 s29, s21, vcc_hi
	s_cselect_b32 s28, s59, vcc_lo
	s_add_i32 m0, s38, 0xc000
	ds_read_b128 v[96:99], v190
	global_load_lds_dwordx4 v178, s[42:43]
	ds_read_b128 v[100:103], v190 offset:1024
	ds_read_b128 v[108:111], v190 offset:2048
	ds_read_b128 v[112:115], v190 offset:3072
	ds_read_b128 v[160:163], v190 offset:4096
	ds_read_b128 v[164:167], v190 offset:5120
	ds_read_b128 v[198:201], v190 offset:6144
	ds_read_b128 v[202:205], v190 offset:7168
	s_add_i32 m0, s38, 0xe000
	s_nop 0
	global_load_lds_dwordx4 v176, s[42:43]
	s_waitcnt lgkmcnt(8)
	s_setprio 1
	s_barrier
	s_waitcnt lgkmcnt(7)
	v_mfma_f32_16x16x32_bf16 v[148:151], v[80:83], v[96:99], v[148:151]
	v_mfma_f32_16x16x32_bf16 v[144:147], v[88:91], v[96:99], v[144:147]
	s_waitcnt lgkmcnt(5)
	v_mfma_f32_16x16x32_bf16 v[136:139], v[80:83], v[108:111], v[136:139]
	v_mfma_f32_16x16x32_bf16 v[128:131], v[88:91], v[108:111], v[128:131]
	s_waitcnt lgkmcnt(3)
	v_mfma_f32_16x16x32_bf16 v[120:123], v[80:83], v[160:163], v[120:123]
	v_mfma_f32_16x16x32_bf16 v[104:107], v[88:91], v[160:163], v[104:107]
	s_waitcnt lgkmcnt(1)
	v_mfma_f32_16x16x32_bf16 v[76:79], v[80:83], v[198:201], v[76:79]
	v_mfma_f32_16x16x32_bf16 v[72:75], v[88:91], v[198:201], v[72:75]
	v_mfma_f32_16x16x32_bf16 v[148:151], v[84:87], v[100:103], v[148:151]
	s_add_i32 s68, s2, s37
	v_mfma_f32_16x16x32_bf16 v[144:147], v[92:95], v[100:103], v[144:147]
	v_lshl_add_u64 v[184:185], s[28:29], 0, v[172:173]
	v_mfma_f32_16x16x32_bf16 v[136:139], v[84:87], v[112:115], v[136:139]
	v_lshl_add_u64 v[194:195], s[28:29], 0, v[168:169]
	v_mfma_f32_16x16x32_bf16 v[128:131], v[92:95], v[112:115], v[128:131]
	v_mfma_f32_16x16x32_bf16 v[120:123], v[84:87], v[164:167], v[120:123]
	v_mfma_f32_16x16x32_bf16 v[104:107], v[92:95], v[164:167], v[104:107]
	s_waitcnt lgkmcnt(0)
	v_mfma_f32_16x16x32_bf16 v[76:79], v[84:87], v[202:205], v[76:79]
	v_mfma_f32_16x16x32_bf16 v[72:75], v[92:95], v[202:205], v[72:75]
	s_barrier
	s_setprio 0
	s_mov_b32 m0, s68
	ds_read_b128 v[206:209], v191
	global_load_lds_dwordx4 v[184:185], off
	ds_read_b128 v[210:213], v191 offset:1024
	ds_read_b128 v[214:217], v191 offset:2048
	ds_read_b128 v[218:221], v191 offset:3072
	s_add_i32 m0, s68, 0x2000
	s_nop 0
	global_load_lds_dwordx4 v[194:195], off
	s_setprio 1
	s_barrier
	s_waitcnt lgkmcnt(3)
	v_mfma_f32_16x16x32_bf16 v[156:159], v[206:209], v[96:99], v[156:159]
	s_waitcnt lgkmcnt(1)
	v_mfma_f32_16x16x32_bf16 v[96:99], v[214:217], v[96:99], v[152:155]
	v_mfma_f32_16x16x32_bf16 v[156:159], v[210:213], v[100:103], v[156:159]
	s_waitcnt lgkmcnt(0)
	v_mfma_f32_16x16x32_bf16 v[96:99], v[218:221], v[100:103], v[96:99]
	v_mfma_f32_16x16x32_bf16 v[100:103], v[206:209], v[108:111], v[140:143]
	v_mfma_f32_16x16x32_bf16 v[108:111], v[214:217], v[108:111], v[132:135]
	v_mfma_f32_16x16x32_bf16 v[116:119], v[214:217], v[160:163], v[116:119]
	v_mfma_f32_16x16x32_bf16 v[68:71], v[206:209], v[198:201], v[68:71]
	v_mfma_f32_16x16x32_bf16 v[64:67], v[214:217], v[198:201], v[64:67]
	v_lshl_add_u64 v[232:233], s[46:47], 0, v[170:171]
	s_mov_b32 m0, s38
	v_mfma_f32_16x16x32_bf16 v[100:103], v[210:213], v[112:115], v[100:103]
	v_lshl_add_u64 v[230:231], s[46:47], 0, v[174:175]
	v_mfma_f32_16x16x32_bf16 v[108:111], v[218:221], v[112:115], v[108:111]
	v_mfma_f32_16x16x32_bf16 v[112:115], v[206:209], v[160:163], v[124:127]
	v_mfma_f32_16x16x32_bf16 v[116:119], v[218:221], v[164:167], v[116:119]
	v_mfma_f32_16x16x32_bf16 v[68:71], v[210:213], v[202:205], v[68:71]
	v_mfma_f32_16x16x32_bf16 v[64:67], v[218:221], v[202:205], v[64:67]
	v_mfma_f32_16x16x32_bf16 v[112:115], v[210:213], v[164:167], v[112:115]
	s_barrier
	s_setprio 0
	ds_read_b128 v[124:127], v190 offset:16384
	global_load_lds_dwordx4 v[230:231], off
	ds_read_b128 v[132:135], v190 offset:17408
	ds_read_b128 v[140:143], v190 offset:18432
	ds_read_b128 v[152:155], v190 offset:19456
	ds_read_b128 v[160:163], v190 offset:20480
	ds_read_b128 v[164:167], v190 offset:21504
	ds_read_b128 v[198:201], v190 offset:22528
	ds_read_b128 v[202:205], v190 offset:23552
	s_mov_b32 m0, s39
	s_nop 0
	global_load_lds_dwordx4 v[232:233], off
	s_waitcnt vmcnt(10)
	s_setprio 1
	s_barrier
	s_waitcnt lgkmcnt(7)
	v_mfma_f32_16x16x32_bf16 v[60:63], v[80:83], v[124:127], v[60:63]
	v_mfma_f32_16x16x32_bf16 v[48:51], v[88:91], v[124:127], v[48:51]
	s_waitcnt lgkmcnt(5)
	v_mfma_f32_16x16x32_bf16 v[40:43], v[80:83], v[140:143], v[40:43]
	v_mfma_f32_16x16x32_bf16 v[32:35], v[88:91], v[140:143], v[32:35]
	s_waitcnt lgkmcnt(3)
	v_mfma_f32_16x16x32_bf16 v[24:27], v[80:83], v[160:163], v[24:27]
	v_mfma_f32_16x16x32_bf16 v[16:19], v[88:91], v[160:163], v[16:19]
	s_waitcnt lgkmcnt(1)
	v_mfma_f32_16x16x32_bf16 v[12:15], v[80:83], v[198:201], v[12:15]
	v_mfma_f32_16x16x32_bf16 v[8:11], v[88:91], v[198:201], v[8:11]
	v_mfma_f32_16x16x32_bf16 v[60:63], v[84:87], v[132:135], v[60:63]
	s_add_u32 s68, s28, 0x80000
	s_addc_u32 s69, s29, 0
	v_mfma_f32_16x16x32_bf16 v[48:51], v[92:95], v[132:135], v[48:51]
	s_add_i32 s70, s67, s37
	v_mfma_f32_16x16x32_bf16 v[40:43], v[84:87], v[152:155], v[40:43]
	v_mfma_f32_16x16x32_bf16 v[32:35], v[92:95], v[152:155], v[32:35]
	v_mfma_f32_16x16x32_bf16 v[24:27], v[84:87], v[164:167], v[24:27]
	v_mfma_f32_16x16x32_bf16 v[16:19], v[92:95], v[164:167], v[16:19]
	s_waitcnt lgkmcnt(0)
	v_mfma_f32_16x16x32_bf16 v[12:15], v[84:87], v[202:205], v[12:15]
	v_mfma_f32_16x16x32_bf16 v[8:11], v[92:95], v[202:205], v[8:11]
	s_barrier
; #define PG8_STAGE(bufoff, gbase, voff) do { _Pragma("unroll") for (int _i = 0; _i < 2; ++_i) \
;         __builtin_amdgcn_global_load_lds((const unsigned*)((const char*)(gbase) + (voff)[_i]), (LAS unsigned*)(lds + (bufoff) + ldsw + _i * 8192), 16, 0, 0); } while (0)
; #define PG8_LDA(dst, b, h) do { _Pragma("unroll") for (int m = 0; m < 4; ++m) _Pragma("unroll") for (int k = 0; k < 2; ++k) dst[m][k] = *(const LAS bf16x8*)(lds + PG8_SA(b, h) + aoff + m * 2048 + k * 1024); } while (0)
; #define PG8_LDB(dst, b, h) do { _Pragma("unroll") for (int n = 0; n < 2; ++n) _Pragma("unroll") for (int k = 0; k < 2; ++k) dst[n][k] = *(const LAS bf16x8*)(lds + PG8_SB(b, h) + boff + n * 2048 + k * 1024); } while (0)
; #define PG8_MMA(ai, bj, At, Bt) do { __builtin_amdgcn_s_setprio(1); _Pragma("unroll") for (int m = 0; m < 4; ++m) _Pragma("unroll") for (int n = 0; n < 2; ++n) _Pragma("unroll") for (int k = 0; k < 2; ++k) \
;         acc[ai][bj][m][n] = __builtin_amdgcn_mfma_f32_16x16x32_bf16(Bt[n][k], At[m][k], acc[ai][bj][m][n], 0, 0, 0); __builtin_amdgcn_s_setprio(0); } while (0)
; #define PG8_WAIT_V(n) asm volatile("s_waitcnt vmcnt(" #n ")" ::: "memory")
; #define PG8_WAIT_L(n) asm volatile("s_waitcnt lgkmcnt(" #n ")" ::: "memory")
; #define PG8_BAR __builtin_amdgcn_s_barrier()
; #define PG8_SCHED __builtin_amdgcn_sched_barrier(0)
; template <class Map, class Epi>
; DI void gemm_phase(LAS unsigned char* lds, const Map& MP, const Epi& E, const int nM, const int nN, const int K, const int lda, const int ldb) {
;     ...
;             PG8_STAGE(PG8_SB(0, 1), b2 + hstepB, voffB);
;             PG8_WAIT_V(6); PG8_BAR; PG8_MMA(1, 1, At, B1); PG8_BAR;
;             PG8_LDB(B0, 1, 0); PG8_SCHED; PG8_LDA(At, 1, 0); PG8_STAGE(PG8_SA(0, 1), a2 + hstepA, voffA);
;             PG8_WAIT_L(8); PG8_BAR; PG8_WAIT_L(0); PG8_MMA(0, 0, At, B0); PG8_BAR; PG8_SCHED;
;             PG8_LDB(B1, 1, 1); PG8_STAGE(PG8_SB(1, 0), b3, voffB);
;             PG8_BAR; PG8_WAIT_L(0); PG8_MMA(0, 1, At, B1); PG8_BAR;
;             PG8_LDA(At, 1, 1); PG8_STAGE(PG8_SA(1, 0), a3, voffA);
;             PG8_BAR; PG8_WAIT_L(0); PG8_MMA(1, 0, At, B0); PG8_BAR; PG8_SCHED;
	s_setprio 0
	s_mov_b32 m0, s70
	s_nop 0
	global_load_lds_dwordx4 v172, s[68:69]
	s_add_i32 m0, s70, 0x2000
	s_nop 0
	global_load_lds_dwordx4 v168, s[68:69]
	s_waitcnt vmcnt(6)
	s_setprio 1
	s_barrier
	v_mfma_f32_16x16x32_bf16 v[56:59], v[206:209], v[124:127], v[56:59]
	v_mfma_f32_16x16x32_bf16 v[52:55], v[214:217], v[124:127], v[52:55]
	s_add_i32 s68, 0, 0x18000
	v_add_u32_e32 v92, s68, v188
	ds_read_b128 v[80:83], v92
	v_mfma_f32_16x16x32_bf16 v[44:47], v[206:209], v[140:143], v[44:47]
	v_mfma_f32_16x16x32_bf16 v[36:39], v[214:217], v[140:143], v[36:39]
	ds_read_b128 v[84:87], v92 offset:1024
	v_mfma_f32_16x16x32_bf16 v[28:31], v[206:209], v[160:163], v[28:31]
	v_mfma_f32_16x16x32_bf16 v[20:23], v[214:217], v[160:163], v[20:23]
	ds_read_b128 v[88:91], v92 offset:2048
	v_mfma_f32_16x16x32_bf16 v[4:7], v[206:209], v[198:201], v[4:7]
	v_mfma_f32_16x16x32_bf16 v[0:3], v[214:217], v[198:201], v[0:3]
	ds_read_b128 v[92:95], v92 offset:3072
	v_mfma_f32_16x16x32_bf16 v[56:59], v[210:213], v[132:135], v[56:59]
	s_add_u32 s46, s46, 0x80000
	s_addc_u32 s47, s47, 0
	v_mfma_f32_16x16x32_bf16 v[52:55], v[218:221], v[132:135], v[52:55]
	v_mfma_f32_16x16x32_bf16 v[44:47], v[210:213], v[152:155], v[44:47]
	v_mfma_f32_16x16x32_bf16 v[36:39], v[218:221], v[152:155], v[36:39]
	v_mfma_f32_16x16x32_bf16 v[28:31], v[210:213], v[164:167], v[28:31]
	v_mfma_f32_16x16x32_bf16 v[20:23], v[218:221], v[164:167], v[20:23]
	v_mfma_f32_16x16x32_bf16 v[4:7], v[210:213], v[202:205], v[4:7]
	v_mfma_f32_16x16x32_bf16 v[0:3], v[218:221], v[202:205], v[0:3]
	s_barrier
	s_setprio 0
	s_mov_b32 m0, s55
	ds_read_b128 v[124:127], v190 offset:32768
	global_load_lds_dwordx4 v174, s[46:47]
	ds_read_b128 v[132:135], v190 offset:33792
	ds_read_b128 v[160:163], v190 offset:34816
	ds_read_b128 v[164:167], v190 offset:35840
	ds_read_b128 v[198:201], v190 offset:36864
	ds_read_b128 v[202:205], v190 offset:37888
	ds_read_b128 v[206:209], v190 offset:38912
	ds_read_b128 v[210:213], v190 offset:39936
	s_mov_b32 m0, s56
	s_nop 0
	global_load_lds_dwordx4 v170, s[46:47]
	s_waitcnt lgkmcnt(8)
	s_setprio 1
	s_barrier
	s_waitcnt lgkmcnt(7)
	v_mfma_f32_16x16x32_bf16 v[140:143], v[80:83], v[124:127], v[148:151]
	s_waitcnt lgkmcnt(6)
	v_mfma_f32_16x16x32_bf16 v[148:151], v[84:87], v[132:135], v[140:143]
	v_mfma_f32_16x16x32_bf16 v[140:143], v[88:91], v[124:127], v[144:147]
	s_waitcnt lgkmcnt(5)
	v_mfma_f32_16x16x32_bf16 v[136:139], v[80:83], v[160:163], v[136:139]
	v_mfma_f32_16x16x32_bf16 v[128:131], v[88:91], v[160:163], v[128:131]
	s_waitcnt lgkmcnt(3)
	v_mfma_f32_16x16x32_bf16 v[120:123], v[80:83], v[198:201], v[120:123]
	v_mfma_f32_16x16x32_bf16 v[104:107], v[88:91], v[198:201], v[104:107]
	s_waitcnt lgkmcnt(1)
	v_mfma_f32_16x16x32_bf16 v[76:79], v[80:83], v[206:209], v[76:79]
	v_mfma_f32_16x16x32_bf16 v[72:75], v[88:91], v[206:209], v[72:75]
	s_add_i32 s46, 0, 0x1c000
	v_mfma_f32_16x16x32_bf16 v[144:147], v[92:95], v[132:135], v[140:143]
	v_add_u32_e32 v140, s46, v188
	v_mfma_f32_16x16x32_bf16 v[136:139], v[84:87], v[164:167], v[136:139]
	s_add_i32 s47, s68, s37
	v_mfma_f32_16x16x32_bf16 v[128:131], v[92:95], v[164:167], v[128:131]
	v_mfma_f32_16x16x32_bf16 v[120:123], v[84:87], v[202:205], v[120:123]
	v_mfma_f32_16x16x32_bf16 v[104:107], v[92:95], v[202:205], v[104:107]
	s_waitcnt lgkmcnt(0)
	v_mfma_f32_16x16x32_bf16 v[76:79], v[84:87], v[210:213], v[76:79]
	v_mfma_f32_16x16x32_bf16 v[72:75], v[92:95], v[210:213], v[72:75]
	s_barrier
	s_setprio 0
	ds_read_b128 v[214:217], v140
	ds_read_b128 v[218:221], v140 offset:1024
	ds_read_b128 v[222:225], v140 offset:2048
	ds_read_b128 v[226:229], v140 offset:3072
	v_lshl_add_u64 v[140:141], v[184:185], 0, s[14:15]
	s_mov_b32 m0, s47
	s_nop 0
	global_load_lds_dwordx4 v[140:141], off
	v_lshl_add_u64 v[140:141], v[194:195], 0, s[14:15]
	s_add_i32 m0, s47, 0x2000
	s_nop 0
	global_load_lds_dwordx4 v[140:141], off
	s_setprio 1
	s_barrier
	s_waitcnt lgkmcnt(1)
	v_mfma_f32_16x16x32_bf16 v[96:99], v[222:225], v[124:127], v[96:99]
	v_mfma_f32_16x16x32_bf16 v[140:143], v[214:217], v[124:127], v[156:159]
	s_waitcnt lgkmcnt(0)
	v_mfma_f32_16x16x32_bf16 v[152:155], v[226:229], v[132:135], v[96:99]
	v_mfma_f32_16x16x32_bf16 v[96:99], v[214:217], v[160:163], v[100:103]
	v_mfma_f32_16x16x32_bf16 v[156:159], v[218:221], v[132:135], v[140:143]
	v_mfma_f32_16x16x32_bf16 v[140:143], v[218:221], v[164:167], v[96:99]
	v_mfma_f32_16x16x32_bf16 v[96:99], v[222:225], v[160:163], v[108:111]
	v_mfma_f32_16x16x32_bf16 v[132:135], v[226:229], v[164:167], v[96:99]
	v_mfma_f32_16x16x32_bf16 v[96:99], v[214:217], v[198:201], v[112:115]
	s_mov_b32 m0, s62
	v_mfma_f32_16x16x32_bf16 v[124:127], v[218:221], v[202:205], v[96:99]
	v_lshl_add_u64 v[184:185], v[230:231], 0, s[14:15]
	v_mfma_f32_16x16x32_bf16 v[96:99], v[222:225], v[198:201], v[116:119]
	v_mfma_f32_16x16x32_bf16 v[68:71], v[214:217], v[206:209], v[68:71]
	v_mfma_f32_16x16x32_bf16 v[64:67], v[222:225], v[206:209], v[64:67]
	v_mfma_f32_16x16x32_bf16 v[116:119], v[226:229], v[202:205], v[96:99]
	v_mfma_f32_16x16x32_bf16 v[68:71], v[218:221], v[210:213], v[68:71]
	v_mfma_f32_16x16x32_bf16 v[64:67], v[226:229], v[210:213], v[64:67]
	s_barrier
	s_setprio 0
	ds_read_b128 v[96:99], v190 offset:49152
	global_load_lds_dwordx4 v[184:185], off
	ds_read_b128 v[100:103], v190 offset:50176
	ds_read_b128 v[108:111], v190 offset:51200
	ds_read_b128 v[112:115], v190 offset:52224
	ds_read_b128 v[160:163], v190 offset:53248
	ds_read_b128 v[164:167], v190 offset:54272
	ds_read_b128 v[198:201], v190 offset:55296
	ds_read_b128 v[202:205], v190 offset:56320
	v_lshl_add_u64 v[184:185], v[232:233], 0, s[14:15]
	s_mov_b32 m0, s63
	s_nop 0
	global_load_lds_dwordx4 v[184:185], off
	s_waitcnt vmcnt(10)
	s_setprio 1
	s_barrier
; #define PG8_STAGE(bufoff, gbase, voff) do { _Pragma("unroll") for (int _i = 0; _i < 2; ++_i) \
;         __builtin_amdgcn_global_load_lds((const unsigned*)((const char*)(gbase) + (voff)[_i]), (LAS unsigned*)(lds + (bufoff) + ldsw + _i * 8192), 16, 0, 0); } while (0)
; #define PG8_MMA(ai, bj, At, Bt) do { __builtin_amdgcn_s_setprio(1); _Pragma("unroll") for (int m = 0; m < 4; ++m) _Pragma("unroll") for (int n = 0; n < 2; ++n) _Pragma("unroll") for (int k = 0; k < 2; ++k) \
;         acc[ai][bj][m][n] = __builtin_amdgcn_mfma_f32_16x16x32_bf16(Bt[n][k], At[m][k], acc[ai][bj][m][n], 0, 0, 0); __builtin_amdgcn_s_setprio(0); } while (0)
; #define PG8_WAIT_V(n) asm volatile("s_waitcnt vmcnt(" #n ")" ::: "memory")
; #define PG8_WAIT_L(n) asm volatile("s_waitcnt lgkmcnt(" #n ")" ::: "memory")
; #define PG8_BAR __builtin_amdgcn_s_barrier()
; #define PG8_SCHED __builtin_amdgcn_sched_barrier(0)
; template <class Map, class Epi>
; DI void gemm_phase(LAS unsigned char* lds, const Map& MP, const Epi& E, const int nM, const int nN, const int K, const int lda, const int ldb) {
;     ...
;             PG8_BAR; PG8_WAIT_L(0); PG8_MMA(1, 0, At, B0); PG8_BAR; PG8_SCHED;
;             PG8_STAGE(PG8_SB(1, 1), b3 + hstepB, voffB);
;             PG8_WAIT_V(6); PG8_BAR; PG8_MMA(1, 1, At, B1); PG8_BAR;
	s_waitcnt lgkmcnt(7)
	v_mfma_f32_16x16x32_bf16 v[60:63], v[80:83], v[96:99], v[60:63]
	v_mfma_f32_16x16x32_bf16 v[48:51], v[88:91], v[96:99], v[48:51]
	s_waitcnt lgkmcnt(5)
	v_mfma_f32_16x16x32_bf16 v[40:43], v[80:83], v[108:111], v[40:43]
	v_mfma_f32_16x16x32_bf16 v[32:35], v[88:91], v[108:111], v[32:35]
	s_waitcnt lgkmcnt(3)
	v_mfma_f32_16x16x32_bf16 v[24:27], v[80:83], v[160:163], v[24:27]
	v_mfma_f32_16x16x32_bf16 v[16:19], v[88:91], v[160:163], v[16:19]
	s_waitcnt lgkmcnt(1)
	v_mfma_f32_16x16x32_bf16 v[12:15], v[80:83], v[198:201], v[12:15]
	v_mfma_f32_16x16x32_bf16 v[8:11], v[88:91], v[198:201], v[8:11]
	v_mfma_f32_16x16x32_bf16 v[60:63], v[84:87], v[100:103], v[60:63]
	s_add_u32 s28, s28, 0x80080
	s_addc_u32 s29, s29, 0
	v_mfma_f32_16x16x32_bf16 v[48:51], v[92:95], v[100:103], v[48:51]
	s_add_i32 s46, s46, s37
	v_mfma_f32_16x16x32_bf16 v[40:43], v[84:87], v[112:115], v[40:43]
	v_mfma_f32_16x16x32_bf16 v[32:35], v[92:95], v[112:115], v[32:35]
	v_mfma_f32_16x16x32_bf16 v[24:27], v[84:87], v[164:167], v[24:27]
	v_mfma_f32_16x16x32_bf16 v[16:19], v[92:95], v[164:167], v[16:19]
	s_waitcnt lgkmcnt(0)
	v_mfma_f32_16x16x32_bf16 v[12:15], v[84:87], v[202:205], v[12:15]
	v_mfma_f32_16x16x32_bf16 v[8:11], v[92:95], v[202:205], v[8:11]
	s_barrier
	s_setprio 0
	s_mov_b32 m0, s46
	s_nop 0
	global_load_lds_dwordx4 v172, s[28:29]
	s_add_i32 m0, s46, 0x2000
	s_nop 0
	global_load_lds_dwordx4 v168, s[28:29]
	s_waitcnt vmcnt(6)
	s_setprio 1
	s_barrier
	v_mfma_f32_16x16x32_bf16 v[56:59], v[214:217], v[96:99], v[56:59]
	v_mfma_f32_16x16x32_bf16 v[52:55], v[222:225], v[96:99], v[52:55]
	ds_read_b128 v[80:83], v189
	v_mfma_f32_16x16x32_bf16 v[44:47], v[214:217], v[108:111], v[44:47]
	v_mfma_f32_16x16x32_bf16 v[36:39], v[222:225], v[108:111], v[36:39]
	ds_read_b128 v[84:87], v189 offset:1024
	v_mfma_f32_16x16x32_bf16 v[28:31], v[214:217], v[160:163], v[28:31]
	v_mfma_f32_16x16x32_bf16 v[20:23], v[222:225], v[160:163], v[20:23]
	ds_read_b128 v[88:91], v189 offset:2048
	v_mfma_f32_16x16x32_bf16 v[4:7], v[214:217], v[198:201], v[4:7]
	v_mfma_f32_16x16x32_bf16 v[0:3], v[222:225], v[198:201], v[0:3]
	ds_read_b128 v[92:95], v189 offset:3072
	v_mfma_f32_16x16x32_bf16 v[56:59], v[218:221], v[100:103], v[56:59]
	s_add_i32 s3, s3, 2
	v_mfma_f32_16x16x32_bf16 v[52:55], v[226:229], v[100:103], v[52:55]
	s_add_u32 vcc_lo, vcc_lo, 0x100
	s_addc_u32 vcc_hi, vcc_hi, 0
	v_mfma_f32_16x16x32_bf16 v[44:47], v[218:221], v[112:115], v[44:47]
	s_add_u32 s42, s42, 0x100
	s_addc_u32 s43, s43, 0
	v_mfma_f32_16x16x32_bf16 v[36:39], v[226:229], v[112:115], v[36:39]
	s_cmp_gt_u32 s3, 29
	v_mfma_f32_16x16x32_bf16 v[28:31], v[218:221], v[164:167], v[28:31]
	v_mfma_f32_16x16x32_bf16 v[20:23], v[226:229], v[164:167], v[20:23]
	v_mfma_f32_16x16x32_bf16 v[4:7], v[218:221], v[202:205], v[4:7]
	v_mfma_f32_16x16x32_bf16 v[0:3], v[226:229], v[202:205], v[0:3]
	s_barrier
	s_setprio 0
	s_cbranch_scc0 .LBB1_2483
; DI float silu_mul(float g, float v) { return g * v * __builtin_amdgcn_rcpf(1.0f + __builtin_amdgcn_exp2f(-LOG2E * g)); }
;     DI void operator()(const f32x4 (&acc)[2][2][4][2], const Unit& u, int wr, int wc, int fr, int fq) const {
;         const int row0 = u.pm * BM + wr * 64 + fr, ch0 = u.pn * 128 + wc * 32 + 8 * fq;
;         f32x4 w0[2], w1[2], w2[2], bb[2];
; #pragma unroll
;         for (int n = 0; n < 2; ++n) { w0[n] = *(const f32x4*)(cw + ch0 + 4 * n); w1[n] = *(const f32x4*)(cw + DFF + ch0 + 4 * n); w2[n] = *(const f32x4*)(cw + 2 * DFF + ch0 + 4 * n); bb[n] = *(const f32x4*)(cb + ch0 + 4 * n); }
; #pragma unroll
;         for (int ai = 0; ai < 2; ++ai)
; #pragma unroll
;             for (int m = 0; m < 4; ++m) {
;                 const bool efirst = (m == 0) && (fr == 0), elast = (m == 3) && (fr == 15);
;                 const int row = row0 + ai * HALF + m * 16;
;                 f32x4 gc[2];
; #pragma unroll
;                 for (int n = 0; n < 2; ++n) {
;                     const f32x4 g = acc[ai][0][m][n];
;                     const f32x4 gprev = acc[ai][0][m > 0 ? m - 1 : 0][n], gnext = acc[ai][0][m < 3 ? m + 1 : 3][n];
;                     f32x4 up, dn;
; #pragma unroll
;                     for (int e = 0; e < 4; ++e) {
;                         const float pu = (m > 0 && fr == 15) ? gprev[e] : g[e];
;                         const float pd = (m < 3 && fr == 0) ? gnext[e] : g[e];
;                         up[e] = dpp_ror1(pu); dn[e] = dpp_ror15(pd);
;                     }
;                     if (efirst) up = (f32x4){0.f, 0.f, 0.f, 0.f};
;                     if (elast) dn = (f32x4){0.f, 0.f, 0.f, 0.f};
;                     gc[n] = w0[n] * up + w1[n] * g + w2[n] * dn + bb[n];
;                 }
;                 if (efirst || elast) {
;                     const size_t eo = (size_t)((row >> 6) * 2 + (elast ? 1 : 0)) * DFF + ch0;
; #pragma unroll
;                     for (int n = 0; n < 2; ++n) { *(f32x4*)(EP + eo + 4 * n) = gc[n]; *(f32x4*)(ER + eo + 4 * n) = acc[ai][0][m][n]; *(f32x4*)(EV + eo + 4 * n) = acc[ai][1][m][n]; }
;                 } else {
;                     const f32x4 v0 = acc[ai][1][m][0], v1 = acc[ai][1][m][1];
;                     u32x4 o;
;                     o[0] = pack2(silu_mul(gc[0][0], v0[0]), silu_mul(gc[0][1], v0[1])); o[1] = pack2(silu_mul(gc[0][2], v0[2]), silu_mul(gc[0][3], v0[3]));
	s_waitcnt lgkmcnt(0)
	s_lshl_b32 s21, s45, 7
	v_mov_b32_e32 v80, v187
	v_mov_b32_e32 v194, v186
	s_or_b32 s21, s21, s57
	v_lshl_add_u32 v184, v80, 3, s21
	v_ashrrev_i32_e32 v185, 31, v184
	v_lshlrev_b64 v[80:81], 2, v[184:185]
	v_lshl_add_u64 v[84:85], s[4:5], 0, v[80:81]
	v_lshl_add_u64 v[88:89], s[16:17], 0, v[80:81]
	v_lshl_add_u64 v[92:93], s[18:19], 0, v[80:81]
	v_lshl_add_u64 v[112:113], s[6:7], 0, v[80:81]
	global_load_dwordx4 v[80:83], v[84:85], off offset:16
	global_load_dwordx4 v[96:99], v[84:85], off
	s_nop 0
	global_load_dwordx4 v[84:87], v[88:89], off offset:16
	global_load_dwordx4 v[100:103], v[88:89], off
	s_nop 0
	global_load_dwordx4 v[88:91], v[92:93], off offset:16
	global_load_dwordx4 v[108:111], v[92:93], off
	s_nop 0
	global_load_dwordx4 v[92:95], v[112:113], off offset:16
	s_nop 0
	global_load_dwordx4 v[112:115], v[112:113], off
	v_cmp_eq_u32_e32 vcc, 0, v194
	s_nop 0
	s_nop 0
	v_cndmask_b32_e32 v161, v148, v136, vcc
	v_cndmask_b32_e32 v162, v149, v137, vcc
	v_cndmask_b32_e32 v163, v150, v138, vcc
	v_mov_b32_dpp v160, v161 row_ror:15 row_mask:0xf bank_mask:0xf
	s_nop 0
	s_nop 0
	v_mov_b32_dpp v161, v162 row_ror:15 row_mask:0xf bank_mask:0xf
	v_mov_b32_dpp v164, v150 row_ror:1 row_mask:0xf bank_mask:0xf
	v_cndmask_b32_e32 v165, v151, v139, vcc
	v_mov_b32_dpp v162, v163 row_ror:15 row_mask:0xf bank_mask:0xf
	v_mov_b32_dpp v195, v151 row_ror:1 row_mask:0xf bank_mask:0xf
	v_mov_b32_dpp v166, v148 row_ror:1 row_mask:0xf bank_mask:0xf
	v_mov_b32_dpp v167, v149 row_ror:1 row_mask:0xf bank_mask:0xf
	v_mov_b32_dpp v163, v165 row_ror:15 row_mask:0xf bank_mask:0xf
	v_cndmask_b32_e64 v165, v195, 0, vcc
	v_cndmask_b32_e64 v164, v164, 0, vcc
	v_cndmask_b32_e64 v167, v167, 0, vcc
	v_cndmask_b32_e64 v166, v166, 0, vcc
	s_nop 0
	s_nop 0
	v_mov_b32_dpp v195, v144 row_ror:1 row_mask:0xf bank_mask:0xf
	v_mov_b32_dpp v196, v145 row_ror:1 row_mask:0xf bank_mask:0xf
	v_mov_b32_dpp v198, v146 row_ror:1 row_mask:0xf bank_mask:0xf
	v_cndmask_b32_e32 v199, v147, v131, vcc
	v_mov_b32_dpp v200, v147 row_ror:1 row_mask:0xf bank_mask:0xf
	v_cndmask_b32_e64 v198, v198, 0, vcc
	v_cndmask_b32_e64 v201, v196, 0, vcc
	s_lshl_b32 s3, s44, 8
	s_add_i32 s3, s3, s49
	v_add_u32_e32 v193, s3, v194
	v_cmp_ne_u32_e64 s[46:47], 0, v194
	s_waitcnt vmcnt(0)
	v_pk_mul_f32 v[164:165], v[98:99], v[164:165]
	v_pk_mul_f32 v[166:167], v[96:97], v[166:167]
	v_pk_fma_f32 v[164:165], v[150:151], v[102:103], v[164:165]
	v_pk_fma_f32 v[166:167], v[148:149], v[100:101], v[166:167]
	v_pk_fma_f32 v[162:163], v[110:111], v[162:163], v[164:165]
	v_cndmask_b32_e32 v165, v144, v128, vcc
	v_pk_fma_f32 v[160:161], v[108:109], v[160:161], v[166:167]
	v_cndmask_b32_e32 v166, v145, v129, vcc
	v_mov_b32_dpp v164, v165 row_ror:15 row_mask:0xf bank_mask:0xf
	v_cndmask_b32_e32 v167, v146, v130, vcc
	v_pk_add_f32 v[162:163], v[114:115], v[162:163]
	v_mov_b32_dpp v165, v166 row_ror:15 row_mask:0xf bank_mask:0xf
	v_pk_add_f32 v[160:161], v[112:113], v[160:161]
	s_nop 0
	v_mov_b32_dpp v166, v167 row_ror:15 row_mask:0xf bank_mask:0xf
	s_nop 1
	v_mov_b32_dpp v167, v199 row_ror:15 row_mask:0xf bank_mask:0xf
	v_cndmask_b32_e64 v199, v200, 0, vcc
	v_cndmask_b32_e64 v200, v195, 0, vcc
	v_pk_mul_f32 v[200:201], v[80:81], v[200:201]
	v_pk_mul_f32 v[198:199], v[82:83], v[198:199]
	v_pk_fma_f32 v[200:201], v[144:145], v[84:85], v[200:201]
	v_pk_fma_f32 v[198:199], v[146:147], v[86:87], v[198:199]
	v_pk_fma_f32 v[164:165], v[88:89], v[164:165], v[200:201]
	v_pk_fma_f32 v[166:167], v[90:91], v[166:167], v[198:199]
	v_pk_add_f32 v[164:165], v[92:93], v[164:165]
	v_pk_add_f32 v[166:167], v[94:95], v[166:167]
	s_and_saveexec_b64 s[28:29], s[46:47]
	s_xor_b64 s[28:29], exec, s[28:29]
	s_cbranch_execz .LBB1_2486
	v_mul_f32_e32 v195, 0xbfb8aa3b, v160
	v_exp_f32_e32 v195, v195
	v_mul_f32_e32 v196, 0xbfb8aa3b, v161
	v_exp_f32_e32 v196, v196
	v_pk_mul_f32 v[160:161], v[156:157], v[160:161]
	v_add_f32_e32 v195, 1.0, v195
	v_rcp_f32_e32 v198, v195
	v_add_f32_e32 v196, 1.0, v196
	v_mul_f32_e32 v195, 0xbfb8aa3b, v162
	v_rcp_f32_e32 v199, v196
	v_exp_f32_e32 v195, v195
	v_mul_f32_e32 v196, 0xbfb8aa3b, v163
	v_exp_f32_e32 v196, v196
	v_pk_mul_f32 v[160:161], v[160:161], v[198:199]
	v_add_f32_e32 v195, 1.0, v195
	v_rcp_f32_e32 v200, v195
	v_add_f32_e32 v195, 1.0, v196
	v_rcp_f32_e32 v201, v195
	v_cvt_pk_bf16_f32 v160, v160, v161
	v_mul_f32_e32 v161, 0xbfb8aa3b, v164
	v_exp_f32_e32 v195, v161
	v_mul_f32_e32 v161, 0xbfb8aa3b, v165
	v_exp_f32_e32 v196, v161
	v_pk_mul_f32 v[162:163], v[158:159], v[162:163]
	v_pk_mul_f32 v[164:165], v[152:153], v[164:165]
	v_pk_mul_f32 v[162:163], v[162:163], v[200:201]
	s_nop 0
	v_cvt_pk_bf16_f32 v161, v162, v163
	v_add_f32_e32 v162, 1.0, v195
	v_mul_f32_e32 v195, 0xbfb8aa3b, v166
	v_add_f32_e32 v163, 1.0, v196
	v_exp_f32_e32 v195, v195
	v_mul_f32_e32 v196, 0xbfb8aa3b, v167
	v_exp_f32_e32 v196, v196
	v_rcp_f32_e32 v162, v162
	v_add_f32_e32 v195, 1.0, v195
	v_rcp_f32_e32 v198, v195
	v_add_f32_e32 v195, 1.0, v196
	v_rcp_f32_e32 v163, v163
	v_rcp_f32_e32 v199, v195
	v_pk_mul_f32 v[166:167], v[154:155], v[166:167]
	v_pk_mul_f32 v[162:163], v[164:165], v[162:163]
	v_pk_mul_f32 v[164:165], v[166:167], v[198:199]
	v_cvt_pk_bf16_f32 v162, v162, v163
	v_cvt_pk_bf16_f32 v163, v164, v165
	v_mov_b64_e32 v[164:165], s[52:53]
	v_mad_i64_i32 v[164:165], s[42:43], v193, s60, v[164:165]
	v_lshl_add_u64 v[164:165], v[184:185], 1, v[164:165]
	global_store_dwordx4 v[164:165], v[160:163], off

; #define PG8_STAGE(bufoff, gbase, voff) do { _Pragma("unroll") for (int _i = 0; _i < 2; ++_i) \
;         __builtin_amdgcn_global_load_lds((const unsigned*)((const char*)(gbase) + (voff)[_i]), (LAS unsigned*)(lds + (bufoff) + ldsw + _i * 8192), 16, 0, 0); } while (0)
; #define PG8_LDA(dst, b, h) do { _Pragma("unroll") for (int m = 0; m < 4; ++m) _Pragma("unroll") for (int k = 0; k < 2; ++k) dst[m][k] = *(const LAS bf16x8*)(lds + PG8_SA(b, h) + aoff + m * 2048 + k * 1024); } while (0)
; #define PG8_LDB(dst, b, h) do { _Pragma("unroll") for (int n = 0; n < 2; ++n) _Pragma("unroll") for (int k = 0; k < 2; ++k) dst[n][k] = *(const LAS bf16x8*)(lds + PG8_SB(b, h) + boff + n * 2048 + k * 1024); } while (0)
; #define PG8_MMA(ai, bj, At, Bt) do { __builtin_amdgcn_s_setprio(1); _Pragma("unroll") for (int m = 0; m < 4; ++m) _Pragma("unroll") for (int n = 0; n < 2; ++n) _Pragma("unroll") for (int k = 0; k < 2; ++k) \
;         acc[ai][bj][m][n] = __builtin_amdgcn_mfma_f32_16x16x32_bf16(Bt[n][k], At[m][k], acc[ai][bj][m][n], 0, 0, 0); __builtin_amdgcn_s_setprio(0); } while (0)
; #define PG8_WAIT_V(n) asm volatile("s_waitcnt vmcnt(" #n ")" ::: "memory")
; #define PG8_WAIT_L(n) asm volatile("s_waitcnt lgkmcnt(" #n ")" ::: "memory")
; #define PG8_BAR __builtin_amdgcn_s_barrier()
; template <class Map, class Epi>
; DI void gemm_phase(LAS unsigned char* lds, const Map& MP, const Epi& E, const int nM, const int nN, const int K, const int lda, const int ldb) {
;     ...
;             const char* a1 = cA + (size_t)(t + 1) * kstep;
;             const char* a2 = last ? nA : cA + (size_t)(t + 2) * kstep; const char* b2 = last ? nB : cB + (size_t)(t + 2) * kstep;
;             const char* a3 = a2 + kstep; const char* b3 = b2 + kstep;
;             PG8_LDB(B0, 0, 0); PG8_SCHED; PG8_LDA(At, 0, 0); PG8_STAGE(PG8_SA(1, 1), a1 + hstepA, voffA);
;             PG8_WAIT_L(8); PG8_BAR; PG8_WAIT_L(0); PG8_MMA(0, 0, At, B0); PG8_BAR; PG8_SCHED;
;             PG8_LDB(B1, 0, 1); PG8_STAGE(PG8_SB(0, 0), b2, voffB);
;             PG8_BAR; PG8_WAIT_L(0); PG8_MMA(0, 1, At, B1); PG8_BAR;
;             PG8_LDA(At, 0, 1); PG8_STAGE(PG8_SA(0, 0), a2, voffA);
;             PG8_BAR; PG8_WAIT_L(0); PG8_MMA(1, 0, At, B0); PG8_BAR; PG8_SCHED;
;             PG8_STAGE(PG8_SB(0, 1), b2 + hstepB, voffB);
;             PG8_WAIT_V(6); PG8_BAR; PG8_MMA(1, 1, At, B1); PG8_BAR;
.LBB1_2653:
	s_add_u32 s10, s8, 0x100
	s_addc_u32 s11, s9, 0
	s_cmpk_eq_i32 s48, 0x54
	s_cselect_b32 s15, s43, s11
	s_cselect_b32 s14, s42, s10
	s_cselect_b32 s13, s45, s39
	s_cselect_b32 s12, s44, s38
	s_add_i32 m0, s22, 0xc000
	ds_read_b128 v[168:171], v150
	global_load_lds_dwordx4 v138, s[8:9]
	ds_read_b128 v[172:175], v150 offset:1024
	ds_read_b128 v[176:179], v150 offset:2048
	ds_read_b128 v[180:183], v150 offset:3072
	ds_read_b128 v[184:187], v150 offset:4096
	ds_read_b128 v[188:191], v150 offset:5120
	ds_read_b128 v[192:195], v150 offset:6144
	ds_read_b128 v[196:199], v150 offset:7168
	s_add_i32 m0, s22, 0xe000
	s_nop 0
	global_load_lds_dwordx4 v136, s[8:9]
	s_waitcnt lgkmcnt(8)
	s_setprio 1
	s_barrier
	s_waitcnt lgkmcnt(7)
	v_mfma_f32_16x16x32_bf16 v[124:127], v[152:155], v[168:171], v[124:127]
	v_mfma_f32_16x16x32_bf16 v[120:123], v[160:163], v[168:171], v[120:123]
	s_waitcnt lgkmcnt(5)
	v_mfma_f32_16x16x32_bf16 v[108:111], v[152:155], v[176:179], v[108:111]
	v_mfma_f32_16x16x32_bf16 v[104:107], v[160:163], v[176:179], v[104:107]
	s_waitcnt lgkmcnt(3)
	v_mfma_f32_16x16x32_bf16 v[92:95], v[152:155], v[184:187], v[92:95]
	v_mfma_f32_16x16x32_bf16 v[88:91], v[160:163], v[184:187], v[88:91]
	s_waitcnt lgkmcnt(1)
	v_mfma_f32_16x16x32_bf16 v[76:79], v[152:155], v[192:195], v[76:79]
	v_mfma_f32_16x16x32_bf16 v[72:75], v[160:163], v[192:195], v[72:75]
	v_mfma_f32_16x16x32_bf16 v[124:127], v[156:159], v[172:175], v[124:127]
	s_add_i32 s8, s33, s20
	v_mfma_f32_16x16x32_bf16 v[120:123], v[164:167], v[172:175], v[120:123]
	v_lshl_add_u64 v[144:145], s[12:13], 0, v[132:133]
	v_mfma_f32_16x16x32_bf16 v[108:111], v[156:159], v[180:183], v[108:111]
	v_lshl_add_u64 v[216:217], s[12:13], 0, v[128:129]
	v_mfma_f32_16x16x32_bf16 v[104:107], v[164:167], v[180:183], v[104:107]
	v_mfma_f32_16x16x32_bf16 v[92:95], v[156:159], v[188:191], v[92:95]
	v_mfma_f32_16x16x32_bf16 v[88:91], v[164:167], v[188:191], v[88:91]
	s_waitcnt lgkmcnt(0)
	v_mfma_f32_16x16x32_bf16 v[76:79], v[156:159], v[196:199], v[76:79]
	v_mfma_f32_16x16x32_bf16 v[72:75], v[164:167], v[196:199], v[72:75]
	s_barrier
	s_setprio 0
	s_mov_b32 m0, s8
	ds_read_b128 v[200:203], v151
	global_load_lds_dwordx4 v[144:145], off
	ds_read_b128 v[204:207], v151 offset:1024
	ds_read_b128 v[208:211], v151 offset:2048
	ds_read_b128 v[212:215], v151 offset:3072
	s_add_i32 m0, s8, 0x2000
	s_nop 0
	global_load_lds_dwordx4 v[216:217], off
	s_setprio 1
	s_barrier
	s_waitcnt lgkmcnt(3)
	v_mfma_f32_16x16x32_bf16 v[116:119], v[200:203], v[168:171], v[116:119]
	s_waitcnt lgkmcnt(1)
	v_mfma_f32_16x16x32_bf16 v[112:115], v[208:211], v[168:171], v[112:115]
	v_mfma_f32_16x16x32_bf16 v[100:103], v[200:203], v[176:179], v[100:103]
	v_mfma_f32_16x16x32_bf16 v[96:99], v[208:211], v[176:179], v[96:99]
	v_mfma_f32_16x16x32_bf16 v[84:87], v[200:203], v[184:187], v[84:87]
	v_mfma_f32_16x16x32_bf16 v[80:83], v[208:211], v[184:187], v[80:83]
	v_mfma_f32_16x16x32_bf16 v[68:71], v[200:203], v[192:195], v[68:71]
	v_mfma_f32_16x16x32_bf16 v[64:67], v[208:211], v[192:195], v[64:67]
	v_mfma_f32_16x16x32_bf16 v[116:119], v[204:207], v[172:175], v[116:119]
	v_lshl_add_u64 v[220:221], s[14:15], 0, v[130:131]
	s_mov_b32 m0, s22
	s_waitcnt lgkmcnt(0)
	v_mfma_f32_16x16x32_bf16 v[112:115], v[212:215], v[172:175], v[112:115]
	v_lshl_add_u64 v[218:219], s[14:15], 0, v[134:135]
	v_mfma_f32_16x16x32_bf16 v[100:103], v[204:207], v[180:183], v[100:103]
	v_mfma_f32_16x16x32_bf16 v[96:99], v[212:215], v[180:183], v[96:99]
	v_mfma_f32_16x16x32_bf16 v[84:87], v[204:207], v[188:191], v[84:87]
	v_mfma_f32_16x16x32_bf16 v[80:83], v[212:215], v[188:191], v[80:83]
	v_mfma_f32_16x16x32_bf16 v[68:71], v[204:207], v[196:199], v[68:71]
	v_mfma_f32_16x16x32_bf16 v[64:67], v[212:215], v[196:199], v[64:67]
	s_barrier
	s_setprio 0
	ds_read_b128 v[168:171], v150 offset:16384
	global_load_lds_dwordx4 v[218:219], off
	ds_read_b128 v[172:175], v150 offset:17408
	ds_read_b128 v[176:179], v150 offset:18432
	ds_read_b128 v[180:183], v150 offset:19456
	ds_read_b128 v[184:187], v150 offset:20480
	ds_read_b128 v[188:191], v150 offset:21504
	ds_read_b128 v[192:195], v150 offset:22528
	ds_read_b128 v[196:199], v150 offset:23552
	s_mov_b32 m0, s23
	s_nop 0
	global_load_lds_dwordx4 v[220:221], off
	s_waitcnt vmcnt(10)
	s_setprio 1
	s_barrier
	s_waitcnt lgkmcnt(7)
	v_mfma_f32_16x16x32_bf16 v[60:63], v[152:155], v[168:171], v[60:63]
	v_mfma_f32_16x16x32_bf16 v[56:59], v[160:163], v[168:171], v[56:59]
	s_waitcnt lgkmcnt(5)
	v_mfma_f32_16x16x32_bf16 v[44:47], v[152:155], v[176:179], v[44:47]
	v_mfma_f32_16x16x32_bf16 v[40:43], v[160:163], v[176:179], v[40:43]
	s_waitcnt lgkmcnt(3)
	v_mfma_f32_16x16x32_bf16 v[28:31], v[152:155], v[184:187], v[28:31]
	v_mfma_f32_16x16x32_bf16 v[24:27], v[160:163], v[184:187], v[24:27]
	s_waitcnt lgkmcnt(1)
	v_mfma_f32_16x16x32_bf16 v[12:15], v[152:155], v[192:195], v[12:15]
	v_mfma_f32_16x16x32_bf16 v[8:11], v[160:163], v[192:195], v[8:11]
	v_mfma_f32_16x16x32_bf16 v[60:63], v[156:159], v[172:175], v[60:63]
	s_add_u32 s8, s12, 0x160000
	s_addc_u32 s9, s13, 0
	v_mfma_f32_16x16x32_bf16 v[56:59], v[164:167], v[172:175], v[56:59]
	s_add_i32 s49, s34, s20
	v_mfma_f32_16x16x32_bf16 v[44:47], v[156:159], v[180:183], v[44:47]
	v_mfma_f32_16x16x32_bf16 v[40:43], v[164:167], v[180:183], v[40:43]
	v_mfma_f32_16x16x32_bf16 v[28:31], v[156:159], v[188:191], v[28:31]
	v_mfma_f32_16x16x32_bf16 v[24:27], v[164:167], v[188:191], v[24:27]
	s_waitcnt lgkmcnt(0)
	v_mfma_f32_16x16x32_bf16 v[12:15], v[156:159], v[196:199], v[12:15]
	v_mfma_f32_16x16x32_bf16 v[8:11], v[164:167], v[196:199], v[8:11]
	s_barrier
; #define PG8_STAGE(bufoff, gbase, voff) do { _Pragma("unroll") for (int _i = 0; _i < 2; ++_i) \
;         __builtin_amdgcn_global_load_lds((const unsigned*)((const char*)(gbase) + (voff)[_i]), (LAS unsigned*)(lds + (bufoff) + ldsw + _i * 8192), 16, 0, 0); } while (0)
; #define PG8_LDA(dst, b, h) do { _Pragma("unroll") for (int m = 0; m < 4; ++m) _Pragma("unroll") for (int k = 0; k < 2; ++k) dst[m][k] = *(const LAS bf16x8*)(lds + PG8_SA(b, h) + aoff + m * 2048 + k * 1024); } while (0)
; #define PG8_LDB(dst, b, h) do { _Pragma("unroll") for (int n = 0; n < 2; ++n) _Pragma("unroll") for (int k = 0; k < 2; ++k) dst[n][k] = *(const LAS bf16x8*)(lds + PG8_SB(b, h) + boff + n * 2048 + k * 1024); } while (0)
; #define PG8_MMA(ai, bj, At, Bt) do { __builtin_amdgcn_s_setprio(1); _Pragma("unroll") for (int m = 0; m < 4; ++m) _Pragma("unroll") for (int n = 0; n < 2; ++n) _Pragma("unroll") for (int k = 0; k < 2; ++k) \
;         acc[ai][bj][m][n] = __builtin_amdgcn_mfma_f32_16x16x32_bf16(Bt[n][k], At[m][k], acc[ai][bj][m][n], 0, 0, 0); __builtin_amdgcn_s_setprio(0); } while (0)
; #define PG8_WAIT_V(n) asm volatile("s_waitcnt vmcnt(" #n ")" ::: "memory")
; #define PG8_WAIT_L(n) asm volatile("s_waitcnt lgkmcnt(" #n ")" ::: "memory")
; #define PG8_BAR __builtin_amdgcn_s_barrier()
; #define PG8_SCHED __builtin_amdgcn_sched_barrier(0)
; template <class Map, class Epi>
; DI void gemm_phase(LAS unsigned char* lds, const Map& MP, const Epi& E, const int nM, const int nN, const int K, const int lda, const int ldb) {
;     ...
;             PG8_STAGE(PG8_SB(0, 1), b2 + hstepB, voffB);
;             PG8_WAIT_V(6); PG8_BAR; PG8_MMA(1, 1, At, B1); PG8_BAR;
;             PG8_LDB(B0, 1, 0); PG8_SCHED; PG8_LDA(At, 1, 0); PG8_STAGE(PG8_SA(0, 1), a2 + hstepA, voffA);
;             PG8_WAIT_L(8); PG8_BAR; PG8_WAIT_L(0); PG8_MMA(0, 0, At, B0); PG8_BAR; PG8_SCHED;
;             PG8_LDB(B1, 1, 1); PG8_STAGE(PG8_SB(1, 0), b3, voffB);
;             PG8_BAR; PG8_WAIT_L(0); PG8_MMA(0, 1, At, B1); PG8_BAR;
;             PG8_LDA(At, 1, 1); PG8_STAGE(PG8_SA(1, 0), a3, voffA);
;             PG8_BAR; PG8_WAIT_L(0); PG8_MMA(1, 0, At, B0); PG8_BAR; PG8_SCHED;
	s_setprio 0
	s_mov_b32 m0, s49
	s_nop 0
	global_load_lds_dwordx4 v132, s[8:9]
	s_add_i32 m0, s49, 0x2000
	s_nop 0
	global_load_lds_dwordx4 v128, s[8:9]
	s_waitcnt vmcnt(6)
	s_setprio 1
	s_barrier
	v_mfma_f32_16x16x32_bf16 v[52:55], v[200:203], v[168:171], v[52:55]
	v_mfma_f32_16x16x32_bf16 v[48:51], v[208:211], v[168:171], v[48:51]
	s_add_i32 s49, 0, 0x18000
	v_add_u32_e32 v164, s49, v148
	ds_read_b128 v[152:155], v164
	v_mfma_f32_16x16x32_bf16 v[36:39], v[200:203], v[176:179], v[36:39]
	v_mfma_f32_16x16x32_bf16 v[32:35], v[208:211], v[176:179], v[32:35]
	ds_read_b128 v[156:159], v164 offset:1024
	v_mfma_f32_16x16x32_bf16 v[20:23], v[200:203], v[184:187], v[20:23]
	v_mfma_f32_16x16x32_bf16 v[16:19], v[208:211], v[184:187], v[16:19]
	ds_read_b128 v[160:163], v164 offset:2048
	v_mfma_f32_16x16x32_bf16 v[4:7], v[200:203], v[192:195], v[4:7]
	v_mfma_f32_16x16x32_bf16 v[0:3], v[208:211], v[192:195], v[0:3]
	ds_read_b128 v[164:167], v164 offset:3072
	v_mfma_f32_16x16x32_bf16 v[52:55], v[204:207], v[172:175], v[52:55]
	s_add_u32 s8, s14, 0x160000
	s_addc_u32 s9, s15, 0
	v_mfma_f32_16x16x32_bf16 v[48:51], v[212:215], v[172:175], v[48:51]
	v_mfma_f32_16x16x32_bf16 v[36:39], v[204:207], v[180:183], v[36:39]
	v_mfma_f32_16x16x32_bf16 v[32:35], v[212:215], v[180:183], v[32:35]
	v_mfma_f32_16x16x32_bf16 v[20:23], v[204:207], v[188:191], v[20:23]
	v_mfma_f32_16x16x32_bf16 v[16:19], v[212:215], v[188:191], v[16:19]
	v_mfma_f32_16x16x32_bf16 v[4:7], v[204:207], v[196:199], v[4:7]
	v_mfma_f32_16x16x32_bf16 v[0:3], v[212:215], v[196:199], v[0:3]
	s_barrier
	s_setprio 0
	s_mov_b32 m0, s24
	ds_read_b128 v[168:171], v150 offset:32768
	global_load_lds_dwordx4 v134, s[8:9]
	ds_read_b128 v[172:175], v150 offset:33792
	ds_read_b128 v[176:179], v150 offset:34816
	ds_read_b128 v[180:183], v150 offset:35840
	ds_read_b128 v[184:187], v150 offset:36864
	ds_read_b128 v[188:191], v150 offset:37888
	ds_read_b128 v[192:195], v150 offset:38912
	ds_read_b128 v[196:199], v150 offset:39936
	s_mov_b32 m0, s25
	s_nop 0
	global_load_lds_dwordx4 v130, s[8:9]
	s_waitcnt lgkmcnt(8)
	s_setprio 1
	s_barrier
	s_waitcnt lgkmcnt(7)
	v_mfma_f32_16x16x32_bf16 v[124:127], v[152:155], v[168:171], v[124:127]
	v_mfma_f32_16x16x32_bf16 v[120:123], v[160:163], v[168:171], v[120:123]
	s_waitcnt lgkmcnt(5)
	v_mfma_f32_16x16x32_bf16 v[108:111], v[152:155], v[176:179], v[108:111]
	v_mfma_f32_16x16x32_bf16 v[104:107], v[160:163], v[176:179], v[104:107]
	s_waitcnt lgkmcnt(3)
	v_mfma_f32_16x16x32_bf16 v[92:95], v[152:155], v[184:187], v[92:95]
	v_mfma_f32_16x16x32_bf16 v[88:91], v[160:163], v[184:187], v[88:91]
	s_waitcnt lgkmcnt(1)
	v_mfma_f32_16x16x32_bf16 v[76:79], v[152:155], v[192:195], v[76:79]
	v_mfma_f32_16x16x32_bf16 v[72:75], v[160:163], v[192:195], v[72:75]
	v_mfma_f32_16x16x32_bf16 v[124:127], v[156:159], v[172:175], v[124:127]
	s_add_i32 s14, 0, 0x1c000
	v_mfma_f32_16x16x32_bf16 v[120:123], v[164:167], v[172:175], v[120:123]
	s_add_i32 s8, s49, s20
	v_mfma_f32_16x16x32_bf16 v[108:111], v[156:159], v[180:183], v[108:111]
	v_add_u32_e32 v212, s14, v148
	v_mfma_f32_16x16x32_bf16 v[104:107], v[164:167], v[180:183], v[104:107]
	v_lshl_add_u64 v[144:145], v[144:145], 0, s[46:47]
	v_mfma_f32_16x16x32_bf16 v[92:95], v[156:159], v[188:191], v[92:95]
	v_mfma_f32_16x16x32_bf16 v[88:91], v[164:167], v[188:191], v[88:91]
	s_waitcnt lgkmcnt(0)
	v_mfma_f32_16x16x32_bf16 v[76:79], v[156:159], v[196:199], v[76:79]
	v_mfma_f32_16x16x32_bf16 v[72:75], v[164:167], v[196:199], v[72:75]
	s_barrier
	s_setprio 0
	s_mov_b32 m0, s8
	ds_read_b128 v[200:203], v212
	global_load_lds_dwordx4 v[144:145], off
	ds_read_b128 v[204:207], v212 offset:1024
	ds_read_b128 v[208:211], v212 offset:2048
	ds_read_b128 v[212:215], v212 offset:3072
	v_lshl_add_u64 v[144:145], v[216:217], 0, s[46:47]
	s_add_i32 m0, s8, 0x2000
	s_nop 0
	global_load_lds_dwordx4 v[144:145], off
	s_setprio 1
	s_barrier
	s_waitcnt lgkmcnt(3)
	v_mfma_f32_16x16x32_bf16 v[116:119], v[200:203], v[168:171], v[116:119]
	s_waitcnt lgkmcnt(1)
	v_mfma_f32_16x16x32_bf16 v[112:115], v[208:211], v[168:171], v[112:115]
	v_mfma_f32_16x16x32_bf16 v[100:103], v[200:203], v[176:179], v[100:103]
	v_mfma_f32_16x16x32_bf16 v[96:99], v[208:211], v[176:179], v[96:99]
	v_mfma_f32_16x16x32_bf16 v[84:87], v[200:203], v[184:187], v[84:87]
	v_mfma_f32_16x16x32_bf16 v[80:83], v[208:211], v[184:187], v[80:83]
	v_mfma_f32_16x16x32_bf16 v[68:71], v[200:203], v[192:195], v[68:71]
	v_mfma_f32_16x16x32_bf16 v[64:67], v[208:211], v[192:195], v[64:67]
	v_mfma_f32_16x16x32_bf16 v[116:119], v[204:207], v[172:175], v[116:119]
	s_mov_b32 m0, s29
	s_waitcnt lgkmcnt(0)
	v_mfma_f32_16x16x32_bf16 v[112:115], v[212:215], v[172:175], v[112:115]
	v_lshl_add_u64 v[144:145], v[218:219], 0, s[46:47]
	v_mfma_f32_16x16x32_bf16 v[100:103], v[204:207], v[180:183], v[100:103]
	v_mfma_f32_16x16x32_bf16 v[96:99], v[212:215], v[180:183], v[96:99]
	v_mfma_f32_16x16x32_bf16 v[84:87], v[204:207], v[188:191], v[84:87]
	v_mfma_f32_16x16x32_bf16 v[80:83], v[212:215], v[188:191], v[80:83]
	v_mfma_f32_16x16x32_bf16 v[68:71], v[204:207], v[196:199], v[68:71]
	v_mfma_f32_16x16x32_bf16 v[64:67], v[212:215], v[196:199], v[64:67]
	s_barrier
	s_setprio 0
	ds_read_b128 v[168:171], v150 offset:49152
	global_load_lds_dwordx4 v[144:145], off
	ds_read_b128 v[172:175], v150 offset:50176
	ds_read_b128 v[176:179], v150 offset:51200
	ds_read_b128 v[180:183], v150 offset:52224
	ds_read_b128 v[184:187], v150 offset:53248
	ds_read_b128 v[188:191], v150 offset:54272
	ds_read_b128 v[192:195], v150 offset:55296
	ds_read_b128 v[196:199], v150 offset:56320
	v_lshl_add_u64 v[144:145], v[220:221], 0, s[46:47]
	s_mov_b32 m0, s30
	s_nop 0
	global_load_lds_dwordx4 v[144:145], off
	s_waitcnt vmcnt(10)
	s_setprio 1
	s_barrier
; DI unsigned pack2(float a, float b) { f32x2 v = {a, b}; hwbf16x2 r = __builtin_convertvector(v, hwbf16x2); return __builtin_bit_cast(unsigned, r); }
; DI float bflo(unsigned w) { return __uint_as_float(w << 16); }
; DI float bfhi(unsigned w) { return __uint_as_float(w & 0xffff0000u); }
; #define PG8_STAGE(bufoff, gbase, voff) do { _Pragma("unroll") for (int _i = 0; _i < 2; ++_i) \
;         __builtin_amdgcn_global_load_lds((const unsigned*)((const char*)(gbase) + (voff)[_i]), (LAS unsigned*)(lds + (bufoff) + ldsw + _i * 8192), 16, 0, 0); } while (0)
; #define PG8_WAIT_V(n) asm volatile("s_waitcnt vmcnt(" #n ")" ::: "memory")
; #define PG8_WAIT_L(n) asm volatile("s_waitcnt lgkmcnt(" #n ")" ::: "memory")
; #define PG8_BAR __builtin_amdgcn_s_barrier()
;     DI void operator()(const f32x4 (&acc)[2][2][4][2], const Unit& u, int wr, int wc, int fr, int fq) const {
;     ...
;             for (int m = 0; m < 4; ++m) { const size_t ro = (size_t)(row0 + ai * HALF + m * 16) * D + col0;
; #pragma unroll
;                 for (int bj = 0; bj < 2; ++bj) {
;                     f32x4 x0, x1;
;                     if constexpr (IB) { const u32x4 w = *(const u32x4*)((const bf16_t*)Xin + ro + bj * HALF);
;                         x0 = (f32x4){bflo(w[0]), bfhi(w[0]), bflo(w[1]), bfhi(w[1])}; x1 = (f32x4){bflo(w[2]), bfhi(w[2]), bflo(w[3]), bfhi(w[3])}; }
;                     else { x0 = *(const f32x4*)((const float*)Xin + ro + bj * HALF); x1 = *(const f32x4*)((const float*)Xin + ro + bj * HALF + 4); }
;                     x0 += acc[ai][bj][m][0] * sc[bj][0]; x1 += acc[ai][bj][m][1] * sc[bj][1];
;                     if constexpr (OB) { u32x4 o; o[0] = pack2(x0[0], x0[1]); o[1] = pack2(x0[2], x0[3]); o[2] = pack2(x1[0], x1[1]); o[3] = pack2(x1[2], x1[3]);
;                         *(u32x4*)((bf16_t*)Xout + ro + bj * HALF) = o; }
;                     else { *(f32x4*)((float*)Xout + ro + bj * HALF) = x0; *(f32x4*)((float*)Xout + ro + bj * HALF + 4) = x1; } } }
; template <class Map, class Epi>
; DI void gemm_phase(LAS unsigned char* lds, const Map& MP, const Epi& E, const int nM, const int nN, const int K, const int lda, const int ldb) {
;     ...
;             PG8_BAR; PG8_WAIT_L(0); PG8_MMA(1, 0, At, B0); PG8_BAR; PG8_SCHED;
;             PG8_STAGE(PG8_SB(1, 1), b3 + hstepB, voffB);
;             PG8_WAIT_V(6); PG8_BAR; PG8_MMA(1, 1, At, B1); PG8_BAR;
	s_waitcnt lgkmcnt(7)
	v_mfma_f32_16x16x32_bf16 v[60:63], v[152:155], v[168:171], v[60:63]
	v_mfma_f32_16x16x32_bf16 v[56:59], v[160:163], v[168:171], v[56:59]
	s_waitcnt lgkmcnt(5)
	v_mfma_f32_16x16x32_bf16 v[44:47], v[152:155], v[176:179], v[44:47]
	v_mfma_f32_16x16x32_bf16 v[40:43], v[160:163], v[176:179], v[40:43]
	s_waitcnt lgkmcnt(3)
	v_mfma_f32_16x16x32_bf16 v[28:31], v[152:155], v[184:187], v[28:31]
	v_mfma_f32_16x16x32_bf16 v[24:27], v[160:163], v[184:187], v[24:27]
	s_waitcnt lgkmcnt(1)
	v_mfma_f32_16x16x32_bf16 v[12:15], v[152:155], v[192:195], v[12:15]
	v_mfma_f32_16x16x32_bf16 v[8:11], v[160:163], v[192:195], v[8:11]
	v_mfma_f32_16x16x32_bf16 v[60:63], v[156:159], v[172:175], v[60:63]
	s_add_u32 s8, s12, 0x160080
	s_addc_u32 s9, s13, 0
	v_mfma_f32_16x16x32_bf16 v[56:59], v[164:167], v[172:175], v[56:59]
	s_add_i32 s12, s14, s20
	v_mfma_f32_16x16x32_bf16 v[44:47], v[156:159], v[180:183], v[44:47]
	v_mfma_f32_16x16x32_bf16 v[40:43], v[164:167], v[180:183], v[40:43]
	v_mfma_f32_16x16x32_bf16 v[28:31], v[156:159], v[188:191], v[28:31]
	v_mfma_f32_16x16x32_bf16 v[24:27], v[164:167], v[188:191], v[24:27]
	s_waitcnt lgkmcnt(0)
	v_mfma_f32_16x16x32_bf16 v[12:15], v[156:159], v[196:199], v[12:15]
	v_mfma_f32_16x16x32_bf16 v[8:11], v[164:167], v[196:199], v[8:11]
	s_barrier
	s_setprio 0
	s_mov_b32 m0, s12
	s_nop 0
	global_load_lds_dwordx4 v132, s[8:9]
	s_add_i32 m0, s12, 0x2000
	s_nop 0
	global_load_lds_dwordx4 v128, s[8:9]
	s_waitcnt vmcnt(6)
	s_setprio 1
	s_barrier
	v_mfma_f32_16x16x32_bf16 v[52:55], v[200:203], v[168:171], v[52:55]
	v_mfma_f32_16x16x32_bf16 v[48:51], v[208:211], v[168:171], v[48:51]
	ds_read_b128 v[152:155], v149
	v_mfma_f32_16x16x32_bf16 v[36:39], v[200:203], v[176:179], v[36:39]
	v_mfma_f32_16x16x32_bf16 v[32:35], v[208:211], v[176:179], v[32:35]
	ds_read_b128 v[156:159], v149 offset:1024
	v_mfma_f32_16x16x32_bf16 v[20:23], v[200:203], v[184:187], v[20:23]
	v_mfma_f32_16x16x32_bf16 v[16:19], v[208:211], v[184:187], v[16:19]
	ds_read_b128 v[160:163], v149 offset:2048
	v_mfma_f32_16x16x32_bf16 v[4:7], v[200:203], v[192:195], v[4:7]
	v_mfma_f32_16x16x32_bf16 v[0:3], v[208:211], v[192:195], v[0:3]
	ds_read_b128 v[164:167], v149 offset:3072
	v_mfma_f32_16x16x32_bf16 v[52:55], v[204:207], v[172:175], v[52:55]
	s_add_i32 s48, s48, 2
	v_mfma_f32_16x16x32_bf16 v[48:51], v[212:215], v[172:175], v[48:51]
	s_add_u32 s38, s38, 0x100
	s_addc_u32 s39, s39, 0
	v_mfma_f32_16x16x32_bf16 v[36:39], v[204:207], v[180:183], v[36:39]
	s_cmpk_gt_u32 s48, 0x55
	v_mfma_f32_16x16x32_bf16 v[32:35], v[212:215], v[180:183], v[32:35]
	s_mov_b64 s[8:9], s[10:11]
	v_mfma_f32_16x16x32_bf16 v[20:23], v[204:207], v[188:191], v[20:23]
	v_mfma_f32_16x16x32_bf16 v[16:19], v[212:215], v[188:191], v[16:19]
	v_mfma_f32_16x16x32_bf16 v[4:7], v[204:207], v[196:199], v[4:7]
	v_mfma_f32_16x16x32_bf16 v[0:3], v[212:215], v[196:199], v[0:3]
	s_barrier
	s_setprio 0
	s_cbranch_scc0 .LBB1_2653
	s_waitcnt lgkmcnt(0)
	v_mov_b32_e32 v144, v147
	v_mov_b32_e32 v152, v146
	s_lshl_b32 s2, s2, 8
	s_lshl_b32 s8, s37, 8
	s_add_i32 s2, s2, s27
	s_or_b32 s8, s8, s28
	v_add_u32_e32 v152, s2, v152
	v_lshl_add_u32 v144, v144, 3, s8
	v_ashrrev_i32_e32 v153, 31, v152
	v_ashrrev_i32_e32 v145, 31, v144
	v_lshlrev_b64 v[152:153], 11, v[152:153]
	v_lshl_add_u64 v[144:145], v[152:153], 0, v[144:145]
	v_lshl_add_u64 v[156:157], v[144:145], 1, s[6:7]
	global_load_dwordx4 v[162:165], v[156:157], off
	global_load_dwordx4 v[166:169], v[156:157], off offset:256
	s_mov_b64 s[98:99], 0x10000
	v_lshl_add_u64 v[154:155], v[156:157], 0, s[98:99]
	global_load_dwordx4 v[170:173], v[154:155], off
	global_load_dwordx4 v[174:177], v[154:155], off offset:256
	s_mov_b64 s[98:99], 0x20000
	v_lshl_add_u64 v[154:155], v[156:157], 0, s[98:99]
	global_load_dwordx4 v[178:181], v[154:155], off
	global_load_dwordx4 v[182:185], v[154:155], off offset:256
	s_mov_b64 s[98:99], 0x30000
	v_lshl_add_u64 v[154:155], v[156:157], 0, s[98:99]
	global_load_dwordx4 v[186:189], v[154:155], off
	global_load_dwordx4 v[190:193], v[154:155], off offset:256
	s_mov_b64 s[98:99], 0x80000
	v_lshl_add_u64 v[154:155], v[156:157], 0, s[98:99]
	global_load_dwordx4 v[194:197], v[154:155], off
	global_load_dwordx4 v[198:201], v[154:155], off offset:256
	s_mov_b64 s[98:99], 0x90000
	v_lshl_add_u64 v[154:155], v[156:157], 0, s[98:99]
	global_load_dwordx4 v[202:205], v[154:155], off
	global_load_dwordx4 v[206:209], v[154:155], off offset:256
	s_mov_b64 s[98:99], 0xa0000
	v_lshl_add_u64 v[154:155], v[156:157], 0, s[98:99]
	global_load_dwordx4 v[210:213], v[154:155], off
	global_load_dwordx4 v[248:251], v[154:155], off offset:256
	s_mov_b64 s[98:99], 0xb0000
	v_lshl_add_u64 v[154:155], v[156:157], 0, s[98:99]
	global_load_dwordx4 v[252:255], v[154:155], off
	s_waitcnt vmcnt(14)
	s_nop 1
	v_mov_b32_e32 v152, v162
	v_mov_b32_e32 v153, v163
	v_mov_b32_e32 v154, v164
	v_mov_b32_e32 v155, v165
	s_mov_b64 s[8:9], 0x8000
	s_and_b64 vcc, exec, s[40:41]
	s_mov_b32 s37, s35
	s_mov_b32 s2, s36
	s_mov_b64 s[10:11], s[44:45]
	s_waitcnt lgkmcnt(0)
	v_lshlrev_b32_e32 v158, 16, v152
	v_and_b32_e32 v159, 0xffff0000, v152
	v_lshlrev_b32_e32 v152, 16, v153
	v_and_b32_e32 v153, 0xffff0000, v153
	v_lshlrev_b32_e32 v160, 16, v154
	v_and_b32_e32 v161, 0xffff0000, v154
	v_lshlrev_b32_e32 v154, 16, v155
	v_and_b32_e32 v155, 0xffff0000, v155
	v_pk_add_f32 v[126:127], v[126:127], v[152:153]
	v_pk_add_f32 v[124:125], v[124:125], v[158:159]
	v_lshl_add_u64 v[152:153], v[144:145], 2, s[4:5]
	v_pk_add_f32 v[122:123], v[122:123], v[154:155]
	v_pk_add_f32 v[120:121], v[120:121], v[160:161]
	global_store_dwordx4 v[152:153], v[124:127], off
	global_store_dwordx4 v[152:153], v[120:123], off offset:16
	s_waitcnt vmcnt(15)
; DI unsigned pack2(float a, float b) { f32x2 v = {a, b}; hwbf16x2 r = __builtin_convertvector(v, hwbf16x2); return __builtin_bit_cast(unsigned, r); }
; DI float bflo(unsigned w) { return __uint_as_float(w << 16); }
; DI float bfhi(unsigned w) { return __uint_as_float(w & 0xffff0000u); }
;     DI void operator()(const f32x4 (&acc)[2][2][4][2], const Unit& u, int wr, int wc, int fr, int fq) const {
;     ...
;             for (int m = 0; m < 4; ++m) { const size_t ro = (size_t)(row0 + ai * HALF + m * 16) * D + col0;
; #pragma unroll
;                 for (int bj = 0; bj < 2; ++bj) {
;                     f32x4 x0, x1;
;                     if constexpr (IB) { const u32x4 w = *(const u32x4*)((const bf16_t*)Xin + ro + bj * HALF);
;                         x0 = (f32x4){bflo(w[0]), bfhi(w[0]), bflo(w[1]), bfhi(w[1])}; x1 = (f32x4){bflo(w[2]), bfhi(w[2]), bflo(w[3]), bfhi(w[3])}; }
;                     else { x0 = *(const f32x4*)((const float*)Xin + ro + bj * HALF); x1 = *(const f32x4*)((const float*)Xin + ro + bj * HALF + 4); }
;                     x0 += acc[ai][bj][m][0] * sc[bj][0]; x1 += acc[ai][bj][m][1] * sc[bj][1];
;                     if constexpr (OB) { u32x4 o; o[0] = pack2(x0[0], x0[1]); o[1] = pack2(x0[2], x0[3]); o[2] = pack2(x1[0], x1[1]); o[3] = pack2(x1[2], x1[3]);
;                         *(u32x4*)((bf16_t*)Xout + ro + bj * HALF) = o; }
;                     else { *(f32x4*)((float*)Xout + ro + bj * HALF) = x0; *(f32x4*)((float*)Xout + ro + bj * HALF + 4) = x1; } } }
	s_nop 1
	v_mov_b32_e32 v120, v166
	v_mov_b32_e32 v121, v167
	v_mov_b32_e32 v122, v168
	v_mov_b32_e32 v123, v169
	s_waitcnt lgkmcnt(0)
	v_lshlrev_b32_e32 v124, 16, v120
	v_and_b32_e32 v125, 0xffff0000, v120
	v_lshlrev_b32_e32 v120, 16, v121
	v_and_b32_e32 v121, 0xffff0000, v121
	v_lshlrev_b32_e32 v126, 16, v122
	v_and_b32_e32 v127, 0xffff0000, v122
	v_lshlrev_b32_e32 v122, 16, v123
	v_and_b32_e32 v123, 0xffff0000, v123
	v_pk_add_f32 v[118:119], v[118:119], v[120:121]
	v_pk_add_f32 v[116:117], v[116:117], v[124:125]
	v_pk_add_f32 v[114:115], v[114:115], v[122:123]
	v_pk_add_f32 v[112:113], v[112:113], v[126:127]
	global_store_dwordx4 v[152:153], v[116:119], off offset:512
	global_store_dwordx4 v[152:153], v[112:115], off offset:528
	s_nop 0
	v_lshl_add_u64 v[116:117], v[144:145], 0, s[8:9]
	v_lshl_add_u64 v[118:119], v[116:117], 1, s[6:7]
	s_waitcnt vmcnt(16)
	s_nop 1
	v_mov_b32_e32 v112, v170
	v_mov_b32_e32 v113, v171
	v_mov_b32_e32 v114, v172
	v_mov_b32_e32 v115, v173
	s_mov_b64 s[8:9], 0x10000
	s_waitcnt lgkmcnt(0)
	v_lshlrev_b32_e32 v120, 16, v112
	v_and_b32_e32 v121, 0xffff0000, v112
	v_lshlrev_b32_e32 v112, 16, v113
	v_and_b32_e32 v113, 0xffff0000, v113
	v_lshlrev_b32_e32 v122, 16, v114
	v_and_b32_e32 v123, 0xffff0000, v114
	v_lshlrev_b32_e32 v114, 16, v115
	v_and_b32_e32 v115, 0xffff0000, v115
	v_pk_add_f32 v[110:111], v[110:111], v[112:113]
	v_pk_add_f32 v[108:109], v[108:109], v[120:121]
	v_lshl_add_u64 v[112:113], v[116:117], 2, s[4:5]
	v_pk_add_f32 v[106:107], v[106:107], v[114:115]
	v_pk_add_f32 v[104:105], v[104:105], v[122:123]
	global_store_dwordx4 v[112:113], v[108:111], off
	global_store_dwordx4 v[112:113], v[104:107], off offset:16
	s_waitcnt vmcnt(17)
	s_nop 1
	v_mov_b32_e32 v104, v174
	v_mov_b32_e32 v105, v175
	v_mov_b32_e32 v106, v176
	v_mov_b32_e32 v107, v177
	s_waitcnt lgkmcnt(0)
	v_lshlrev_b32_e32 v108, 16, v104
	v_and_b32_e32 v109, 0xffff0000, v104
	v_lshlrev_b32_e32 v104, 16, v105
	v_and_b32_e32 v105, 0xffff0000, v105
	v_lshlrev_b32_e32 v110, 16, v106
	v_and_b32_e32 v111, 0xffff0000, v106
	v_lshlrev_b32_e32 v106, 16, v107
	v_and_b32_e32 v107, 0xffff0000, v107
	v_pk_add_f32 v[102:103], v[102:103], v[104:105]
	v_pk_add_f32 v[100:101], v[100:101], v[108:109]
	v_pk_add_f32 v[98:99], v[98:99], v[106:107]
	v_pk_add_f32 v[96:97], v[96:97], v[110:111]
	global_store_dwordx4 v[112:113], v[100:103], off offset:512
	global_store_dwordx4 v[112:113], v[96:99], off offset:528
	s_nop 0
	v_lshl_add_u64 v[100:101], v[144:145], 0, s[8:9]
	v_lshl_add_u64 v[102:103], v[100:101], 1, s[6:7]
	s_waitcnt vmcnt(18)
	s_nop 1
	v_mov_b32_e32 v96, v178
	v_mov_b32_e32 v97, v179
	v_mov_b32_e32 v98, v180
	v_mov_b32_e32 v99, v181
	s_mov_b64 s[8:9], 0x18000
	s_waitcnt lgkmcnt(0)
	v_lshlrev_b32_e32 v104, 16, v96
	v_and_b32_e32 v105, 0xffff0000, v96
	v_lshlrev_b32_e32 v96, 16, v97
	v_and_b32_e32 v97, 0xffff0000, v97
	v_lshlrev_b32_e32 v106, 16, v98
	v_and_b32_e32 v107, 0xffff0000, v98
	v_lshlrev_b32_e32 v98, 16, v99
	v_and_b32_e32 v99, 0xffff0000, v99
	v_pk_add_f32 v[94:95], v[94:95], v[96:97]
	v_pk_add_f32 v[92:93], v[92:93], v[104:105]
	v_lshl_add_u64 v[96:97], v[100:101], 2, s[4:5]
	v_pk_add_f32 v[90:91], v[90:91], v[98:99]
	v_pk_add_f32 v[88:89], v[88:89], v[106:107]
	global_store_dwordx4 v[96:97], v[92:95], off
	global_store_dwordx4 v[96:97], v[88:91], off offset:16
	s_waitcnt vmcnt(19)
	s_nop 1
	v_mov_b32_e32 v88, v182
	v_mov_b32_e32 v89, v183
	v_mov_b32_e32 v90, v184
	v_mov_b32_e32 v91, v185
	s_waitcnt lgkmcnt(0)
	v_lshlrev_b32_e32 v92, 16, v88
	v_and_b32_e32 v93, 0xffff0000, v88
	v_lshlrev_b32_e32 v88, 16, v89
	v_and_b32_e32 v89, 0xffff0000, v89
	v_lshlrev_b32_e32 v94, 16, v90
	v_and_b32_e32 v95, 0xffff0000, v90
	v_lshlrev_b32_e32 v90, 16, v91
	v_and_b32_e32 v91, 0xffff0000, v91
	v_pk_add_f32 v[86:87], v[86:87], v[88:89]
	v_pk_add_f32 v[84:85], v[84:85], v[92:93]
	v_pk_add_f32 v[82:83], v[82:83], v[90:91]
	v_pk_add_f32 v[80:81], v[80:81], v[94:95]
	global_store_dwordx4 v[96:97], v[84:87], off offset:512
	global_store_dwordx4 v[96:97], v[80:83], off offset:528
	s_nop 0
	v_lshl_add_u64 v[84:85], v[144:145], 0, s[8:9]
	v_lshl_add_u64 v[86:87], v[84:85], 1, s[6:7]
	s_waitcnt vmcnt(20)
	s_nop 1
	v_mov_b32_e32 v80, v186
	v_mov_b32_e32 v81, v187
	v_mov_b32_e32 v82, v188
	v_mov_b32_e32 v83, v189
	s_mov_b64 s[8:9], 0x40000
	s_waitcnt lgkmcnt(0)
	v_lshlrev_b32_e32 v88, 16, v80
	v_and_b32_e32 v89, 0xffff0000, v80
	v_lshlrev_b32_e32 v80, 16, v81
	v_and_b32_e32 v81, 0xffff0000, v81
	v_lshlrev_b32_e32 v90, 16, v82
	v_and_b32_e32 v91, 0xffff0000, v82
	v_lshlrev_b32_e32 v82, 16, v83
	v_and_b32_e32 v83, 0xffff0000, v83
	v_pk_add_f32 v[78:79], v[78:79], v[80:81]
	v_pk_add_f32 v[76:77], v[76:77], v[88:89]
	v_lshl_add_u64 v[80:81], v[84:85], 2, s[4:5]
	v_pk_add_f32 v[74:75], v[74:75], v[82:83]
	v_pk_add_f32 v[72:73], v[72:73], v[90:91]
	global_store_dwordx4 v[80:81], v[76:79], off
	global_store_dwordx4 v[80:81], v[72:75], off offset:16
	s_waitcnt vmcnt(21)
	s_nop 1
	v_mov_b32_e32 v72, v190
	v_mov_b32_e32 v73, v191
	v_mov_b32_e32 v74, v192
	v_mov_b32_e32 v75, v193
	s_waitcnt lgkmcnt(0)
	v_lshlrev_b32_e32 v76, 16, v72
	v_and_b32_e32 v77, 0xffff0000, v72
	v_lshlrev_b32_e32 v72, 16, v73
	v_and_b32_e32 v73, 0xffff0000, v73
	v_lshlrev_b32_e32 v78, 16, v74
	v_and_b32_e32 v79, 0xffff0000, v74
	v_lshlrev_b32_e32 v74, 16, v75
	v_and_b32_e32 v75, 0xffff0000, v75
	v_pk_add_f32 v[70:71], v[70:71], v[72:73]
	v_pk_add_f32 v[68:69], v[68:69], v[76:77]
	v_pk_add_f32 v[66:67], v[66:67], v[74:75]
	v_pk_add_f32 v[64:65], v[64:65], v[78:79]
	global_store_dwordx4 v[80:81], v[68:71], off offset:512
	global_store_dwordx4 v[80:81], v[64:67], off offset:528
	s_nop 0
	v_lshl_add_u64 v[68:69], v[144:145], 0, s[8:9]
	v_lshl_add_u64 v[70:71], v[68:69], 1, s[6:7]
	s_waitcnt vmcnt(22)
; DI unsigned pack2(float a, float b) { f32x2 v = {a, b}; hwbf16x2 r = __builtin_convertvector(v, hwbf16x2); return __builtin_bit_cast(unsigned, r); }
; DI float bflo(unsigned w) { return __uint_as_float(w << 16); }
; DI float bfhi(unsigned w) { return __uint_as_float(w & 0xffff0000u); }
;     DI const char* a(const Unit& u) const { return (const char*)(A + (size_t)u.pm * BM * lda); }
; #define PG8_BAR __builtin_amdgcn_s_barrier()
;     DI void operator()(const f32x4 (&acc)[2][2][4][2], const Unit& u, int wr, int wc, int fr, int fq) const {
;     ...
;             for (int m = 0; m < 4; ++m) { const size_t ro = (size_t)(row0 + ai * HALF + m * 16) * D + col0;
; #pragma unroll
;                 for (int bj = 0; bj < 2; ++bj) {
;                     f32x4 x0, x1;
;                     if constexpr (IB) { const u32x4 w = *(const u32x4*)((const bf16_t*)Xin + ro + bj * HALF);
;                         x0 = (f32x4){bflo(w[0]), bfhi(w[0]), bflo(w[1]), bfhi(w[1])}; x1 = (f32x4){bflo(w[2]), bfhi(w[2]), bflo(w[3]), bfhi(w[3])}; }
;                     else { x0 = *(const f32x4*)((const float*)Xin + ro + bj * HALF); x1 = *(const f32x4*)((const float*)Xin + ro + bj * HALF + 4); }
;                     x0 += acc[ai][bj][m][0] * sc[bj][0]; x1 += acc[ai][bj][m][1] * sc[bj][1];
;                     if constexpr (OB) { u32x4 o; o[0] = pack2(x0[0], x0[1]); o[1] = pack2(x0[2], x0[3]); o[2] = pack2(x1[0], x1[1]); o[3] = pack2(x1[2], x1[3]);
;                         *(u32x4*)((bf16_t*)Xout + ro + bj * HALF) = o; }
;                     else { *(f32x4*)((float*)Xout + ro + bj * HALF) = x0; *(f32x4*)((float*)Xout + ro + bj * HALF + 4) = x1; } } }
; template <class Map, class Epi>
; DI void gemm_phase(LAS unsigned char* lds, const Map& MP, const Epi& E, const int nM, const int nN, const int K, const int lda, const int ldb) {
;     ...
;         { int frr = fr, fqq = fq; asm volatile("" : "+v"(frr), "+v"(fqq)); E(acc, cur, wr, wc, frr, fqq); }
;         if (!has_next) break;
; #pragma unroll
;         for (int a = 0; a < 2; ++a)
; #pragma unroll
;             for (int b = 0; b < 2; ++b)
; #pragma unroll
;                 for (int m = 0; m < 4; ++m)
; #pragma unroll
;                     for (int n = 0; n < 2; ++n) acc[a][b][m][n] = (f32x4){0.f, 0.f, 0.f, 0.f};
;         cur = nxt; cA = nA; cB = nB; ++ui;
;     }
;     PG8_WAIT_V(0);
;     if (wr == 0) PG8_BAR;
;     PG8_BAR;
	s_nop 1
	v_mov_b32_e32 v64, v194
	v_mov_b32_e32 v65, v195
	v_mov_b32_e32 v66, v196
	v_mov_b32_e32 v67, v197
	s_mov_b64 s[8:9], 0x48000
	s_waitcnt lgkmcnt(0)
	v_lshlrev_b32_e32 v72, 16, v64
	v_and_b32_e32 v73, 0xffff0000, v64
	v_lshlrev_b32_e32 v64, 16, v65
	v_and_b32_e32 v65, 0xffff0000, v65
	v_lshlrev_b32_e32 v74, 16, v66
	v_and_b32_e32 v75, 0xffff0000, v66
	v_lshlrev_b32_e32 v66, 16, v67
	v_and_b32_e32 v67, 0xffff0000, v67
	v_pk_add_f32 v[62:63], v[62:63], v[64:65]
	v_pk_add_f32 v[60:61], v[60:61], v[72:73]
	v_lshl_add_u64 v[64:65], v[68:69], 2, s[4:5]
	v_pk_add_f32 v[58:59], v[58:59], v[66:67]
	v_pk_add_f32 v[56:57], v[56:57], v[74:75]
	global_store_dwordx4 v[64:65], v[60:63], off
	global_store_dwordx4 v[64:65], v[56:59], off offset:16
	s_waitcnt vmcnt(23)
	s_nop 1
	v_mov_b32_e32 v56, v198
	v_mov_b32_e32 v57, v199
	v_mov_b32_e32 v58, v200
	v_mov_b32_e32 v59, v201
	s_waitcnt lgkmcnt(0)
	v_lshlrev_b32_e32 v60, 16, v56
	v_and_b32_e32 v61, 0xffff0000, v56
	v_lshlrev_b32_e32 v56, 16, v57
	v_and_b32_e32 v57, 0xffff0000, v57
	v_lshlrev_b32_e32 v62, 16, v58
	v_and_b32_e32 v63, 0xffff0000, v58
	v_lshlrev_b32_e32 v58, 16, v59
	v_and_b32_e32 v59, 0xffff0000, v59
	v_pk_add_f32 v[54:55], v[54:55], v[56:57]
	v_pk_add_f32 v[52:53], v[52:53], v[60:61]
	v_pk_add_f32 v[50:51], v[50:51], v[58:59]
	v_pk_add_f32 v[48:49], v[48:49], v[62:63]
	global_store_dwordx4 v[64:65], v[52:55], off offset:512
	global_store_dwordx4 v[64:65], v[48:51], off offset:528
	s_nop 0
	v_lshl_add_u64 v[52:53], v[144:145], 0, s[8:9]
	v_lshl_add_u64 v[54:55], v[52:53], 1, s[6:7]
	s_waitcnt vmcnt(24)
	s_nop 1
	v_mov_b32_e32 v48, v202
	v_mov_b32_e32 v49, v203
	v_mov_b32_e32 v50, v204
	v_mov_b32_e32 v51, v205
	s_mov_b64 s[8:9], 0x50000
	s_waitcnt lgkmcnt(0)
	v_lshlrev_b32_e32 v56, 16, v48
	v_and_b32_e32 v57, 0xffff0000, v48
	v_lshlrev_b32_e32 v48, 16, v49
	v_and_b32_e32 v49, 0xffff0000, v49
	v_lshlrev_b32_e32 v58, 16, v50
	v_and_b32_e32 v59, 0xffff0000, v50
	v_lshlrev_b32_e32 v50, 16, v51
	v_and_b32_e32 v51, 0xffff0000, v51
	v_pk_add_f32 v[46:47], v[46:47], v[48:49]
	v_pk_add_f32 v[44:45], v[44:45], v[56:57]
	v_lshl_add_u64 v[48:49], v[52:53], 2, s[4:5]
	v_pk_add_f32 v[42:43], v[42:43], v[50:51]
	v_pk_add_f32 v[40:41], v[40:41], v[58:59]
	global_store_dwordx4 v[48:49], v[44:47], off
	global_store_dwordx4 v[48:49], v[40:43], off offset:16
	s_waitcnt vmcnt(25)
	s_nop 1
	v_mov_b32_e32 v40, v206
	v_mov_b32_e32 v41, v207
	v_mov_b32_e32 v42, v208
	v_mov_b32_e32 v43, v209
	s_waitcnt lgkmcnt(0)
	v_lshlrev_b32_e32 v44, 16, v40
	v_and_b32_e32 v45, 0xffff0000, v40
	v_lshlrev_b32_e32 v40, 16, v41
	v_and_b32_e32 v41, 0xffff0000, v41
	v_lshlrev_b32_e32 v46, 16, v42
	v_and_b32_e32 v47, 0xffff0000, v42
	v_lshlrev_b32_e32 v42, 16, v43
	v_and_b32_e32 v43, 0xffff0000, v43
	v_pk_add_f32 v[38:39], v[38:39], v[40:41]
	v_pk_add_f32 v[36:37], v[36:37], v[44:45]
	v_pk_add_f32 v[34:35], v[34:35], v[42:43]
	v_pk_add_f32 v[32:33], v[32:33], v[46:47]
	global_store_dwordx4 v[48:49], v[36:39], off offset:512
	global_store_dwordx4 v[48:49], v[32:35], off offset:528
	s_nop 0
	v_lshl_add_u64 v[36:37], v[144:145], 0, s[8:9]
	v_lshl_add_u64 v[38:39], v[36:37], 1, s[6:7]
	s_waitcnt vmcnt(26)
	s_nop 1
	v_mov_b32_e32 v32, v210
	v_mov_b32_e32 v33, v211
	v_mov_b32_e32 v34, v212
	v_mov_b32_e32 v35, v213
	s_mov_b64 s[8:9], 0x58000
	s_waitcnt lgkmcnt(0)
	v_lshlrev_b32_e32 v40, 16, v32
	v_and_b32_e32 v41, 0xffff0000, v32
	v_lshlrev_b32_e32 v32, 16, v33
	v_and_b32_e32 v33, 0xffff0000, v33
	v_lshlrev_b32_e32 v42, 16, v34
	v_and_b32_e32 v43, 0xffff0000, v34
	v_lshlrev_b32_e32 v34, 16, v35
	v_and_b32_e32 v35, 0xffff0000, v35
	v_pk_add_f32 v[30:31], v[30:31], v[32:33]
	v_pk_add_f32 v[28:29], v[28:29], v[40:41]
	v_lshl_add_u64 v[32:33], v[36:37], 2, s[4:5]
	v_pk_add_f32 v[26:27], v[26:27], v[34:35]
	v_pk_add_f32 v[24:25], v[24:25], v[42:43]
	global_store_dwordx4 v[32:33], v[28:31], off
	global_store_dwordx4 v[32:33], v[24:27], off offset:16
	s_waitcnt vmcnt(27)
	s_nop 1
	v_mov_b32_e32 v24, v248
	v_mov_b32_e32 v25, v249
	v_mov_b32_e32 v26, v250
	v_mov_b32_e32 v27, v251
	s_waitcnt lgkmcnt(0)
	v_lshlrev_b32_e32 v28, 16, v24
	v_and_b32_e32 v29, 0xffff0000, v24
	v_lshlrev_b32_e32 v24, 16, v25
	v_and_b32_e32 v25, 0xffff0000, v25
	v_lshlrev_b32_e32 v30, 16, v26
	v_and_b32_e32 v31, 0xffff0000, v26
	v_lshlrev_b32_e32 v26, 16, v27
	v_and_b32_e32 v27, 0xffff0000, v27
	v_pk_add_f32 v[22:23], v[22:23], v[24:25]
	v_pk_add_f32 v[20:21], v[20:21], v[28:29]
	v_pk_add_f32 v[18:19], v[18:19], v[26:27]
	v_pk_add_f32 v[16:17], v[16:17], v[30:31]
	global_store_dwordx4 v[32:33], v[20:23], off offset:512
	global_store_dwordx4 v[32:33], v[16:19], off offset:528
	s_nop 0
	v_lshl_add_u64 v[20:21], v[144:145], 0, s[8:9]
	v_lshl_add_u64 v[22:23], v[20:21], 1, s[6:7]
	s_waitcnt vmcnt(28)
	s_nop 1
	v_mov_b32_e32 v16, v252
	v_mov_b32_e32 v17, v253
	v_mov_b32_e32 v18, v254
	v_mov_b32_e32 v19, v255
	s_mov_b64 s[8:9], s[42:43]
	s_waitcnt lgkmcnt(0)
	v_lshlrev_b32_e32 v24, 16, v16
	v_and_b32_e32 v25, 0xffff0000, v16
	v_lshlrev_b32_e32 v16, 16, v17
	v_and_b32_e32 v17, 0xffff0000, v17
	v_lshlrev_b32_e32 v26, 16, v18
	v_and_b32_e32 v27, 0xffff0000, v18
	v_lshlrev_b32_e32 v18, 16, v19
	v_and_b32_e32 v19, 0xffff0000, v19
	v_pk_add_f32 v[14:15], v[14:15], v[16:17]
	v_pk_add_f32 v[12:13], v[12:13], v[24:25]
	v_lshl_add_u64 v[16:17], v[20:21], 2, s[4:5]
	v_pk_add_f32 v[10:11], v[10:11], v[18:19]
	v_pk_add_f32 v[8:9], v[8:9], v[26:27]
	global_store_dwordx4 v[16:17], v[12:15], off
	global_store_dwordx4 v[16:17], v[8:11], off offset:16
	global_load_dwordx4 v[8:11], v[22:23], off offset:256
	s_waitcnt vmcnt(0) lgkmcnt(0)
	v_lshlrev_b32_e32 v12, 16, v8
	v_and_b32_e32 v13, 0xffff0000, v8
	v_lshlrev_b32_e32 v8, 16, v9
	v_and_b32_e32 v9, 0xffff0000, v9
	v_lshlrev_b32_e32 v14, 16, v10
	v_and_b32_e32 v15, 0xffff0000, v10
	v_lshlrev_b32_e32 v10, 16, v11
	v_and_b32_e32 v11, 0xffff0000, v11
	v_pk_add_f32 v[6:7], v[6:7], v[8:9]
	v_pk_add_f32 v[4:5], v[4:5], v[12:13]
	v_pk_add_f32 v[2:3], v[2:3], v[10:11]
	v_pk_add_f32 v[0:1], v[0:1], v[14:15]
	global_store_dwordx4 v[16:17], v[4:7], off offset:512
	global_store_dwordx4 v[16:17], v[0:3], off offset:528
	s_cbranch_vccz .LBB1_2646
	s_waitcnt vmcnt(0)
	s_cmpk_gt_u32 s3, 0xff
	s_cbranch_scc1 .LBB1_2657
	s_barrier
